# K-loop MFMA order: accumulator pairs walked in a snake so that every consecutive MFMA pair shares the accumulator or one source fragment
# speedup vs baseline: 1.0158x; 1.0104x over previous
; #define PG8_STAGE(bufoff, gbase, voff) do { _Pragma("unroll") for (int _i = 0; _i < 2; ++_i) \
;         __builtin_amdgcn_global_load_lds((const unsigned*)((const char*)(gbase) + (voff)[_i]), (PG8_LAS unsigned*)(lds + (bufoff) + ldsw + _i * 8192), 16, 0, 0); } while (0)
; #define PG8_LDA(dst, b, h) do { _Pragma("unroll") for (int m = 0; m < 4; ++m) _Pragma("unroll") for (int k = 0; k < 2; ++k) dst[m][k] = *(const PG8_LAS bf16x8*)(lds + PG8_SA(b, h) + aoff + m * 2048 + k * 1024); } while (0)
; #define PG8_LDB(dst, b, h) do { _Pragma("unroll") for (int n = 0; n < 2; ++n) _Pragma("unroll") for (int k = 0; k < 2; ++k) dst[n][k] = *(const PG8_LAS bf16x8*)(lds + PG8_SB(b, h) + boff + n * 2048 + k * 1024); } while (0)
; #define PG8_MMA(ai, bj, At, Bt) do { __builtin_amdgcn_s_setprio(1); _Pragma("unroll") for (int m = 0; m < 4; ++m) _Pragma("unroll") for (int n = 0; n < 2; ++n) _Pragma("unroll") for (int k = 0; k < 2; ++k) \
;         acc[ai][bj][m][n] = __builtin_amdgcn_mfma_f32_16x16x32_bf16(Bt[n][k], At[m][k], acc[ai][bj][m][n], 0, 0, 0); __builtin_amdgcn_s_setprio(0); } while (0)
; #define PG8_WAIT_V(n) asm volatile("s_waitcnt vmcnt(" #n ")" ::: "memory")
; #define PG8_WAIT_L(n) asm volatile("s_waitcnt lgkmcnt(" #n ")" ::: "memory")
; #define PG8_BAR __builtin_amdgcn_s_barrier()
; template <class Epi, class Sched, bool ALIGN_EPI = false, bool SP2 = false>
; __device__ __forceinline__ void gemm_phase(PG8_LAS unsigned char* lds, const Gemm g, const Sched& S, const Epi& E) {
;     ...
;             const char* a1 = cA + (size_t)(t + 1) * kstep;
;             const char* a2 = last ? nA : cA + (size_t)(t + 2) * kstep; const char* b2 = last ? nB : cB + (size_t)(t + 2) * kstep;
;             const char* a3 = a2 + kstep; const char* b3 = b2 + kstep;
;             if (last && has_next) S.a_ready(nxt);
;             if constexpr (SP2) {
;             PG8_LDB(B0, 0, 0); PG8_LDB(B1, 0, 1); PG8_SCHED; PG8_LDA(At, 0, 0); PG8_STAGE(PG8_SA(1, 1), a1 + hstep, voffA);
;             PG8_WAIT_V(8); PG8_WAIT_L(0); PG8_BAR; PG8_MMA(0, 0, At, B0); PG8_MMA(0, 1, At, B1); PG8_BAR; PG8_SCHED;
;             PG8_LDA(At, 0, 1); PG8_STAGE(PG8_SB(0, 0), b2, voffB); PG8_STAGE(PG8_SB(0, 1), b2 + hstep, voffB); PG8_STAGE(PG8_SA(0, 0), a2, voffA);
;             PG8_WAIT_V(8); PG8_WAIT_L(0); PG8_BAR; PG8_MMA(1, 0, At, B0); PG8_MMA(1, 1, At, B1); PG8_BAR; PG8_SCHED;
.LBB0_110:
	ds_read_b128 v[136:139], v161
	ds_read_b128 v[140:143], v161 offset:1024
	ds_read_b128 v[176:179], v161 offset:2048
	ds_read_b128 v[180:183], v161 offset:3072
	ds_read_b128 v[184:187], v162
	ds_read_b128 v[202:205], v162 offset:1024
	ds_read_b128 v[206:209], v162 offset:2048
	ds_read_b128 v[210:213], v162 offset:3072
	s_add_u32 s28, s52, 0xfff80080
	s_addc_u32 s29, s53, -1
	s_cmp_eq_u32 s74, 28
	s_cselect_b32 s49, s25, s29
	s_cselect_b32 s48, s34, s28
	s_cselect_b32 s29, s23, s73
	s_cselect_b32 s28, s35, s72
	v_lshl_add_u64 v[246:247], s[52:53], 0, v[128:129]
	s_add_i32 m0, s9, 0xc000
	ds_read_b128 v[214:217], v163
	ds_read_b128 v[218:221], v163 offset:1024
	ds_read_b128 v[222:225], v163 offset:2048
	ds_read_b128 v[226:229], v163 offset:3072
	ds_read_b128 v[230:233], v163 offset:4096
	ds_read_b128 v[234:237], v163 offset:5120
	ds_read_b128 v[238:241], v163 offset:6144
	ds_read_b128 v[242:245], v163 offset:7168
	global_load_lds_dwordx4 v[246:247], off
	v_lshl_add_u64 v[246:247], s[52:53], 0, v[130:131]
	s_add_i32 m0, s9, 0xe000
	s_nop 0
	global_load_lds_dwordx4 v[246:247], off
	s_waitcnt vmcnt(8)
	s_waitcnt lgkmcnt(0)
	s_barrier
	s_setprio 1
	s_waitcnt lgkmcnt(0)
	v_mfma_f32_16x16x32_bf16 v[124:127], v[136:139], v[214:217], v[124:127]
	v_mfma_f32_16x16x32_bf16 v[124:127], v[140:143], v[218:221], v[124:127]
	v_mfma_f32_16x16x32_bf16 v[120:123], v[180:183], v[218:221], v[120:123]
	v_mfma_f32_16x16x32_bf16 v[120:123], v[176:179], v[214:217], v[120:123]
	v_mfma_f32_16x16x32_bf16 v[104:107], v[176:179], v[222:225], v[104:107]
	v_mfma_f32_16x16x32_bf16 v[104:107], v[180:183], v[226:229], v[104:107]
	v_mfma_f32_16x16x32_bf16 v[108:111], v[140:143], v[226:229], v[108:111]
	v_mfma_f32_16x16x32_bf16 v[108:111], v[136:139], v[222:225], v[108:111]
	v_mfma_f32_16x16x32_bf16 v[96:99], v[136:139], v[230:233], v[96:99]
	v_mfma_f32_16x16x32_bf16 v[96:99], v[140:143], v[234:237], v[96:99]
	v_mfma_f32_16x16x32_bf16 v[88:91], v[180:183], v[234:237], v[88:91]
	v_mfma_f32_16x16x32_bf16 v[88:91], v[176:179], v[230:233], v[88:91]
	v_mfma_f32_16x16x32_bf16 v[72:75], v[176:179], v[238:241], v[72:75]
	v_mfma_f32_16x16x32_bf16 v[72:75], v[180:183], v[242:245], v[72:75]
	v_mfma_f32_16x16x32_bf16 v[80:83], v[140:143], v[242:245], v[80:83]
	v_mfma_f32_16x16x32_bf16 v[80:83], v[136:139], v[238:241], v[80:83]
	s_setprio 0
	s_setprio 1
	v_mfma_f32_16x16x32_bf16 v[116:119], v[184:187], v[214:217], v[116:119]
	v_mfma_f32_16x16x32_bf16 v[116:119], v[202:205], v[218:221], v[116:119]
	v_mfma_f32_16x16x32_bf16 v[112:115], v[210:213], v[218:221], v[112:115]
	v_mfma_f32_16x16x32_bf16 v[112:115], v[206:209], v[214:217], v[112:115]
	v_mfma_f32_16x16x32_bf16 v[92:95], v[206:209], v[222:225], v[92:95]
	v_mfma_f32_16x16x32_bf16 v[92:95], v[210:213], v[226:229], v[92:95]
	v_mfma_f32_16x16x32_bf16 v[100:103], v[202:205], v[226:229], v[100:103]
	v_mfma_f32_16x16x32_bf16 v[100:103], v[184:187], v[222:225], v[100:103]
	v_mfma_f32_16x16x32_bf16 v[84:87], v[184:187], v[230:233], v[84:87]
	v_mfma_f32_16x16x32_bf16 v[84:87], v[202:205], v[234:237], v[84:87]
	v_mfma_f32_16x16x32_bf16 v[76:79], v[210:213], v[234:237], v[76:79]
	v_mfma_f32_16x16x32_bf16 v[76:79], v[206:209], v[230:233], v[76:79]
	s_setprio 2
	s_barrier
	v_mfma_f32_16x16x32_bf16 v[64:67], v[206:209], v[238:241], v[64:67]
	v_mfma_f32_16x16x32_bf16 v[64:67], v[210:213], v[242:245], v[64:67]
	v_mfma_f32_16x16x32_bf16 v[68:71], v[202:205], v[242:245], v[68:71]
	v_mfma_f32_16x16x32_bf16 v[68:71], v[184:187], v[238:241], v[68:71]
	s_setprio 0
	s_add_i32 s75, s63, s45
	v_lshl_add_u64 v[246:247], s[28:29], 0, v[166:167]
	s_mov_b32 m0, s75
	ds_read_b128 v[214:217], v163 offset:16384
	ds_read_b128 v[218:221], v163 offset:17408
	ds_read_b128 v[222:225], v163 offset:18432
	ds_read_b128 v[226:229], v163 offset:19456
	ds_read_b128 v[230:233], v163 offset:20480
	ds_read_b128 v[234:237], v163 offset:21504
	ds_read_b128 v[238:241], v163 offset:22528
	ds_read_b128 v[242:245], v163 offset:23552
	global_load_lds_dwordx4 v[246:247], off
	s_add_i32 m0, s75, 0x2000
	s_add_u32 s76, s28, 0x80000
	v_lshl_add_u64 v[248:249], s[28:29], 0, v[170:171]
	s_addc_u32 s77, s29, 0
	s_add_i32 s75, s64, s45
	global_load_lds_dwordx4 v[248:249], off
	v_lshl_add_u64 v[250:251], s[76:77], 0, v[166:167]
	s_mov_b32 m0, s75
	v_lshl_add_u64 v[252:253], s[48:49], 0, v[168:169]
	global_load_lds_dwordx4 v[250:251], off
	v_lshl_add_u64 v[250:251], s[76:77], 0, v[170:171]
	s_add_i32 m0, s75, 0x2000
	s_nop 0
	global_load_lds_dwordx4 v[250:251], off
	v_lshl_add_u64 v[250:251], s[48:49], 0, v[164:165]
	s_mov_b32 m0, s9
	s_nop 0
	global_load_lds_dwordx4 v[250:251], off
	s_mov_b32 m0, s57
	s_nop 0
	global_load_lds_dwordx4 v[252:253], off
	s_waitcnt vmcnt(8)
	s_waitcnt lgkmcnt(0)
	s_barrier
; #define PG8_STAGE(bufoff, gbase, voff) do { _Pragma("unroll") for (int _i = 0; _i < 2; ++_i) \
;         __builtin_amdgcn_global_load_lds((const unsigned*)((const char*)(gbase) + (voff)[_i]), (PG8_LAS unsigned*)(lds + (bufoff) + ldsw + _i * 8192), 16, 0, 0); } while (0)
; #define PG8_LDA(dst, b, h) do { _Pragma("unroll") for (int m = 0; m < 4; ++m) _Pragma("unroll") for (int k = 0; k < 2; ++k) dst[m][k] = *(const PG8_LAS bf16x8*)(lds + PG8_SA(b, h) + aoff + m * 2048 + k * 1024); } while (0)
; #define PG8_LDB(dst, b, h) do { _Pragma("unroll") for (int n = 0; n < 2; ++n) _Pragma("unroll") for (int k = 0; k < 2; ++k) dst[n][k] = *(const PG8_LAS bf16x8*)(lds + PG8_SB(b, h) + boff + n * 2048 + k * 1024); } while (0)
; #define PG8_MMA(ai, bj, At, Bt) do { __builtin_amdgcn_s_setprio(1); _Pragma("unroll") for (int m = 0; m < 4; ++m) _Pragma("unroll") for (int n = 0; n < 2; ++n) _Pragma("unroll") for (int k = 0; k < 2; ++k) \
;         acc[ai][bj][m][n] = __builtin_amdgcn_mfma_f32_16x16x32_bf16(Bt[n][k], At[m][k], acc[ai][bj][m][n], 0, 0, 0); __builtin_amdgcn_s_setprio(0); } while (0)
; #define PG8_WAIT_V(n) asm volatile("s_waitcnt vmcnt(" #n ")" ::: "memory")
; #define PG8_WAIT_L(n) asm volatile("s_waitcnt lgkmcnt(" #n ")" ::: "memory")
; #define PG8_BAR __builtin_amdgcn_s_barrier()
; #define PG8_SCHED __builtin_amdgcn_sched_barrier(0)
; template <class Epi, class Sched, bool ALIGN_EPI = false, bool SP2 = false>
; __device__ __forceinline__ void gemm_phase(PG8_LAS unsigned char* lds, const Gemm g, const Sched& S, const Epi& E) {
;     ...
;             PG8_WAIT_V(8); PG8_WAIT_L(0); PG8_BAR; PG8_MMA(1, 0, At, B0); PG8_MMA(1, 1, At, B1); PG8_BAR; PG8_SCHED;
;             PG8_LDB(B0, 1, 0); PG8_LDB(B1, 1, 1); PG8_SCHED; PG8_LDA(At, 1, 0); PG8_STAGE(PG8_SA(0, 1), a2 + hstep, voffA);
;             PG8_WAIT_V(8); PG8_WAIT_L(0); PG8_BAR; PG8_MMA(0, 0, At, B0); PG8_MMA(0, 1, At, B1); PG8_BAR; PG8_SCHED;
;             PG8_LDA(At, 1, 1); PG8_STAGE(PG8_SB(1, 0), b3, voffB); PG8_STAGE(PG8_SB(1, 1), b3 + hstep, voffB); PG8_STAGE(PG8_SA(1, 0), a3, voffA);
	s_setprio 1
	s_waitcnt lgkmcnt(0)
	v_mfma_f32_16x16x32_bf16 v[60:63], v[136:139], v[214:217], v[60:63]
	v_mfma_f32_16x16x32_bf16 v[60:63], v[140:143], v[218:221], v[60:63]
	v_mfma_f32_16x16x32_bf16 v[56:59], v[180:183], v[218:221], v[56:59]
	v_mfma_f32_16x16x32_bf16 v[56:59], v[176:179], v[214:217], v[56:59]
	v_mfma_f32_16x16x32_bf16 v[40:43], v[176:179], v[222:225], v[40:43]
	v_mfma_f32_16x16x32_bf16 v[40:43], v[180:183], v[226:229], v[40:43]
	v_mfma_f32_16x16x32_bf16 v[48:51], v[140:143], v[226:229], v[48:51]
	v_mfma_f32_16x16x32_bf16 v[48:51], v[136:139], v[222:225], v[48:51]
	v_mfma_f32_16x16x32_bf16 v[32:35], v[136:139], v[230:233], v[32:35]
	v_mfma_f32_16x16x32_bf16 v[32:35], v[140:143], v[234:237], v[32:35]
	v_mfma_f32_16x16x32_bf16 v[24:27], v[180:183], v[234:237], v[24:27]
	v_mfma_f32_16x16x32_bf16 v[24:27], v[176:179], v[230:233], v[24:27]
	v_mfma_f32_16x16x32_bf16 v[8:11], v[176:179], v[238:241], v[8:11]
	v_mfma_f32_16x16x32_bf16 v[8:11], v[180:183], v[242:245], v[8:11]
	v_mfma_f32_16x16x32_bf16 v[12:15], v[140:143], v[242:245], v[12:15]
	v_mfma_f32_16x16x32_bf16 v[12:15], v[136:139], v[238:241], v[12:15]
	s_setprio 0
	s_setprio 1
	v_mfma_f32_16x16x32_bf16 v[52:55], v[184:187], v[214:217], v[52:55]
	v_mfma_f32_16x16x32_bf16 v[52:55], v[202:205], v[218:221], v[52:55]
	v_mfma_f32_16x16x32_bf16 v[44:47], v[210:213], v[218:221], v[44:47]
	v_mfma_f32_16x16x32_bf16 v[44:47], v[206:209], v[214:217], v[44:47]
	v_mfma_f32_16x16x32_bf16 v[28:31], v[206:209], v[222:225], v[28:31]
	v_mfma_f32_16x16x32_bf16 v[28:31], v[210:213], v[226:229], v[28:31]
	v_mfma_f32_16x16x32_bf16 v[36:39], v[202:205], v[226:229], v[36:39]
	v_mfma_f32_16x16x32_bf16 v[36:39], v[184:187], v[222:225], v[36:39]
	v_mfma_f32_16x16x32_bf16 v[20:23], v[184:187], v[230:233], v[20:23]
	v_mfma_f32_16x16x32_bf16 v[20:23], v[202:205], v[234:237], v[20:23]
	v_mfma_f32_16x16x32_bf16 v[16:19], v[210:213], v[234:237], v[16:19]
	v_mfma_f32_16x16x32_bf16 v[16:19], v[206:209], v[230:233], v[16:19]
	s_setprio 2
	s_barrier
	v_mfma_f32_16x16x32_bf16 v[0:3], v[206:209], v[238:241], v[0:3]
	v_mfma_f32_16x16x32_bf16 v[0:3], v[210:213], v[242:245], v[0:3]
	v_mfma_f32_16x16x32_bf16 v[4:7], v[202:205], v[242:245], v[4:7]
	v_mfma_f32_16x16x32_bf16 v[4:7], v[184:187], v[238:241], v[4:7]
	s_setprio 0
	s_add_i32 s75, 0, 0x18000
	v_add_u32_e32 v144, s75, v151
	s_add_i32 s76, 0, 0x1c000
	ds_read_b128 v[136:139], v144
	ds_read_b128 v[140:143], v144 offset:1024
	ds_read_b128 v[176:179], v144 offset:2048
	ds_read_b128 v[180:183], v144 offset:3072
	v_add_u32_e32 v144, s76, v151
	ds_read_b128 v[184:187], v144
	ds_read_b128 v[202:205], v144 offset:1024
	ds_read_b128 v[206:209], v144 offset:2048
	ds_read_b128 v[210:213], v144 offset:3072
	s_add_u32 s48, s48, 0x80000
	s_addc_u32 s49, s49, 0
	s_mov_b32 m0, s58
	v_lshl_add_u64 v[200:201], s[48:49], 0, v[164:165]
	ds_read_b128 v[214:217], v163 offset:32768
	ds_read_b128 v[218:221], v163 offset:33792
	ds_read_b128 v[222:225], v163 offset:34816
	ds_read_b128 v[226:229], v163 offset:35840
	ds_read_b128 v[230:233], v163 offset:36864
	ds_read_b128 v[234:237], v163 offset:37888
	ds_read_b128 v[238:241], v163 offset:38912
	ds_read_b128 v[242:245], v163 offset:39936
	global_load_lds_dwordx4 v[200:201], off
	v_lshl_add_u64 v[200:201], s[48:49], 0, v[168:169]
	s_mov_b32 m0, s59
	s_nop 0
	global_load_lds_dwordx4 v[200:201], off
	s_waitcnt vmcnt(8)
	s_waitcnt lgkmcnt(0)
	s_barrier
	s_setprio 1
	s_waitcnt lgkmcnt(0)
	v_mfma_f32_16x16x32_bf16 v[124:127], v[136:139], v[214:217], v[124:127]
	v_mfma_f32_16x16x32_bf16 v[124:127], v[140:143], v[218:221], v[124:127]
	v_mfma_f32_16x16x32_bf16 v[120:123], v[180:183], v[218:221], v[120:123]
	v_mfma_f32_16x16x32_bf16 v[120:123], v[176:179], v[214:217], v[120:123]
	v_mfma_f32_16x16x32_bf16 v[104:107], v[176:179], v[222:225], v[104:107]
	v_mfma_f32_16x16x32_bf16 v[104:107], v[180:183], v[226:229], v[104:107]
	v_mfma_f32_16x16x32_bf16 v[108:111], v[140:143], v[226:229], v[108:111]
	v_mfma_f32_16x16x32_bf16 v[108:111], v[136:139], v[222:225], v[108:111]
	v_mfma_f32_16x16x32_bf16 v[96:99], v[136:139], v[230:233], v[96:99]
	v_mfma_f32_16x16x32_bf16 v[96:99], v[140:143], v[234:237], v[96:99]
	v_mfma_f32_16x16x32_bf16 v[88:91], v[180:183], v[234:237], v[88:91]
	v_mfma_f32_16x16x32_bf16 v[88:91], v[176:179], v[230:233], v[88:91]
	v_mfma_f32_16x16x32_bf16 v[72:75], v[176:179], v[238:241], v[72:75]
	v_mfma_f32_16x16x32_bf16 v[72:75], v[180:183], v[242:245], v[72:75]
	v_mfma_f32_16x16x32_bf16 v[80:83], v[140:143], v[242:245], v[80:83]
	v_mfma_f32_16x16x32_bf16 v[80:83], v[136:139], v[238:241], v[80:83]
	s_setprio 0
	s_setprio 1
	v_mfma_f32_16x16x32_bf16 v[116:119], v[184:187], v[214:217], v[116:119]
	v_mfma_f32_16x16x32_bf16 v[116:119], v[202:205], v[218:221], v[116:119]
	v_mfma_f32_16x16x32_bf16 v[112:115], v[210:213], v[218:221], v[112:115]
	v_mfma_f32_16x16x32_bf16 v[112:115], v[206:209], v[214:217], v[112:115]
	v_mfma_f32_16x16x32_bf16 v[92:95], v[206:209], v[222:225], v[92:95]
	v_mfma_f32_16x16x32_bf16 v[92:95], v[210:213], v[226:229], v[92:95]
	v_mfma_f32_16x16x32_bf16 v[100:103], v[202:205], v[226:229], v[100:103]
	v_mfma_f32_16x16x32_bf16 v[100:103], v[184:187], v[222:225], v[100:103]
	v_mfma_f32_16x16x32_bf16 v[84:87], v[184:187], v[230:233], v[84:87]
	v_mfma_f32_16x16x32_bf16 v[84:87], v[202:205], v[234:237], v[84:87]
	v_mfma_f32_16x16x32_bf16 v[76:79], v[210:213], v[234:237], v[76:79]
	v_mfma_f32_16x16x32_bf16 v[76:79], v[206:209], v[230:233], v[76:79]
	s_setprio 2
	s_barrier
; #define PG8_STAGE(bufoff, gbase, voff) do { _Pragma("unroll") for (int _i = 0; _i < 2; ++_i) \
;         __builtin_amdgcn_global_load_lds((const unsigned*)((const char*)(gbase) + (voff)[_i]), (PG8_LAS unsigned*)(lds + (bufoff) + ldsw + _i * 8192), 16, 0, 0); } while (0)
; #define PG8_LDA(dst, b, h) do { _Pragma("unroll") for (int m = 0; m < 4; ++m) _Pragma("unroll") for (int k = 0; k < 2; ++k) dst[m][k] = *(const PG8_LAS bf16x8*)(lds + PG8_SA(b, h) + aoff + m * 2048 + k * 1024); } while (0)
; #define PG8_MMA(ai, bj, At, Bt) do { __builtin_amdgcn_s_setprio(1); _Pragma("unroll") for (int m = 0; m < 4; ++m) _Pragma("unroll") for (int n = 0; n < 2; ++n) _Pragma("unroll") for (int k = 0; k < 2; ++k) \
;         acc[ai][bj][m][n] = __builtin_amdgcn_mfma_f32_16x16x32_bf16(Bt[n][k], At[m][k], acc[ai][bj][m][n], 0, 0, 0); __builtin_amdgcn_s_setprio(0); } while (0)
; #define PG8_WAIT_V(n) asm volatile("s_waitcnt vmcnt(" #n ")" ::: "memory")
; #define PG8_WAIT_L(n) asm volatile("s_waitcnt lgkmcnt(" #n ")" ::: "memory")
; #define PG8_BAR __builtin_amdgcn_s_barrier()
; #define PG8_SCHED __builtin_amdgcn_sched_barrier(0)
; template <class Epi, class Sched, bool ALIGN_EPI = false, bool SP2 = false>
; __device__ __forceinline__ void gemm_phase(PG8_LAS unsigned char* lds, const Gemm g, const Sched& S, const Epi& E) {
;     ...
;         for (int t = 0; t < nt; t += 2) {
;     ...
;             PG8_WAIT_V(8); PG8_WAIT_L(0); PG8_BAR; PG8_MMA(0, 0, At, B0); PG8_MMA(0, 1, At, B1); PG8_BAR; PG8_SCHED;
;             PG8_LDA(At, 1, 1); PG8_STAGE(PG8_SB(1, 0), b3, voffB); PG8_STAGE(PG8_SB(1, 1), b3 + hstep, voffB); PG8_STAGE(PG8_SA(1, 0), a3, voffA);
;             PG8_WAIT_V(8); PG8_WAIT_L(0); PG8_BAR; PG8_MMA(1, 0, At, B0); PG8_MMA(1, 1, At, B1); PG8_BAR; PG8_SCHED;
	v_mfma_f32_16x16x32_bf16 v[64:67], v[206:209], v[238:241], v[64:67]
	v_mfma_f32_16x16x32_bf16 v[64:67], v[210:213], v[242:245], v[64:67]
	v_mfma_f32_16x16x32_bf16 v[68:71], v[202:205], v[242:245], v[68:71]
	v_mfma_f32_16x16x32_bf16 v[68:71], v[184:187], v[238:241], v[68:71]
	s_setprio 0
	s_add_i32 s48, s75, s45
	v_lshl_add_u64 v[200:201], v[246:247], 0, s[18:19]
	s_mov_b32 m0, s48
	ds_read_b128 v[214:217], v163 offset:49152
	ds_read_b128 v[218:221], v163 offset:50176
	ds_read_b128 v[222:225], v163 offset:51200
	ds_read_b128 v[226:229], v163 offset:52224
	ds_read_b128 v[230:233], v163 offset:53248
	ds_read_b128 v[234:237], v163 offset:54272
	ds_read_b128 v[238:241], v163 offset:55296
	ds_read_b128 v[242:245], v163 offset:56320
	global_load_lds_dwordx4 v[200:201], off
	s_add_i32 m0, s48, 0x2000
	s_add_u32 s28, s28, 0x80080
	v_lshl_add_u64 v[200:201], v[248:249], 0, s[18:19]
	s_addc_u32 s29, s29, 0
	s_add_i32 s48, s76, s45
	global_load_lds_dwordx4 v[200:201], off
	v_lshl_add_u64 v[200:201], s[28:29], 0, v[166:167]
	s_mov_b32 m0, s48
	s_nop 0
	global_load_lds_dwordx4 v[200:201], off
	v_lshl_add_u64 v[200:201], s[28:29], 0, v[170:171]
	s_add_i32 m0, s48, 0x2000
	s_nop 0
	global_load_lds_dwordx4 v[200:201], off
	v_lshl_add_u64 v[200:201], v[250:251], 0, s[18:19]
	s_mov_b32 m0, s61
	s_nop 0
	global_load_lds_dwordx4 v[200:201], off
	v_lshl_add_u64 v[200:201], v[252:253], 0, s[18:19]
	s_mov_b32 m0, s62
	s_nop 0
	global_load_lds_dwordx4 v[200:201], off
	s_waitcnt vmcnt(8)
	s_waitcnt lgkmcnt(0)
	s_barrier
	s_setprio 1
	s_waitcnt lgkmcnt(0)
	v_mfma_f32_16x16x32_bf16 v[60:63], v[136:139], v[214:217], v[60:63]
	v_mfma_f32_16x16x32_bf16 v[60:63], v[140:143], v[218:221], v[60:63]
	v_mfma_f32_16x16x32_bf16 v[56:59], v[180:183], v[218:221], v[56:59]
	v_mfma_f32_16x16x32_bf16 v[56:59], v[176:179], v[214:217], v[56:59]
	v_mfma_f32_16x16x32_bf16 v[40:43], v[176:179], v[222:225], v[40:43]
	v_mfma_f32_16x16x32_bf16 v[40:43], v[180:183], v[226:229], v[40:43]
	v_mfma_f32_16x16x32_bf16 v[48:51], v[140:143], v[226:229], v[48:51]
	v_mfma_f32_16x16x32_bf16 v[48:51], v[136:139], v[222:225], v[48:51]
	v_mfma_f32_16x16x32_bf16 v[32:35], v[136:139], v[230:233], v[32:35]
	v_mfma_f32_16x16x32_bf16 v[32:35], v[140:143], v[234:237], v[32:35]
	v_mfma_f32_16x16x32_bf16 v[24:27], v[180:183], v[234:237], v[24:27]
	v_mfma_f32_16x16x32_bf16 v[24:27], v[176:179], v[230:233], v[24:27]
	v_mfma_f32_16x16x32_bf16 v[8:11], v[176:179], v[238:241], v[8:11]
	v_mfma_f32_16x16x32_bf16 v[8:11], v[180:183], v[242:245], v[8:11]
	v_mfma_f32_16x16x32_bf16 v[12:15], v[140:143], v[242:245], v[12:15]
	v_mfma_f32_16x16x32_bf16 v[12:15], v[136:139], v[238:241], v[12:15]
	s_setprio 0
	s_setprio 1
	v_mfma_f32_16x16x32_bf16 v[52:55], v[184:187], v[214:217], v[52:55]
	v_mfma_f32_16x16x32_bf16 v[52:55], v[202:205], v[218:221], v[52:55]
	v_mfma_f32_16x16x32_bf16 v[44:47], v[210:213], v[218:221], v[44:47]
	v_mfma_f32_16x16x32_bf16 v[44:47], v[206:209], v[214:217], v[44:47]
	v_mfma_f32_16x16x32_bf16 v[28:31], v[206:209], v[222:225], v[28:31]
	v_mfma_f32_16x16x32_bf16 v[28:31], v[210:213], v[226:229], v[28:31]
	v_mfma_f32_16x16x32_bf16 v[36:39], v[202:205], v[226:229], v[36:39]
	v_mfma_f32_16x16x32_bf16 v[36:39], v[184:187], v[222:225], v[36:39]
	v_mfma_f32_16x16x32_bf16 v[20:23], v[184:187], v[230:233], v[20:23]
	v_mfma_f32_16x16x32_bf16 v[20:23], v[202:205], v[234:237], v[20:23]
	v_mfma_f32_16x16x32_bf16 v[16:19], v[210:213], v[234:237], v[16:19]
	v_mfma_f32_16x16x32_bf16 v[16:19], v[206:209], v[230:233], v[16:19]
	s_setprio 2
	s_barrier
	v_mfma_f32_16x16x32_bf16 v[0:3], v[206:209], v[238:241], v[0:3]
	v_mfma_f32_16x16x32_bf16 v[0:3], v[210:213], v[242:245], v[0:3]
	v_mfma_f32_16x16x32_bf16 v[4:7], v[202:205], v[242:245], v[4:7]
	v_mfma_f32_16x16x32_bf16 v[4:7], v[184:187], v[238:241], v[4:7]
	s_setprio 0
	s_add_i32 s74, s74, 2
	s_add_u32 s52, s52, 0x100
	s_addc_u32 s53, s53, 0
	s_add_u32 s72, s72, 0x100
	s_addc_u32 s73, s73, 0
	s_cmp_gt_u32 s74, 29
	s_cbranch_scc0 .LBB0_110
	s_and_b64 vcc, exec, s[20:21]
	s_cbranch_vccz .LBB0_113
	s_barrier

; #define PG8_STAGE(bufoff, gbase, voff) do { _Pragma("unroll") for (int _i = 0; _i < 2; ++_i) \
;         __builtin_amdgcn_global_load_lds((const unsigned*)((const char*)(gbase) + (voff)[_i]), (PG8_LAS unsigned*)(lds + (bufoff) + ldsw + _i * 8192), 16, 0, 0); } while (0)
; #define PG8_LDA(dst, b, h) do { _Pragma("unroll") for (int m = 0; m < 4; ++m) _Pragma("unroll") for (int k = 0; k < 2; ++k) dst[m][k] = *(const PG8_LAS bf16x8*)(lds + PG8_SA(b, h) + aoff + m * 2048 + k * 1024); } while (0)
; #define PG8_LDB(dst, b, h) do { _Pragma("unroll") for (int n = 0; n < 2; ++n) _Pragma("unroll") for (int k = 0; k < 2; ++k) dst[n][k] = *(const PG8_LAS bf16x8*)(lds + PG8_SB(b, h) + boff + n * 2048 + k * 1024); } while (0)
; #define PG8_MMA(ai, bj, At, Bt) do { __builtin_amdgcn_s_setprio(1); _Pragma("unroll") for (int m = 0; m < 4; ++m) _Pragma("unroll") for (int n = 0; n < 2; ++n) _Pragma("unroll") for (int k = 0; k < 2; ++k) \
;         acc[ai][bj][m][n] = __builtin_amdgcn_mfma_f32_16x16x32_bf16(Bt[n][k], At[m][k], acc[ai][bj][m][n], 0, 0, 0); __builtin_amdgcn_s_setprio(0); } while (0)
; #define PG8_WAIT_V(n) asm volatile("s_waitcnt vmcnt(" #n ")" ::: "memory")
; #define PG8_WAIT_L(n) asm volatile("s_waitcnt lgkmcnt(" #n ")" ::: "memory")
; template <class Epi, class Sched, bool ALIGN_EPI = false, bool SP2 = false>
; __device__ __forceinline__ void gemm_phase(PG8_LAS unsigned char* lds, const Gemm g, const Sched& S, const Epi& E) {
;     ...
;             const bool last = (t == nt - 2);
;             const char* a1 = cA + (size_t)(t + 1) * kstep;
;             const char* a2 = last ? nA : cA + (size_t)(t + 2) * kstep; const char* b2 = last ? nB : cB + (size_t)(t + 2) * kstep;
;             const char* a3 = a2 + kstep; const char* b3 = b2 + kstep;
;             if (last && has_next) S.a_ready(nxt);
;             if constexpr (SP2) {
;             PG8_LDB(B0, 0, 0); PG8_LDB(B1, 0, 1); PG8_SCHED; PG8_LDA(At, 0, 0); PG8_STAGE(PG8_SA(1, 1), a1 + hstep, voffA);
;             PG8_WAIT_V(8); PG8_WAIT_L(0); PG8_BAR; PG8_MMA(0, 0, At, B0); PG8_MMA(0, 1, At, B1); PG8_BAR; PG8_SCHED;
;             PG8_LDA(At, 0, 1); PG8_STAGE(PG8_SB(0, 0), b2, voffB); PG8_STAGE(PG8_SB(0, 1), b2 + hstep, voffB); PG8_STAGE(PG8_SA(0, 0), a2, voffA);
;             PG8_WAIT_V(8); PG8_WAIT_L(0); PG8_BAR; PG8_MMA(1, 0, At, B0); PG8_MMA(1, 1, At, B1); PG8_BAR; PG8_SCHED;
.LBB0_177:
	ds_read_b128 v[80:83], v171
	ds_read_b128 v[84:87], v171 offset:1024
	ds_read_b128 v[92:95], v171 offset:2048
	ds_read_b128 v[100:103], v171 offset:3072
	ds_read_b128 v[144:147], v206
	ds_read_b128 v[148:151], v206 offset:1024
	ds_read_b128 v[152:155], v206 offset:2048
	ds_read_b128 v[156:159], v206 offset:3072
	s_add_u32 s28, s72, 0xffea0080
	s_addc_u32 s29, s73, -1
	s_cmpk_eq_i32 s76, 0x54
	s_cselect_b32 s49, s69, s29
	s_cselect_b32 s48, s68, s28
	s_cselect_b32 s29, s71, s35
	s_cselect_b32 s28, s70, s34
	v_lshl_add_u64 v[234:235], s[72:73], 0, v[174:175]
	s_add_i32 m0, s40, 0xc000
	ds_read_b128 v[180:183], v207
	ds_read_b128 v[184:187], v207 offset:1024
	ds_read_b128 v[210:213], v207 offset:2048
	ds_read_b128 v[214:217], v207 offset:3072
	ds_read_b128 v[218:221], v207 offset:4096
	ds_read_b128 v[222:225], v207 offset:5120
	ds_read_b128 v[226:229], v207 offset:6144
	ds_read_b128 v[230:233], v207 offset:7168
	global_load_lds_dwordx4 v[234:235], off
	v_lshl_add_u64 v[234:235], s[72:73], 0, v[176:177]
	s_add_i32 m0, s40, 0xe000
	s_nop 0
	global_load_lds_dwordx4 v[234:235], off
	s_waitcnt vmcnt(8)
	s_waitcnt lgkmcnt(0)
	s_barrier
	s_setprio 1
	s_waitcnt lgkmcnt(0)
	v_mfma_f32_16x16x32_bf16 v[140:143], v[80:83], v[180:183], v[140:143]
	v_mfma_f32_16x16x32_bf16 v[140:143], v[84:87], v[184:187], v[140:143]
	v_mfma_f32_16x16x32_bf16 v[136:139], v[100:103], v[184:187], v[136:139]
	v_mfma_f32_16x16x32_bf16 v[136:139], v[92:95], v[180:183], v[136:139]
	v_mfma_f32_16x16x32_bf16 v[120:123], v[92:95], v[210:213], v[120:123]
	v_mfma_f32_16x16x32_bf16 v[120:123], v[100:103], v[214:217], v[120:123]
	v_mfma_f32_16x16x32_bf16 v[124:127], v[84:87], v[214:217], v[124:127]
	v_mfma_f32_16x16x32_bf16 v[124:127], v[80:83], v[210:213], v[124:127]
	v_mfma_f32_16x16x32_bf16 v[108:111], v[80:83], v[218:221], v[108:111]
	v_mfma_f32_16x16x32_bf16 v[108:111], v[84:87], v[222:225], v[108:111]
	v_mfma_f32_16x16x32_bf16 v[104:107], v[100:103], v[222:225], v[104:107]
	v_mfma_f32_16x16x32_bf16 v[104:107], v[92:95], v[218:221], v[104:107]
	v_mfma_f32_16x16x32_bf16 v[72:75], v[92:95], v[226:229], v[72:75]
	v_mfma_f32_16x16x32_bf16 v[72:75], v[100:103], v[230:233], v[72:75]
	v_mfma_f32_16x16x32_bf16 v[76:79], v[84:87], v[230:233], v[76:79]
	v_mfma_f32_16x16x32_bf16 v[76:79], v[80:83], v[226:229], v[76:79]
	s_setprio 0
	s_setprio 1
	v_mfma_f32_16x16x32_bf16 v[132:135], v[144:147], v[180:183], v[132:135]
	v_mfma_f32_16x16x32_bf16 v[132:135], v[148:151], v[184:187], v[132:135]
	v_mfma_f32_16x16x32_bf16 v[128:131], v[156:159], v[184:187], v[128:131]
	v_mfma_f32_16x16x32_bf16 v[128:131], v[152:155], v[180:183], v[128:131]
	v_mfma_f32_16x16x32_bf16 v[112:115], v[152:155], v[210:213], v[112:115]
	v_mfma_f32_16x16x32_bf16 v[112:115], v[156:159], v[214:217], v[112:115]
	v_mfma_f32_16x16x32_bf16 v[116:119], v[148:151], v[214:217], v[116:119]
	v_mfma_f32_16x16x32_bf16 v[116:119], v[144:147], v[210:213], v[116:119]
	v_mfma_f32_16x16x32_bf16 v[96:99], v[144:147], v[218:221], v[96:99]
	v_mfma_f32_16x16x32_bf16 v[96:99], v[148:151], v[222:225], v[96:99]
	v_mfma_f32_16x16x32_bf16 v[88:91], v[156:159], v[222:225], v[88:91]
	v_mfma_f32_16x16x32_bf16 v[88:91], v[152:155], v[218:221], v[88:91]
	s_setprio 2
	s_barrier
	v_mfma_f32_16x16x32_bf16 v[64:67], v[152:155], v[226:229], v[64:67]
	v_mfma_f32_16x16x32_bf16 v[64:67], v[156:159], v[230:233], v[64:67]
	v_mfma_f32_16x16x32_bf16 v[68:71], v[148:151], v[230:233], v[68:71]
	v_mfma_f32_16x16x32_bf16 v[68:71], v[144:147], v[226:229], v[68:71]
	s_setprio 0
	s_add_i32 s77, s61, s13
	v_lshl_add_u64 v[234:235], s[28:29], 0, v[160:161]
	s_mov_b32 m0, s77
	ds_read_b128 v[180:183], v207 offset:16384
	ds_read_b128 v[184:187], v207 offset:17408
	ds_read_b128 v[210:213], v207 offset:18432
	ds_read_b128 v[214:217], v207 offset:19456
	ds_read_b128 v[218:221], v207 offset:20480
	ds_read_b128 v[222:225], v207 offset:21504
	ds_read_b128 v[226:229], v207 offset:22528
	ds_read_b128 v[230:233], v207 offset:23552
	global_load_lds_dwordx4 v[234:235], off
	s_add_i32 m0, s77, 0x2000
	s_add_u32 s78, s28, 0x160000
	v_lshl_add_u64 v[236:237], s[28:29], 0, v[162:163]
	s_addc_u32 s79, s29, 0
	s_add_i32 s77, s62, s13
	global_load_lds_dwordx4 v[236:237], off
	v_lshl_add_u64 v[238:239], s[78:79], 0, v[160:161]
	s_mov_b32 m0, s77
	v_lshl_add_u64 v[240:241], s[48:49], 0, v[162:163]
	global_load_lds_dwordx4 v[238:239], off
	v_lshl_add_u64 v[238:239], s[78:79], 0, v[162:163]
	s_add_i32 m0, s77, 0x2000
	s_nop 0
	global_load_lds_dwordx4 v[238:239], off
	v_lshl_add_u64 v[238:239], s[48:49], 0, v[160:161]
	s_mov_b32 m0, s40
	s_nop 0
	global_load_lds_dwordx4 v[238:239], off
	s_mov_b32 m0, s41
	s_nop 0
	global_load_lds_dwordx4 v[240:241], off
	s_waitcnt vmcnt(8)
	s_waitcnt lgkmcnt(0)
	s_barrier
; #define PG8_STAGE(bufoff, gbase, voff) do { _Pragma("unroll") for (int _i = 0; _i < 2; ++_i) \
;         __builtin_amdgcn_global_load_lds((const unsigned*)((const char*)(gbase) + (voff)[_i]), (PG8_LAS unsigned*)(lds + (bufoff) + ldsw + _i * 8192), 16, 0, 0); } while (0)
; #define PG8_LDA(dst, b, h) do { _Pragma("unroll") for (int m = 0; m < 4; ++m) _Pragma("unroll") for (int k = 0; k < 2; ++k) dst[m][k] = *(const PG8_LAS bf16x8*)(lds + PG8_SA(b, h) + aoff + m * 2048 + k * 1024); } while (0)
; #define PG8_LDB(dst, b, h) do { _Pragma("unroll") for (int n = 0; n < 2; ++n) _Pragma("unroll") for (int k = 0; k < 2; ++k) dst[n][k] = *(const PG8_LAS bf16x8*)(lds + PG8_SB(b, h) + boff + n * 2048 + k * 1024); } while (0)
; #define PG8_MMA(ai, bj, At, Bt) do { __builtin_amdgcn_s_setprio(1); _Pragma("unroll") for (int m = 0; m < 4; ++m) _Pragma("unroll") for (int n = 0; n < 2; ++n) _Pragma("unroll") for (int k = 0; k < 2; ++k) \
;         acc[ai][bj][m][n] = __builtin_amdgcn_mfma_f32_16x16x32_bf16(Bt[n][k], At[m][k], acc[ai][bj][m][n], 0, 0, 0); __builtin_amdgcn_s_setprio(0); } while (0)
; #define PG8_WAIT_V(n) asm volatile("s_waitcnt vmcnt(" #n ")" ::: "memory")
; #define PG8_WAIT_L(n) asm volatile("s_waitcnt lgkmcnt(" #n ")" ::: "memory")
; #define PG8_BAR __builtin_amdgcn_s_barrier()
; #define PG8_SCHED __builtin_amdgcn_sched_barrier(0)
; template <class Epi, class Sched, bool ALIGN_EPI = false, bool SP2 = false>
; __device__ __forceinline__ void gemm_phase(PG8_LAS unsigned char* lds, const Gemm g, const Sched& S, const Epi& E) {
;     ...
;             PG8_WAIT_V(8); PG8_WAIT_L(0); PG8_BAR; PG8_MMA(1, 0, At, B0); PG8_MMA(1, 1, At, B1); PG8_BAR; PG8_SCHED;
;             PG8_LDB(B0, 1, 0); PG8_LDB(B1, 1, 1); PG8_SCHED; PG8_LDA(At, 1, 0); PG8_STAGE(PG8_SA(0, 1), a2 + hstep, voffA);
;             PG8_WAIT_V(8); PG8_WAIT_L(0); PG8_BAR; PG8_MMA(0, 0, At, B0); PG8_MMA(0, 1, At, B1); PG8_BAR; PG8_SCHED;
	s_setprio 1
	s_waitcnt lgkmcnt(0)
	v_mfma_f32_16x16x32_bf16 v[60:63], v[80:83], v[180:183], v[60:63]
	v_mfma_f32_16x16x32_bf16 v[60:63], v[84:87], v[184:187], v[60:63]
	v_mfma_f32_16x16x32_bf16 v[56:59], v[100:103], v[184:187], v[56:59]
	v_mfma_f32_16x16x32_bf16 v[56:59], v[92:95], v[180:183], v[56:59]
	v_mfma_f32_16x16x32_bf16 v[40:43], v[92:95], v[210:213], v[40:43]
	v_mfma_f32_16x16x32_bf16 v[40:43], v[100:103], v[214:217], v[40:43]
	v_mfma_f32_16x16x32_bf16 v[44:47], v[84:87], v[214:217], v[44:47]
	v_mfma_f32_16x16x32_bf16 v[44:47], v[80:83], v[210:213], v[44:47]
	v_mfma_f32_16x16x32_bf16 v[28:31], v[80:83], v[218:221], v[28:31]
	v_mfma_f32_16x16x32_bf16 v[28:31], v[84:87], v[222:225], v[28:31]
	v_mfma_f32_16x16x32_bf16 v[24:27], v[100:103], v[222:225], v[24:27]
	v_mfma_f32_16x16x32_bf16 v[24:27], v[92:95], v[218:221], v[24:27]
	v_mfma_f32_16x16x32_bf16 v[8:11], v[92:95], v[226:229], v[8:11]
	v_mfma_f32_16x16x32_bf16 v[8:11], v[100:103], v[230:233], v[8:11]
	v_mfma_f32_16x16x32_bf16 v[12:15], v[84:87], v[230:233], v[12:15]
	v_mfma_f32_16x16x32_bf16 v[12:15], v[80:83], v[226:229], v[12:15]
	s_setprio 0
	s_setprio 1
	v_mfma_f32_16x16x32_bf16 v[52:55], v[144:147], v[180:183], v[52:55]
	v_mfma_f32_16x16x32_bf16 v[52:55], v[148:151], v[184:187], v[52:55]
	v_mfma_f32_16x16x32_bf16 v[48:51], v[156:159], v[184:187], v[48:51]
	v_mfma_f32_16x16x32_bf16 v[48:51], v[152:155], v[180:183], v[48:51]
	v_mfma_f32_16x16x32_bf16 v[32:35], v[152:155], v[210:213], v[32:35]
	v_mfma_f32_16x16x32_bf16 v[32:35], v[156:159], v[214:217], v[32:35]
	v_mfma_f32_16x16x32_bf16 v[36:39], v[148:151], v[214:217], v[36:39]
	v_mfma_f32_16x16x32_bf16 v[36:39], v[144:147], v[210:213], v[36:39]
	v_mfma_f32_16x16x32_bf16 v[20:23], v[144:147], v[218:221], v[20:23]
	v_mfma_f32_16x16x32_bf16 v[20:23], v[148:151], v[222:225], v[20:23]
	v_mfma_f32_16x16x32_bf16 v[16:19], v[156:159], v[222:225], v[16:19]
	v_mfma_f32_16x16x32_bf16 v[16:19], v[152:155], v[218:221], v[16:19]
	s_setprio 2
	s_barrier
	v_mfma_f32_16x16x32_bf16 v[0:3], v[152:155], v[226:229], v[0:3]
	v_mfma_f32_16x16x32_bf16 v[0:3], v[156:159], v[230:233], v[0:3]
	v_mfma_f32_16x16x32_bf16 v[4:7], v[148:151], v[230:233], v[4:7]
	v_mfma_f32_16x16x32_bf16 v[4:7], v[144:147], v[226:229], v[4:7]
	s_setprio 0
	s_add_i32 s77, 0, 0x18000
	s_add_i32 s78, 0, 0x1c000
	v_add_u32_e32 v100, s77, v167
	v_add_u32_e32 v156, s78, v167
	ds_read_b128 v[80:83], v100
	ds_read_b128 v[84:87], v100 offset:1024
	ds_read_b128 v[92:95], v100 offset:2048
	ds_read_b128 v[100:103], v100 offset:3072
	ds_read_b128 v[144:147], v156
	ds_read_b128 v[148:151], v156 offset:1024
	ds_read_b128 v[152:155], v156 offset:2048
	ds_read_b128 v[156:159], v156 offset:3072
	s_add_u32 s48, s48, 0x160000
	s_addc_u32 s49, s49, 0
	s_mov_b32 m0, s44
	v_lshl_add_u64 v[242:243], s[48:49], 0, v[160:161]
	ds_read_b128 v[180:183], v207 offset:32768
	ds_read_b128 v[184:187], v207 offset:33792
	ds_read_b128 v[210:213], v207 offset:34816
	ds_read_b128 v[214:217], v207 offset:35840
	ds_read_b128 v[218:221], v207 offset:36864
	ds_read_b128 v[222:225], v207 offset:37888
	ds_read_b128 v[226:229], v207 offset:38912
	ds_read_b128 v[230:233], v207 offset:39936
	global_load_lds_dwordx4 v[242:243], off
	v_lshl_add_u64 v[242:243], s[48:49], 0, v[162:163]
	s_mov_b32 m0, s45
	s_nop 0
	global_load_lds_dwordx4 v[242:243], off
	s_waitcnt vmcnt(8)
	s_waitcnt lgkmcnt(0)
	s_barrier
	s_setprio 1
	s_waitcnt lgkmcnt(0)
	v_mfma_f32_16x16x32_bf16 v[140:143], v[80:83], v[180:183], v[140:143]
	v_mfma_f32_16x16x32_bf16 v[140:143], v[84:87], v[184:187], v[140:143]
	v_mfma_f32_16x16x32_bf16 v[136:139], v[100:103], v[184:187], v[136:139]
	v_mfma_f32_16x16x32_bf16 v[136:139], v[92:95], v[180:183], v[136:139]
	v_mfma_f32_16x16x32_bf16 v[120:123], v[92:95], v[210:213], v[120:123]
	v_mfma_f32_16x16x32_bf16 v[120:123], v[100:103], v[214:217], v[120:123]
	v_mfma_f32_16x16x32_bf16 v[124:127], v[84:87], v[214:217], v[124:127]
	v_mfma_f32_16x16x32_bf16 v[124:127], v[80:83], v[210:213], v[124:127]
	v_mfma_f32_16x16x32_bf16 v[108:111], v[80:83], v[218:221], v[108:111]
	v_mfma_f32_16x16x32_bf16 v[108:111], v[84:87], v[222:225], v[108:111]
	v_mfma_f32_16x16x32_bf16 v[104:107], v[100:103], v[222:225], v[104:107]
	v_mfma_f32_16x16x32_bf16 v[104:107], v[92:95], v[218:221], v[104:107]
	v_mfma_f32_16x16x32_bf16 v[72:75], v[92:95], v[226:229], v[72:75]
	v_mfma_f32_16x16x32_bf16 v[72:75], v[100:103], v[230:233], v[72:75]
	v_mfma_f32_16x16x32_bf16 v[76:79], v[84:87], v[230:233], v[76:79]
	v_mfma_f32_16x16x32_bf16 v[76:79], v[80:83], v[226:229], v[76:79]
	s_setprio 0
	s_setprio 1
	v_mfma_f32_16x16x32_bf16 v[132:135], v[144:147], v[180:183], v[132:135]
	v_mfma_f32_16x16x32_bf16 v[132:135], v[148:151], v[184:187], v[132:135]
	v_mfma_f32_16x16x32_bf16 v[128:131], v[156:159], v[184:187], v[128:131]
	v_mfma_f32_16x16x32_bf16 v[128:131], v[152:155], v[180:183], v[128:131]
	v_mfma_f32_16x16x32_bf16 v[112:115], v[152:155], v[210:213], v[112:115]
	v_mfma_f32_16x16x32_bf16 v[112:115], v[156:159], v[214:217], v[112:115]
	v_mfma_f32_16x16x32_bf16 v[116:119], v[148:151], v[214:217], v[116:119]
	v_mfma_f32_16x16x32_bf16 v[116:119], v[144:147], v[210:213], v[116:119]
	v_mfma_f32_16x16x32_bf16 v[96:99], v[144:147], v[218:221], v[96:99]
	v_mfma_f32_16x16x32_bf16 v[96:99], v[148:151], v[222:225], v[96:99]
	v_mfma_f32_16x16x32_bf16 v[88:91], v[156:159], v[222:225], v[88:91]
	v_mfma_f32_16x16x32_bf16 v[88:91], v[152:155], v[218:221], v[88:91]
	s_setprio 2
	s_barrier
; #define PG8_STAGE(bufoff, gbase, voff) do { _Pragma("unroll") for (int _i = 0; _i < 2; ++_i) \
;         __builtin_amdgcn_global_load_lds((const unsigned*)((const char*)(gbase) + (voff)[_i]), (PG8_LAS unsigned*)(lds + (bufoff) + ldsw + _i * 8192), 16, 0, 0); } while (0)
; #define PG8_LDA(dst, b, h) do { _Pragma("unroll") for (int m = 0; m < 4; ++m) _Pragma("unroll") for (int k = 0; k < 2; ++k) dst[m][k] = *(const PG8_LAS bf16x8*)(lds + PG8_SA(b, h) + aoff + m * 2048 + k * 1024); } while (0)
; #define PG8_MMA(ai, bj, At, Bt) do { __builtin_amdgcn_s_setprio(1); _Pragma("unroll") for (int m = 0; m < 4; ++m) _Pragma("unroll") for (int n = 0; n < 2; ++n) _Pragma("unroll") for (int k = 0; k < 2; ++k) \
;         acc[ai][bj][m][n] = __builtin_amdgcn_mfma_f32_16x16x32_bf16(Bt[n][k], At[m][k], acc[ai][bj][m][n], 0, 0, 0); __builtin_amdgcn_s_setprio(0); } while (0)
; #define PG8_WAIT_V(n) asm volatile("s_waitcnt vmcnt(" #n ")" ::: "memory")
; #define PG8_WAIT_L(n) asm volatile("s_waitcnt lgkmcnt(" #n ")" ::: "memory")
; #define PG8_BAR __builtin_amdgcn_s_barrier()
; #define PG8_SCHED __builtin_amdgcn_sched_barrier(0)
; template <class Epi, class Sched, bool ALIGN_EPI = false, bool SP2 = false>
; __device__ __forceinline__ void gemm_phase(PG8_LAS unsigned char* lds, const Gemm g, const Sched& S, const Epi& E) {
;     ...
;         for (int t = 0; t < nt; t += 2) {
;     ...
;             PG8_WAIT_V(8); PG8_WAIT_L(0); PG8_BAR; PG8_MMA(0, 0, At, B0); PG8_MMA(0, 1, At, B1); PG8_BAR; PG8_SCHED;
;             PG8_LDA(At, 1, 1); PG8_STAGE(PG8_SB(1, 0), b3, voffB); PG8_STAGE(PG8_SB(1, 1), b3 + hstep, voffB); PG8_STAGE(PG8_SA(1, 0), a3, voffA);
;             PG8_WAIT_V(8); PG8_WAIT_L(0); PG8_BAR; PG8_MMA(1, 0, At, B0); PG8_MMA(1, 1, At, B1); PG8_BAR; PG8_SCHED;
	v_mfma_f32_16x16x32_bf16 v[64:67], v[152:155], v[226:229], v[64:67]
	v_mfma_f32_16x16x32_bf16 v[64:67], v[156:159], v[230:233], v[64:67]
	v_mfma_f32_16x16x32_bf16 v[68:71], v[148:151], v[230:233], v[68:71]
	v_mfma_f32_16x16x32_bf16 v[68:71], v[144:147], v[226:229], v[68:71]
	s_setprio 0
	s_add_i32 s48, s77, s13
	v_lshl_add_u64 v[234:235], v[234:235], 0, s[50:51]
	s_mov_b32 m0, s48
	ds_read_b128 v[180:183], v207 offset:49152
	ds_read_b128 v[184:187], v207 offset:50176
	ds_read_b128 v[210:213], v207 offset:51200
	ds_read_b128 v[214:217], v207 offset:52224
	ds_read_b128 v[218:221], v207 offset:53248
	ds_read_b128 v[222:225], v207 offset:54272
	ds_read_b128 v[226:229], v207 offset:55296
	ds_read_b128 v[230:233], v207 offset:56320
	global_load_lds_dwordx4 v[234:235], off
	s_add_i32 m0, s48, 0x2000
	s_add_u32 s28, s28, 0x160080
	v_lshl_add_u64 v[234:235], v[236:237], 0, s[50:51]
	s_addc_u32 s29, s29, 0
	s_add_i32 s48, s78, s13
	global_load_lds_dwordx4 v[234:235], off
	v_lshl_add_u64 v[234:235], s[28:29], 0, v[160:161]
	s_mov_b32 m0, s48
	s_nop 0
	global_load_lds_dwordx4 v[234:235], off
	v_lshl_add_u64 v[234:235], s[28:29], 0, v[162:163]
	s_add_i32 m0, s48, 0x2000
	s_nop 0
	global_load_lds_dwordx4 v[234:235], off
	v_lshl_add_u64 v[234:235], v[238:239], 0, s[50:51]
	s_mov_b32 m0, s56
	s_nop 0
	global_load_lds_dwordx4 v[234:235], off
	v_lshl_add_u64 v[234:235], v[240:241], 0, s[50:51]
	s_mov_b32 m0, s57
	s_nop 0
	global_load_lds_dwordx4 v[234:235], off
	s_waitcnt vmcnt(8)
	s_waitcnt lgkmcnt(0)
	s_barrier
	s_setprio 1
	s_waitcnt lgkmcnt(0)
	v_mfma_f32_16x16x32_bf16 v[60:63], v[80:83], v[180:183], v[60:63]
	v_mfma_f32_16x16x32_bf16 v[60:63], v[84:87], v[184:187], v[60:63]
	v_mfma_f32_16x16x32_bf16 v[56:59], v[100:103], v[184:187], v[56:59]
	v_mfma_f32_16x16x32_bf16 v[56:59], v[92:95], v[180:183], v[56:59]
	v_mfma_f32_16x16x32_bf16 v[40:43], v[92:95], v[210:213], v[40:43]
	v_mfma_f32_16x16x32_bf16 v[40:43], v[100:103], v[214:217], v[40:43]
	v_mfma_f32_16x16x32_bf16 v[44:47], v[84:87], v[214:217], v[44:47]
	v_mfma_f32_16x16x32_bf16 v[44:47], v[80:83], v[210:213], v[44:47]
	v_mfma_f32_16x16x32_bf16 v[28:31], v[80:83], v[218:221], v[28:31]
	v_mfma_f32_16x16x32_bf16 v[28:31], v[84:87], v[222:225], v[28:31]
	v_mfma_f32_16x16x32_bf16 v[24:27], v[100:103], v[222:225], v[24:27]
	v_mfma_f32_16x16x32_bf16 v[24:27], v[92:95], v[218:221], v[24:27]
	v_mfma_f32_16x16x32_bf16 v[8:11], v[92:95], v[226:229], v[8:11]
	v_mfma_f32_16x16x32_bf16 v[8:11], v[100:103], v[230:233], v[8:11]
	v_mfma_f32_16x16x32_bf16 v[12:15], v[84:87], v[230:233], v[12:15]
	v_mfma_f32_16x16x32_bf16 v[12:15], v[80:83], v[226:229], v[12:15]
	s_setprio 0
	s_setprio 1
	v_mfma_f32_16x16x32_bf16 v[52:55], v[144:147], v[180:183], v[52:55]
	v_mfma_f32_16x16x32_bf16 v[52:55], v[148:151], v[184:187], v[52:55]
	v_mfma_f32_16x16x32_bf16 v[48:51], v[156:159], v[184:187], v[48:51]
	v_mfma_f32_16x16x32_bf16 v[48:51], v[152:155], v[180:183], v[48:51]
	v_mfma_f32_16x16x32_bf16 v[32:35], v[152:155], v[210:213], v[32:35]
	v_mfma_f32_16x16x32_bf16 v[32:35], v[156:159], v[214:217], v[32:35]
	v_mfma_f32_16x16x32_bf16 v[36:39], v[148:151], v[214:217], v[36:39]
	v_mfma_f32_16x16x32_bf16 v[36:39], v[144:147], v[210:213], v[36:39]
	v_mfma_f32_16x16x32_bf16 v[20:23], v[144:147], v[218:221], v[20:23]
	v_mfma_f32_16x16x32_bf16 v[20:23], v[148:151], v[222:225], v[20:23]
	v_mfma_f32_16x16x32_bf16 v[16:19], v[156:159], v[222:225], v[16:19]
	v_mfma_f32_16x16x32_bf16 v[16:19], v[152:155], v[218:221], v[16:19]
	s_setprio 2
	s_barrier
	v_mfma_f32_16x16x32_bf16 v[0:3], v[152:155], v[226:229], v[0:3]
	v_mfma_f32_16x16x32_bf16 v[0:3], v[156:159], v[230:233], v[0:3]
	v_mfma_f32_16x16x32_bf16 v[4:7], v[148:151], v[230:233], v[4:7]
	v_mfma_f32_16x16x32_bf16 v[4:7], v[144:147], v[226:229], v[4:7]
	s_setprio 0
	s_add_i32 s76, s76, 2
	s_add_u32 s72, s72, 0x100
	s_addc_u32 s73, s73, 0
	s_add_u32 s34, s34, 0x100
	s_addc_u32 s35, s35, 0
	s_cmpk_gt_u32 s76, 0x55
	s_cbranch_scc0 .LBB0_177
	s_and_b64 vcc, exec, s[52:53]
	s_cbranch_vccz .LBB0_180
	s_barrier

; #define PG8_STAGE(bufoff, gbase, voff) do { _Pragma("unroll") for (int _i = 0; _i < 2; ++_i) \
;         __builtin_amdgcn_global_load_lds((const unsigned*)((const char*)(gbase) + (voff)[_i]), (PG8_LAS unsigned*)(lds + (bufoff) + ldsw + _i * 8192), 16, 0, 0); } while (0)
; #define PG8_LDA(dst, b, h) do { _Pragma("unroll") for (int m = 0; m < 4; ++m) _Pragma("unroll") for (int k = 0; k < 2; ++k) dst[m][k] = *(const PG8_LAS bf16x8*)(lds + PG8_SA(b, h) + aoff + m * 2048 + k * 1024); } while (0)
; #define PG8_LDB(dst, b, h) do { _Pragma("unroll") for (int n = 0; n < 2; ++n) _Pragma("unroll") for (int k = 0; k < 2; ++k) dst[n][k] = *(const PG8_LAS bf16x8*)(lds + PG8_SB(b, h) + boff + n * 2048 + k * 1024); } while (0)
; #define PG8_MMA(ai, bj, At, Bt) do { __builtin_amdgcn_s_setprio(1); _Pragma("unroll") for (int m = 0; m < 4; ++m) _Pragma("unroll") for (int n = 0; n < 2; ++n) _Pragma("unroll") for (int k = 0; k < 2; ++k) \
;         acc[ai][bj][m][n] = __builtin_amdgcn_mfma_f32_16x16x32_bf16(Bt[n][k], At[m][k], acc[ai][bj][m][n], 0, 0, 0); __builtin_amdgcn_s_setprio(0); } while (0)
; #define PG8_WAIT_V(n) asm volatile("s_waitcnt vmcnt(" #n ")" ::: "memory")
; #define PG8_WAIT_L(n) asm volatile("s_waitcnt lgkmcnt(" #n ")" ::: "memory")
; template <class Epi, class Sched, bool ALIGN_EPI = false, bool SP2 = false>
; __device__ __forceinline__ void gemm_phase(PG8_LAS unsigned char* lds, const Gemm g, const Sched& S, const Epi& E) {
;     ...
;             const bool last = (t == nt - 2);
;             const char* a1 = cA + (size_t)(t + 1) * kstep;
;             const char* a2 = last ? nA : cA + (size_t)(t + 2) * kstep; const char* b2 = last ? nB : cB + (size_t)(t + 2) * kstep;
;             const char* a3 = a2 + kstep; const char* b3 = b2 + kstep;
;             if (last && has_next) S.a_ready(nxt);
;             if constexpr (SP2) {
;             PG8_LDB(B0, 0, 0); PG8_LDB(B1, 0, 1); PG8_SCHED; PG8_LDA(At, 0, 0); PG8_STAGE(PG8_SA(1, 1), a1 + hstep, voffA);
;             PG8_WAIT_V(8); PG8_WAIT_L(0); PG8_BAR; PG8_MMA(0, 0, At, B0); PG8_MMA(0, 1, At, B1); PG8_BAR; PG8_SCHED;
;             PG8_LDA(At, 0, 1); PG8_STAGE(PG8_SB(0, 0), b2, voffB); PG8_STAGE(PG8_SB(0, 1), b2 + hstep, voffB); PG8_STAGE(PG8_SA(0, 0), a2, voffA);
;             PG8_WAIT_V(8); PG8_WAIT_L(0); PG8_BAR; PG8_MMA(1, 0, At, B0); PG8_MMA(1, 1, At, B1); PG8_BAR; PG8_SCHED;
.LBB0_231:
	ds_read_b128 v[142:145], v153
	ds_read_b128 v[146:149], v153 offset:1024
	ds_read_b128 v[174:177], v153 offset:2048
	ds_read_b128 v[178:181], v153 offset:3072
	ds_read_b128 v[182:185], v154
	ds_read_b128 v[206:209], v154 offset:1024
	ds_read_b128 v[210:213], v154 offset:2048
	ds_read_b128 v[214:217], v154 offset:3072
	s_add_u32 s28, s84, 0xfff80080
	s_addc_u32 s29, s85, -1
	s_cmp_eq_u32 s97, 28
	s_cselect_b32 s49, s34, s29
	s_cselect_b32 s48, s35, s28
	s_cselect_b32 s29, s75, s96
	s_cselect_b32 s28, s77, s95
	v_lshl_add_u64 v[158:159], s[84:85], 0, v[134:135]
	s_add_i32 m0, s56, 0xc000
	ds_read_b128 v[218:221], v155
	ds_read_b128 v[222:225], v155 offset:1024
	ds_read_b128 v[226:229], v155 offset:2048
	ds_read_b128 v[230:233], v155 offset:3072
	ds_read_b128 v[234:237], v155 offset:4096
	ds_read_b128 v[238:241], v155 offset:5120
	ds_read_b128 v[242:245], v155 offset:6144
	ds_read_b128 v[246:249], v155 offset:7168
	global_load_lds_dwordx4 v[158:159], off
	v_lshl_add_u64 v[158:159], s[84:85], 0, v[136:137]
	s_add_i32 m0, s56, 0xe000
	s_nop 0
	global_load_lds_dwordx4 v[158:159], off
	s_waitcnt vmcnt(8)
	s_waitcnt lgkmcnt(0)
	s_barrier
	s_setprio 1
	s_waitcnt lgkmcnt(0)
	v_mfma_f32_16x16x32_bf16 v[124:127], v[142:145], v[218:221], v[124:127]
	v_mfma_f32_16x16x32_bf16 v[124:127], v[146:149], v[222:225], v[124:127]
	v_mfma_f32_16x16x32_bf16 v[120:123], v[178:181], v[222:225], v[120:123]
	v_mfma_f32_16x16x32_bf16 v[120:123], v[174:177], v[218:221], v[120:123]
	v_mfma_f32_16x16x32_bf16 v[104:107], v[174:177], v[226:229], v[104:107]
	v_mfma_f32_16x16x32_bf16 v[104:107], v[178:181], v[230:233], v[104:107]
	v_mfma_f32_16x16x32_bf16 v[108:111], v[146:149], v[230:233], v[108:111]
	v_mfma_f32_16x16x32_bf16 v[108:111], v[142:145], v[226:229], v[108:111]
	v_mfma_f32_16x16x32_bf16 v[92:95], v[142:145], v[234:237], v[92:95]
	v_mfma_f32_16x16x32_bf16 v[92:95], v[146:149], v[238:241], v[92:95]
	v_mfma_f32_16x16x32_bf16 v[88:91], v[178:181], v[238:241], v[88:91]
	v_mfma_f32_16x16x32_bf16 v[88:91], v[174:177], v[234:237], v[88:91]
	v_mfma_f32_16x16x32_bf16 v[72:75], v[174:177], v[242:245], v[72:75]
	v_mfma_f32_16x16x32_bf16 v[72:75], v[178:181], v[246:249], v[72:75]
	v_mfma_f32_16x16x32_bf16 v[76:79], v[146:149], v[246:249], v[76:79]
	v_mfma_f32_16x16x32_bf16 v[76:79], v[142:145], v[242:245], v[76:79]
	s_setprio 0
	s_setprio 1
	v_mfma_f32_16x16x32_bf16 v[116:119], v[182:185], v[218:221], v[116:119]
	v_mfma_f32_16x16x32_bf16 v[116:119], v[206:209], v[222:225], v[116:119]
	v_mfma_f32_16x16x32_bf16 v[112:115], v[214:217], v[222:225], v[112:115]
	v_mfma_f32_16x16x32_bf16 v[112:115], v[210:213], v[218:221], v[112:115]
	v_mfma_f32_16x16x32_bf16 v[96:99], v[210:213], v[226:229], v[96:99]
	v_mfma_f32_16x16x32_bf16 v[96:99], v[214:217], v[230:233], v[96:99]
	v_mfma_f32_16x16x32_bf16 v[100:103], v[206:209], v[230:233], v[100:103]
	v_mfma_f32_16x16x32_bf16 v[100:103], v[182:185], v[226:229], v[100:103]
	v_mfma_f32_16x16x32_bf16 v[84:87], v[182:185], v[234:237], v[84:87]
	v_mfma_f32_16x16x32_bf16 v[84:87], v[206:209], v[238:241], v[84:87]
	v_mfma_f32_16x16x32_bf16 v[80:83], v[214:217], v[238:241], v[80:83]
	v_mfma_f32_16x16x32_bf16 v[80:83], v[210:213], v[234:237], v[80:83]
	s_setprio 2
	s_barrier
	v_mfma_f32_16x16x32_bf16 v[64:67], v[210:213], v[242:245], v[64:67]
	v_mfma_f32_16x16x32_bf16 v[64:67], v[214:217], v[246:249], v[64:67]
	v_mfma_f32_16x16x32_bf16 v[68:71], v[206:209], v[246:249], v[68:71]
	v_mfma_f32_16x16x32_bf16 v[68:71], v[182:185], v[242:245], v[68:71]
	s_setprio 0
	s_add_i32 vcc_lo, s83, s13
	v_lshl_add_u64 v[158:159], s[28:29], 0, v[166:167]
	s_mov_b32 m0, vcc_lo
	ds_read_b128 v[218:221], v155 offset:16384
	ds_read_b128 v[222:225], v155 offset:17408
	ds_read_b128 v[226:229], v155 offset:18432
	ds_read_b128 v[230:233], v155 offset:19456
	ds_read_b128 v[234:237], v155 offset:20480
	ds_read_b128 v[238:241], v155 offset:21504
	ds_read_b128 v[242:245], v155 offset:22528
	ds_read_b128 v[246:249], v155 offset:23552
	global_load_lds_dwordx4 v[158:159], off
	s_add_i32 m0, vcc_lo, 0x2000
	s_add_u32 vcc_lo, s28, 0x80000
	v_lshl_add_u64 v[186:187], s[28:29], 0, v[170:171]
	s_addc_u32 vcc_hi, s29, 0
	s_add_i32 s44, s90, s13
	global_load_lds_dwordx4 v[186:187], off
	v_lshl_add_u64 v[250:251], vcc, 0, v[166:167]
	s_mov_b32 m0, s44
	v_lshl_add_u64 v[252:253], s[48:49], 0, v[168:169]
	global_load_lds_dwordx4 v[250:251], off
	v_lshl_add_u64 v[250:251], vcc, 0, v[170:171]
	s_add_i32 m0, s44, 0x2000
	s_nop 0
	global_load_lds_dwordx4 v[250:251], off
	v_lshl_add_u64 v[250:251], s[48:49], 0, v[164:165]
	s_mov_b32 m0, s56
	s_nop 0
	global_load_lds_dwordx4 v[250:251], off
	s_mov_b32 m0, s57
	s_nop 0
	global_load_lds_dwordx4 v[252:253], off
	s_waitcnt vmcnt(8)
	s_waitcnt lgkmcnt(0)
	s_barrier
; #define PG8_STAGE(bufoff, gbase, voff) do { _Pragma("unroll") for (int _i = 0; _i < 2; ++_i) \
;         __builtin_amdgcn_global_load_lds((const unsigned*)((const char*)(gbase) + (voff)[_i]), (PG8_LAS unsigned*)(lds + (bufoff) + ldsw + _i * 8192), 16, 0, 0); } while (0)
; #define PG8_LDA(dst, b, h) do { _Pragma("unroll") for (int m = 0; m < 4; ++m) _Pragma("unroll") for (int k = 0; k < 2; ++k) dst[m][k] = *(const PG8_LAS bf16x8*)(lds + PG8_SA(b, h) + aoff + m * 2048 + k * 1024); } while (0)
; #define PG8_LDB(dst, b, h) do { _Pragma("unroll") for (int n = 0; n < 2; ++n) _Pragma("unroll") for (int k = 0; k < 2; ++k) dst[n][k] = *(const PG8_LAS bf16x8*)(lds + PG8_SB(b, h) + boff + n * 2048 + k * 1024); } while (0)
; #define PG8_MMA(ai, bj, At, Bt) do { __builtin_amdgcn_s_setprio(1); _Pragma("unroll") for (int m = 0; m < 4; ++m) _Pragma("unroll") for (int n = 0; n < 2; ++n) _Pragma("unroll") for (int k = 0; k < 2; ++k) \
;         acc[ai][bj][m][n] = __builtin_amdgcn_mfma_f32_16x16x32_bf16(Bt[n][k], At[m][k], acc[ai][bj][m][n], 0, 0, 0); __builtin_amdgcn_s_setprio(0); } while (0)
; #define PG8_WAIT_V(n) asm volatile("s_waitcnt vmcnt(" #n ")" ::: "memory")
; #define PG8_WAIT_L(n) asm volatile("s_waitcnt lgkmcnt(" #n ")" ::: "memory")
; #define PG8_BAR __builtin_amdgcn_s_barrier()
; #define PG8_SCHED __builtin_amdgcn_sched_barrier(0)
; template <class Epi, class Sched, bool ALIGN_EPI = false, bool SP2 = false>
; __device__ __forceinline__ void gemm_phase(PG8_LAS unsigned char* lds, const Gemm g, const Sched& S, const Epi& E) {
;     ...
;             PG8_WAIT_V(8); PG8_WAIT_L(0); PG8_BAR; PG8_MMA(1, 0, At, B0); PG8_MMA(1, 1, At, B1); PG8_BAR; PG8_SCHED;
;             PG8_LDB(B0, 1, 0); PG8_LDB(B1, 1, 1); PG8_SCHED; PG8_LDA(At, 1, 0); PG8_STAGE(PG8_SA(0, 1), a2 + hstep, voffA);
;             PG8_WAIT_V(8); PG8_WAIT_L(0); PG8_BAR; PG8_MMA(0, 0, At, B0); PG8_MMA(0, 1, At, B1); PG8_BAR; PG8_SCHED;
	s_setprio 1
	s_waitcnt lgkmcnt(0)
	v_mfma_f32_16x16x32_bf16 v[60:63], v[142:145], v[218:221], v[60:63]
	v_mfma_f32_16x16x32_bf16 v[60:63], v[146:149], v[222:225], v[60:63]
	v_mfma_f32_16x16x32_bf16 v[56:59], v[178:181], v[222:225], v[56:59]
	v_mfma_f32_16x16x32_bf16 v[56:59], v[174:177], v[218:221], v[56:59]
	v_mfma_f32_16x16x32_bf16 v[40:43], v[174:177], v[226:229], v[40:43]
	v_mfma_f32_16x16x32_bf16 v[40:43], v[178:181], v[230:233], v[40:43]
	v_mfma_f32_16x16x32_bf16 v[44:47], v[146:149], v[230:233], v[44:47]
	v_mfma_f32_16x16x32_bf16 v[44:47], v[142:145], v[226:229], v[44:47]
	v_mfma_f32_16x16x32_bf16 v[28:31], v[142:145], v[234:237], v[28:31]
	v_mfma_f32_16x16x32_bf16 v[28:31], v[146:149], v[238:241], v[28:31]
	v_mfma_f32_16x16x32_bf16 v[24:27], v[178:181], v[238:241], v[24:27]
	v_mfma_f32_16x16x32_bf16 v[24:27], v[174:177], v[234:237], v[24:27]
	v_mfma_f32_16x16x32_bf16 v[8:11], v[174:177], v[242:245], v[8:11]
	v_mfma_f32_16x16x32_bf16 v[8:11], v[178:181], v[246:249], v[8:11]
	v_mfma_f32_16x16x32_bf16 v[12:15], v[146:149], v[246:249], v[12:15]
	v_mfma_f32_16x16x32_bf16 v[12:15], v[142:145], v[242:245], v[12:15]
	s_setprio 0
	s_setprio 1
	v_mfma_f32_16x16x32_bf16 v[52:55], v[182:185], v[218:221], v[52:55]
	v_mfma_f32_16x16x32_bf16 v[52:55], v[206:209], v[222:225], v[52:55]
	v_mfma_f32_16x16x32_bf16 v[48:51], v[214:217], v[222:225], v[48:51]
	v_mfma_f32_16x16x32_bf16 v[48:51], v[210:213], v[218:221], v[48:51]
	v_mfma_f32_16x16x32_bf16 v[32:35], v[210:213], v[226:229], v[32:35]
	v_mfma_f32_16x16x32_bf16 v[32:35], v[214:217], v[230:233], v[32:35]
	v_mfma_f32_16x16x32_bf16 v[36:39], v[206:209], v[230:233], v[36:39]
	v_mfma_f32_16x16x32_bf16 v[36:39], v[182:185], v[226:229], v[36:39]
	v_mfma_f32_16x16x32_bf16 v[20:23], v[182:185], v[234:237], v[20:23]
	v_mfma_f32_16x16x32_bf16 v[20:23], v[206:209], v[238:241], v[20:23]
	v_mfma_f32_16x16x32_bf16 v[16:19], v[214:217], v[238:241], v[16:19]
	v_mfma_f32_16x16x32_bf16 v[16:19], v[210:213], v[234:237], v[16:19]
	s_setprio 2
	s_barrier
	v_mfma_f32_16x16x32_bf16 v[0:3], v[210:213], v[242:245], v[0:3]
	v_mfma_f32_16x16x32_bf16 v[0:3], v[214:217], v[246:249], v[0:3]
	v_mfma_f32_16x16x32_bf16 v[4:7], v[206:209], v[246:249], v[4:7]
	v_mfma_f32_16x16x32_bf16 v[4:7], v[182:185], v[242:245], v[4:7]
	s_setprio 0
	s_add_i32 s44, 0, 0x18000
	v_add_u32_e32 v161, s44, v151
	s_add_i32 s45, 0, 0x1c000
	ds_read_b128 v[142:145], v161
	ds_read_b128 v[146:149], v161 offset:1024
	ds_read_b128 v[174:177], v161 offset:2048
	ds_read_b128 v[178:181], v161 offset:3072
	v_add_u32_e32 v161, s45, v151
	ds_read_b128 v[182:185], v161
	ds_read_b128 v[206:209], v161 offset:1024
	ds_read_b128 v[210:213], v161 offset:2048
	ds_read_b128 v[214:217], v161 offset:3072
	s_add_u32 s48, s48, 0x80000
	s_addc_u32 s49, s49, 0
	s_mov_b32 m0, s60
	v_lshl_add_u64 v[200:201], s[48:49], 0, v[164:165]
	ds_read_b128 v[218:221], v155 offset:32768
	ds_read_b128 v[222:225], v155 offset:33792
	ds_read_b128 v[226:229], v155 offset:34816
	ds_read_b128 v[230:233], v155 offset:35840
	ds_read_b128 v[234:237], v155 offset:36864
	ds_read_b128 v[238:241], v155 offset:37888
	ds_read_b128 v[242:245], v155 offset:38912
	ds_read_b128 v[246:249], v155 offset:39936
	global_load_lds_dwordx4 v[200:201], off
	v_lshl_add_u64 v[200:201], s[48:49], 0, v[168:169]
	s_mov_b32 m0, s61
	s_nop 0
	global_load_lds_dwordx4 v[200:201], off
	s_waitcnt vmcnt(8)
	s_waitcnt lgkmcnt(0)
	s_barrier
	s_setprio 1
	s_waitcnt lgkmcnt(0)
	v_mfma_f32_16x16x32_bf16 v[124:127], v[142:145], v[218:221], v[124:127]
	v_mfma_f32_16x16x32_bf16 v[124:127], v[146:149], v[222:225], v[124:127]
	v_mfma_f32_16x16x32_bf16 v[120:123], v[178:181], v[222:225], v[120:123]
	v_mfma_f32_16x16x32_bf16 v[120:123], v[174:177], v[218:221], v[120:123]
	v_mfma_f32_16x16x32_bf16 v[104:107], v[174:177], v[226:229], v[104:107]
	v_mfma_f32_16x16x32_bf16 v[104:107], v[178:181], v[230:233], v[104:107]
	v_mfma_f32_16x16x32_bf16 v[108:111], v[146:149], v[230:233], v[108:111]
	v_mfma_f32_16x16x32_bf16 v[108:111], v[142:145], v[226:229], v[108:111]
	v_mfma_f32_16x16x32_bf16 v[92:95], v[142:145], v[234:237], v[92:95]
	v_mfma_f32_16x16x32_bf16 v[92:95], v[146:149], v[238:241], v[92:95]
	v_mfma_f32_16x16x32_bf16 v[88:91], v[178:181], v[238:241], v[88:91]
	v_mfma_f32_16x16x32_bf16 v[88:91], v[174:177], v[234:237], v[88:91]
	v_mfma_f32_16x16x32_bf16 v[72:75], v[174:177], v[242:245], v[72:75]
	v_mfma_f32_16x16x32_bf16 v[72:75], v[178:181], v[246:249], v[72:75]
	v_mfma_f32_16x16x32_bf16 v[76:79], v[146:149], v[246:249], v[76:79]
	v_mfma_f32_16x16x32_bf16 v[76:79], v[142:145], v[242:245], v[76:79]
	s_setprio 0
	s_setprio 1
	v_mfma_f32_16x16x32_bf16 v[116:119], v[182:185], v[218:221], v[116:119]
	v_mfma_f32_16x16x32_bf16 v[116:119], v[206:209], v[222:225], v[116:119]
	v_mfma_f32_16x16x32_bf16 v[112:115], v[214:217], v[222:225], v[112:115]
	v_mfma_f32_16x16x32_bf16 v[112:115], v[210:213], v[218:221], v[112:115]
	v_mfma_f32_16x16x32_bf16 v[96:99], v[210:213], v[226:229], v[96:99]
	v_mfma_f32_16x16x32_bf16 v[96:99], v[214:217], v[230:233], v[96:99]
	v_mfma_f32_16x16x32_bf16 v[100:103], v[206:209], v[230:233], v[100:103]
	v_mfma_f32_16x16x32_bf16 v[100:103], v[182:185], v[226:229], v[100:103]
	v_mfma_f32_16x16x32_bf16 v[84:87], v[182:185], v[234:237], v[84:87]
	v_mfma_f32_16x16x32_bf16 v[84:87], v[206:209], v[238:241], v[84:87]
	v_mfma_f32_16x16x32_bf16 v[80:83], v[214:217], v[238:241], v[80:83]
	v_mfma_f32_16x16x32_bf16 v[80:83], v[210:213], v[234:237], v[80:83]
	s_setprio 2
	s_barrier
; #define PG8_STAGE(bufoff, gbase, voff) do { _Pragma("unroll") for (int _i = 0; _i < 2; ++_i) \
;         __builtin_amdgcn_global_load_lds((const unsigned*)((const char*)(gbase) + (voff)[_i]), (PG8_LAS unsigned*)(lds + (bufoff) + ldsw + _i * 8192), 16, 0, 0); } while (0)
; #define PG8_LDA(dst, b, h) do { _Pragma("unroll") for (int m = 0; m < 4; ++m) _Pragma("unroll") for (int k = 0; k < 2; ++k) dst[m][k] = *(const PG8_LAS bf16x8*)(lds + PG8_SA(b, h) + aoff + m * 2048 + k * 1024); } while (0)
; #define PG8_MMA(ai, bj, At, Bt) do { __builtin_amdgcn_s_setprio(1); _Pragma("unroll") for (int m = 0; m < 4; ++m) _Pragma("unroll") for (int n = 0; n < 2; ++n) _Pragma("unroll") for (int k = 0; k < 2; ++k) \
;         acc[ai][bj][m][n] = __builtin_amdgcn_mfma_f32_16x16x32_bf16(Bt[n][k], At[m][k], acc[ai][bj][m][n], 0, 0, 0); __builtin_amdgcn_s_setprio(0); } while (0)
; #define PG8_WAIT_V(n) asm volatile("s_waitcnt vmcnt(" #n ")" ::: "memory")
; #define PG8_WAIT_L(n) asm volatile("s_waitcnt lgkmcnt(" #n ")" ::: "memory")
; #define PG8_BAR __builtin_amdgcn_s_barrier()
; #define PG8_SCHED __builtin_amdgcn_sched_barrier(0)
;     __device__ __forceinline__ void operator()(const f32x4 (&acc)[2][2][4][2], const Unit& u, int wr, int wc, int fr, int fq) const {
;     ...
;         if (u.pn < 8) {
; template <class Epi, class Sched, bool ALIGN_EPI = false, bool SP2 = false>
; __device__ __forceinline__ void gemm_phase(PG8_LAS unsigned char* lds, const Gemm g, const Sched& S, const Epi& E) {
;     ...
;             PG8_WAIT_V(8); PG8_WAIT_L(0); PG8_BAR; PG8_MMA(0, 0, At, B0); PG8_MMA(0, 1, At, B1); PG8_BAR; PG8_SCHED;
;             PG8_LDA(At, 1, 1); PG8_STAGE(PG8_SB(1, 0), b3, voffB); PG8_STAGE(PG8_SB(1, 1), b3 + hstep, voffB); PG8_STAGE(PG8_SA(1, 0), a3, voffA);
;             PG8_WAIT_V(8); PG8_WAIT_L(0); PG8_BAR; PG8_MMA(1, 0, At, B0); PG8_MMA(1, 1, At, B1); PG8_BAR; PG8_SCHED;
	v_mfma_f32_16x16x32_bf16 v[64:67], v[210:213], v[242:245], v[64:67]
	v_mfma_f32_16x16x32_bf16 v[64:67], v[214:217], v[246:249], v[64:67]
	v_mfma_f32_16x16x32_bf16 v[68:71], v[206:209], v[246:249], v[68:71]
	v_mfma_f32_16x16x32_bf16 v[68:71], v[182:185], v[242:245], v[68:71]
	s_setprio 0
	s_add_i32 s44, s44, s13
	v_lshl_add_u64 v[158:159], v[158:159], 0, s[52:53]
	s_mov_b32 m0, s44
	ds_read_b128 v[218:221], v155 offset:49152
	ds_read_b128 v[222:225], v155 offset:50176
	ds_read_b128 v[226:229], v155 offset:51200
	ds_read_b128 v[230:233], v155 offset:52224
	ds_read_b128 v[234:237], v155 offset:53248
	ds_read_b128 v[238:241], v155 offset:54272
	ds_read_b128 v[242:245], v155 offset:55296
	ds_read_b128 v[246:249], v155 offset:56320
	global_load_lds_dwordx4 v[158:159], off
	s_add_i32 m0, s44, 0x2000
	s_add_u32 s28, s28, 0x80080
	v_lshl_add_u64 v[158:159], v[186:187], 0, s[52:53]
	s_addc_u32 s29, s29, 0
	s_add_i32 s44, s45, s13
	global_load_lds_dwordx4 v[158:159], off
	v_lshl_add_u64 v[158:159], s[28:29], 0, v[166:167]
	s_mov_b32 m0, s44
	s_nop 0
	global_load_lds_dwordx4 v[158:159], off
	v_lshl_add_u64 v[158:159], s[28:29], 0, v[170:171]
	s_add_i32 m0, s44, 0x2000
	s_nop 0
	global_load_lds_dwordx4 v[158:159], off
	v_lshl_add_u64 v[158:159], v[250:251], 0, s[52:53]
	s_mov_b32 m0, s62
	s_nop 0
	global_load_lds_dwordx4 v[158:159], off
	v_lshl_add_u64 v[158:159], v[252:253], 0, s[52:53]
	s_mov_b32 m0, s63
	s_nop 0
	global_load_lds_dwordx4 v[158:159], off
	s_waitcnt vmcnt(8)
	s_waitcnt lgkmcnt(0)
	s_barrier
	s_setprio 1
	s_waitcnt lgkmcnt(0)
	v_mfma_f32_16x16x32_bf16 v[60:63], v[142:145], v[218:221], v[60:63]
	v_mfma_f32_16x16x32_bf16 v[60:63], v[146:149], v[222:225], v[60:63]
	v_mfma_f32_16x16x32_bf16 v[56:59], v[178:181], v[222:225], v[56:59]
	v_mfma_f32_16x16x32_bf16 v[56:59], v[174:177], v[218:221], v[56:59]
	v_mfma_f32_16x16x32_bf16 v[40:43], v[174:177], v[226:229], v[40:43]
	v_mfma_f32_16x16x32_bf16 v[40:43], v[178:181], v[230:233], v[40:43]
	v_mfma_f32_16x16x32_bf16 v[44:47], v[146:149], v[230:233], v[44:47]
	v_mfma_f32_16x16x32_bf16 v[44:47], v[142:145], v[226:229], v[44:47]
	v_mfma_f32_16x16x32_bf16 v[28:31], v[142:145], v[234:237], v[28:31]
	v_mfma_f32_16x16x32_bf16 v[28:31], v[146:149], v[238:241], v[28:31]
	v_mfma_f32_16x16x32_bf16 v[24:27], v[178:181], v[238:241], v[24:27]
	v_mfma_f32_16x16x32_bf16 v[24:27], v[174:177], v[234:237], v[24:27]
	v_mfma_f32_16x16x32_bf16 v[8:11], v[174:177], v[242:245], v[8:11]
	v_mfma_f32_16x16x32_bf16 v[8:11], v[178:181], v[246:249], v[8:11]
	v_mfma_f32_16x16x32_bf16 v[12:15], v[146:149], v[246:249], v[12:15]
	v_mfma_f32_16x16x32_bf16 v[12:15], v[142:145], v[242:245], v[12:15]
	s_setprio 0
	s_setprio 1
	v_mfma_f32_16x16x32_bf16 v[52:55], v[182:185], v[218:221], v[52:55]
	v_mfma_f32_16x16x32_bf16 v[52:55], v[206:209], v[222:225], v[52:55]
	v_mfma_f32_16x16x32_bf16 v[48:51], v[214:217], v[222:225], v[48:51]
	v_mfma_f32_16x16x32_bf16 v[48:51], v[210:213], v[218:221], v[48:51]
	v_mfma_f32_16x16x32_bf16 v[32:35], v[210:213], v[226:229], v[32:35]
	v_mfma_f32_16x16x32_bf16 v[32:35], v[214:217], v[230:233], v[32:35]
	v_mfma_f32_16x16x32_bf16 v[36:39], v[206:209], v[230:233], v[36:39]
	v_mfma_f32_16x16x32_bf16 v[36:39], v[182:185], v[226:229], v[36:39]
	v_mfma_f32_16x16x32_bf16 v[20:23], v[182:185], v[234:237], v[20:23]
	v_mfma_f32_16x16x32_bf16 v[20:23], v[206:209], v[238:241], v[20:23]
	v_mfma_f32_16x16x32_bf16 v[16:19], v[214:217], v[238:241], v[16:19]
	v_mfma_f32_16x16x32_bf16 v[16:19], v[210:213], v[234:237], v[16:19]
	s_setprio 2
	s_barrier
	v_mfma_f32_16x16x32_bf16 v[0:3], v[210:213], v[242:245], v[0:3]
	v_mfma_f32_16x16x32_bf16 v[0:3], v[214:217], v[246:249], v[0:3]
	v_mfma_f32_16x16x32_bf16 v[4:7], v[206:209], v[246:249], v[4:7]
	v_mfma_f32_16x16x32_bf16 v[4:7], v[182:185], v[242:245], v[4:7]
	s_setprio 0
	s_add_i32 s97, s97, 2
	s_add_u32 s84, s84, 0x100
	s_addc_u32 s85, s85, 0
	s_add_u32 s95, s95, 0x100
	s_addc_u32 s96, s96, 0
	s_cmp_gt_u32 s97, 29
	s_cbranch_scc0 .LBB0_231
	s_and_b64 vcc, exec, s[72:73]
	s_cbranch_vccz .LBB0_236
	s_barrier
	v_lshl_add_u32 v142, s82, 8, v150
	s_cmp_gt_i32 s94, 7
	s_mov_b64 s[28:29], -1
	s_cbranch_scc1 .LBB0_237

; #define PG8_STAGE(bufoff, gbase, voff) do { _Pragma("unroll") for (int _i = 0; _i < 2; ++_i) \
;         __builtin_amdgcn_global_load_lds((const unsigned*)((const char*)(gbase) + (voff)[_i]), (PG8_LAS unsigned*)(lds + (bufoff) + ldsw + _i * 8192), 16, 0, 0); } while (0)
; #define PG8_LDA(dst, b, h) do { _Pragma("unroll") for (int m = 0; m < 4; ++m) _Pragma("unroll") for (int k = 0; k < 2; ++k) dst[m][k] = *(const PG8_LAS bf16x8*)(lds + PG8_SA(b, h) + aoff + m * 2048 + k * 1024); } while (0)
; #define PG8_LDB(dst, b, h) do { _Pragma("unroll") for (int n = 0; n < 2; ++n) _Pragma("unroll") for (int k = 0; k < 2; ++k) dst[n][k] = *(const PG8_LAS bf16x8*)(lds + PG8_SB(b, h) + boff + n * 2048 + k * 1024); } while (0)
; #define PG8_MMA(ai, bj, At, Bt) do { __builtin_amdgcn_s_setprio(1); _Pragma("unroll") for (int m = 0; m < 4; ++m) _Pragma("unroll") for (int n = 0; n < 2; ++n) _Pragma("unroll") for (int k = 0; k < 2; ++k) \
;         acc[ai][bj][m][n] = __builtin_amdgcn_mfma_f32_16x16x32_bf16(Bt[n][k], At[m][k], acc[ai][bj][m][n], 0, 0, 0); __builtin_amdgcn_s_setprio(0); } while (0)
; #define PG8_WAIT_V(n) asm volatile("s_waitcnt vmcnt(" #n ")" ::: "memory")
; #define PG8_WAIT_L(n) asm volatile("s_waitcnt lgkmcnt(" #n ")" ::: "memory")
; template <class Epi, class Sched, bool ALIGN_EPI = false, bool SP2 = false>
; __device__ __forceinline__ void gemm_phase(PG8_LAS unsigned char* lds, const Gemm g, const Sched& S, const Epi& E) {
;     ...
;             const bool last = (t == nt - 2);
;             const char* a1 = cA + (size_t)(t + 1) * kstep;
;             const char* a2 = last ? nA : cA + (size_t)(t + 2) * kstep; const char* b2 = last ? nB : cB + (size_t)(t + 2) * kstep;
;             const char* a3 = a2 + kstep; const char* b3 = b2 + kstep;
;             if (last && has_next) S.a_ready(nxt);
;             if constexpr (SP2) {
;             PG8_LDB(B0, 0, 0); PG8_LDB(B1, 0, 1); PG8_SCHED; PG8_LDA(At, 0, 0); PG8_STAGE(PG8_SA(1, 1), a1 + hstep, voffA);
;             PG8_WAIT_V(8); PG8_WAIT_L(0); PG8_BAR; PG8_MMA(0, 0, At, B0); PG8_MMA(0, 1, At, B1); PG8_BAR; PG8_SCHED;
;             PG8_LDA(At, 0, 1); PG8_STAGE(PG8_SB(0, 0), b2, voffB); PG8_STAGE(PG8_SB(0, 1), b2 + hstep, voffB); PG8_STAGE(PG8_SA(0, 0), a2, voffA);
;             PG8_WAIT_V(8); PG8_WAIT_L(0); PG8_BAR; PG8_MMA(1, 0, At, B0); PG8_MMA(1, 1, At, B1); PG8_BAR; PG8_SCHED;
.LBB0_362:
	ds_read_b128 v[80:83], v171
	ds_read_b128 v[84:87], v171 offset:1024
	ds_read_b128 v[92:95], v171 offset:2048
	ds_read_b128 v[100:103], v171 offset:3072
	ds_read_b128 v[144:147], v186
	ds_read_b128 v[148:151], v186 offset:1024
	ds_read_b128 v[152:155], v186 offset:2048
	ds_read_b128 v[156:159], v186 offset:3072
	s_add_u32 s28, s74, 0xfff80080
	s_addc_u32 s29, s75, -1
	s_cmp_eq_u32 s77, 28
	s_cselect_b32 s49, s23, s29
	s_cselect_b32 s48, s34, s28
	s_cselect_b32 s29, s21, s76
	s_cselect_b32 s28, s35, s73
	v_lshl_add_u64 v[200:201], s[74:75], 0, v[172:173]
	s_add_i32 m0, s38, 0xc000
	ds_read_b128 v[178:181], v187
	ds_read_b128 v[182:185], v187 offset:1024
	ds_read_b128 v[206:209], v187 offset:2048
	ds_read_b128 v[210:213], v187 offset:3072
	ds_read_b128 v[214:217], v187 offset:4096
	ds_read_b128 v[218:221], v187 offset:5120
	ds_read_b128 v[222:225], v187 offset:6144
	ds_read_b128 v[226:229], v187 offset:7168
	global_load_lds_dwordx4 v[200:201], off
	v_lshl_add_u64 v[200:201], s[74:75], 0, v[174:175]
	s_add_i32 m0, s38, 0xe000
	s_nop 0
	global_load_lds_dwordx4 v[200:201], off
	s_waitcnt vmcnt(8)
	s_waitcnt lgkmcnt(0)
	s_barrier
	s_setprio 1
	s_waitcnt lgkmcnt(0)
	v_mfma_f32_16x16x32_bf16 v[140:143], v[80:83], v[178:181], v[140:143]
	v_mfma_f32_16x16x32_bf16 v[140:143], v[84:87], v[182:185], v[140:143]
	v_mfma_f32_16x16x32_bf16 v[136:139], v[100:103], v[182:185], v[136:139]
	v_mfma_f32_16x16x32_bf16 v[136:139], v[92:95], v[178:181], v[136:139]
	v_mfma_f32_16x16x32_bf16 v[120:123], v[92:95], v[206:209], v[120:123]
	v_mfma_f32_16x16x32_bf16 v[120:123], v[100:103], v[210:213], v[120:123]
	v_mfma_f32_16x16x32_bf16 v[124:127], v[84:87], v[210:213], v[124:127]
	v_mfma_f32_16x16x32_bf16 v[124:127], v[80:83], v[206:209], v[124:127]
	v_mfma_f32_16x16x32_bf16 v[108:111], v[80:83], v[214:217], v[108:111]
	v_mfma_f32_16x16x32_bf16 v[108:111], v[84:87], v[218:221], v[108:111]
	v_mfma_f32_16x16x32_bf16 v[104:107], v[100:103], v[218:221], v[104:107]
	v_mfma_f32_16x16x32_bf16 v[104:107], v[92:95], v[214:217], v[104:107]
	v_mfma_f32_16x16x32_bf16 v[72:75], v[92:95], v[222:225], v[72:75]
	v_mfma_f32_16x16x32_bf16 v[72:75], v[100:103], v[226:229], v[72:75]
	v_mfma_f32_16x16x32_bf16 v[76:79], v[84:87], v[226:229], v[76:79]
	v_mfma_f32_16x16x32_bf16 v[76:79], v[80:83], v[222:225], v[76:79]
	s_setprio 0
	s_setprio 1
	v_mfma_f32_16x16x32_bf16 v[132:135], v[144:147], v[178:181], v[132:135]
	v_mfma_f32_16x16x32_bf16 v[132:135], v[148:151], v[182:185], v[132:135]
	v_mfma_f32_16x16x32_bf16 v[128:131], v[156:159], v[182:185], v[128:131]
	v_mfma_f32_16x16x32_bf16 v[128:131], v[152:155], v[178:181], v[128:131]
	v_mfma_f32_16x16x32_bf16 v[112:115], v[152:155], v[206:209], v[112:115]
	v_mfma_f32_16x16x32_bf16 v[112:115], v[156:159], v[210:213], v[112:115]
	v_mfma_f32_16x16x32_bf16 v[116:119], v[148:151], v[210:213], v[116:119]
	v_mfma_f32_16x16x32_bf16 v[116:119], v[144:147], v[206:209], v[116:119]
	v_mfma_f32_16x16x32_bf16 v[96:99], v[144:147], v[214:217], v[96:99]
	v_mfma_f32_16x16x32_bf16 v[96:99], v[148:151], v[218:221], v[96:99]
	v_mfma_f32_16x16x32_bf16 v[88:91], v[156:159], v[218:221], v[88:91]
	v_mfma_f32_16x16x32_bf16 v[88:91], v[152:155], v[214:217], v[88:91]
	s_setprio 2
	s_barrier
	v_mfma_f32_16x16x32_bf16 v[64:67], v[152:155], v[222:225], v[64:67]
	v_mfma_f32_16x16x32_bf16 v[64:67], v[156:159], v[226:229], v[64:67]
	v_mfma_f32_16x16x32_bf16 v[68:71], v[148:151], v[226:229], v[68:71]
	v_mfma_f32_16x16x32_bf16 v[68:71], v[144:147], v[222:225], v[68:71]
	s_setprio 0
	s_add_i32 s44, s62, s13
	v_lshl_add_u64 v[200:201], s[28:29], 0, v[164:165]
	s_mov_b32 m0, s44
	ds_read_b128 v[178:181], v187 offset:16384
	ds_read_b128 v[182:185], v187 offset:17408
	ds_read_b128 v[206:209], v187 offset:18432
	ds_read_b128 v[210:213], v187 offset:19456
	ds_read_b128 v[214:217], v187 offset:20480
	ds_read_b128 v[218:221], v187 offset:21504
	ds_read_b128 v[222:225], v187 offset:22528
	ds_read_b128 v[226:229], v187 offset:23552
	global_load_lds_dwordx4 v[200:201], off
	s_add_i32 m0, s44, 0x2000
	s_add_u32 s78, s28, 0x80000
	v_lshl_add_u64 v[230:231], s[28:29], 0, v[168:169]
	s_addc_u32 s79, s29, 0
	s_add_i32 s44, s63, s13
	global_load_lds_dwordx4 v[230:231], off
	v_lshl_add_u64 v[232:233], s[78:79], 0, v[164:165]
	s_mov_b32 m0, s44
	v_lshl_add_u64 v[234:235], s[48:49], 0, v[168:169]
	global_load_lds_dwordx4 v[232:233], off
	v_lshl_add_u64 v[232:233], s[78:79], 0, v[168:169]
	s_add_i32 m0, s44, 0x2000
	s_nop 0
	global_load_lds_dwordx4 v[232:233], off
	v_lshl_add_u64 v[232:233], s[48:49], 0, v[164:165]
	s_mov_b32 m0, s38
	s_nop 0
	global_load_lds_dwordx4 v[232:233], off
	s_mov_b32 m0, s39
	s_nop 0
	global_load_lds_dwordx4 v[234:235], off
	s_waitcnt vmcnt(8)
	s_waitcnt lgkmcnt(0)
	s_barrier
; #define PG8_STAGE(bufoff, gbase, voff) do { _Pragma("unroll") for (int _i = 0; _i < 2; ++_i) \
;         __builtin_amdgcn_global_load_lds((const unsigned*)((const char*)(gbase) + (voff)[_i]), (PG8_LAS unsigned*)(lds + (bufoff) + ldsw + _i * 8192), 16, 0, 0); } while (0)
; #define PG8_LDA(dst, b, h) do { _Pragma("unroll") for (int m = 0; m < 4; ++m) _Pragma("unroll") for (int k = 0; k < 2; ++k) dst[m][k] = *(const PG8_LAS bf16x8*)(lds + PG8_SA(b, h) + aoff + m * 2048 + k * 1024); } while (0)
; #define PG8_LDB(dst, b, h) do { _Pragma("unroll") for (int n = 0; n < 2; ++n) _Pragma("unroll") for (int k = 0; k < 2; ++k) dst[n][k] = *(const PG8_LAS bf16x8*)(lds + PG8_SB(b, h) + boff + n * 2048 + k * 1024); } while (0)
; #define PG8_MMA(ai, bj, At, Bt) do { __builtin_amdgcn_s_setprio(1); _Pragma("unroll") for (int m = 0; m < 4; ++m) _Pragma("unroll") for (int n = 0; n < 2; ++n) _Pragma("unroll") for (int k = 0; k < 2; ++k) \
;         acc[ai][bj][m][n] = __builtin_amdgcn_mfma_f32_16x16x32_bf16(Bt[n][k], At[m][k], acc[ai][bj][m][n], 0, 0, 0); __builtin_amdgcn_s_setprio(0); } while (0)
; #define PG8_WAIT_V(n) asm volatile("s_waitcnt vmcnt(" #n ")" ::: "memory")
; #define PG8_WAIT_L(n) asm volatile("s_waitcnt lgkmcnt(" #n ")" ::: "memory")
; #define PG8_BAR __builtin_amdgcn_s_barrier()
; #define PG8_SCHED __builtin_amdgcn_sched_barrier(0)
; template <class Epi, class Sched, bool ALIGN_EPI = false, bool SP2 = false>
; __device__ __forceinline__ void gemm_phase(PG8_LAS unsigned char* lds, const Gemm g, const Sched& S, const Epi& E) {
;     ...
;             PG8_WAIT_V(8); PG8_WAIT_L(0); PG8_BAR; PG8_MMA(1, 0, At, B0); PG8_MMA(1, 1, At, B1); PG8_BAR; PG8_SCHED;
;             PG8_LDB(B0, 1, 0); PG8_LDB(B1, 1, 1); PG8_SCHED; PG8_LDA(At, 1, 0); PG8_STAGE(PG8_SA(0, 1), a2 + hstep, voffA);
;             PG8_WAIT_V(8); PG8_WAIT_L(0); PG8_BAR; PG8_MMA(0, 0, At, B0); PG8_MMA(0, 1, At, B1); PG8_BAR; PG8_SCHED;
	s_setprio 1
	s_waitcnt lgkmcnt(0)
	v_mfma_f32_16x16x32_bf16 v[60:63], v[80:83], v[178:181], v[60:63]
	v_mfma_f32_16x16x32_bf16 v[60:63], v[84:87], v[182:185], v[60:63]
	v_mfma_f32_16x16x32_bf16 v[56:59], v[100:103], v[182:185], v[56:59]
	v_mfma_f32_16x16x32_bf16 v[56:59], v[92:95], v[178:181], v[56:59]
	v_mfma_f32_16x16x32_bf16 v[40:43], v[92:95], v[206:209], v[40:43]
	v_mfma_f32_16x16x32_bf16 v[40:43], v[100:103], v[210:213], v[40:43]
	v_mfma_f32_16x16x32_bf16 v[44:47], v[84:87], v[210:213], v[44:47]
	v_mfma_f32_16x16x32_bf16 v[44:47], v[80:83], v[206:209], v[44:47]
	v_mfma_f32_16x16x32_bf16 v[28:31], v[80:83], v[214:217], v[28:31]
	v_mfma_f32_16x16x32_bf16 v[28:31], v[84:87], v[218:221], v[28:31]
	v_mfma_f32_16x16x32_bf16 v[24:27], v[100:103], v[218:221], v[24:27]
	v_mfma_f32_16x16x32_bf16 v[24:27], v[92:95], v[214:217], v[24:27]
	v_mfma_f32_16x16x32_bf16 v[8:11], v[92:95], v[222:225], v[8:11]
	v_mfma_f32_16x16x32_bf16 v[8:11], v[100:103], v[226:229], v[8:11]
	v_mfma_f32_16x16x32_bf16 v[12:15], v[84:87], v[226:229], v[12:15]
	v_mfma_f32_16x16x32_bf16 v[12:15], v[80:83], v[222:225], v[12:15]
	s_setprio 0
	s_setprio 1
	v_mfma_f32_16x16x32_bf16 v[52:55], v[144:147], v[178:181], v[52:55]
	v_mfma_f32_16x16x32_bf16 v[52:55], v[148:151], v[182:185], v[52:55]
	v_mfma_f32_16x16x32_bf16 v[48:51], v[156:159], v[182:185], v[48:51]
	v_mfma_f32_16x16x32_bf16 v[48:51], v[152:155], v[178:181], v[48:51]
	v_mfma_f32_16x16x32_bf16 v[32:35], v[152:155], v[206:209], v[32:35]
	v_mfma_f32_16x16x32_bf16 v[32:35], v[156:159], v[210:213], v[32:35]
	v_mfma_f32_16x16x32_bf16 v[36:39], v[148:151], v[210:213], v[36:39]
	v_mfma_f32_16x16x32_bf16 v[36:39], v[144:147], v[206:209], v[36:39]
	v_mfma_f32_16x16x32_bf16 v[20:23], v[144:147], v[214:217], v[20:23]
	v_mfma_f32_16x16x32_bf16 v[20:23], v[148:151], v[218:221], v[20:23]
	v_mfma_f32_16x16x32_bf16 v[16:19], v[156:159], v[218:221], v[16:19]
	v_mfma_f32_16x16x32_bf16 v[16:19], v[152:155], v[214:217], v[16:19]
	s_setprio 2
	s_barrier
	v_mfma_f32_16x16x32_bf16 v[0:3], v[152:155], v[222:225], v[0:3]
	v_mfma_f32_16x16x32_bf16 v[0:3], v[156:159], v[226:229], v[0:3]
	v_mfma_f32_16x16x32_bf16 v[4:7], v[148:151], v[226:229], v[4:7]
	v_mfma_f32_16x16x32_bf16 v[4:7], v[144:147], v[222:225], v[4:7]
	s_setprio 0
	s_add_i32 s44, 0, 0x18000
	s_add_i32 s45, 0, 0x1c000
	v_add_u32_e32 v100, s44, v163
	v_add_u32_e32 v156, s45, v163
	ds_read_b128 v[80:83], v100
	ds_read_b128 v[84:87], v100 offset:1024
	ds_read_b128 v[92:95], v100 offset:2048
	ds_read_b128 v[100:103], v100 offset:3072
	ds_read_b128 v[144:147], v156
	ds_read_b128 v[148:151], v156 offset:1024
	ds_read_b128 v[152:155], v156 offset:2048
	ds_read_b128 v[156:159], v156 offset:3072
	s_add_u32 s48, s48, 0x80000
	s_addc_u32 s49, s49, 0
	s_mov_b32 m0, s40
	v_lshl_add_u64 v[236:237], s[48:49], 0, v[164:165]
	ds_read_b128 v[178:181], v187 offset:32768
	ds_read_b128 v[182:185], v187 offset:33792
	ds_read_b128 v[206:209], v187 offset:34816
	ds_read_b128 v[210:213], v187 offset:35840
	ds_read_b128 v[214:217], v187 offset:36864
	ds_read_b128 v[218:221], v187 offset:37888
	ds_read_b128 v[222:225], v187 offset:38912
	ds_read_b128 v[226:229], v187 offset:39936
	global_load_lds_dwordx4 v[236:237], off
	v_lshl_add_u64 v[236:237], s[48:49], 0, v[168:169]
	s_mov_b32 m0, s41
	s_nop 0
	global_load_lds_dwordx4 v[236:237], off
	s_waitcnt vmcnt(8)
	s_waitcnt lgkmcnt(0)
	s_barrier
	s_setprio 1
	s_waitcnt lgkmcnt(0)
	v_mfma_f32_16x16x32_bf16 v[140:143], v[80:83], v[178:181], v[140:143]
	v_mfma_f32_16x16x32_bf16 v[140:143], v[84:87], v[182:185], v[140:143]
	v_mfma_f32_16x16x32_bf16 v[136:139], v[100:103], v[182:185], v[136:139]
	v_mfma_f32_16x16x32_bf16 v[136:139], v[92:95], v[178:181], v[136:139]
	v_mfma_f32_16x16x32_bf16 v[120:123], v[92:95], v[206:209], v[120:123]
	v_mfma_f32_16x16x32_bf16 v[120:123], v[100:103], v[210:213], v[120:123]
	v_mfma_f32_16x16x32_bf16 v[124:127], v[84:87], v[210:213], v[124:127]
	v_mfma_f32_16x16x32_bf16 v[124:127], v[80:83], v[206:209], v[124:127]
	v_mfma_f32_16x16x32_bf16 v[108:111], v[80:83], v[214:217], v[108:111]
	v_mfma_f32_16x16x32_bf16 v[108:111], v[84:87], v[218:221], v[108:111]
	v_mfma_f32_16x16x32_bf16 v[104:107], v[100:103], v[218:221], v[104:107]
	v_mfma_f32_16x16x32_bf16 v[104:107], v[92:95], v[214:217], v[104:107]
	v_mfma_f32_16x16x32_bf16 v[72:75], v[92:95], v[222:225], v[72:75]
	v_mfma_f32_16x16x32_bf16 v[72:75], v[100:103], v[226:229], v[72:75]
	v_mfma_f32_16x16x32_bf16 v[76:79], v[84:87], v[226:229], v[76:79]
	v_mfma_f32_16x16x32_bf16 v[76:79], v[80:83], v[222:225], v[76:79]
	s_setprio 0
	s_setprio 1
	v_mfma_f32_16x16x32_bf16 v[132:135], v[144:147], v[178:181], v[132:135]
	v_mfma_f32_16x16x32_bf16 v[132:135], v[148:151], v[182:185], v[132:135]
	v_mfma_f32_16x16x32_bf16 v[128:131], v[156:159], v[182:185], v[128:131]
	v_mfma_f32_16x16x32_bf16 v[128:131], v[152:155], v[178:181], v[128:131]
	v_mfma_f32_16x16x32_bf16 v[112:115], v[152:155], v[206:209], v[112:115]
	v_mfma_f32_16x16x32_bf16 v[112:115], v[156:159], v[210:213], v[112:115]
	v_mfma_f32_16x16x32_bf16 v[116:119], v[148:151], v[210:213], v[116:119]
	v_mfma_f32_16x16x32_bf16 v[116:119], v[144:147], v[206:209], v[116:119]
	v_mfma_f32_16x16x32_bf16 v[96:99], v[144:147], v[214:217], v[96:99]
	v_mfma_f32_16x16x32_bf16 v[96:99], v[148:151], v[218:221], v[96:99]
	v_mfma_f32_16x16x32_bf16 v[88:91], v[156:159], v[218:221], v[88:91]
	v_mfma_f32_16x16x32_bf16 v[88:91], v[152:155], v[214:217], v[88:91]
	s_setprio 2
	s_barrier
; #define PG8_STAGE(bufoff, gbase, voff) do { _Pragma("unroll") for (int _i = 0; _i < 2; ++_i) \
;         __builtin_amdgcn_global_load_lds((const unsigned*)((const char*)(gbase) + (voff)[_i]), (PG8_LAS unsigned*)(lds + (bufoff) + ldsw + _i * 8192), 16, 0, 0); } while (0)
; #define PG8_LDA(dst, b, h) do { _Pragma("unroll") for (int m = 0; m < 4; ++m) _Pragma("unroll") for (int k = 0; k < 2; ++k) dst[m][k] = *(const PG8_LAS bf16x8*)(lds + PG8_SA(b, h) + aoff + m * 2048 + k * 1024); } while (0)
; #define PG8_MMA(ai, bj, At, Bt) do { __builtin_amdgcn_s_setprio(1); _Pragma("unroll") for (int m = 0; m < 4; ++m) _Pragma("unroll") for (int n = 0; n < 2; ++n) _Pragma("unroll") for (int k = 0; k < 2; ++k) \
;         acc[ai][bj][m][n] = __builtin_amdgcn_mfma_f32_16x16x32_bf16(Bt[n][k], At[m][k], acc[ai][bj][m][n], 0, 0, 0); __builtin_amdgcn_s_setprio(0); } while (0)
; #define PG8_WAIT_V(n) asm volatile("s_waitcnt vmcnt(" #n ")" ::: "memory")
; #define PG8_WAIT_L(n) asm volatile("s_waitcnt lgkmcnt(" #n ")" ::: "memory")
; #define PG8_BAR __builtin_amdgcn_s_barrier()
; #define PG8_SCHED __builtin_amdgcn_sched_barrier(0)
; template <class Epi, class Sched, bool ALIGN_EPI = false, bool SP2 = false>
; __device__ __forceinline__ void gemm_phase(PG8_LAS unsigned char* lds, const Gemm g, const Sched& S, const Epi& E) {
;     ...
;         for (int t = 0; t < nt; t += 2) {
;     ...
;             PG8_WAIT_V(8); PG8_WAIT_L(0); PG8_BAR; PG8_MMA(0, 0, At, B0); PG8_MMA(0, 1, At, B1); PG8_BAR; PG8_SCHED;
;             PG8_LDA(At, 1, 1); PG8_STAGE(PG8_SB(1, 0), b3, voffB); PG8_STAGE(PG8_SB(1, 1), b3 + hstep, voffB); PG8_STAGE(PG8_SA(1, 0), a3, voffA);
;             PG8_WAIT_V(8); PG8_WAIT_L(0); PG8_BAR; PG8_MMA(1, 0, At, B0); PG8_MMA(1, 1, At, B1); PG8_BAR; PG8_SCHED;
	v_mfma_f32_16x16x32_bf16 v[64:67], v[152:155], v[222:225], v[64:67]
	v_mfma_f32_16x16x32_bf16 v[64:67], v[156:159], v[226:229], v[64:67]
	v_mfma_f32_16x16x32_bf16 v[68:71], v[148:151], v[226:229], v[68:71]
	v_mfma_f32_16x16x32_bf16 v[68:71], v[144:147], v[222:225], v[68:71]
	s_setprio 0
	s_add_i32 s44, s44, s13
	v_lshl_add_u64 v[200:201], v[200:201], 0, s[16:17]
	s_mov_b32 m0, s44
	ds_read_b128 v[178:181], v187 offset:49152
	ds_read_b128 v[182:185], v187 offset:50176
	ds_read_b128 v[206:209], v187 offset:51200
	ds_read_b128 v[210:213], v187 offset:52224
	ds_read_b128 v[214:217], v187 offset:53248
	ds_read_b128 v[218:221], v187 offset:54272
	ds_read_b128 v[222:225], v187 offset:55296
	ds_read_b128 v[226:229], v187 offset:56320
	global_load_lds_dwordx4 v[200:201], off
	s_add_i32 m0, s44, 0x2000
	s_add_u32 s28, s28, 0x80080
	v_lshl_add_u64 v[200:201], v[230:231], 0, s[16:17]
	s_addc_u32 s29, s29, 0
	s_add_i32 s44, s45, s13
	global_load_lds_dwordx4 v[200:201], off
	v_lshl_add_u64 v[200:201], s[28:29], 0, v[164:165]
	s_mov_b32 m0, s44
	s_nop 0
	global_load_lds_dwordx4 v[200:201], off
	v_lshl_add_u64 v[200:201], s[28:29], 0, v[168:169]
	s_add_i32 m0, s44, 0x2000
	s_nop 0
	global_load_lds_dwordx4 v[200:201], off
	v_lshl_add_u64 v[200:201], v[232:233], 0, s[16:17]
	s_mov_b32 m0, s56
	s_nop 0
	global_load_lds_dwordx4 v[200:201], off
	v_lshl_add_u64 v[200:201], v[234:235], 0, s[16:17]
	s_mov_b32 m0, s57
	s_nop 0
	global_load_lds_dwordx4 v[200:201], off
	s_waitcnt vmcnt(8)
	s_waitcnt lgkmcnt(0)
	s_barrier
	s_setprio 1
	s_waitcnt lgkmcnt(0)
	v_mfma_f32_16x16x32_bf16 v[60:63], v[80:83], v[178:181], v[60:63]
	v_mfma_f32_16x16x32_bf16 v[60:63], v[84:87], v[182:185], v[60:63]
	v_mfma_f32_16x16x32_bf16 v[56:59], v[100:103], v[182:185], v[56:59]
	v_mfma_f32_16x16x32_bf16 v[56:59], v[92:95], v[178:181], v[56:59]
	v_mfma_f32_16x16x32_bf16 v[40:43], v[92:95], v[206:209], v[40:43]
	v_mfma_f32_16x16x32_bf16 v[40:43], v[100:103], v[210:213], v[40:43]
	v_mfma_f32_16x16x32_bf16 v[44:47], v[84:87], v[210:213], v[44:47]
	v_mfma_f32_16x16x32_bf16 v[44:47], v[80:83], v[206:209], v[44:47]
	v_mfma_f32_16x16x32_bf16 v[28:31], v[80:83], v[214:217], v[28:31]
	v_mfma_f32_16x16x32_bf16 v[28:31], v[84:87], v[218:221], v[28:31]
	v_mfma_f32_16x16x32_bf16 v[24:27], v[100:103], v[218:221], v[24:27]
	v_mfma_f32_16x16x32_bf16 v[24:27], v[92:95], v[214:217], v[24:27]
	v_mfma_f32_16x16x32_bf16 v[8:11], v[92:95], v[222:225], v[8:11]
	v_mfma_f32_16x16x32_bf16 v[8:11], v[100:103], v[226:229], v[8:11]
	v_mfma_f32_16x16x32_bf16 v[12:15], v[84:87], v[226:229], v[12:15]
	v_mfma_f32_16x16x32_bf16 v[12:15], v[80:83], v[222:225], v[12:15]
	s_setprio 0
	s_setprio 1
	v_mfma_f32_16x16x32_bf16 v[52:55], v[144:147], v[178:181], v[52:55]
	v_mfma_f32_16x16x32_bf16 v[52:55], v[148:151], v[182:185], v[52:55]
	v_mfma_f32_16x16x32_bf16 v[48:51], v[156:159], v[182:185], v[48:51]
	v_mfma_f32_16x16x32_bf16 v[48:51], v[152:155], v[178:181], v[48:51]
	v_mfma_f32_16x16x32_bf16 v[32:35], v[152:155], v[206:209], v[32:35]
	v_mfma_f32_16x16x32_bf16 v[32:35], v[156:159], v[210:213], v[32:35]
	v_mfma_f32_16x16x32_bf16 v[36:39], v[148:151], v[210:213], v[36:39]
	v_mfma_f32_16x16x32_bf16 v[36:39], v[144:147], v[206:209], v[36:39]
	v_mfma_f32_16x16x32_bf16 v[20:23], v[144:147], v[214:217], v[20:23]
	v_mfma_f32_16x16x32_bf16 v[20:23], v[148:151], v[218:221], v[20:23]
	v_mfma_f32_16x16x32_bf16 v[16:19], v[156:159], v[218:221], v[16:19]
	v_mfma_f32_16x16x32_bf16 v[16:19], v[152:155], v[214:217], v[16:19]
	s_setprio 2
	s_barrier
	v_mfma_f32_16x16x32_bf16 v[0:3], v[152:155], v[222:225], v[0:3]
	v_mfma_f32_16x16x32_bf16 v[0:3], v[156:159], v[226:229], v[0:3]
	v_mfma_f32_16x16x32_bf16 v[4:7], v[148:151], v[226:229], v[4:7]
	v_mfma_f32_16x16x32_bf16 v[4:7], v[144:147], v[222:225], v[4:7]
	s_setprio 0
	s_add_i32 s77, s77, 2
	s_add_u32 s74, s74, 0x100
	s_addc_u32 s75, s75, 0
	s_add_u32 s73, s73, 0x100
	s_addc_u32 s76, s76, 0
	s_cmp_gt_u32 s77, 29
	s_cbranch_scc0 .LBB0_362
	s_and_b64 vcc, exec, s[18:19]
	s_cbranch_vccz .LBB0_365
	s_barrier

; #define PG8_STAGE(bufoff, gbase, voff) do { _Pragma("unroll") for (int _i = 0; _i < 2; ++_i) \
;         __builtin_amdgcn_global_load_lds((const unsigned*)((const char*)(gbase) + (voff)[_i]), (PG8_LAS unsigned*)(lds + (bufoff) + ldsw + _i * 8192), 16, 0, 0); } while (0)
; #define PG8_LDA(dst, b, h) do { _Pragma("unroll") for (int m = 0; m < 4; ++m) _Pragma("unroll") for (int k = 0; k < 2; ++k) dst[m][k] = *(const PG8_LAS bf16x8*)(lds + PG8_SA(b, h) + aoff + m * 2048 + k * 1024); } while (0)
; #define PG8_LDB(dst, b, h) do { _Pragma("unroll") for (int n = 0; n < 2; ++n) _Pragma("unroll") for (int k = 0; k < 2; ++k) dst[n][k] = *(const PG8_LAS bf16x8*)(lds + PG8_SB(b, h) + boff + n * 2048 + k * 1024); } while (0)
; #define PG8_MMA(ai, bj, At, Bt) do { __builtin_amdgcn_s_setprio(1); _Pragma("unroll") for (int m = 0; m < 4; ++m) _Pragma("unroll") for (int n = 0; n < 2; ++n) _Pragma("unroll") for (int k = 0; k < 2; ++k) \
;         acc[ai][bj][m][n] = __builtin_amdgcn_mfma_f32_16x16x32_bf16(Bt[n][k], At[m][k], acc[ai][bj][m][n], 0, 0, 0); __builtin_amdgcn_s_setprio(0); } while (0)
; #define PG8_WAIT_V(n) asm volatile("s_waitcnt vmcnt(" #n ")" ::: "memory")
; #define PG8_WAIT_L(n) asm volatile("s_waitcnt lgkmcnt(" #n ")" ::: "memory")
; template <class Epi, class Sched, bool ALIGN_EPI = false, bool SP2 = false>
; __device__ __forceinline__ void gemm_phase(PG8_LAS unsigned char* lds, const Gemm g, const Sched& S, const Epi& E) {
;     ...
;             const bool last = (t == nt - 2);
;             const char* a1 = cA + (size_t)(t + 1) * kstep;
;             const char* a2 = last ? nA : cA + (size_t)(t + 2) * kstep; const char* b2 = last ? nB : cB + (size_t)(t + 2) * kstep;
;             const char* a3 = a2 + kstep; const char* b3 = b2 + kstep;
;             if (last && has_next) S.a_ready(nxt);
;             if constexpr (SP2) {
;             PG8_LDB(B0, 0, 0); PG8_LDB(B1, 0, 1); PG8_SCHED; PG8_LDA(At, 0, 0); PG8_STAGE(PG8_SA(1, 1), a1 + hstep, voffA);
;             PG8_WAIT_V(8); PG8_WAIT_L(0); PG8_BAR; PG8_MMA(0, 0, At, B0); PG8_MMA(0, 1, At, B1); PG8_BAR; PG8_SCHED;
;             PG8_LDA(At, 0, 1); PG8_STAGE(PG8_SB(0, 0), b2, voffB); PG8_STAGE(PG8_SB(0, 1), b2 + hstep, voffB); PG8_STAGE(PG8_SA(0, 0), a2, voffA);
;             PG8_WAIT_V(8); PG8_WAIT_L(0); PG8_BAR; PG8_MMA(1, 0, At, B0); PG8_MMA(1, 1, At, B1); PG8_BAR; PG8_SCHED;
.LBB0_416:
	ds_read_b128 v[136:139], v156
	ds_read_b128 v[140:143], v156 offset:1024
	ds_read_b128 v[172:175], v156 offset:2048
	ds_read_b128 v[176:179], v156 offset:3072
	ds_read_b128 v[180:183], v157
	ds_read_b128 v[184:187], v157 offset:1024
	ds_read_b128 v[206:209], v157 offset:2048
	ds_read_b128 v[210:213], v157 offset:3072
	s_add_u32 s28, s68, 0xfff80080
	s_addc_u32 s29, s69, -1
	s_cmp_eq_u32 s79, 28
	s_cselect_b32 s49, s34, s29
	s_cselect_b32 s48, s35, s28
	s_cselect_b32 s29, s23, s78
	s_cselect_b32 s28, s63, s77
	v_lshl_add_u64 v[200:201], s[68:69], 0, v[128:129]
	s_add_i32 m0, s15, 0xc000
	ds_read_b128 v[214:217], v158
	ds_read_b128 v[218:221], v158 offset:1024
	ds_read_b128 v[222:225], v158 offset:2048
	ds_read_b128 v[226:229], v158 offset:3072
	ds_read_b128 v[230:233], v158 offset:4096
	ds_read_b128 v[234:237], v158 offset:5120
	ds_read_b128 v[238:241], v158 offset:6144
	ds_read_b128 v[242:245], v158 offset:7168
	global_load_lds_dwordx4 v[200:201], off
	v_lshl_add_u64 v[200:201], s[68:69], 0, v[130:131]
	s_add_i32 m0, s15, 0xe000
	s_nop 0
	global_load_lds_dwordx4 v[200:201], off
	s_waitcnt vmcnt(8)
	s_waitcnt lgkmcnt(0)
	s_barrier
	s_setprio 1
	s_waitcnt lgkmcnt(0)
	v_mfma_f32_16x16x32_bf16 v[124:127], v[136:139], v[214:217], v[124:127]
	v_mfma_f32_16x16x32_bf16 v[124:127], v[140:143], v[218:221], v[124:127]
	v_mfma_f32_16x16x32_bf16 v[120:123], v[176:179], v[218:221], v[120:123]
	v_mfma_f32_16x16x32_bf16 v[120:123], v[172:175], v[214:217], v[120:123]
	v_mfma_f32_16x16x32_bf16 v[104:107], v[172:175], v[222:225], v[104:107]
	v_mfma_f32_16x16x32_bf16 v[104:107], v[176:179], v[226:229], v[104:107]
	v_mfma_f32_16x16x32_bf16 v[108:111], v[140:143], v[226:229], v[108:111]
	v_mfma_f32_16x16x32_bf16 v[108:111], v[136:139], v[222:225], v[108:111]
	v_mfma_f32_16x16x32_bf16 v[96:99], v[136:139], v[230:233], v[96:99]
	v_mfma_f32_16x16x32_bf16 v[96:99], v[140:143], v[234:237], v[96:99]
	v_mfma_f32_16x16x32_bf16 v[88:91], v[176:179], v[234:237], v[88:91]
	v_mfma_f32_16x16x32_bf16 v[88:91], v[172:175], v[230:233], v[88:91]
	v_mfma_f32_16x16x32_bf16 v[72:75], v[172:175], v[238:241], v[72:75]
	v_mfma_f32_16x16x32_bf16 v[72:75], v[176:179], v[242:245], v[72:75]
	v_mfma_f32_16x16x32_bf16 v[80:83], v[140:143], v[242:245], v[80:83]
	v_mfma_f32_16x16x32_bf16 v[80:83], v[136:139], v[238:241], v[80:83]
	s_setprio 0
	s_setprio 1
	v_mfma_f32_16x16x32_bf16 v[116:119], v[180:183], v[214:217], v[116:119]
	v_mfma_f32_16x16x32_bf16 v[116:119], v[184:187], v[218:221], v[116:119]
	v_mfma_f32_16x16x32_bf16 v[112:115], v[210:213], v[218:221], v[112:115]
	v_mfma_f32_16x16x32_bf16 v[112:115], v[206:209], v[214:217], v[112:115]
	v_mfma_f32_16x16x32_bf16 v[92:95], v[206:209], v[222:225], v[92:95]
	v_mfma_f32_16x16x32_bf16 v[92:95], v[210:213], v[226:229], v[92:95]
	v_mfma_f32_16x16x32_bf16 v[100:103], v[184:187], v[226:229], v[100:103]
	v_mfma_f32_16x16x32_bf16 v[100:103], v[180:183], v[222:225], v[100:103]
	v_mfma_f32_16x16x32_bf16 v[84:87], v[180:183], v[230:233], v[84:87]
	v_mfma_f32_16x16x32_bf16 v[84:87], v[184:187], v[234:237], v[84:87]
	v_mfma_f32_16x16x32_bf16 v[76:79], v[210:213], v[234:237], v[76:79]
	v_mfma_f32_16x16x32_bf16 v[76:79], v[206:209], v[230:233], v[76:79]
	s_setprio 2
	s_barrier
	v_mfma_f32_16x16x32_bf16 v[64:67], v[206:209], v[238:241], v[64:67]
	v_mfma_f32_16x16x32_bf16 v[64:67], v[210:213], v[242:245], v[64:67]
	v_mfma_f32_16x16x32_bf16 v[68:71], v[184:187], v[242:245], v[68:71]
	v_mfma_f32_16x16x32_bf16 v[68:71], v[180:183], v[238:241], v[68:71]
	s_setprio 0
	s_add_i32 s44, s72, s39
	v_lshl_add_u64 v[200:201], s[28:29], 0, v[166:167]
	s_mov_b32 m0, s44
	ds_read_b128 v[214:217], v158 offset:16384
	ds_read_b128 v[218:221], v158 offset:17408
	ds_read_b128 v[222:225], v158 offset:18432
	ds_read_b128 v[226:229], v158 offset:19456
	ds_read_b128 v[230:233], v158 offset:20480
	ds_read_b128 v[234:237], v158 offset:21504
	ds_read_b128 v[238:241], v158 offset:22528
	ds_read_b128 v[242:245], v158 offset:23552
	global_load_lds_dwordx4 v[200:201], off
	s_add_i32 m0, s44, 0x2000
	s_add_u32 s80, s28, 0x80000
	v_lshl_add_u64 v[246:247], s[28:29], 0, v[170:171]
	s_addc_u32 s81, s29, 0
	s_add_i32 s44, s73, s39
	global_load_lds_dwordx4 v[246:247], off
	v_lshl_add_u64 v[248:249], s[80:81], 0, v[166:167]
	s_mov_b32 m0, s44
	v_lshl_add_u64 v[250:251], s[48:49], 0, v[168:169]
	global_load_lds_dwordx4 v[248:249], off
	v_lshl_add_u64 v[248:249], s[80:81], 0, v[170:171]
	s_add_i32 m0, s44, 0x2000
	s_nop 0
	global_load_lds_dwordx4 v[248:249], off
	v_lshl_add_u64 v[248:249], s[48:49], 0, v[164:165]
	s_mov_b32 m0, s15
	s_nop 0
	global_load_lds_dwordx4 v[248:249], off
	s_mov_b32 m0, s41
	s_nop 0
	global_load_lds_dwordx4 v[250:251], off
	s_waitcnt vmcnt(8)
	s_waitcnt lgkmcnt(0)
	s_barrier
; #define PG8_STAGE(bufoff, gbase, voff) do { _Pragma("unroll") for (int _i = 0; _i < 2; ++_i) \
;         __builtin_amdgcn_global_load_lds((const unsigned*)((const char*)(gbase) + (voff)[_i]), (PG8_LAS unsigned*)(lds + (bufoff) + ldsw + _i * 8192), 16, 0, 0); } while (0)
; #define PG8_LDA(dst, b, h) do { _Pragma("unroll") for (int m = 0; m < 4; ++m) _Pragma("unroll") for (int k = 0; k < 2; ++k) dst[m][k] = *(const PG8_LAS bf16x8*)(lds + PG8_SA(b, h) + aoff + m * 2048 + k * 1024); } while (0)
; #define PG8_LDB(dst, b, h) do { _Pragma("unroll") for (int n = 0; n < 2; ++n) _Pragma("unroll") for (int k = 0; k < 2; ++k) dst[n][k] = *(const PG8_LAS bf16x8*)(lds + PG8_SB(b, h) + boff + n * 2048 + k * 1024); } while (0)
; #define PG8_MMA(ai, bj, At, Bt) do { __builtin_amdgcn_s_setprio(1); _Pragma("unroll") for (int m = 0; m < 4; ++m) _Pragma("unroll") for (int n = 0; n < 2; ++n) _Pragma("unroll") for (int k = 0; k < 2; ++k) \
;         acc[ai][bj][m][n] = __builtin_amdgcn_mfma_f32_16x16x32_bf16(Bt[n][k], At[m][k], acc[ai][bj][m][n], 0, 0, 0); __builtin_amdgcn_s_setprio(0); } while (0)
; #define PG8_WAIT_V(n) asm volatile("s_waitcnt vmcnt(" #n ")" ::: "memory")
; #define PG8_WAIT_L(n) asm volatile("s_waitcnt lgkmcnt(" #n ")" ::: "memory")
; #define PG8_BAR __builtin_amdgcn_s_barrier()
; #define PG8_SCHED __builtin_amdgcn_sched_barrier(0)
; template <class Epi, class Sched, bool ALIGN_EPI = false, bool SP2 = false>
; __device__ __forceinline__ void gemm_phase(PG8_LAS unsigned char* lds, const Gemm g, const Sched& S, const Epi& E) {
;     ...
;             PG8_WAIT_V(8); PG8_WAIT_L(0); PG8_BAR; PG8_MMA(1, 0, At, B0); PG8_MMA(1, 1, At, B1); PG8_BAR; PG8_SCHED;
;             PG8_LDB(B0, 1, 0); PG8_LDB(B1, 1, 1); PG8_SCHED; PG8_LDA(At, 1, 0); PG8_STAGE(PG8_SA(0, 1), a2 + hstep, voffA);
;             PG8_WAIT_V(8); PG8_WAIT_L(0); PG8_BAR; PG8_MMA(0, 0, At, B0); PG8_MMA(0, 1, At, B1); PG8_BAR; PG8_SCHED;
	s_setprio 1
	s_waitcnt lgkmcnt(0)
	v_mfma_f32_16x16x32_bf16 v[60:63], v[136:139], v[214:217], v[60:63]
	v_mfma_f32_16x16x32_bf16 v[60:63], v[140:143], v[218:221], v[60:63]
	v_mfma_f32_16x16x32_bf16 v[56:59], v[176:179], v[218:221], v[56:59]
	v_mfma_f32_16x16x32_bf16 v[56:59], v[172:175], v[214:217], v[56:59]
	v_mfma_f32_16x16x32_bf16 v[40:43], v[172:175], v[222:225], v[40:43]
	v_mfma_f32_16x16x32_bf16 v[40:43], v[176:179], v[226:229], v[40:43]
	v_mfma_f32_16x16x32_bf16 v[48:51], v[140:143], v[226:229], v[48:51]
	v_mfma_f32_16x16x32_bf16 v[48:51], v[136:139], v[222:225], v[48:51]
	v_mfma_f32_16x16x32_bf16 v[32:35], v[136:139], v[230:233], v[32:35]
	v_mfma_f32_16x16x32_bf16 v[32:35], v[140:143], v[234:237], v[32:35]
	v_mfma_f32_16x16x32_bf16 v[24:27], v[176:179], v[234:237], v[24:27]
	v_mfma_f32_16x16x32_bf16 v[24:27], v[172:175], v[230:233], v[24:27]
	v_mfma_f32_16x16x32_bf16 v[8:11], v[172:175], v[238:241], v[8:11]
	v_mfma_f32_16x16x32_bf16 v[8:11], v[176:179], v[242:245], v[8:11]
	v_mfma_f32_16x16x32_bf16 v[12:15], v[140:143], v[242:245], v[12:15]
	v_mfma_f32_16x16x32_bf16 v[12:15], v[136:139], v[238:241], v[12:15]
	s_setprio 0
	s_setprio 1
	v_mfma_f32_16x16x32_bf16 v[52:55], v[180:183], v[214:217], v[52:55]
	v_mfma_f32_16x16x32_bf16 v[52:55], v[184:187], v[218:221], v[52:55]
	v_mfma_f32_16x16x32_bf16 v[44:47], v[210:213], v[218:221], v[44:47]
	v_mfma_f32_16x16x32_bf16 v[44:47], v[206:209], v[214:217], v[44:47]
	v_mfma_f32_16x16x32_bf16 v[28:31], v[206:209], v[222:225], v[28:31]
	v_mfma_f32_16x16x32_bf16 v[28:31], v[210:213], v[226:229], v[28:31]
	v_mfma_f32_16x16x32_bf16 v[36:39], v[184:187], v[226:229], v[36:39]
	v_mfma_f32_16x16x32_bf16 v[36:39], v[180:183], v[222:225], v[36:39]
	v_mfma_f32_16x16x32_bf16 v[20:23], v[180:183], v[230:233], v[20:23]
	v_mfma_f32_16x16x32_bf16 v[20:23], v[184:187], v[234:237], v[20:23]
	v_mfma_f32_16x16x32_bf16 v[16:19], v[210:213], v[234:237], v[16:19]
	v_mfma_f32_16x16x32_bf16 v[16:19], v[206:209], v[230:233], v[16:19]
	s_setprio 2
	s_barrier
	v_mfma_f32_16x16x32_bf16 v[0:3], v[206:209], v[238:241], v[0:3]
	v_mfma_f32_16x16x32_bf16 v[0:3], v[210:213], v[242:245], v[0:3]
	v_mfma_f32_16x16x32_bf16 v[4:7], v[184:187], v[242:245], v[4:7]
	v_mfma_f32_16x16x32_bf16 v[4:7], v[180:183], v[238:241], v[4:7]
	s_setprio 0
	s_add_i32 s44, 0, 0x18000
	v_add_u32_e32 v144, s44, v146
	s_add_i32 s45, 0, 0x1c000
	ds_read_b128 v[136:139], v144
	ds_read_b128 v[140:143], v144 offset:1024
	ds_read_b128 v[172:175], v144 offset:2048
	ds_read_b128 v[176:179], v144 offset:3072
	v_add_u32_e32 v144, s45, v146
	ds_read_b128 v[180:183], v144
	ds_read_b128 v[184:187], v144 offset:1024
	ds_read_b128 v[206:209], v144 offset:2048
	ds_read_b128 v[210:213], v144 offset:3072
	s_add_u32 s48, s48, 0x80000
	s_addc_u32 s49, s49, 0
	s_mov_b32 m0, s56
	v_lshl_add_u64 v[252:253], s[48:49], 0, v[164:165]
	ds_read_b128 v[214:217], v158 offset:32768
	ds_read_b128 v[218:221], v158 offset:33792
	ds_read_b128 v[222:225], v158 offset:34816
	ds_read_b128 v[226:229], v158 offset:35840
	ds_read_b128 v[230:233], v158 offset:36864
	ds_read_b128 v[234:237], v158 offset:37888
	ds_read_b128 v[238:241], v158 offset:38912
	ds_read_b128 v[242:245], v158 offset:39936
	global_load_lds_dwordx4 v[252:253], off
	v_lshl_add_u64 v[252:253], s[48:49], 0, v[168:169]
	s_mov_b32 m0, s57
	s_nop 0
	global_load_lds_dwordx4 v[252:253], off
	s_waitcnt vmcnt(8)
	s_waitcnt lgkmcnt(0)
	s_barrier
	s_setprio 1
	s_waitcnt lgkmcnt(0)
	v_mfma_f32_16x16x32_bf16 v[124:127], v[136:139], v[214:217], v[124:127]
	v_mfma_f32_16x16x32_bf16 v[124:127], v[140:143], v[218:221], v[124:127]
	v_mfma_f32_16x16x32_bf16 v[120:123], v[176:179], v[218:221], v[120:123]
	v_mfma_f32_16x16x32_bf16 v[120:123], v[172:175], v[214:217], v[120:123]
	v_mfma_f32_16x16x32_bf16 v[104:107], v[172:175], v[222:225], v[104:107]
	v_mfma_f32_16x16x32_bf16 v[104:107], v[176:179], v[226:229], v[104:107]
	v_mfma_f32_16x16x32_bf16 v[108:111], v[140:143], v[226:229], v[108:111]
	v_mfma_f32_16x16x32_bf16 v[108:111], v[136:139], v[222:225], v[108:111]
	v_mfma_f32_16x16x32_bf16 v[96:99], v[136:139], v[230:233], v[96:99]
	v_mfma_f32_16x16x32_bf16 v[96:99], v[140:143], v[234:237], v[96:99]
	v_mfma_f32_16x16x32_bf16 v[88:91], v[176:179], v[234:237], v[88:91]
	v_mfma_f32_16x16x32_bf16 v[88:91], v[172:175], v[230:233], v[88:91]
	v_mfma_f32_16x16x32_bf16 v[72:75], v[172:175], v[238:241], v[72:75]
	v_mfma_f32_16x16x32_bf16 v[72:75], v[176:179], v[242:245], v[72:75]
	v_mfma_f32_16x16x32_bf16 v[80:83], v[140:143], v[242:245], v[80:83]
	v_mfma_f32_16x16x32_bf16 v[80:83], v[136:139], v[238:241], v[80:83]
	s_setprio 0
	s_setprio 1
	v_mfma_f32_16x16x32_bf16 v[116:119], v[180:183], v[214:217], v[116:119]
	v_mfma_f32_16x16x32_bf16 v[116:119], v[184:187], v[218:221], v[116:119]
	v_mfma_f32_16x16x32_bf16 v[112:115], v[210:213], v[218:221], v[112:115]
	v_mfma_f32_16x16x32_bf16 v[112:115], v[206:209], v[214:217], v[112:115]
	v_mfma_f32_16x16x32_bf16 v[92:95], v[206:209], v[222:225], v[92:95]
	v_mfma_f32_16x16x32_bf16 v[92:95], v[210:213], v[226:229], v[92:95]
	v_mfma_f32_16x16x32_bf16 v[100:103], v[184:187], v[226:229], v[100:103]
	v_mfma_f32_16x16x32_bf16 v[100:103], v[180:183], v[222:225], v[100:103]
	v_mfma_f32_16x16x32_bf16 v[84:87], v[180:183], v[230:233], v[84:87]
	v_mfma_f32_16x16x32_bf16 v[84:87], v[184:187], v[234:237], v[84:87]
	v_mfma_f32_16x16x32_bf16 v[76:79], v[210:213], v[234:237], v[76:79]
	v_mfma_f32_16x16x32_bf16 v[76:79], v[206:209], v[230:233], v[76:79]
	s_setprio 2
	s_barrier
; #define PG8_STAGE(bufoff, gbase, voff) do { _Pragma("unroll") for (int _i = 0; _i < 2; ++_i) \
;         __builtin_amdgcn_global_load_lds((const unsigned*)((const char*)(gbase) + (voff)[_i]), (PG8_LAS unsigned*)(lds + (bufoff) + ldsw + _i * 8192), 16, 0, 0); } while (0)
; #define PG8_LDA(dst, b, h) do { _Pragma("unroll") for (int m = 0; m < 4; ++m) _Pragma("unroll") for (int k = 0; k < 2; ++k) dst[m][k] = *(const PG8_LAS bf16x8*)(lds + PG8_SA(b, h) + aoff + m * 2048 + k * 1024); } while (0)
; #define PG8_MMA(ai, bj, At, Bt) do { __builtin_amdgcn_s_setprio(1); _Pragma("unroll") for (int m = 0; m < 4; ++m) _Pragma("unroll") for (int n = 0; n < 2; ++n) _Pragma("unroll") for (int k = 0; k < 2; ++k) \
;         acc[ai][bj][m][n] = __builtin_amdgcn_mfma_f32_16x16x32_bf16(Bt[n][k], At[m][k], acc[ai][bj][m][n], 0, 0, 0); __builtin_amdgcn_s_setprio(0); } while (0)
; #define PG8_WAIT_V(n) asm volatile("s_waitcnt vmcnt(" #n ")" ::: "memory")
; #define PG8_WAIT_L(n) asm volatile("s_waitcnt lgkmcnt(" #n ")" ::: "memory")
; #define PG8_BAR __builtin_amdgcn_s_barrier()
; #define PG8_SCHED __builtin_amdgcn_sched_barrier(0)
; template <class Epi, class Sched, bool ALIGN_EPI = false, bool SP2 = false>
; __device__ __forceinline__ void gemm_phase(PG8_LAS unsigned char* lds, const Gemm g, const Sched& S, const Epi& E) {
;     ...
;         for (int t = 0; t < nt; t += 2) {
;     ...
;             PG8_WAIT_V(8); PG8_WAIT_L(0); PG8_BAR; PG8_MMA(0, 0, At, B0); PG8_MMA(0, 1, At, B1); PG8_BAR; PG8_SCHED;
;             PG8_LDA(At, 1, 1); PG8_STAGE(PG8_SB(1, 0), b3, voffB); PG8_STAGE(PG8_SB(1, 1), b3 + hstep, voffB); PG8_STAGE(PG8_SA(1, 0), a3, voffA);
;             PG8_WAIT_V(8); PG8_WAIT_L(0); PG8_BAR; PG8_MMA(1, 0, At, B0); PG8_MMA(1, 1, At, B1); PG8_BAR; PG8_SCHED;
	v_mfma_f32_16x16x32_bf16 v[64:67], v[206:209], v[238:241], v[64:67]
	v_mfma_f32_16x16x32_bf16 v[64:67], v[210:213], v[242:245], v[64:67]
	v_mfma_f32_16x16x32_bf16 v[68:71], v[184:187], v[242:245], v[68:71]
	v_mfma_f32_16x16x32_bf16 v[68:71], v[180:183], v[238:241], v[68:71]
	s_setprio 0
	s_add_i32 s44, s44, s39
	v_lshl_add_u64 v[200:201], v[200:201], 0, s[18:19]
	s_mov_b32 m0, s44
	ds_read_b128 v[214:217], v158 offset:49152
	ds_read_b128 v[218:221], v158 offset:50176
	ds_read_b128 v[222:225], v158 offset:51200
	ds_read_b128 v[226:229], v158 offset:52224
	ds_read_b128 v[230:233], v158 offset:53248
	ds_read_b128 v[234:237], v158 offset:54272
	ds_read_b128 v[238:241], v158 offset:55296
	ds_read_b128 v[242:245], v158 offset:56320
	global_load_lds_dwordx4 v[200:201], off
	s_add_i32 m0, s44, 0x2000
	s_add_u32 s28, s28, 0x80080
	v_lshl_add_u64 v[200:201], v[246:247], 0, s[18:19]
	s_addc_u32 s29, s29, 0
	s_add_i32 s44, s45, s39
	global_load_lds_dwordx4 v[200:201], off
	v_lshl_add_u64 v[200:201], s[28:29], 0, v[166:167]
	s_mov_b32 m0, s44
	s_nop 0
	global_load_lds_dwordx4 v[200:201], off
	v_lshl_add_u64 v[200:201], s[28:29], 0, v[170:171]
	s_add_i32 m0, s44, 0x2000
	s_nop 0
	global_load_lds_dwordx4 v[200:201], off
	v_lshl_add_u64 v[200:201], v[248:249], 0, s[18:19]
	s_mov_b32 m0, s70
	s_nop 0
	global_load_lds_dwordx4 v[200:201], off
	v_lshl_add_u64 v[200:201], v[250:251], 0, s[18:19]
	s_mov_b32 m0, s71
	s_nop 0
	global_load_lds_dwordx4 v[200:201], off
	s_waitcnt vmcnt(8)
	s_waitcnt lgkmcnt(0)
	s_barrier
	s_setprio 1
	s_waitcnt lgkmcnt(0)
	v_mfma_f32_16x16x32_bf16 v[60:63], v[136:139], v[214:217], v[60:63]
	v_mfma_f32_16x16x32_bf16 v[60:63], v[140:143], v[218:221], v[60:63]
	v_mfma_f32_16x16x32_bf16 v[56:59], v[176:179], v[218:221], v[56:59]
	v_mfma_f32_16x16x32_bf16 v[56:59], v[172:175], v[214:217], v[56:59]
	v_mfma_f32_16x16x32_bf16 v[40:43], v[172:175], v[222:225], v[40:43]
	v_mfma_f32_16x16x32_bf16 v[40:43], v[176:179], v[226:229], v[40:43]
	v_mfma_f32_16x16x32_bf16 v[48:51], v[140:143], v[226:229], v[48:51]
	v_mfma_f32_16x16x32_bf16 v[48:51], v[136:139], v[222:225], v[48:51]
	v_mfma_f32_16x16x32_bf16 v[32:35], v[136:139], v[230:233], v[32:35]
	v_mfma_f32_16x16x32_bf16 v[32:35], v[140:143], v[234:237], v[32:35]
	v_mfma_f32_16x16x32_bf16 v[24:27], v[176:179], v[234:237], v[24:27]
	v_mfma_f32_16x16x32_bf16 v[24:27], v[172:175], v[230:233], v[24:27]
	v_mfma_f32_16x16x32_bf16 v[8:11], v[172:175], v[238:241], v[8:11]
	v_mfma_f32_16x16x32_bf16 v[8:11], v[176:179], v[242:245], v[8:11]
	v_mfma_f32_16x16x32_bf16 v[12:15], v[140:143], v[242:245], v[12:15]
	v_mfma_f32_16x16x32_bf16 v[12:15], v[136:139], v[238:241], v[12:15]
	s_setprio 0
	s_setprio 1
	v_mfma_f32_16x16x32_bf16 v[52:55], v[180:183], v[214:217], v[52:55]
	v_mfma_f32_16x16x32_bf16 v[52:55], v[184:187], v[218:221], v[52:55]
	v_mfma_f32_16x16x32_bf16 v[44:47], v[210:213], v[218:221], v[44:47]
	v_mfma_f32_16x16x32_bf16 v[44:47], v[206:209], v[214:217], v[44:47]
	v_mfma_f32_16x16x32_bf16 v[28:31], v[206:209], v[222:225], v[28:31]
	v_mfma_f32_16x16x32_bf16 v[28:31], v[210:213], v[226:229], v[28:31]
	v_mfma_f32_16x16x32_bf16 v[36:39], v[184:187], v[226:229], v[36:39]
	v_mfma_f32_16x16x32_bf16 v[36:39], v[180:183], v[222:225], v[36:39]
	v_mfma_f32_16x16x32_bf16 v[20:23], v[180:183], v[230:233], v[20:23]
	v_mfma_f32_16x16x32_bf16 v[20:23], v[184:187], v[234:237], v[20:23]
	v_mfma_f32_16x16x32_bf16 v[16:19], v[210:213], v[234:237], v[16:19]
	v_mfma_f32_16x16x32_bf16 v[16:19], v[206:209], v[230:233], v[16:19]
	s_setprio 2
	s_barrier
	v_mfma_f32_16x16x32_bf16 v[0:3], v[206:209], v[238:241], v[0:3]
	v_mfma_f32_16x16x32_bf16 v[0:3], v[210:213], v[242:245], v[0:3]
	v_mfma_f32_16x16x32_bf16 v[4:7], v[184:187], v[242:245], v[4:7]
	v_mfma_f32_16x16x32_bf16 v[4:7], v[180:183], v[238:241], v[4:7]
	s_setprio 0
	s_add_i32 s79, s79, 2
	s_add_u32 s68, s68, 0x100
	s_addc_u32 s69, s69, 0
	s_add_u32 s77, s77, 0x100
	s_addc_u32 s78, s78, 0
	s_cmp_gt_u32 s79, 29
	s_cbranch_scc0 .LBB0_416
	s_and_b64 vcc, exec, s[20:21]
	s_cbranch_vccz .LBB0_419
	s_barrier

; #define PG8_STAGE(bufoff, gbase, voff) do { _Pragma("unroll") for (int _i = 0; _i < 2; ++_i) \
;         __builtin_amdgcn_global_load_lds((const unsigned*)((const char*)(gbase) + (voff)[_i]), (PG8_LAS unsigned*)(lds + (bufoff) + ldsw + _i * 8192), 16, 0, 0); } while (0)
; #define PG8_LDA(dst, b, h) do { _Pragma("unroll") for (int m = 0; m < 4; ++m) _Pragma("unroll") for (int k = 0; k < 2; ++k) dst[m][k] = *(const PG8_LAS bf16x8*)(lds + PG8_SA(b, h) + aoff + m * 2048 + k * 1024); } while (0)
; #define PG8_LDB(dst, b, h) do { _Pragma("unroll") for (int n = 0; n < 2; ++n) _Pragma("unroll") for (int k = 0; k < 2; ++k) dst[n][k] = *(const PG8_LAS bf16x8*)(lds + PG8_SB(b, h) + boff + n * 2048 + k * 1024); } while (0)
; #define PG8_MMA(ai, bj, At, Bt) do { __builtin_amdgcn_s_setprio(1); _Pragma("unroll") for (int m = 0; m < 4; ++m) _Pragma("unroll") for (int n = 0; n < 2; ++n) _Pragma("unroll") for (int k = 0; k < 2; ++k) \
;         acc[ai][bj][m][n] = __builtin_amdgcn_mfma_f32_16x16x32_bf16(Bt[n][k], At[m][k], acc[ai][bj][m][n], 0, 0, 0); __builtin_amdgcn_s_setprio(0); } while (0)
; #define PG8_WAIT_V(n) asm volatile("s_waitcnt vmcnt(" #n ")" ::: "memory")
; #define PG8_WAIT_L(n) asm volatile("s_waitcnt lgkmcnt(" #n ")" ::: "memory")
; template <class Epi, class Sched, bool ALIGN_EPI = false, bool SP2 = false>
; __device__ __forceinline__ void gemm_phase(PG8_LAS unsigned char* lds, const Gemm g, const Sched& S, const Epi& E) {
;     ...
;             const bool last = (t == nt - 2);
;             const char* a1 = cA + (size_t)(t + 1) * kstep;
;             const char* a2 = last ? nA : cA + (size_t)(t + 2) * kstep; const char* b2 = last ? nB : cB + (size_t)(t + 2) * kstep;
;             const char* a3 = a2 + kstep; const char* b3 = b2 + kstep;
;             if (last && has_next) S.a_ready(nxt);
;             if constexpr (SP2) {
;             PG8_LDB(B0, 0, 0); PG8_LDB(B1, 0, 1); PG8_SCHED; PG8_LDA(At, 0, 0); PG8_STAGE(PG8_SA(1, 1), a1 + hstep, voffA);
;             PG8_WAIT_V(8); PG8_WAIT_L(0); PG8_BAR; PG8_MMA(0, 0, At, B0); PG8_MMA(0, 1, At, B1); PG8_BAR; PG8_SCHED;
;             PG8_LDA(At, 0, 1); PG8_STAGE(PG8_SB(0, 0), b2, voffB); PG8_STAGE(PG8_SB(0, 1), b2 + hstep, voffB); PG8_STAGE(PG8_SA(0, 0), a2, voffA);
;             PG8_WAIT_V(8); PG8_WAIT_L(0); PG8_BAR; PG8_MMA(1, 0, At, B0); PG8_MMA(1, 1, At, B1); PG8_BAR; PG8_SCHED;
.LBB0_482:
	ds_read_b128 v[76:79], v171
	ds_read_b128 v[84:87], v171 offset:1024
	ds_read_b128 v[92:95], v171 offset:2048
	ds_read_b128 v[96:99], v171 offset:3072
	ds_read_b128 v[144:147], v186
	ds_read_b128 v[148:151], v186 offset:1024
	ds_read_b128 v[152:155], v186 offset:2048
	ds_read_b128 v[156:159], v186 offset:3072
	s_add_u32 s28, s64, 0xffea0080
	s_addc_u32 s29, s65, -1
	s_cmpk_eq_i32 s77, 0x54
	s_cselect_b32 s49, s39, s29
	s_cselect_b32 s48, s38, s28
	s_cselect_b32 s29, s63, s35
	s_cselect_b32 s28, s62, s34
	v_lshl_add_u64 v[200:201], s[64:65], 0, v[172:173]
	s_add_i32 m0, s56, 0xc000
	ds_read_b128 v[178:181], v187
	ds_read_b128 v[182:185], v187 offset:1024
	ds_read_b128 v[206:209], v187 offset:2048
	ds_read_b128 v[210:213], v187 offset:3072
	ds_read_b128 v[214:217], v187 offset:4096
	ds_read_b128 v[218:221], v187 offset:5120
	ds_read_b128 v[222:225], v187 offset:6144
	ds_read_b128 v[226:229], v187 offset:7168
	global_load_lds_dwordx4 v[200:201], off
	v_lshl_add_u64 v[200:201], s[64:65], 0, v[174:175]
	s_add_i32 m0, s56, 0xe000
	s_nop 0
	global_load_lds_dwordx4 v[200:201], off
	s_waitcnt vmcnt(8)
	s_waitcnt lgkmcnt(0)
	s_barrier
	s_setprio 1
	s_waitcnt lgkmcnt(0)
	v_mfma_f32_16x16x32_bf16 v[140:143], v[76:79], v[178:181], v[140:143]
	v_mfma_f32_16x16x32_bf16 v[140:143], v[84:87], v[182:185], v[140:143]
	v_mfma_f32_16x16x32_bf16 v[136:139], v[96:99], v[182:185], v[136:139]
	v_mfma_f32_16x16x32_bf16 v[136:139], v[92:95], v[178:181], v[136:139]
	v_mfma_f32_16x16x32_bf16 v[120:123], v[92:95], v[206:209], v[120:123]
	v_mfma_f32_16x16x32_bf16 v[120:123], v[96:99], v[210:213], v[120:123]
	v_mfma_f32_16x16x32_bf16 v[124:127], v[84:87], v[210:213], v[124:127]
	v_mfma_f32_16x16x32_bf16 v[124:127], v[76:79], v[206:209], v[124:127]
	v_mfma_f32_16x16x32_bf16 v[108:111], v[76:79], v[214:217], v[108:111]
	v_mfma_f32_16x16x32_bf16 v[108:111], v[84:87], v[218:221], v[108:111]
	v_mfma_f32_16x16x32_bf16 v[104:107], v[96:99], v[218:221], v[104:107]
	v_mfma_f32_16x16x32_bf16 v[104:107], v[92:95], v[214:217], v[104:107]
	v_mfma_f32_16x16x32_bf16 v[72:75], v[92:95], v[222:225], v[72:75]
	v_mfma_f32_16x16x32_bf16 v[72:75], v[96:99], v[226:229], v[72:75]
	v_mfma_f32_16x16x32_bf16 v[80:83], v[84:87], v[226:229], v[80:83]
	v_mfma_f32_16x16x32_bf16 v[80:83], v[76:79], v[222:225], v[80:83]
	s_setprio 0
	s_setprio 1
	v_mfma_f32_16x16x32_bf16 v[132:135], v[144:147], v[178:181], v[132:135]
	v_mfma_f32_16x16x32_bf16 v[132:135], v[148:151], v[182:185], v[132:135]
	v_mfma_f32_16x16x32_bf16 v[128:131], v[156:159], v[182:185], v[128:131]
	v_mfma_f32_16x16x32_bf16 v[128:131], v[152:155], v[178:181], v[128:131]
	v_mfma_f32_16x16x32_bf16 v[112:115], v[152:155], v[206:209], v[112:115]
	v_mfma_f32_16x16x32_bf16 v[112:115], v[156:159], v[210:213], v[112:115]
	v_mfma_f32_16x16x32_bf16 v[116:119], v[148:151], v[210:213], v[116:119]
	v_mfma_f32_16x16x32_bf16 v[116:119], v[144:147], v[206:209], v[116:119]
	v_mfma_f32_16x16x32_bf16 v[100:103], v[144:147], v[214:217], v[100:103]
	v_mfma_f32_16x16x32_bf16 v[100:103], v[148:151], v[218:221], v[100:103]
	v_mfma_f32_16x16x32_bf16 v[88:91], v[156:159], v[218:221], v[88:91]
	v_mfma_f32_16x16x32_bf16 v[88:91], v[152:155], v[214:217], v[88:91]
	s_setprio 2
	s_barrier
	v_mfma_f32_16x16x32_bf16 v[64:67], v[152:155], v[222:225], v[64:67]
	v_mfma_f32_16x16x32_bf16 v[64:67], v[156:159], v[226:229], v[64:67]
	v_mfma_f32_16x16x32_bf16 v[68:71], v[148:151], v[226:229], v[68:71]
	v_mfma_f32_16x16x32_bf16 v[68:71], v[144:147], v[222:225], v[68:71]
	s_setprio 0
	s_add_i32 s44, s70, s41
	v_lshl_add_u64 v[200:201], s[28:29], 0, v[160:161]
	s_mov_b32 m0, s44
	ds_read_b128 v[178:181], v187 offset:16384
	ds_read_b128 v[182:185], v187 offset:17408
	ds_read_b128 v[206:209], v187 offset:18432
	ds_read_b128 v[210:213], v187 offset:19456
	ds_read_b128 v[214:217], v187 offset:20480
	ds_read_b128 v[218:221], v187 offset:21504
	ds_read_b128 v[222:225], v187 offset:22528
	ds_read_b128 v[226:229], v187 offset:23552
	global_load_lds_dwordx4 v[200:201], off
	s_add_i32 m0, s44, 0x2000
	s_add_u32 s78, s28, 0x160000
	v_lshl_add_u64 v[230:231], s[28:29], 0, v[162:163]
	s_addc_u32 s79, s29, 0
	s_add_i32 s44, s71, s41
	global_load_lds_dwordx4 v[230:231], off
	v_lshl_add_u64 v[232:233], s[78:79], 0, v[160:161]
	s_mov_b32 m0, s44
	v_lshl_add_u64 v[234:235], s[48:49], 0, v[162:163]
	global_load_lds_dwordx4 v[232:233], off
	v_lshl_add_u64 v[232:233], s[78:79], 0, v[162:163]
	s_add_i32 m0, s44, 0x2000
	s_nop 0
	global_load_lds_dwordx4 v[232:233], off
	v_lshl_add_u64 v[232:233], s[48:49], 0, v[160:161]
	s_mov_b32 m0, s56
	s_nop 0
	global_load_lds_dwordx4 v[232:233], off
	s_mov_b32 m0, s57
	s_nop 0
	global_load_lds_dwordx4 v[234:235], off
	s_waitcnt vmcnt(8)
	s_waitcnt lgkmcnt(0)
	s_barrier
; #define PG8_STAGE(bufoff, gbase, voff) do { _Pragma("unroll") for (int _i = 0; _i < 2; ++_i) \
;         __builtin_amdgcn_global_load_lds((const unsigned*)((const char*)(gbase) + (voff)[_i]), (PG8_LAS unsigned*)(lds + (bufoff) + ldsw + _i * 8192), 16, 0, 0); } while (0)
; #define PG8_LDA(dst, b, h) do { _Pragma("unroll") for (int m = 0; m < 4; ++m) _Pragma("unroll") for (int k = 0; k < 2; ++k) dst[m][k] = *(const PG8_LAS bf16x8*)(lds + PG8_SA(b, h) + aoff + m * 2048 + k * 1024); } while (0)
; #define PG8_LDB(dst, b, h) do { _Pragma("unroll") for (int n = 0; n < 2; ++n) _Pragma("unroll") for (int k = 0; k < 2; ++k) dst[n][k] = *(const PG8_LAS bf16x8*)(lds + PG8_SB(b, h) + boff + n * 2048 + k * 1024); } while (0)
; #define PG8_MMA(ai, bj, At, Bt) do { __builtin_amdgcn_s_setprio(1); _Pragma("unroll") for (int m = 0; m < 4; ++m) _Pragma("unroll") for (int n = 0; n < 2; ++n) _Pragma("unroll") for (int k = 0; k < 2; ++k) \
;         acc[ai][bj][m][n] = __builtin_amdgcn_mfma_f32_16x16x32_bf16(Bt[n][k], At[m][k], acc[ai][bj][m][n], 0, 0, 0); __builtin_amdgcn_s_setprio(0); } while (0)
; #define PG8_WAIT_V(n) asm volatile("s_waitcnt vmcnt(" #n ")" ::: "memory")
; #define PG8_WAIT_L(n) asm volatile("s_waitcnt lgkmcnt(" #n ")" ::: "memory")
; #define PG8_BAR __builtin_amdgcn_s_barrier()
; #define PG8_SCHED __builtin_amdgcn_sched_barrier(0)
; template <class Epi, class Sched, bool ALIGN_EPI = false, bool SP2 = false>
; __device__ __forceinline__ void gemm_phase(PG8_LAS unsigned char* lds, const Gemm g, const Sched& S, const Epi& E) {
;     ...
;             PG8_WAIT_V(8); PG8_WAIT_L(0); PG8_BAR; PG8_MMA(1, 0, At, B0); PG8_MMA(1, 1, At, B1); PG8_BAR; PG8_SCHED;
;             PG8_LDB(B0, 1, 0); PG8_LDB(B1, 1, 1); PG8_SCHED; PG8_LDA(At, 1, 0); PG8_STAGE(PG8_SA(0, 1), a2 + hstep, voffA);
;             PG8_WAIT_V(8); PG8_WAIT_L(0); PG8_BAR; PG8_MMA(0, 0, At, B0); PG8_MMA(0, 1, At, B1); PG8_BAR; PG8_SCHED;
	s_setprio 1
	s_waitcnt lgkmcnt(0)
	v_mfma_f32_16x16x32_bf16 v[60:63], v[76:79], v[178:181], v[60:63]
	v_mfma_f32_16x16x32_bf16 v[60:63], v[84:87], v[182:185], v[60:63]
	v_mfma_f32_16x16x32_bf16 v[56:59], v[96:99], v[182:185], v[56:59]
	v_mfma_f32_16x16x32_bf16 v[56:59], v[92:95], v[178:181], v[56:59]
	v_mfma_f32_16x16x32_bf16 v[40:43], v[92:95], v[206:209], v[40:43]
	v_mfma_f32_16x16x32_bf16 v[40:43], v[96:99], v[210:213], v[40:43]
	v_mfma_f32_16x16x32_bf16 v[44:47], v[84:87], v[210:213], v[44:47]
	v_mfma_f32_16x16x32_bf16 v[44:47], v[76:79], v[206:209], v[44:47]
	v_mfma_f32_16x16x32_bf16 v[28:31], v[76:79], v[214:217], v[28:31]
	v_mfma_f32_16x16x32_bf16 v[28:31], v[84:87], v[218:221], v[28:31]
	v_mfma_f32_16x16x32_bf16 v[24:27], v[96:99], v[218:221], v[24:27]
	v_mfma_f32_16x16x32_bf16 v[24:27], v[92:95], v[214:217], v[24:27]
	v_mfma_f32_16x16x32_bf16 v[8:11], v[92:95], v[222:225], v[8:11]
	v_mfma_f32_16x16x32_bf16 v[8:11], v[96:99], v[226:229], v[8:11]
	v_mfma_f32_16x16x32_bf16 v[12:15], v[84:87], v[226:229], v[12:15]
	v_mfma_f32_16x16x32_bf16 v[12:15], v[76:79], v[222:225], v[12:15]
	s_setprio 0
	s_setprio 1
	v_mfma_f32_16x16x32_bf16 v[52:55], v[144:147], v[178:181], v[52:55]
	v_mfma_f32_16x16x32_bf16 v[52:55], v[148:151], v[182:185], v[52:55]
	v_mfma_f32_16x16x32_bf16 v[48:51], v[156:159], v[182:185], v[48:51]
	v_mfma_f32_16x16x32_bf16 v[48:51], v[152:155], v[178:181], v[48:51]
	v_mfma_f32_16x16x32_bf16 v[32:35], v[152:155], v[206:209], v[32:35]
	v_mfma_f32_16x16x32_bf16 v[32:35], v[156:159], v[210:213], v[32:35]
	v_mfma_f32_16x16x32_bf16 v[36:39], v[148:151], v[210:213], v[36:39]
	v_mfma_f32_16x16x32_bf16 v[36:39], v[144:147], v[206:209], v[36:39]
	v_mfma_f32_16x16x32_bf16 v[20:23], v[144:147], v[214:217], v[20:23]
	v_mfma_f32_16x16x32_bf16 v[20:23], v[148:151], v[218:221], v[20:23]
	v_mfma_f32_16x16x32_bf16 v[16:19], v[156:159], v[218:221], v[16:19]
	v_mfma_f32_16x16x32_bf16 v[16:19], v[152:155], v[214:217], v[16:19]
	s_setprio 2
	s_barrier
	v_mfma_f32_16x16x32_bf16 v[0:3], v[152:155], v[222:225], v[0:3]
	v_mfma_f32_16x16x32_bf16 v[0:3], v[156:159], v[226:229], v[0:3]
	v_mfma_f32_16x16x32_bf16 v[4:7], v[148:151], v[226:229], v[4:7]
	v_mfma_f32_16x16x32_bf16 v[4:7], v[144:147], v[222:225], v[4:7]
	s_setprio 0
	s_add_i32 s44, 0, 0x18000
	s_add_i32 s45, 0, 0x1c000
	v_add_u32_e32 v96, s44, v167
	v_add_u32_e32 v156, s45, v167
	ds_read_b128 v[76:79], v96
	ds_read_b128 v[84:87], v96 offset:1024
	ds_read_b128 v[92:95], v96 offset:2048
	ds_read_b128 v[96:99], v96 offset:3072
	ds_read_b128 v[144:147], v156
	ds_read_b128 v[148:151], v156 offset:1024
	ds_read_b128 v[152:155], v156 offset:2048
	ds_read_b128 v[156:159], v156 offset:3072
	s_add_u32 s48, s48, 0x160000
	s_addc_u32 s49, s49, 0
	s_mov_b32 m0, s61
	v_lshl_add_u64 v[236:237], s[48:49], 0, v[160:161]
	ds_read_b128 v[178:181], v187 offset:32768
	ds_read_b128 v[182:185], v187 offset:33792
	ds_read_b128 v[206:209], v187 offset:34816
	ds_read_b128 v[210:213], v187 offset:35840
	ds_read_b128 v[214:217], v187 offset:36864
	ds_read_b128 v[218:221], v187 offset:37888
	ds_read_b128 v[222:225], v187 offset:38912
	ds_read_b128 v[226:229], v187 offset:39936
	global_load_lds_dwordx4 v[236:237], off
	v_lshl_add_u64 v[236:237], s[48:49], 0, v[162:163]
	s_mov_b32 m0, s66
	s_nop 0
	global_load_lds_dwordx4 v[236:237], off
	s_waitcnt vmcnt(8)
	s_waitcnt lgkmcnt(0)
	s_barrier
	s_setprio 1
	s_waitcnt lgkmcnt(0)
	v_mfma_f32_16x16x32_bf16 v[140:143], v[76:79], v[178:181], v[140:143]
	v_mfma_f32_16x16x32_bf16 v[140:143], v[84:87], v[182:185], v[140:143]
	v_mfma_f32_16x16x32_bf16 v[136:139], v[96:99], v[182:185], v[136:139]
	v_mfma_f32_16x16x32_bf16 v[136:139], v[92:95], v[178:181], v[136:139]
	v_mfma_f32_16x16x32_bf16 v[120:123], v[92:95], v[206:209], v[120:123]
	v_mfma_f32_16x16x32_bf16 v[120:123], v[96:99], v[210:213], v[120:123]
	v_mfma_f32_16x16x32_bf16 v[124:127], v[84:87], v[210:213], v[124:127]
	v_mfma_f32_16x16x32_bf16 v[124:127], v[76:79], v[206:209], v[124:127]
	v_mfma_f32_16x16x32_bf16 v[108:111], v[76:79], v[214:217], v[108:111]
	v_mfma_f32_16x16x32_bf16 v[108:111], v[84:87], v[218:221], v[108:111]
	v_mfma_f32_16x16x32_bf16 v[104:107], v[96:99], v[218:221], v[104:107]
	v_mfma_f32_16x16x32_bf16 v[104:107], v[92:95], v[214:217], v[104:107]
	v_mfma_f32_16x16x32_bf16 v[72:75], v[92:95], v[222:225], v[72:75]
	v_mfma_f32_16x16x32_bf16 v[72:75], v[96:99], v[226:229], v[72:75]
	v_mfma_f32_16x16x32_bf16 v[80:83], v[84:87], v[226:229], v[80:83]
	v_mfma_f32_16x16x32_bf16 v[80:83], v[76:79], v[222:225], v[80:83]
	s_setprio 0
	s_setprio 1
	v_mfma_f32_16x16x32_bf16 v[132:135], v[144:147], v[178:181], v[132:135]
	v_mfma_f32_16x16x32_bf16 v[132:135], v[148:151], v[182:185], v[132:135]
	v_mfma_f32_16x16x32_bf16 v[128:131], v[156:159], v[182:185], v[128:131]
	v_mfma_f32_16x16x32_bf16 v[128:131], v[152:155], v[178:181], v[128:131]
	v_mfma_f32_16x16x32_bf16 v[112:115], v[152:155], v[206:209], v[112:115]
	v_mfma_f32_16x16x32_bf16 v[112:115], v[156:159], v[210:213], v[112:115]
	v_mfma_f32_16x16x32_bf16 v[116:119], v[148:151], v[210:213], v[116:119]
	v_mfma_f32_16x16x32_bf16 v[116:119], v[144:147], v[206:209], v[116:119]
	v_mfma_f32_16x16x32_bf16 v[100:103], v[144:147], v[214:217], v[100:103]
	v_mfma_f32_16x16x32_bf16 v[100:103], v[148:151], v[218:221], v[100:103]
	v_mfma_f32_16x16x32_bf16 v[88:91], v[156:159], v[218:221], v[88:91]
	v_mfma_f32_16x16x32_bf16 v[88:91], v[152:155], v[214:217], v[88:91]
	s_setprio 2
	s_barrier
; #define PG8_STAGE(bufoff, gbase, voff) do { _Pragma("unroll") for (int _i = 0; _i < 2; ++_i) \
;         __builtin_amdgcn_global_load_lds((const unsigned*)((const char*)(gbase) + (voff)[_i]), (PG8_LAS unsigned*)(lds + (bufoff) + ldsw + _i * 8192), 16, 0, 0); } while (0)
; #define PG8_LDA(dst, b, h) do { _Pragma("unroll") for (int m = 0; m < 4; ++m) _Pragma("unroll") for (int k = 0; k < 2; ++k) dst[m][k] = *(const PG8_LAS bf16x8*)(lds + PG8_SA(b, h) + aoff + m * 2048 + k * 1024); } while (0)
; #define PG8_MMA(ai, bj, At, Bt) do { __builtin_amdgcn_s_setprio(1); _Pragma("unroll") for (int m = 0; m < 4; ++m) _Pragma("unroll") for (int n = 0; n < 2; ++n) _Pragma("unroll") for (int k = 0; k < 2; ++k) \
;         acc[ai][bj][m][n] = __builtin_amdgcn_mfma_f32_16x16x32_bf16(Bt[n][k], At[m][k], acc[ai][bj][m][n], 0, 0, 0); __builtin_amdgcn_s_setprio(0); } while (0)
; #define PG8_WAIT_V(n) asm volatile("s_waitcnt vmcnt(" #n ")" ::: "memory")
; #define PG8_WAIT_L(n) asm volatile("s_waitcnt lgkmcnt(" #n ")" ::: "memory")
; #define PG8_BAR __builtin_amdgcn_s_barrier()
; #define PG8_SCHED __builtin_amdgcn_sched_barrier(0)
; template <class Epi, class Sched, bool ALIGN_EPI = false, bool SP2 = false>
; __device__ __forceinline__ void gemm_phase(PG8_LAS unsigned char* lds, const Gemm g, const Sched& S, const Epi& E) {
;     ...
;         for (int t = 0; t < nt; t += 2) {
;     ...
;             PG8_WAIT_V(8); PG8_WAIT_L(0); PG8_BAR; PG8_MMA(0, 0, At, B0); PG8_MMA(0, 1, At, B1); PG8_BAR; PG8_SCHED;
;             PG8_LDA(At, 1, 1); PG8_STAGE(PG8_SB(1, 0), b3, voffB); PG8_STAGE(PG8_SB(1, 1), b3 + hstep, voffB); PG8_STAGE(PG8_SA(1, 0), a3, voffA);
;             PG8_WAIT_V(8); PG8_WAIT_L(0); PG8_BAR; PG8_MMA(1, 0, At, B0); PG8_MMA(1, 1, At, B1); PG8_BAR; PG8_SCHED;
	v_mfma_f32_16x16x32_bf16 v[64:67], v[152:155], v[222:225], v[64:67]
	v_mfma_f32_16x16x32_bf16 v[64:67], v[156:159], v[226:229], v[64:67]
	v_mfma_f32_16x16x32_bf16 v[68:71], v[148:151], v[226:229], v[68:71]
	v_mfma_f32_16x16x32_bf16 v[68:71], v[144:147], v[222:225], v[68:71]
	s_setprio 0
	s_add_i32 s44, s44, s41
	v_lshl_add_u64 v[200:201], v[200:201], 0, s[20:21]
	s_mov_b32 m0, s44
	ds_read_b128 v[178:181], v187 offset:49152
	ds_read_b128 v[182:185], v187 offset:50176
	ds_read_b128 v[206:209], v187 offset:51200
	ds_read_b128 v[210:213], v187 offset:52224
	ds_read_b128 v[214:217], v187 offset:53248
	ds_read_b128 v[218:221], v187 offset:54272
	ds_read_b128 v[222:225], v187 offset:55296
	ds_read_b128 v[226:229], v187 offset:56320
	global_load_lds_dwordx4 v[200:201], off
	s_add_i32 m0, s44, 0x2000
	s_add_u32 s28, s28, 0x160080
	v_lshl_add_u64 v[200:201], v[230:231], 0, s[20:21]
	s_addc_u32 s29, s29, 0
	s_add_i32 s44, s45, s41
	global_load_lds_dwordx4 v[200:201], off
	v_lshl_add_u64 v[200:201], s[28:29], 0, v[160:161]
	s_mov_b32 m0, s44
	s_nop 0
	global_load_lds_dwordx4 v[200:201], off
	v_lshl_add_u64 v[200:201], s[28:29], 0, v[162:163]
	s_add_i32 m0, s44, 0x2000
	s_nop 0
	global_load_lds_dwordx4 v[200:201], off
	v_lshl_add_u64 v[200:201], v[232:233], 0, s[20:21]
	s_mov_b32 m0, s67
	s_nop 0
	global_load_lds_dwordx4 v[200:201], off
	v_lshl_add_u64 v[200:201], v[234:235], 0, s[20:21]
	s_mov_b32 m0, s68
	s_nop 0
	global_load_lds_dwordx4 v[200:201], off
	s_waitcnt vmcnt(8)
	s_waitcnt lgkmcnt(0)
	s_barrier
	s_setprio 1
	s_waitcnt lgkmcnt(0)
	v_mfma_f32_16x16x32_bf16 v[60:63], v[76:79], v[178:181], v[60:63]
	v_mfma_f32_16x16x32_bf16 v[60:63], v[84:87], v[182:185], v[60:63]
	v_mfma_f32_16x16x32_bf16 v[56:59], v[96:99], v[182:185], v[56:59]
	v_mfma_f32_16x16x32_bf16 v[56:59], v[92:95], v[178:181], v[56:59]
	v_mfma_f32_16x16x32_bf16 v[40:43], v[92:95], v[206:209], v[40:43]
	v_mfma_f32_16x16x32_bf16 v[40:43], v[96:99], v[210:213], v[40:43]
	v_mfma_f32_16x16x32_bf16 v[44:47], v[84:87], v[210:213], v[44:47]
	v_mfma_f32_16x16x32_bf16 v[44:47], v[76:79], v[206:209], v[44:47]
	v_mfma_f32_16x16x32_bf16 v[28:31], v[76:79], v[214:217], v[28:31]
	v_mfma_f32_16x16x32_bf16 v[28:31], v[84:87], v[218:221], v[28:31]
	v_mfma_f32_16x16x32_bf16 v[24:27], v[96:99], v[218:221], v[24:27]
	v_mfma_f32_16x16x32_bf16 v[24:27], v[92:95], v[214:217], v[24:27]
	v_mfma_f32_16x16x32_bf16 v[8:11], v[92:95], v[222:225], v[8:11]
	v_mfma_f32_16x16x32_bf16 v[8:11], v[96:99], v[226:229], v[8:11]
	v_mfma_f32_16x16x32_bf16 v[12:15], v[84:87], v[226:229], v[12:15]
	v_mfma_f32_16x16x32_bf16 v[12:15], v[76:79], v[222:225], v[12:15]
	s_setprio 0
	s_setprio 1
	v_mfma_f32_16x16x32_bf16 v[52:55], v[144:147], v[178:181], v[52:55]
	v_mfma_f32_16x16x32_bf16 v[52:55], v[148:151], v[182:185], v[52:55]
	v_mfma_f32_16x16x32_bf16 v[48:51], v[156:159], v[182:185], v[48:51]
	v_mfma_f32_16x16x32_bf16 v[48:51], v[152:155], v[178:181], v[48:51]
	v_mfma_f32_16x16x32_bf16 v[32:35], v[152:155], v[206:209], v[32:35]
	v_mfma_f32_16x16x32_bf16 v[32:35], v[156:159], v[210:213], v[32:35]
	v_mfma_f32_16x16x32_bf16 v[36:39], v[148:151], v[210:213], v[36:39]
	v_mfma_f32_16x16x32_bf16 v[36:39], v[144:147], v[206:209], v[36:39]
	v_mfma_f32_16x16x32_bf16 v[20:23], v[144:147], v[214:217], v[20:23]
	v_mfma_f32_16x16x32_bf16 v[20:23], v[148:151], v[218:221], v[20:23]
	v_mfma_f32_16x16x32_bf16 v[16:19], v[156:159], v[218:221], v[16:19]
	v_mfma_f32_16x16x32_bf16 v[16:19], v[152:155], v[214:217], v[16:19]
	s_setprio 2
	s_barrier
	v_mfma_f32_16x16x32_bf16 v[0:3], v[152:155], v[222:225], v[0:3]
	v_mfma_f32_16x16x32_bf16 v[0:3], v[156:159], v[226:229], v[0:3]
	v_mfma_f32_16x16x32_bf16 v[4:7], v[148:151], v[226:229], v[4:7]
	v_mfma_f32_16x16x32_bf16 v[4:7], v[144:147], v[222:225], v[4:7]
	s_setprio 0
	s_add_i32 s77, s77, 2
	s_add_u32 s64, s64, 0x100
	s_addc_u32 s65, s65, 0
	s_add_u32 s34, s34, 0x100
	s_addc_u32 s35, s35, 0
	s_cmpk_gt_u32 s77, 0x55
	s_cbranch_scc0 .LBB0_482
	s_and_b64 vcc, exec, s[22:23]
	s_cbranch_vccz .LBB0_485
	s_barrier

; #define PG8_STAGE(bufoff, gbase, voff) do { _Pragma("unroll") for (int _i = 0; _i < 2; ++_i) \
;         __builtin_amdgcn_global_load_lds((const unsigned*)((const char*)(gbase) + (voff)[_i]), (PG8_LAS unsigned*)(lds + (bufoff) + ldsw + _i * 8192), 16, 0, 0); } while (0)
; #define PG8_LDA(dst, b, h) do { _Pragma("unroll") for (int m = 0; m < 4; ++m) _Pragma("unroll") for (int k = 0; k < 2; ++k) dst[m][k] = *(const PG8_LAS bf16x8*)(lds + PG8_SA(b, h) + aoff + m * 2048 + k * 1024); } while (0)
; #define PG8_LDB(dst, b, h) do { _Pragma("unroll") for (int n = 0; n < 2; ++n) _Pragma("unroll") for (int k = 0; k < 2; ++k) dst[n][k] = *(const PG8_LAS bf16x8*)(lds + PG8_SB(b, h) + boff + n * 2048 + k * 1024); } while (0)
; #define PG8_MMA(ai, bj, At, Bt) do { __builtin_amdgcn_s_setprio(1); _Pragma("unroll") for (int m = 0; m < 4; ++m) _Pragma("unroll") for (int n = 0; n < 2; ++n) _Pragma("unroll") for (int k = 0; k < 2; ++k) \
;         acc[ai][bj][m][n] = __builtin_amdgcn_mfma_f32_16x16x32_bf16(Bt[n][k], At[m][k], acc[ai][bj][m][n], 0, 0, 0); __builtin_amdgcn_s_setprio(0); } while (0)
; #define PG8_WAIT_V(n) asm volatile("s_waitcnt vmcnt(" #n ")" ::: "memory")
; #define PG8_WAIT_L(n) asm volatile("s_waitcnt lgkmcnt(" #n ")" ::: "memory")
; template <class Epi, class Sched, bool ALIGN_EPI = false, bool SP2 = false>
; __device__ __forceinline__ void gemm_phase(PG8_LAS unsigned char* lds, const Gemm g, const Sched& S, const Epi& E) {
;     ...
;             const bool last = (t == nt - 2);
;             const char* a1 = cA + (size_t)(t + 1) * kstep;
;             const char* a2 = last ? nA : cA + (size_t)(t + 2) * kstep; const char* b2 = last ? nB : cB + (size_t)(t + 2) * kstep;
;             const char* a3 = a2 + kstep; const char* b3 = b2 + kstep;
;             if (last && has_next) S.a_ready(nxt);
;             if constexpr (SP2) {
;             PG8_LDB(B0, 0, 0); PG8_LDB(B1, 0, 1); PG8_SCHED; PG8_LDA(At, 0, 0); PG8_STAGE(PG8_SA(1, 1), a1 + hstep, voffA);
;             PG8_WAIT_V(8); PG8_WAIT_L(0); PG8_BAR; PG8_MMA(0, 0, At, B0); PG8_MMA(0, 1, At, B1); PG8_BAR; PG8_SCHED;
;             PG8_LDA(At, 0, 1); PG8_STAGE(PG8_SB(0, 0), b2, voffB); PG8_STAGE(PG8_SB(0, 1), b2 + hstep, voffB); PG8_STAGE(PG8_SA(0, 0), a2, voffA);
;             PG8_WAIT_V(8); PG8_WAIT_L(0); PG8_BAR; PG8_MMA(1, 0, At, B0); PG8_MMA(1, 1, At, B1); PG8_BAR; PG8_SCHED;
.LBB0_536:
	ds_read_b128 v[136:139], v156
	ds_read_b128 v[140:143], v156 offset:1024
	ds_read_b128 v[172:175], v156 offset:2048
	ds_read_b128 v[176:179], v156 offset:3072
	ds_read_b128 v[180:183], v157
	ds_read_b128 v[184:187], v157 offset:1024
	ds_read_b128 v[206:209], v157 offset:2048
	ds_read_b128 v[210:213], v157 offset:3072
	s_add_u32 s28, s66, 0xfff80080
	s_addc_u32 s29, s67, -1
	s_cmp_eq_u32 s79, 28
	s_cselect_b32 s49, s34, s29
	s_cselect_b32 s48, s35, s28
	s_cselect_b32 s29, s23, s78
	s_cselect_b32 s28, s39, s77
	v_lshl_add_u64 v[200:201], s[66:67], 0, v[128:129]
	s_add_i32 m0, s11, 0xc000
	ds_read_b128 v[214:217], v158
	ds_read_b128 v[218:221], v158 offset:1024
	ds_read_b128 v[222:225], v158 offset:2048
	ds_read_b128 v[226:229], v158 offset:3072
	ds_read_b128 v[230:233], v158 offset:4096
	ds_read_b128 v[234:237], v158 offset:5120
	ds_read_b128 v[238:241], v158 offset:6144
	ds_read_b128 v[242:245], v158 offset:7168
	global_load_lds_dwordx4 v[200:201], off
	v_lshl_add_u64 v[200:201], s[66:67], 0, v[130:131]
	s_add_i32 m0, s11, 0xe000
	s_nop 0
	global_load_lds_dwordx4 v[200:201], off
	s_waitcnt vmcnt(8)
	s_waitcnt lgkmcnt(0)
	s_barrier
	s_setprio 1
	s_waitcnt lgkmcnt(0)
	v_mfma_f32_16x16x32_bf16 v[124:127], v[136:139], v[214:217], v[124:127]
	v_mfma_f32_16x16x32_bf16 v[124:127], v[140:143], v[218:221], v[124:127]
	v_mfma_f32_16x16x32_bf16 v[120:123], v[176:179], v[218:221], v[120:123]
	v_mfma_f32_16x16x32_bf16 v[120:123], v[172:175], v[214:217], v[120:123]
	v_mfma_f32_16x16x32_bf16 v[104:107], v[172:175], v[222:225], v[104:107]
	v_mfma_f32_16x16x32_bf16 v[104:107], v[176:179], v[226:229], v[104:107]
	v_mfma_f32_16x16x32_bf16 v[108:111], v[140:143], v[226:229], v[108:111]
	v_mfma_f32_16x16x32_bf16 v[108:111], v[136:139], v[222:225], v[108:111]
	v_mfma_f32_16x16x32_bf16 v[96:99], v[136:139], v[230:233], v[96:99]
	v_mfma_f32_16x16x32_bf16 v[96:99], v[140:143], v[234:237], v[96:99]
	v_mfma_f32_16x16x32_bf16 v[88:91], v[176:179], v[234:237], v[88:91]
	v_mfma_f32_16x16x32_bf16 v[88:91], v[172:175], v[230:233], v[88:91]
	v_mfma_f32_16x16x32_bf16 v[72:75], v[172:175], v[238:241], v[72:75]
	v_mfma_f32_16x16x32_bf16 v[72:75], v[176:179], v[242:245], v[72:75]
	v_mfma_f32_16x16x32_bf16 v[80:83], v[140:143], v[242:245], v[80:83]
	v_mfma_f32_16x16x32_bf16 v[80:83], v[136:139], v[238:241], v[80:83]
	s_setprio 0
	s_setprio 1
	v_mfma_f32_16x16x32_bf16 v[116:119], v[180:183], v[214:217], v[116:119]
	v_mfma_f32_16x16x32_bf16 v[116:119], v[184:187], v[218:221], v[116:119]
	v_mfma_f32_16x16x32_bf16 v[112:115], v[210:213], v[218:221], v[112:115]
	v_mfma_f32_16x16x32_bf16 v[112:115], v[206:209], v[214:217], v[112:115]
	v_mfma_f32_16x16x32_bf16 v[92:95], v[206:209], v[222:225], v[92:95]
	v_mfma_f32_16x16x32_bf16 v[92:95], v[210:213], v[226:229], v[92:95]
	v_mfma_f32_16x16x32_bf16 v[100:103], v[184:187], v[226:229], v[100:103]
	v_mfma_f32_16x16x32_bf16 v[100:103], v[180:183], v[222:225], v[100:103]
	v_mfma_f32_16x16x32_bf16 v[84:87], v[180:183], v[230:233], v[84:87]
	v_mfma_f32_16x16x32_bf16 v[84:87], v[184:187], v[234:237], v[84:87]
	v_mfma_f32_16x16x32_bf16 v[76:79], v[210:213], v[234:237], v[76:79]
	v_mfma_f32_16x16x32_bf16 v[76:79], v[206:209], v[230:233], v[76:79]
	s_setprio 2
	s_barrier
	v_mfma_f32_16x16x32_bf16 v[64:67], v[206:209], v[238:241], v[64:67]
	v_mfma_f32_16x16x32_bf16 v[64:67], v[210:213], v[242:245], v[64:67]
	v_mfma_f32_16x16x32_bf16 v[68:71], v[184:187], v[242:245], v[68:71]
	v_mfma_f32_16x16x32_bf16 v[68:71], v[180:183], v[238:241], v[68:71]
	s_setprio 0
	s_add_i32 s44, s72, s41
	v_lshl_add_u64 v[200:201], s[28:29], 0, v[166:167]
	s_mov_b32 m0, s44
	ds_read_b128 v[214:217], v158 offset:16384
	ds_read_b128 v[218:221], v158 offset:17408
	ds_read_b128 v[222:225], v158 offset:18432
	ds_read_b128 v[226:229], v158 offset:19456
	ds_read_b128 v[230:233], v158 offset:20480
	ds_read_b128 v[234:237], v158 offset:21504
	ds_read_b128 v[238:241], v158 offset:22528
	ds_read_b128 v[242:245], v158 offset:23552
	global_load_lds_dwordx4 v[200:201], off
	s_add_i32 m0, s44, 0x2000
	s_add_u32 s80, s28, 0x80000
	v_lshl_add_u64 v[246:247], s[28:29], 0, v[170:171]
	s_addc_u32 s81, s29, 0
	s_add_i32 s44, s73, s41
	global_load_lds_dwordx4 v[246:247], off
	v_lshl_add_u64 v[248:249], s[80:81], 0, v[166:167]
	s_mov_b32 m0, s44
	v_lshl_add_u64 v[250:251], s[48:49], 0, v[168:169]
	global_load_lds_dwordx4 v[248:249], off
	v_lshl_add_u64 v[248:249], s[80:81], 0, v[170:171]
	s_add_i32 m0, s44, 0x2000
	s_nop 0
	global_load_lds_dwordx4 v[248:249], off
	v_lshl_add_u64 v[248:249], s[48:49], 0, v[164:165]
	s_mov_b32 m0, s11
	s_nop 0
	global_load_lds_dwordx4 v[248:249], off
	s_mov_b32 m0, s57
	s_nop 0
	global_load_lds_dwordx4 v[250:251], off
	s_waitcnt vmcnt(8)
	s_waitcnt lgkmcnt(0)
	s_barrier
; #define PG8_STAGE(bufoff, gbase, voff) do { _Pragma("unroll") for (int _i = 0; _i < 2; ++_i) \
;         __builtin_amdgcn_global_load_lds((const unsigned*)((const char*)(gbase) + (voff)[_i]), (PG8_LAS unsigned*)(lds + (bufoff) + ldsw + _i * 8192), 16, 0, 0); } while (0)
; #define PG8_LDA(dst, b, h) do { _Pragma("unroll") for (int m = 0; m < 4; ++m) _Pragma("unroll") for (int k = 0; k < 2; ++k) dst[m][k] = *(const PG8_LAS bf16x8*)(lds + PG8_SA(b, h) + aoff + m * 2048 + k * 1024); } while (0)
; #define PG8_LDB(dst, b, h) do { _Pragma("unroll") for (int n = 0; n < 2; ++n) _Pragma("unroll") for (int k = 0; k < 2; ++k) dst[n][k] = *(const PG8_LAS bf16x8*)(lds + PG8_SB(b, h) + boff + n * 2048 + k * 1024); } while (0)
; #define PG8_MMA(ai, bj, At, Bt) do { __builtin_amdgcn_s_setprio(1); _Pragma("unroll") for (int m = 0; m < 4; ++m) _Pragma("unroll") for (int n = 0; n < 2; ++n) _Pragma("unroll") for (int k = 0; k < 2; ++k) \
;         acc[ai][bj][m][n] = __builtin_amdgcn_mfma_f32_16x16x32_bf16(Bt[n][k], At[m][k], acc[ai][bj][m][n], 0, 0, 0); __builtin_amdgcn_s_setprio(0); } while (0)
; #define PG8_WAIT_V(n) asm volatile("s_waitcnt vmcnt(" #n ")" ::: "memory")
; #define PG8_WAIT_L(n) asm volatile("s_waitcnt lgkmcnt(" #n ")" ::: "memory")
; #define PG8_BAR __builtin_amdgcn_s_barrier()
; #define PG8_SCHED __builtin_amdgcn_sched_barrier(0)
; template <class Epi, class Sched, bool ALIGN_EPI = false, bool SP2 = false>
; __device__ __forceinline__ void gemm_phase(PG8_LAS unsigned char* lds, const Gemm g, const Sched& S, const Epi& E) {
;     ...
;             PG8_WAIT_V(8); PG8_WAIT_L(0); PG8_BAR; PG8_MMA(1, 0, At, B0); PG8_MMA(1, 1, At, B1); PG8_BAR; PG8_SCHED;
;             PG8_LDB(B0, 1, 0); PG8_LDB(B1, 1, 1); PG8_SCHED; PG8_LDA(At, 1, 0); PG8_STAGE(PG8_SA(0, 1), a2 + hstep, voffA);
;             PG8_WAIT_V(8); PG8_WAIT_L(0); PG8_BAR; PG8_MMA(0, 0, At, B0); PG8_MMA(0, 1, At, B1); PG8_BAR; PG8_SCHED;
	s_setprio 1
	s_waitcnt lgkmcnt(0)
	v_mfma_f32_16x16x32_bf16 v[60:63], v[136:139], v[214:217], v[60:63]
	v_mfma_f32_16x16x32_bf16 v[60:63], v[140:143], v[218:221], v[60:63]
	v_mfma_f32_16x16x32_bf16 v[56:59], v[176:179], v[218:221], v[56:59]
	v_mfma_f32_16x16x32_bf16 v[56:59], v[172:175], v[214:217], v[56:59]
	v_mfma_f32_16x16x32_bf16 v[40:43], v[172:175], v[222:225], v[40:43]
	v_mfma_f32_16x16x32_bf16 v[40:43], v[176:179], v[226:229], v[40:43]
	v_mfma_f32_16x16x32_bf16 v[48:51], v[140:143], v[226:229], v[48:51]
	v_mfma_f32_16x16x32_bf16 v[48:51], v[136:139], v[222:225], v[48:51]
	v_mfma_f32_16x16x32_bf16 v[32:35], v[136:139], v[230:233], v[32:35]
	v_mfma_f32_16x16x32_bf16 v[32:35], v[140:143], v[234:237], v[32:35]
	v_mfma_f32_16x16x32_bf16 v[24:27], v[176:179], v[234:237], v[24:27]
	v_mfma_f32_16x16x32_bf16 v[24:27], v[172:175], v[230:233], v[24:27]
	v_mfma_f32_16x16x32_bf16 v[8:11], v[172:175], v[238:241], v[8:11]
	v_mfma_f32_16x16x32_bf16 v[8:11], v[176:179], v[242:245], v[8:11]
	v_mfma_f32_16x16x32_bf16 v[12:15], v[140:143], v[242:245], v[12:15]
	v_mfma_f32_16x16x32_bf16 v[12:15], v[136:139], v[238:241], v[12:15]
	s_setprio 0
	s_setprio 1
	v_mfma_f32_16x16x32_bf16 v[52:55], v[180:183], v[214:217], v[52:55]
	v_mfma_f32_16x16x32_bf16 v[52:55], v[184:187], v[218:221], v[52:55]
	v_mfma_f32_16x16x32_bf16 v[44:47], v[210:213], v[218:221], v[44:47]
	v_mfma_f32_16x16x32_bf16 v[44:47], v[206:209], v[214:217], v[44:47]
	v_mfma_f32_16x16x32_bf16 v[28:31], v[206:209], v[222:225], v[28:31]
	v_mfma_f32_16x16x32_bf16 v[28:31], v[210:213], v[226:229], v[28:31]
	v_mfma_f32_16x16x32_bf16 v[36:39], v[184:187], v[226:229], v[36:39]
	v_mfma_f32_16x16x32_bf16 v[36:39], v[180:183], v[222:225], v[36:39]
	v_mfma_f32_16x16x32_bf16 v[20:23], v[180:183], v[230:233], v[20:23]
	v_mfma_f32_16x16x32_bf16 v[20:23], v[184:187], v[234:237], v[20:23]
	v_mfma_f32_16x16x32_bf16 v[16:19], v[210:213], v[234:237], v[16:19]
	v_mfma_f32_16x16x32_bf16 v[16:19], v[206:209], v[230:233], v[16:19]
	s_setprio 2
	s_barrier
	v_mfma_f32_16x16x32_bf16 v[0:3], v[206:209], v[238:241], v[0:3]
	v_mfma_f32_16x16x32_bf16 v[0:3], v[210:213], v[242:245], v[0:3]
	v_mfma_f32_16x16x32_bf16 v[4:7], v[184:187], v[242:245], v[4:7]
	v_mfma_f32_16x16x32_bf16 v[4:7], v[180:183], v[238:241], v[4:7]
	s_setprio 0
	s_add_i32 s44, 0, 0x18000
	v_add_u32_e32 v144, s44, v146
	s_add_i32 s45, 0, 0x1c000
	ds_read_b128 v[136:139], v144
	ds_read_b128 v[140:143], v144 offset:1024
	ds_read_b128 v[172:175], v144 offset:2048
	ds_read_b128 v[176:179], v144 offset:3072
	v_add_u32_e32 v144, s45, v146
	ds_read_b128 v[180:183], v144
	ds_read_b128 v[184:187], v144 offset:1024
	ds_read_b128 v[206:209], v144 offset:2048
	ds_read_b128 v[210:213], v144 offset:3072
	s_add_u32 s48, s48, 0x80000
	s_addc_u32 s49, s49, 0
	s_mov_b32 m0, s61
	v_lshl_add_u64 v[252:253], s[48:49], 0, v[164:165]
	ds_read_b128 v[214:217], v158 offset:32768
	ds_read_b128 v[218:221], v158 offset:33792
	ds_read_b128 v[222:225], v158 offset:34816
	ds_read_b128 v[226:229], v158 offset:35840
	ds_read_b128 v[230:233], v158 offset:36864
	ds_read_b128 v[234:237], v158 offset:37888
	ds_read_b128 v[238:241], v158 offset:38912
	ds_read_b128 v[242:245], v158 offset:39936
	global_load_lds_dwordx4 v[252:253], off
	v_lshl_add_u64 v[252:253], s[48:49], 0, v[168:169]
	s_mov_b32 m0, s68
	s_nop 0
	global_load_lds_dwordx4 v[252:253], off
	s_waitcnt vmcnt(8)
	s_waitcnt lgkmcnt(0)
	s_barrier
	s_setprio 1
	s_waitcnt lgkmcnt(0)
	v_mfma_f32_16x16x32_bf16 v[124:127], v[136:139], v[214:217], v[124:127]
	v_mfma_f32_16x16x32_bf16 v[124:127], v[140:143], v[218:221], v[124:127]
	v_mfma_f32_16x16x32_bf16 v[120:123], v[176:179], v[218:221], v[120:123]
	v_mfma_f32_16x16x32_bf16 v[120:123], v[172:175], v[214:217], v[120:123]
	v_mfma_f32_16x16x32_bf16 v[104:107], v[172:175], v[222:225], v[104:107]
	v_mfma_f32_16x16x32_bf16 v[104:107], v[176:179], v[226:229], v[104:107]
	v_mfma_f32_16x16x32_bf16 v[108:111], v[140:143], v[226:229], v[108:111]
	v_mfma_f32_16x16x32_bf16 v[108:111], v[136:139], v[222:225], v[108:111]
	v_mfma_f32_16x16x32_bf16 v[96:99], v[136:139], v[230:233], v[96:99]
	v_mfma_f32_16x16x32_bf16 v[96:99], v[140:143], v[234:237], v[96:99]
	v_mfma_f32_16x16x32_bf16 v[88:91], v[176:179], v[234:237], v[88:91]
	v_mfma_f32_16x16x32_bf16 v[88:91], v[172:175], v[230:233], v[88:91]
	v_mfma_f32_16x16x32_bf16 v[72:75], v[172:175], v[238:241], v[72:75]
	v_mfma_f32_16x16x32_bf16 v[72:75], v[176:179], v[242:245], v[72:75]
	v_mfma_f32_16x16x32_bf16 v[80:83], v[140:143], v[242:245], v[80:83]
	v_mfma_f32_16x16x32_bf16 v[80:83], v[136:139], v[238:241], v[80:83]
	s_setprio 0
	s_setprio 1
	v_mfma_f32_16x16x32_bf16 v[116:119], v[180:183], v[214:217], v[116:119]
	v_mfma_f32_16x16x32_bf16 v[116:119], v[184:187], v[218:221], v[116:119]
	v_mfma_f32_16x16x32_bf16 v[112:115], v[210:213], v[218:221], v[112:115]
	v_mfma_f32_16x16x32_bf16 v[112:115], v[206:209], v[214:217], v[112:115]
	v_mfma_f32_16x16x32_bf16 v[92:95], v[206:209], v[222:225], v[92:95]
	v_mfma_f32_16x16x32_bf16 v[92:95], v[210:213], v[226:229], v[92:95]
	v_mfma_f32_16x16x32_bf16 v[100:103], v[184:187], v[226:229], v[100:103]
	v_mfma_f32_16x16x32_bf16 v[100:103], v[180:183], v[222:225], v[100:103]
	v_mfma_f32_16x16x32_bf16 v[84:87], v[180:183], v[230:233], v[84:87]
	v_mfma_f32_16x16x32_bf16 v[84:87], v[184:187], v[234:237], v[84:87]
	v_mfma_f32_16x16x32_bf16 v[76:79], v[210:213], v[234:237], v[76:79]
	v_mfma_f32_16x16x32_bf16 v[76:79], v[206:209], v[230:233], v[76:79]
	s_setprio 2
	s_barrier
; #define PG8_STAGE(bufoff, gbase, voff) do { _Pragma("unroll") for (int _i = 0; _i < 2; ++_i) \
;         __builtin_amdgcn_global_load_lds((const unsigned*)((const char*)(gbase) + (voff)[_i]), (PG8_LAS unsigned*)(lds + (bufoff) + ldsw + _i * 8192), 16, 0, 0); } while (0)
; #define PG8_LDA(dst, b, h) do { _Pragma("unroll") for (int m = 0; m < 4; ++m) _Pragma("unroll") for (int k = 0; k < 2; ++k) dst[m][k] = *(const PG8_LAS bf16x8*)(lds + PG8_SA(b, h) + aoff + m * 2048 + k * 1024); } while (0)
; #define PG8_MMA(ai, bj, At, Bt) do { __builtin_amdgcn_s_setprio(1); _Pragma("unroll") for (int m = 0; m < 4; ++m) _Pragma("unroll") for (int n = 0; n < 2; ++n) _Pragma("unroll") for (int k = 0; k < 2; ++k) \
;         acc[ai][bj][m][n] = __builtin_amdgcn_mfma_f32_16x16x32_bf16(Bt[n][k], At[m][k], acc[ai][bj][m][n], 0, 0, 0); __builtin_amdgcn_s_setprio(0); } while (0)
; #define PG8_WAIT_V(n) asm volatile("s_waitcnt vmcnt(" #n ")" ::: "memory")
; #define PG8_WAIT_L(n) asm volatile("s_waitcnt lgkmcnt(" #n ")" ::: "memory")
; #define PG8_BAR __builtin_amdgcn_s_barrier()
; #define PG8_SCHED __builtin_amdgcn_sched_barrier(0)
; template <class Epi, class Sched, bool ALIGN_EPI = false, bool SP2 = false>
; __device__ __forceinline__ void gemm_phase(PG8_LAS unsigned char* lds, const Gemm g, const Sched& S, const Epi& E) {
;     ...
;         for (int t = 0; t < nt; t += 2) {
;     ...
;             PG8_WAIT_V(8); PG8_WAIT_L(0); PG8_BAR; PG8_MMA(0, 0, At, B0); PG8_MMA(0, 1, At, B1); PG8_BAR; PG8_SCHED;
;             PG8_LDA(At, 1, 1); PG8_STAGE(PG8_SB(1, 0), b3, voffB); PG8_STAGE(PG8_SB(1, 1), b3 + hstep, voffB); PG8_STAGE(PG8_SA(1, 0), a3, voffA);
;             PG8_WAIT_V(8); PG8_WAIT_L(0); PG8_BAR; PG8_MMA(1, 0, At, B0); PG8_MMA(1, 1, At, B1); PG8_BAR; PG8_SCHED;
	v_mfma_f32_16x16x32_bf16 v[64:67], v[206:209], v[238:241], v[64:67]
	v_mfma_f32_16x16x32_bf16 v[64:67], v[210:213], v[242:245], v[64:67]
	v_mfma_f32_16x16x32_bf16 v[68:71], v[184:187], v[242:245], v[68:71]
	v_mfma_f32_16x16x32_bf16 v[68:71], v[180:183], v[238:241], v[68:71]
	s_setprio 0
	s_add_i32 s44, s44, s41
	v_lshl_add_u64 v[200:201], v[200:201], 0, s[18:19]
	s_mov_b32 m0, s44
	ds_read_b128 v[214:217], v158 offset:49152
	ds_read_b128 v[218:221], v158 offset:50176
	ds_read_b128 v[222:225], v158 offset:51200
	ds_read_b128 v[226:229], v158 offset:52224
	ds_read_b128 v[230:233], v158 offset:53248
	ds_read_b128 v[234:237], v158 offset:54272
	ds_read_b128 v[238:241], v158 offset:55296
	ds_read_b128 v[242:245], v158 offset:56320
	global_load_lds_dwordx4 v[200:201], off
	s_add_i32 m0, s44, 0x2000
	s_add_u32 s28, s28, 0x80080
	v_lshl_add_u64 v[200:201], v[246:247], 0, s[18:19]
	s_addc_u32 s29, s29, 0
	s_add_i32 s44, s45, s41
	global_load_lds_dwordx4 v[200:201], off
	v_lshl_add_u64 v[200:201], s[28:29], 0, v[166:167]
	s_mov_b32 m0, s44
	s_nop 0
	global_load_lds_dwordx4 v[200:201], off
	v_lshl_add_u64 v[200:201], s[28:29], 0, v[170:171]
	s_add_i32 m0, s44, 0x2000
	s_nop 0
	global_load_lds_dwordx4 v[200:201], off
	v_lshl_add_u64 v[200:201], v[248:249], 0, s[18:19]
	s_mov_b32 m0, s70
	s_nop 0
	global_load_lds_dwordx4 v[200:201], off
	v_lshl_add_u64 v[200:201], v[250:251], 0, s[18:19]
	s_mov_b32 m0, s71
	s_nop 0
	global_load_lds_dwordx4 v[200:201], off
	s_waitcnt vmcnt(8)
	s_waitcnt lgkmcnt(0)
	s_barrier
	s_setprio 1
	s_waitcnt lgkmcnt(0)
	v_mfma_f32_16x16x32_bf16 v[60:63], v[136:139], v[214:217], v[60:63]
	v_mfma_f32_16x16x32_bf16 v[60:63], v[140:143], v[218:221], v[60:63]
	v_mfma_f32_16x16x32_bf16 v[56:59], v[176:179], v[218:221], v[56:59]
	v_mfma_f32_16x16x32_bf16 v[56:59], v[172:175], v[214:217], v[56:59]
	v_mfma_f32_16x16x32_bf16 v[40:43], v[172:175], v[222:225], v[40:43]
	v_mfma_f32_16x16x32_bf16 v[40:43], v[176:179], v[226:229], v[40:43]
	v_mfma_f32_16x16x32_bf16 v[48:51], v[140:143], v[226:229], v[48:51]
	v_mfma_f32_16x16x32_bf16 v[48:51], v[136:139], v[222:225], v[48:51]
	v_mfma_f32_16x16x32_bf16 v[32:35], v[136:139], v[230:233], v[32:35]
	v_mfma_f32_16x16x32_bf16 v[32:35], v[140:143], v[234:237], v[32:35]
	v_mfma_f32_16x16x32_bf16 v[24:27], v[176:179], v[234:237], v[24:27]
	v_mfma_f32_16x16x32_bf16 v[24:27], v[172:175], v[230:233], v[24:27]
	v_mfma_f32_16x16x32_bf16 v[8:11], v[172:175], v[238:241], v[8:11]
	v_mfma_f32_16x16x32_bf16 v[8:11], v[176:179], v[242:245], v[8:11]
	v_mfma_f32_16x16x32_bf16 v[12:15], v[140:143], v[242:245], v[12:15]
	v_mfma_f32_16x16x32_bf16 v[12:15], v[136:139], v[238:241], v[12:15]
	s_setprio 0
	s_setprio 1
	v_mfma_f32_16x16x32_bf16 v[52:55], v[180:183], v[214:217], v[52:55]
	v_mfma_f32_16x16x32_bf16 v[52:55], v[184:187], v[218:221], v[52:55]
	v_mfma_f32_16x16x32_bf16 v[44:47], v[210:213], v[218:221], v[44:47]
	v_mfma_f32_16x16x32_bf16 v[44:47], v[206:209], v[214:217], v[44:47]
	v_mfma_f32_16x16x32_bf16 v[28:31], v[206:209], v[222:225], v[28:31]
	v_mfma_f32_16x16x32_bf16 v[28:31], v[210:213], v[226:229], v[28:31]
	v_mfma_f32_16x16x32_bf16 v[36:39], v[184:187], v[226:229], v[36:39]
	v_mfma_f32_16x16x32_bf16 v[36:39], v[180:183], v[222:225], v[36:39]
	v_mfma_f32_16x16x32_bf16 v[20:23], v[180:183], v[230:233], v[20:23]
	v_mfma_f32_16x16x32_bf16 v[20:23], v[184:187], v[234:237], v[20:23]
	v_mfma_f32_16x16x32_bf16 v[16:19], v[210:213], v[234:237], v[16:19]
	v_mfma_f32_16x16x32_bf16 v[16:19], v[206:209], v[230:233], v[16:19]
	s_setprio 2
	s_barrier
	v_mfma_f32_16x16x32_bf16 v[0:3], v[206:209], v[238:241], v[0:3]
	v_mfma_f32_16x16x32_bf16 v[0:3], v[210:213], v[242:245], v[0:3]
	v_mfma_f32_16x16x32_bf16 v[4:7], v[184:187], v[242:245], v[4:7]
	v_mfma_f32_16x16x32_bf16 v[4:7], v[180:183], v[238:241], v[4:7]
	s_setprio 0
	s_add_i32 s79, s79, 2
	s_add_u32 s66, s66, 0x100
	s_addc_u32 s67, s67, 0
	s_add_u32 s77, s77, 0x100
	s_addc_u32 s78, s78, 0
	s_cmp_gt_u32 s79, 29
	s_cbranch_scc0 .LBB0_536
	s_and_b64 vcc, exec, s[20:21]
	s_cbranch_vccz .LBB0_539
	s_barrier

; #define PG8_STAGE(bufoff, gbase, voff) do { _Pragma("unroll") for (int _i = 0; _i < 2; ++_i) \
;         __builtin_amdgcn_global_load_lds((const unsigned*)((const char*)(gbase) + (voff)[_i]), (PG8_LAS unsigned*)(lds + (bufoff) + ldsw + _i * 8192), 16, 0, 0); } while (0)
; #define PG8_LDA(dst, b, h) do { _Pragma("unroll") for (int m = 0; m < 4; ++m) _Pragma("unroll") for (int k = 0; k < 2; ++k) dst[m][k] = *(const PG8_LAS bf16x8*)(lds + PG8_SA(b, h) + aoff + m * 2048 + k * 1024); } while (0)
; #define PG8_LDB(dst, b, h) do { _Pragma("unroll") for (int n = 0; n < 2; ++n) _Pragma("unroll") for (int k = 0; k < 2; ++k) dst[n][k] = *(const PG8_LAS bf16x8*)(lds + PG8_SB(b, h) + boff + n * 2048 + k * 1024); } while (0)
; #define PG8_MMA(ai, bj, At, Bt) do { __builtin_amdgcn_s_setprio(1); _Pragma("unroll") for (int m = 0; m < 4; ++m) _Pragma("unroll") for (int n = 0; n < 2; ++n) _Pragma("unroll") for (int k = 0; k < 2; ++k) \
;         acc[ai][bj][m][n] = __builtin_amdgcn_mfma_f32_16x16x32_bf16(Bt[n][k], At[m][k], acc[ai][bj][m][n], 0, 0, 0); __builtin_amdgcn_s_setprio(0); } while (0)
; #define PG8_WAIT_V(n) asm volatile("s_waitcnt vmcnt(" #n ")" ::: "memory")
; #define PG8_WAIT_L(n) asm volatile("s_waitcnt lgkmcnt(" #n ")" ::: "memory")
; template <class Epi, class Sched, bool ALIGN_EPI = false, bool SP2 = false>
; __device__ __forceinline__ void gemm_phase(PG8_LAS unsigned char* lds, const Gemm g, const Sched& S, const Epi& E) {
;     ...
;             const bool last = (t == nt - 2);
;             const char* a1 = cA + (size_t)(t + 1) * kstep;
;             const char* a2 = last ? nA : cA + (size_t)(t + 2) * kstep; const char* b2 = last ? nB : cB + (size_t)(t + 2) * kstep;
;             const char* a3 = a2 + kstep; const char* b3 = b2 + kstep;
;             if (last && has_next) S.a_ready(nxt);
;             if constexpr (SP2) {
;             PG8_LDB(B0, 0, 0); PG8_LDB(B1, 0, 1); PG8_SCHED; PG8_LDA(At, 0, 0); PG8_STAGE(PG8_SA(1, 1), a1 + hstep, voffA);
;             PG8_WAIT_V(8); PG8_WAIT_L(0); PG8_BAR; PG8_MMA(0, 0, At, B0); PG8_MMA(0, 1, At, B1); PG8_BAR; PG8_SCHED;
;             PG8_LDA(At, 0, 1); PG8_STAGE(PG8_SB(0, 0), b2, voffB); PG8_STAGE(PG8_SB(0, 1), b2 + hstep, voffB); PG8_STAGE(PG8_SA(0, 0), a2, voffA);
;             PG8_WAIT_V(8); PG8_WAIT_L(0); PG8_BAR; PG8_MMA(1, 0, At, B0); PG8_MMA(1, 1, At, B1); PG8_BAR; PG8_SCHED;
.LBB0_602:
	ds_read_b128 v[76:79], v171
	ds_read_b128 v[84:87], v171 offset:1024
	ds_read_b128 v[92:95], v171 offset:2048
	ds_read_b128 v[96:99], v171 offset:3072
	ds_read_b128 v[144:147], v186
	ds_read_b128 v[148:151], v186 offset:1024
	ds_read_b128 v[152:155], v186 offset:2048
	ds_read_b128 v[156:159], v186 offset:3072
	s_add_u32 s28, s62, 0xffea0080
	s_addc_u32 s29, s63, -1
	s_cmpk_eq_i32 s77, 0x54
	s_cselect_b32 s49, s39, s29
	s_cselect_b32 s48, s38, s28
	s_cselect_b32 s29, s41, s35
	s_cselect_b32 s28, s40, s34
	v_lshl_add_u64 v[200:201], s[62:63], 0, v[172:173]
	s_add_i32 m0, s61, 0xc000
	ds_read_b128 v[178:181], v187
	ds_read_b128 v[182:185], v187 offset:1024
	ds_read_b128 v[206:209], v187 offset:2048
	ds_read_b128 v[210:213], v187 offset:3072
	ds_read_b128 v[214:217], v187 offset:4096
	ds_read_b128 v[218:221], v187 offset:5120
	ds_read_b128 v[222:225], v187 offset:6144
	ds_read_b128 v[226:229], v187 offset:7168
	global_load_lds_dwordx4 v[200:201], off
	v_lshl_add_u64 v[200:201], s[62:63], 0, v[174:175]
	s_add_i32 m0, s61, 0xe000
	s_nop 0
	global_load_lds_dwordx4 v[200:201], off
	s_waitcnt vmcnt(8)
	s_waitcnt lgkmcnt(0)
	s_barrier
	s_setprio 1
	s_waitcnt lgkmcnt(0)
	v_mfma_f32_16x16x32_bf16 v[140:143], v[76:79], v[178:181], v[140:143]
	v_mfma_f32_16x16x32_bf16 v[140:143], v[84:87], v[182:185], v[140:143]
	v_mfma_f32_16x16x32_bf16 v[136:139], v[96:99], v[182:185], v[136:139]
	v_mfma_f32_16x16x32_bf16 v[136:139], v[92:95], v[178:181], v[136:139]
	v_mfma_f32_16x16x32_bf16 v[120:123], v[92:95], v[206:209], v[120:123]
	v_mfma_f32_16x16x32_bf16 v[120:123], v[96:99], v[210:213], v[120:123]
	v_mfma_f32_16x16x32_bf16 v[124:127], v[84:87], v[210:213], v[124:127]
	v_mfma_f32_16x16x32_bf16 v[124:127], v[76:79], v[206:209], v[124:127]
	v_mfma_f32_16x16x32_bf16 v[108:111], v[76:79], v[214:217], v[108:111]
	v_mfma_f32_16x16x32_bf16 v[108:111], v[84:87], v[218:221], v[108:111]
	v_mfma_f32_16x16x32_bf16 v[104:107], v[96:99], v[218:221], v[104:107]
	v_mfma_f32_16x16x32_bf16 v[104:107], v[92:95], v[214:217], v[104:107]
	v_mfma_f32_16x16x32_bf16 v[72:75], v[92:95], v[222:225], v[72:75]
	v_mfma_f32_16x16x32_bf16 v[72:75], v[96:99], v[226:229], v[72:75]
	v_mfma_f32_16x16x32_bf16 v[80:83], v[84:87], v[226:229], v[80:83]
	v_mfma_f32_16x16x32_bf16 v[80:83], v[76:79], v[222:225], v[80:83]
	s_setprio 0
	s_setprio 1
	v_mfma_f32_16x16x32_bf16 v[132:135], v[144:147], v[178:181], v[132:135]
	v_mfma_f32_16x16x32_bf16 v[132:135], v[148:151], v[182:185], v[132:135]
	v_mfma_f32_16x16x32_bf16 v[128:131], v[156:159], v[182:185], v[128:131]
	v_mfma_f32_16x16x32_bf16 v[128:131], v[152:155], v[178:181], v[128:131]
	v_mfma_f32_16x16x32_bf16 v[112:115], v[152:155], v[206:209], v[112:115]
	v_mfma_f32_16x16x32_bf16 v[112:115], v[156:159], v[210:213], v[112:115]
	v_mfma_f32_16x16x32_bf16 v[116:119], v[148:151], v[210:213], v[116:119]
	v_mfma_f32_16x16x32_bf16 v[116:119], v[144:147], v[206:209], v[116:119]
	v_mfma_f32_16x16x32_bf16 v[100:103], v[144:147], v[214:217], v[100:103]
	v_mfma_f32_16x16x32_bf16 v[100:103], v[148:151], v[218:221], v[100:103]
	v_mfma_f32_16x16x32_bf16 v[88:91], v[156:159], v[218:221], v[88:91]
	v_mfma_f32_16x16x32_bf16 v[88:91], v[152:155], v[214:217], v[88:91]
	s_setprio 2
	s_barrier
	v_mfma_f32_16x16x32_bf16 v[64:67], v[152:155], v[222:225], v[64:67]
	v_mfma_f32_16x16x32_bf16 v[64:67], v[156:159], v[226:229], v[64:67]
	v_mfma_f32_16x16x32_bf16 v[68:71], v[148:151], v[226:229], v[68:71]
	v_mfma_f32_16x16x32_bf16 v[68:71], v[144:147], v[222:225], v[68:71]
	s_setprio 0
	s_add_i32 s44, s70, s57
	v_lshl_add_u64 v[200:201], s[28:29], 0, v[160:161]
	s_mov_b32 m0, s44
	ds_read_b128 v[178:181], v187 offset:16384
	ds_read_b128 v[182:185], v187 offset:17408
	ds_read_b128 v[206:209], v187 offset:18432
	ds_read_b128 v[210:213], v187 offset:19456
	ds_read_b128 v[214:217], v187 offset:20480
	ds_read_b128 v[218:221], v187 offset:21504
	ds_read_b128 v[222:225], v187 offset:22528
	ds_read_b128 v[226:229], v187 offset:23552
	global_load_lds_dwordx4 v[200:201], off
	s_add_i32 m0, s44, 0x2000
	s_add_u32 s78, s28, 0x160000
	v_lshl_add_u64 v[230:231], s[28:29], 0, v[162:163]
	s_addc_u32 s79, s29, 0
	s_add_i32 s44, s71, s57
	global_load_lds_dwordx4 v[230:231], off
	v_lshl_add_u64 v[232:233], s[78:79], 0, v[160:161]
	s_mov_b32 m0, s44
	v_lshl_add_u64 v[234:235], s[48:49], 0, v[162:163]
	global_load_lds_dwordx4 v[232:233], off
	v_lshl_add_u64 v[232:233], s[78:79], 0, v[162:163]
	s_add_i32 m0, s44, 0x2000
	s_nop 0
	global_load_lds_dwordx4 v[232:233], off
	v_lshl_add_u64 v[232:233], s[48:49], 0, v[160:161]
	s_mov_b32 m0, s61
	s_nop 0
	global_load_lds_dwordx4 v[232:233], off
	s_mov_b32 m0, s64
	s_nop 0
	global_load_lds_dwordx4 v[234:235], off
	s_waitcnt vmcnt(8)
	s_waitcnt lgkmcnt(0)
	s_barrier
; #define PG8_STAGE(bufoff, gbase, voff) do { _Pragma("unroll") for (int _i = 0; _i < 2; ++_i) \
;         __builtin_amdgcn_global_load_lds((const unsigned*)((const char*)(gbase) + (voff)[_i]), (PG8_LAS unsigned*)(lds + (bufoff) + ldsw + _i * 8192), 16, 0, 0); } while (0)
; #define PG8_LDA(dst, b, h) do { _Pragma("unroll") for (int m = 0; m < 4; ++m) _Pragma("unroll") for (int k = 0; k < 2; ++k) dst[m][k] = *(const PG8_LAS bf16x8*)(lds + PG8_SA(b, h) + aoff + m * 2048 + k * 1024); } while (0)
; #define PG8_LDB(dst, b, h) do { _Pragma("unroll") for (int n = 0; n < 2; ++n) _Pragma("unroll") for (int k = 0; k < 2; ++k) dst[n][k] = *(const PG8_LAS bf16x8*)(lds + PG8_SB(b, h) + boff + n * 2048 + k * 1024); } while (0)
; #define PG8_MMA(ai, bj, At, Bt) do { __builtin_amdgcn_s_setprio(1); _Pragma("unroll") for (int m = 0; m < 4; ++m) _Pragma("unroll") for (int n = 0; n < 2; ++n) _Pragma("unroll") for (int k = 0; k < 2; ++k) \
;         acc[ai][bj][m][n] = __builtin_amdgcn_mfma_f32_16x16x32_bf16(Bt[n][k], At[m][k], acc[ai][bj][m][n], 0, 0, 0); __builtin_amdgcn_s_setprio(0); } while (0)
; #define PG8_WAIT_V(n) asm volatile("s_waitcnt vmcnt(" #n ")" ::: "memory")
; template <class Epi, class Sched, bool ALIGN_EPI = false, bool SP2 = false>
; __device__ __forceinline__ void gemm_phase(PG8_LAS unsigned char* lds, const Gemm g, const Sched& S, const Epi& E) {
;     ...
;             PG8_LDB(B0, 0, 0); PG8_LDB(B1, 0, 1); PG8_SCHED; PG8_LDA(At, 0, 0); PG8_STAGE(PG8_SA(1, 1), a1 + hstep, voffA);
;             PG8_WAIT_V(8); PG8_WAIT_L(0); PG8_BAR; PG8_MMA(0, 0, At, B0); PG8_MMA(0, 1, At, B1); PG8_BAR; PG8_SCHED;
;             PG8_LDA(At, 0, 1); PG8_STAGE(PG8_SB(0, 0), b2, voffB); PG8_STAGE(PG8_SB(0, 1), b2 + hstep, voffB); PG8_STAGE(PG8_SA(0, 0), a2, voffA);
;             PG8_WAIT_V(8); PG8_WAIT_L(0); PG8_BAR; PG8_MMA(1, 0, At, B0); PG8_MMA(1, 1, At, B1); PG8_BAR; PG8_SCHED;
;             PG8_LDB(B0, 1, 0); PG8_LDB(B1, 1, 1); PG8_SCHED; PG8_LDA(At, 1, 0); PG8_STAGE(PG8_SA(0, 1), a2 + hstep, voffA);
;             PG8_WAIT_V(8); PG8_WAIT_L(0); PG8_BAR; PG8_MMA(0, 0, At, B0); PG8_MMA(0, 1, At, B1); PG8_BAR; PG8_SCHED;
;             PG8_LDA(At, 1, 1); PG8_STAGE(PG8_SB(1, 0), b3, voffB); PG8_STAGE(PG8_SB(1, 1), b3 + hstep, voffB); PG8_STAGE(PG8_SA(1, 0), a3, voffA);
;             PG8_WAIT_V(8); PG8_WAIT_L(0); PG8_BAR; PG8_MMA(1, 0, At, B0); PG8_MMA(1, 1, At, B1); PG8_BAR; PG8_SCHED;
	s_setprio 1
	s_waitcnt lgkmcnt(0)
	v_mfma_f32_16x16x32_bf16 v[60:63], v[76:79], v[178:181], v[60:63]
	v_mfma_f32_16x16x32_bf16 v[60:63], v[84:87], v[182:185], v[60:63]
	v_mfma_f32_16x16x32_bf16 v[56:59], v[96:99], v[182:185], v[56:59]
	v_mfma_f32_16x16x32_bf16 v[56:59], v[92:95], v[178:181], v[56:59]
	v_mfma_f32_16x16x32_bf16 v[40:43], v[92:95], v[206:209], v[40:43]
	v_mfma_f32_16x16x32_bf16 v[40:43], v[96:99], v[210:213], v[40:43]
	v_mfma_f32_16x16x32_bf16 v[44:47], v[84:87], v[210:213], v[44:47]
	v_mfma_f32_16x16x32_bf16 v[44:47], v[76:79], v[206:209], v[44:47]
	v_mfma_f32_16x16x32_bf16 v[28:31], v[76:79], v[214:217], v[28:31]
	v_mfma_f32_16x16x32_bf16 v[28:31], v[84:87], v[218:221], v[28:31]
	v_mfma_f32_16x16x32_bf16 v[24:27], v[96:99], v[218:221], v[24:27]
	v_mfma_f32_16x16x32_bf16 v[24:27], v[92:95], v[214:217], v[24:27]
	v_mfma_f32_16x16x32_bf16 v[8:11], v[92:95], v[222:225], v[8:11]
	v_mfma_f32_16x16x32_bf16 v[8:11], v[96:99], v[226:229], v[8:11]
	v_mfma_f32_16x16x32_bf16 v[12:15], v[84:87], v[226:229], v[12:15]
	v_mfma_f32_16x16x32_bf16 v[12:15], v[76:79], v[222:225], v[12:15]
	s_setprio 0
	s_setprio 1
	v_mfma_f32_16x16x32_bf16 v[52:55], v[144:147], v[178:181], v[52:55]
	v_mfma_f32_16x16x32_bf16 v[52:55], v[148:151], v[182:185], v[52:55]
	v_mfma_f32_16x16x32_bf16 v[48:51], v[156:159], v[182:185], v[48:51]
	v_mfma_f32_16x16x32_bf16 v[48:51], v[152:155], v[178:181], v[48:51]
	v_mfma_f32_16x16x32_bf16 v[32:35], v[152:155], v[206:209], v[32:35]
	v_mfma_f32_16x16x32_bf16 v[32:35], v[156:159], v[210:213], v[32:35]
	v_mfma_f32_16x16x32_bf16 v[36:39], v[148:151], v[210:213], v[36:39]
	v_mfma_f32_16x16x32_bf16 v[36:39], v[144:147], v[206:209], v[36:39]
	v_mfma_f32_16x16x32_bf16 v[20:23], v[144:147], v[214:217], v[20:23]
	v_mfma_f32_16x16x32_bf16 v[20:23], v[148:151], v[218:221], v[20:23]
	v_mfma_f32_16x16x32_bf16 v[16:19], v[156:159], v[218:221], v[16:19]
	v_mfma_f32_16x16x32_bf16 v[16:19], v[152:155], v[214:217], v[16:19]
	s_setprio 2
	s_barrier
	v_mfma_f32_16x16x32_bf16 v[0:3], v[152:155], v[222:225], v[0:3]
	v_mfma_f32_16x16x32_bf16 v[0:3], v[156:159], v[226:229], v[0:3]
	v_mfma_f32_16x16x32_bf16 v[4:7], v[148:151], v[226:229], v[4:7]
	v_mfma_f32_16x16x32_bf16 v[4:7], v[144:147], v[222:225], v[4:7]
	s_setprio 0
	s_add_i32 s44, 0, 0x18000
	s_add_i32 s45, 0, 0x1c000
	v_add_u32_e32 v96, s44, v167
	v_add_u32_e32 v156, s45, v167
	ds_read_b128 v[76:79], v96
	ds_read_b128 v[84:87], v96 offset:1024
	ds_read_b128 v[92:95], v96 offset:2048
	ds_read_b128 v[96:99], v96 offset:3072
	ds_read_b128 v[144:147], v156
	ds_read_b128 v[148:151], v156 offset:1024
	ds_read_b128 v[152:155], v156 offset:2048
	ds_read_b128 v[156:159], v156 offset:3072
	s_add_u32 s48, s48, 0x160000
	s_addc_u32 s49, s49, 0
	s_mov_b32 m0, s65
	v_lshl_add_u64 v[236:237], s[48:49], 0, v[160:161]
	ds_read_b128 v[178:181], v187 offset:32768
	ds_read_b128 v[182:185], v187 offset:33792
	ds_read_b128 v[206:209], v187 offset:34816
	ds_read_b128 v[210:213], v187 offset:35840
	ds_read_b128 v[214:217], v187 offset:36864
	ds_read_b128 v[218:221], v187 offset:37888
	ds_read_b128 v[222:225], v187 offset:38912
	ds_read_b128 v[226:229], v187 offset:39936
	global_load_lds_dwordx4 v[236:237], off
	v_lshl_add_u64 v[236:237], s[48:49], 0, v[162:163]
	s_mov_b32 m0, s66
	s_nop 0
	global_load_lds_dwordx4 v[236:237], off
	s_waitcnt vmcnt(8)
	s_waitcnt lgkmcnt(0)
	s_barrier
	s_setprio 1
	s_waitcnt lgkmcnt(0)
	v_mfma_f32_16x16x32_bf16 v[140:143], v[76:79], v[178:181], v[140:143]
	v_mfma_f32_16x16x32_bf16 v[140:143], v[84:87], v[182:185], v[140:143]
	v_mfma_f32_16x16x32_bf16 v[136:139], v[96:99], v[182:185], v[136:139]
	v_mfma_f32_16x16x32_bf16 v[136:139], v[92:95], v[178:181], v[136:139]
	v_mfma_f32_16x16x32_bf16 v[120:123], v[92:95], v[206:209], v[120:123]
	v_mfma_f32_16x16x32_bf16 v[120:123], v[96:99], v[210:213], v[120:123]
	v_mfma_f32_16x16x32_bf16 v[124:127], v[84:87], v[210:213], v[124:127]
	v_mfma_f32_16x16x32_bf16 v[124:127], v[76:79], v[206:209], v[124:127]
	v_mfma_f32_16x16x32_bf16 v[108:111], v[76:79], v[214:217], v[108:111]
	v_mfma_f32_16x16x32_bf16 v[108:111], v[84:87], v[218:221], v[108:111]
	v_mfma_f32_16x16x32_bf16 v[104:107], v[96:99], v[218:221], v[104:107]
	v_mfma_f32_16x16x32_bf16 v[104:107], v[92:95], v[214:217], v[104:107]
	v_mfma_f32_16x16x32_bf16 v[72:75], v[92:95], v[222:225], v[72:75]
	v_mfma_f32_16x16x32_bf16 v[72:75], v[96:99], v[226:229], v[72:75]
	v_mfma_f32_16x16x32_bf16 v[80:83], v[84:87], v[226:229], v[80:83]
	v_mfma_f32_16x16x32_bf16 v[80:83], v[76:79], v[222:225], v[80:83]
	s_setprio 0
	s_setprio 1
	v_mfma_f32_16x16x32_bf16 v[132:135], v[144:147], v[178:181], v[132:135]
	v_mfma_f32_16x16x32_bf16 v[132:135], v[148:151], v[182:185], v[132:135]
	v_mfma_f32_16x16x32_bf16 v[128:131], v[156:159], v[182:185], v[128:131]
	v_mfma_f32_16x16x32_bf16 v[128:131], v[152:155], v[178:181], v[128:131]
	v_mfma_f32_16x16x32_bf16 v[112:115], v[152:155], v[206:209], v[112:115]
	v_mfma_f32_16x16x32_bf16 v[112:115], v[156:159], v[210:213], v[112:115]
	v_mfma_f32_16x16x32_bf16 v[116:119], v[148:151], v[210:213], v[116:119]
	v_mfma_f32_16x16x32_bf16 v[116:119], v[144:147], v[206:209], v[116:119]
	v_mfma_f32_16x16x32_bf16 v[100:103], v[144:147], v[214:217], v[100:103]
	v_mfma_f32_16x16x32_bf16 v[100:103], v[148:151], v[218:221], v[100:103]
	v_mfma_f32_16x16x32_bf16 v[88:91], v[156:159], v[218:221], v[88:91]
	v_mfma_f32_16x16x32_bf16 v[88:91], v[152:155], v[214:217], v[88:91]
	s_setprio 2
	s_barrier
; #define PG8_STAGE(bufoff, gbase, voff) do { _Pragma("unroll") for (int _i = 0; _i < 2; ++_i) \
;         __builtin_amdgcn_global_load_lds((const unsigned*)((const char*)(gbase) + (voff)[_i]), (PG8_LAS unsigned*)(lds + (bufoff) + ldsw + _i * 8192), 16, 0, 0); } while (0)
; #define PG8_LDA(dst, b, h) do { _Pragma("unroll") for (int m = 0; m < 4; ++m) _Pragma("unroll") for (int k = 0; k < 2; ++k) dst[m][k] = *(const PG8_LAS bf16x8*)(lds + PG8_SA(b, h) + aoff + m * 2048 + k * 1024); } while (0)
; #define PG8_LDB(dst, b, h) do { _Pragma("unroll") for (int n = 0; n < 2; ++n) _Pragma("unroll") for (int k = 0; k < 2; ++k) dst[n][k] = *(const PG8_LAS bf16x8*)(lds + PG8_SB(b, h) + boff + n * 2048 + k * 1024); } while (0)
; template <class Epi, class Sched, bool ALIGN_EPI = false, bool SP2 = false>
; __device__ __forceinline__ void gemm_phase(PG8_LAS unsigned char* lds, const Gemm g, const Sched& S, const Epi& E) {
;     ...
;         for (int t = 0; t < nt; t += 2) {
;             const bool last = (t == nt - 2);
;             const char* a1 = cA + (size_t)(t + 1) * kstep;
;             const char* a2 = last ? nA : cA + (size_t)(t + 2) * kstep; const char* b2 = last ? nB : cB + (size_t)(t + 2) * kstep;
;             const char* a3 = a2 + kstep; const char* b3 = b2 + kstep;
;             if (last && has_next) S.a_ready(nxt);
;             if constexpr (SP2) {
;             PG8_LDB(B0, 0, 0); PG8_LDB(B1, 0, 1); PG8_SCHED; PG8_LDA(At, 0, 0); PG8_STAGE(PG8_SA(1, 1), a1 + hstep, voffA);
;             PG8_WAIT_V(8); PG8_WAIT_L(0); PG8_BAR; PG8_MMA(0, 0, At, B0); PG8_MMA(0, 1, At, B1); PG8_BAR; PG8_SCHED;
;             PG8_LDA(At, 0, 1); PG8_STAGE(PG8_SB(0, 0), b2, voffB); PG8_STAGE(PG8_SB(0, 1), b2 + hstep, voffB); PG8_STAGE(PG8_SA(0, 0), a2, voffA);
;             PG8_WAIT_V(8); PG8_WAIT_L(0); PG8_BAR; PG8_MMA(1, 0, At, B0); PG8_MMA(1, 1, At, B1); PG8_BAR; PG8_SCHED;
;             PG8_LDB(B0, 1, 0); PG8_LDB(B1, 1, 1); PG8_SCHED; PG8_LDA(At, 1, 0); PG8_STAGE(PG8_SA(0, 1), a2 + hstep, voffA);
;             PG8_WAIT_V(8); PG8_WAIT_L(0); PG8_BAR; PG8_MMA(0, 0, At, B0); PG8_MMA(0, 1, At, B1); PG8_BAR; PG8_SCHED;
;             PG8_LDA(At, 1, 1); PG8_STAGE(PG8_SB(1, 0), b3, voffB); PG8_STAGE(PG8_SB(1, 1), b3 + hstep, voffB); PG8_STAGE(PG8_SA(1, 0), a3, voffA);
;             PG8_WAIT_V(8); PG8_WAIT_L(0); PG8_BAR; PG8_MMA(1, 0, At, B0); PG8_MMA(1, 1, At, B1); PG8_BAR; PG8_SCHED;
	v_mfma_f32_16x16x32_bf16 v[64:67], v[152:155], v[222:225], v[64:67]
	v_mfma_f32_16x16x32_bf16 v[64:67], v[156:159], v[226:229], v[64:67]
	v_mfma_f32_16x16x32_bf16 v[68:71], v[148:151], v[226:229], v[68:71]
	v_mfma_f32_16x16x32_bf16 v[68:71], v[144:147], v[222:225], v[68:71]
	s_setprio 0
	s_add_i32 s44, s44, s57
	v_lshl_add_u64 v[200:201], v[200:201], 0, s[20:21]
	s_mov_b32 m0, s44
	ds_read_b128 v[178:181], v187 offset:49152
	ds_read_b128 v[182:185], v187 offset:50176
	ds_read_b128 v[206:209], v187 offset:51200
	ds_read_b128 v[210:213], v187 offset:52224
	ds_read_b128 v[214:217], v187 offset:53248
	ds_read_b128 v[218:221], v187 offset:54272
	ds_read_b128 v[222:225], v187 offset:55296
	ds_read_b128 v[226:229], v187 offset:56320
	global_load_lds_dwordx4 v[200:201], off
	s_add_i32 m0, s44, 0x2000
	s_add_u32 s28, s28, 0x160080
	v_lshl_add_u64 v[200:201], v[230:231], 0, s[20:21]
	s_addc_u32 s29, s29, 0
	s_add_i32 s44, s45, s57
	global_load_lds_dwordx4 v[200:201], off
	v_lshl_add_u64 v[200:201], s[28:29], 0, v[160:161]
	s_mov_b32 m0, s44
	s_nop 0
	global_load_lds_dwordx4 v[200:201], off
	v_lshl_add_u64 v[200:201], s[28:29], 0, v[162:163]
	s_add_i32 m0, s44, 0x2000
	s_nop 0
	global_load_lds_dwordx4 v[200:201], off
	v_lshl_add_u64 v[200:201], v[232:233], 0, s[20:21]
	s_mov_b32 m0, s67
	s_nop 0
	global_load_lds_dwordx4 v[200:201], off
	v_lshl_add_u64 v[200:201], v[234:235], 0, s[20:21]
	s_mov_b32 m0, s68
	s_nop 0
	global_load_lds_dwordx4 v[200:201], off
	s_waitcnt vmcnt(8)
	s_waitcnt lgkmcnt(0)
	s_barrier
	s_setprio 1
	s_waitcnt lgkmcnt(0)
	v_mfma_f32_16x16x32_bf16 v[60:63], v[76:79], v[178:181], v[60:63]
	v_mfma_f32_16x16x32_bf16 v[60:63], v[84:87], v[182:185], v[60:63]
	v_mfma_f32_16x16x32_bf16 v[56:59], v[96:99], v[182:185], v[56:59]
	v_mfma_f32_16x16x32_bf16 v[56:59], v[92:95], v[178:181], v[56:59]
	v_mfma_f32_16x16x32_bf16 v[40:43], v[92:95], v[206:209], v[40:43]
	v_mfma_f32_16x16x32_bf16 v[40:43], v[96:99], v[210:213], v[40:43]
	v_mfma_f32_16x16x32_bf16 v[44:47], v[84:87], v[210:213], v[44:47]
	v_mfma_f32_16x16x32_bf16 v[44:47], v[76:79], v[206:209], v[44:47]
	v_mfma_f32_16x16x32_bf16 v[28:31], v[76:79], v[214:217], v[28:31]
	v_mfma_f32_16x16x32_bf16 v[28:31], v[84:87], v[218:221], v[28:31]
	v_mfma_f32_16x16x32_bf16 v[24:27], v[96:99], v[218:221], v[24:27]
	v_mfma_f32_16x16x32_bf16 v[24:27], v[92:95], v[214:217], v[24:27]
	v_mfma_f32_16x16x32_bf16 v[8:11], v[92:95], v[222:225], v[8:11]
	v_mfma_f32_16x16x32_bf16 v[8:11], v[96:99], v[226:229], v[8:11]
	v_mfma_f32_16x16x32_bf16 v[12:15], v[84:87], v[226:229], v[12:15]
	v_mfma_f32_16x16x32_bf16 v[12:15], v[76:79], v[222:225], v[12:15]
	s_setprio 0
	s_setprio 1
	v_mfma_f32_16x16x32_bf16 v[52:55], v[144:147], v[178:181], v[52:55]
	v_mfma_f32_16x16x32_bf16 v[52:55], v[148:151], v[182:185], v[52:55]
	v_mfma_f32_16x16x32_bf16 v[48:51], v[156:159], v[182:185], v[48:51]
	v_mfma_f32_16x16x32_bf16 v[48:51], v[152:155], v[178:181], v[48:51]
	v_mfma_f32_16x16x32_bf16 v[32:35], v[152:155], v[206:209], v[32:35]
	v_mfma_f32_16x16x32_bf16 v[32:35], v[156:159], v[210:213], v[32:35]
	v_mfma_f32_16x16x32_bf16 v[36:39], v[148:151], v[210:213], v[36:39]
	v_mfma_f32_16x16x32_bf16 v[36:39], v[144:147], v[206:209], v[36:39]
	v_mfma_f32_16x16x32_bf16 v[20:23], v[144:147], v[214:217], v[20:23]
	v_mfma_f32_16x16x32_bf16 v[20:23], v[148:151], v[218:221], v[20:23]
	v_mfma_f32_16x16x32_bf16 v[16:19], v[156:159], v[218:221], v[16:19]
	v_mfma_f32_16x16x32_bf16 v[16:19], v[152:155], v[214:217], v[16:19]
	s_setprio 2
	s_barrier
	v_mfma_f32_16x16x32_bf16 v[0:3], v[152:155], v[222:225], v[0:3]
	v_mfma_f32_16x16x32_bf16 v[0:3], v[156:159], v[226:229], v[0:3]
	v_mfma_f32_16x16x32_bf16 v[4:7], v[148:151], v[226:229], v[4:7]
	v_mfma_f32_16x16x32_bf16 v[4:7], v[144:147], v[222:225], v[4:7]
	s_setprio 0
	s_add_i32 s77, s77, 2
	s_add_u32 s62, s62, 0x100
	s_addc_u32 s63, s63, 0
	s_add_u32 s34, s34, 0x100
	s_addc_u32 s35, s35, 0
	s_cmpk_gt_u32 s77, 0x55
	s_cbranch_scc0 .LBB0_602
	s_and_b64 vcc, exec, s[22:23]
	s_cbranch_vccz .LBB0_605
	s_barrier

; #define PG8_STAGE(bufoff, gbase, voff) do { _Pragma("unroll") for (int _i = 0; _i < 2; ++_i) \
;         __builtin_amdgcn_global_load_lds((const unsigned*)((const char*)(gbase) + (voff)[_i]), (PG8_LAS unsigned*)(lds + (bufoff) + ldsw + _i * 8192), 16, 0, 0); } while (0)
; #define PG8_LDA(dst, b, h) do { _Pragma("unroll") for (int m = 0; m < 4; ++m) _Pragma("unroll") for (int k = 0; k < 2; ++k) dst[m][k] = *(const PG8_LAS bf16x8*)(lds + PG8_SA(b, h) + aoff + m * 2048 + k * 1024); } while (0)
; #define PG8_LDB(dst, b, h) do { _Pragma("unroll") for (int n = 0; n < 2; ++n) _Pragma("unroll") for (int k = 0; k < 2; ++k) dst[n][k] = *(const PG8_LAS bf16x8*)(lds + PG8_SB(b, h) + boff + n * 2048 + k * 1024); } while (0)
; #define PG8_BAR __builtin_amdgcn_s_barrier()
; template <class Epi, class Sched, bool ALIGN_EPI = false, bool SP2 = false>
; __device__ __forceinline__ void gemm_phase(PG8_LAS unsigned char* lds, const Gemm g, const Sched& S, const Epi& E) {
;     ...
;             const bool last = (t == nt - 2);
;             const char* a1 = cA + (size_t)(t + 1) * kstep;
;             const char* a2 = last ? nA : cA + (size_t)(t + 2) * kstep; const char* b2 = last ? nB : cB + (size_t)(t + 2) * kstep;
;             const char* a3 = a2 + kstep; const char* b3 = b2 + kstep;
;             if (last && has_next) S.a_ready(nxt);
;             if constexpr (SP2) {
;             PG8_LDB(B0, 0, 0); PG8_LDB(B1, 0, 1); PG8_SCHED; PG8_LDA(At, 0, 0); PG8_STAGE(PG8_SA(1, 1), a1 + hstep, voffA);
;             PG8_WAIT_V(8); PG8_WAIT_L(0); PG8_BAR; PG8_MMA(0, 0, At, B0); PG8_MMA(0, 1, At, B1); PG8_BAR; PG8_SCHED;
;             PG8_LDA(At, 0, 1); PG8_STAGE(PG8_SB(0, 0), b2, voffB); PG8_STAGE(PG8_SB(0, 1), b2 + hstep, voffB); PG8_STAGE(PG8_SA(0, 0), a2, voffA);
;             PG8_WAIT_V(8); PG8_WAIT_L(0); PG8_BAR; PG8_MMA(1, 0, At, B0); PG8_MMA(1, 1, At, B1); PG8_BAR; PG8_SCHED;
;             PG8_LDB(B0, 1, 0); PG8_LDB(B1, 1, 1); PG8_SCHED; PG8_LDA(At, 1, 0); PG8_STAGE(PG8_SA(0, 1), a2 + hstep, voffA);
;             PG8_WAIT_V(8); PG8_WAIT_L(0); PG8_BAR; PG8_MMA(0, 0, At, B0); PG8_MMA(0, 1, At, B1); PG8_BAR; PG8_SCHED;
;             PG8_LDA(At, 1, 1); PG8_STAGE(PG8_SB(1, 0), b3, voffB); PG8_STAGE(PG8_SB(1, 1), b3 + hstep, voffB); PG8_STAGE(PG8_SA(1, 0), a3, voffA);
;             PG8_WAIT_V(8); PG8_WAIT_L(0); PG8_BAR; PG8_MMA(1, 0, At, B0); PG8_MMA(1, 1, At, B1); PG8_BAR; PG8_SCHED;
.LBB0_719:
	ds_read_b128 v[88:91], v208
	ds_read_b128 v[96:99], v208 offset:1024
	ds_read_b128 v[136:139], v208 offset:2048
	ds_read_b128 v[140:143], v208 offset:3072
	ds_read_b128 v[144:147], v209
	ds_read_b128 v[148:151], v209 offset:1024
	ds_read_b128 v[152:155], v209 offset:2048
	ds_read_b128 v[156:159], v209 offset:3072
	s_add_u32 s44, s62, 0xfff80080
	s_addc_u32 s45, s63, -1
	s_cmp_eq_u32 s76, 28
	s_cselect_b32 s59, s29, s45
	s_cselect_b32 s58, s34, s44
	s_cselect_b32 s57, s23, s75
	s_cselect_b32 s56, s35, s74
	v_lshl_add_u64 v[200:201], s[62:63], 0, v[172:173]
	s_add_i32 m0, s49, 0xc000
	ds_read_b128 v[178:181], v210
	ds_read_b128 v[182:185], v210 offset:1024
	ds_read_b128 v[186:189], v210 offset:2048
	ds_read_b128 v[212:215], v210 offset:3072
	ds_read_b128 v[216:219], v210 offset:4096
	ds_read_b128 v[220:223], v210 offset:5120
	ds_read_b128 v[224:227], v210 offset:6144
	ds_read_b128 v[228:231], v210 offset:7168
	global_load_lds_dwordx4 v[200:201], off
	v_lshl_add_u64 v[200:201], s[62:63], 0, v[174:175]
	s_add_i32 m0, s49, 0xe000
	s_nop 0
	global_load_lds_dwordx4 v[200:201], off
	s_waitcnt vmcnt(8)
	s_waitcnt lgkmcnt(0)
	s_barrier
	s_setprio 1
	s_waitcnt lgkmcnt(0)
	v_mfma_f32_16x16x32_bf16 v[128:131], v[88:91], v[178:181], v[128:131]
	v_mfma_f32_16x16x32_bf16 v[128:131], v[96:99], v[182:185], v[128:131]
	v_mfma_f32_16x16x32_bf16 v[120:123], v[140:143], v[182:185], v[120:123]
	v_mfma_f32_16x16x32_bf16 v[120:123], v[136:139], v[178:181], v[120:123]
	v_mfma_f32_16x16x32_bf16 v[108:111], v[136:139], v[186:189], v[108:111]
	v_mfma_f32_16x16x32_bf16 v[108:111], v[140:143], v[212:215], v[108:111]
	v_mfma_f32_16x16x32_bf16 v[116:119], v[96:99], v[212:215], v[116:119]
	v_mfma_f32_16x16x32_bf16 v[116:119], v[88:91], v[186:189], v[116:119]
	v_mfma_f32_16x16x32_bf16 v[100:103], v[88:91], v[216:219], v[100:103]
	v_mfma_f32_16x16x32_bf16 v[100:103], v[96:99], v[220:223], v[100:103]
	v_mfma_f32_16x16x32_bf16 v[84:87], v[140:143], v[220:223], v[84:87]
	v_mfma_f32_16x16x32_bf16 v[84:87], v[136:139], v[216:219], v[84:87]
	v_mfma_f32_16x16x32_bf16 v[68:71], v[136:139], v[224:227], v[68:71]
	v_mfma_f32_16x16x32_bf16 v[68:71], v[140:143], v[228:231], v[68:71]
	v_mfma_f32_16x16x32_bf16 v[76:79], v[96:99], v[228:231], v[76:79]
	v_mfma_f32_16x16x32_bf16 v[76:79], v[88:91], v[224:227], v[76:79]
	s_setprio 0
	s_setprio 1
	v_mfma_f32_16x16x32_bf16 v[132:135], v[144:147], v[178:181], v[132:135]
	v_mfma_f32_16x16x32_bf16 v[132:135], v[148:151], v[182:185], v[132:135]
	v_mfma_f32_16x16x32_bf16 v[124:127], v[156:159], v[182:185], v[124:127]
	v_mfma_f32_16x16x32_bf16 v[124:127], v[152:155], v[178:181], v[124:127]
	v_mfma_f32_16x16x32_bf16 v[104:107], v[152:155], v[186:189], v[104:107]
	v_mfma_f32_16x16x32_bf16 v[104:107], v[156:159], v[212:215], v[104:107]
	v_mfma_f32_16x16x32_bf16 v[112:115], v[148:151], v[212:215], v[112:115]
	v_mfma_f32_16x16x32_bf16 v[112:115], v[144:147], v[186:189], v[112:115]
	v_mfma_f32_16x16x32_bf16 v[92:95], v[144:147], v[216:219], v[92:95]
	v_mfma_f32_16x16x32_bf16 v[92:95], v[148:151], v[220:223], v[92:95]
	v_mfma_f32_16x16x32_bf16 v[80:83], v[156:159], v[220:223], v[80:83]
	v_mfma_f32_16x16x32_bf16 v[80:83], v[152:155], v[216:219], v[80:83]
	s_setprio 2
	s_barrier
	v_mfma_f32_16x16x32_bf16 v[64:67], v[152:155], v[224:227], v[64:67]
	v_mfma_f32_16x16x32_bf16 v[64:67], v[156:159], v[228:231], v[64:67]
	v_mfma_f32_16x16x32_bf16 v[72:75], v[148:151], v[228:231], v[72:75]
	v_mfma_f32_16x16x32_bf16 v[72:75], v[144:147], v[224:227], v[72:75]
	s_setprio 0
	s_add_i32 s44, s71, s65
	v_lshl_add_u64 v[200:201], s[56:57], 0, v[164:165]
	s_mov_b32 m0, s44
	ds_read_b128 v[178:181], v210 offset:16384
	ds_read_b128 v[182:185], v210 offset:17408
	ds_read_b128 v[186:189], v210 offset:18432
	ds_read_b128 v[212:215], v210 offset:19456
	ds_read_b128 v[216:219], v210 offset:20480
	ds_read_b128 v[220:223], v210 offset:21504
	ds_read_b128 v[224:227], v210 offset:22528
	ds_read_b128 v[228:231], v210 offset:23552
	global_load_lds_dwordx4 v[200:201], off
	s_add_i32 m0, s44, 0x2000
	s_add_u32 s78, s56, 0x80000
	v_lshl_add_u64 v[232:233], s[56:57], 0, v[168:169]
	s_addc_u32 s79, s57, 0
	s_add_i32 s44, s72, s65
	global_load_lds_dwordx4 v[232:233], off
	v_lshl_add_u64 v[234:235], s[78:79], 0, v[164:165]
	s_mov_b32 m0, s44
	v_lshl_add_u64 v[236:237], s[58:59], 0, v[168:169]
	global_load_lds_dwordx4 v[234:235], off
	v_lshl_add_u64 v[234:235], s[78:79], 0, v[168:169]
	s_add_i32 m0, s44, 0x2000
	s_nop 0
	global_load_lds_dwordx4 v[234:235], off
	v_lshl_add_u64 v[234:235], s[58:59], 0, v[164:165]
	s_mov_b32 m0, s49
	s_nop 0
	global_load_lds_dwordx4 v[234:235], off
	s_mov_b32 m0, s61
	s_nop 0
	global_load_lds_dwordx4 v[236:237], off
	s_waitcnt vmcnt(8)
	s_waitcnt lgkmcnt(0)
	s_barrier
; #define PG8_STAGE(bufoff, gbase, voff) do { _Pragma("unroll") for (int _i = 0; _i < 2; ++_i) \
;         __builtin_amdgcn_global_load_lds((const unsigned*)((const char*)(gbase) + (voff)[_i]), (PG8_LAS unsigned*)(lds + (bufoff) + ldsw + _i * 8192), 16, 0, 0); } while (0)
; #define PG8_LDA(dst, b, h) do { _Pragma("unroll") for (int m = 0; m < 4; ++m) _Pragma("unroll") for (int k = 0; k < 2; ++k) dst[m][k] = *(const PG8_LAS bf16x8*)(lds + PG8_SA(b, h) + aoff + m * 2048 + k * 1024); } while (0)
; #define PG8_LDB(dst, b, h) do { _Pragma("unroll") for (int n = 0; n < 2; ++n) _Pragma("unroll") for (int k = 0; k < 2; ++k) dst[n][k] = *(const PG8_LAS bf16x8*)(lds + PG8_SB(b, h) + boff + n * 2048 + k * 1024); } while (0)
; #define PG8_MMA(ai, bj, At, Bt) do { __builtin_amdgcn_s_setprio(1); _Pragma("unroll") for (int m = 0; m < 4; ++m) _Pragma("unroll") for (int n = 0; n < 2; ++n) _Pragma("unroll") for (int k = 0; k < 2; ++k) \
;         acc[ai][bj][m][n] = __builtin_amdgcn_mfma_f32_16x16x32_bf16(Bt[n][k], At[m][k], acc[ai][bj][m][n], 0, 0, 0); __builtin_amdgcn_s_setprio(0); } while (0)
; #define PG8_WAIT_V(n) asm volatile("s_waitcnt vmcnt(" #n ")" ::: "memory")
; template <class Epi, class Sched, bool ALIGN_EPI = false, bool SP2 = false>
; __device__ __forceinline__ void gemm_phase(PG8_LAS unsigned char* lds, const Gemm g, const Sched& S, const Epi& E) {
;     ...
;             PG8_LDB(B0, 0, 0); PG8_LDB(B1, 0, 1); PG8_SCHED; PG8_LDA(At, 0, 0); PG8_STAGE(PG8_SA(1, 1), a1 + hstep, voffA);
;             PG8_WAIT_V(8); PG8_WAIT_L(0); PG8_BAR; PG8_MMA(0, 0, At, B0); PG8_MMA(0, 1, At, B1); PG8_BAR; PG8_SCHED;
;             PG8_LDA(At, 0, 1); PG8_STAGE(PG8_SB(0, 0), b2, voffB); PG8_STAGE(PG8_SB(0, 1), b2 + hstep, voffB); PG8_STAGE(PG8_SA(0, 0), a2, voffA);
;             PG8_WAIT_V(8); PG8_WAIT_L(0); PG8_BAR; PG8_MMA(1, 0, At, B0); PG8_MMA(1, 1, At, B1); PG8_BAR; PG8_SCHED;
;             PG8_LDB(B0, 1, 0); PG8_LDB(B1, 1, 1); PG8_SCHED; PG8_LDA(At, 1, 0); PG8_STAGE(PG8_SA(0, 1), a2 + hstep, voffA);
;             PG8_WAIT_V(8); PG8_WAIT_L(0); PG8_BAR; PG8_MMA(0, 0, At, B0); PG8_MMA(0, 1, At, B1); PG8_BAR; PG8_SCHED;
;             PG8_LDA(At, 1, 1); PG8_STAGE(PG8_SB(1, 0), b3, voffB); PG8_STAGE(PG8_SB(1, 1), b3 + hstep, voffB); PG8_STAGE(PG8_SA(1, 0), a3, voffA);
;             PG8_WAIT_V(8); PG8_WAIT_L(0); PG8_BAR; PG8_MMA(1, 0, At, B0); PG8_MMA(1, 1, At, B1); PG8_BAR; PG8_SCHED;
	s_setprio 1
	s_waitcnt lgkmcnt(0)
	v_mfma_f32_16x16x32_bf16 v[56:59], v[88:91], v[178:181], v[56:59]
	v_mfma_f32_16x16x32_bf16 v[56:59], v[96:99], v[182:185], v[56:59]
	v_mfma_f32_16x16x32_bf16 v[48:51], v[140:143], v[182:185], v[48:51]
	v_mfma_f32_16x16x32_bf16 v[48:51], v[136:139], v[178:181], v[48:51]
	v_mfma_f32_16x16x32_bf16 v[36:39], v[136:139], v[186:189], v[36:39]
	v_mfma_f32_16x16x32_bf16 v[36:39], v[140:143], v[212:215], v[36:39]
	v_mfma_f32_16x16x32_bf16 v[44:47], v[96:99], v[212:215], v[44:47]
	v_mfma_f32_16x16x32_bf16 v[44:47], v[88:91], v[186:189], v[44:47]
	v_mfma_f32_16x16x32_bf16 v[28:31], v[88:91], v[216:219], v[28:31]
	v_mfma_f32_16x16x32_bf16 v[28:31], v[96:99], v[220:223], v[28:31]
	v_mfma_f32_16x16x32_bf16 v[20:23], v[140:143], v[220:223], v[20:23]
	v_mfma_f32_16x16x32_bf16 v[20:23], v[136:139], v[216:219], v[20:23]
	v_mfma_f32_16x16x32_bf16 v[4:7], v[136:139], v[224:227], v[4:7]
	v_mfma_f32_16x16x32_bf16 v[4:7], v[140:143], v[228:231], v[4:7]
	v_mfma_f32_16x16x32_bf16 v[12:15], v[96:99], v[228:231], v[12:15]
	v_mfma_f32_16x16x32_bf16 v[12:15], v[88:91], v[224:227], v[12:15]
	s_setprio 0
	s_setprio 1
	v_mfma_f32_16x16x32_bf16 v[60:63], v[144:147], v[178:181], v[60:63]
	v_mfma_f32_16x16x32_bf16 v[60:63], v[148:151], v[182:185], v[60:63]
	v_mfma_f32_16x16x32_bf16 v[52:55], v[156:159], v[182:185], v[52:55]
	v_mfma_f32_16x16x32_bf16 v[52:55], v[152:155], v[178:181], v[52:55]
	v_mfma_f32_16x16x32_bf16 v[32:35], v[152:155], v[186:189], v[32:35]
	v_mfma_f32_16x16x32_bf16 v[32:35], v[156:159], v[212:215], v[32:35]
	v_mfma_f32_16x16x32_bf16 v[40:43], v[148:151], v[212:215], v[40:43]
	v_mfma_f32_16x16x32_bf16 v[40:43], v[144:147], v[186:189], v[40:43]
	v_mfma_f32_16x16x32_bf16 v[24:27], v[144:147], v[216:219], v[24:27]
	v_mfma_f32_16x16x32_bf16 v[24:27], v[148:151], v[220:223], v[24:27]
	v_mfma_f32_16x16x32_bf16 v[16:19], v[156:159], v[220:223], v[16:19]
	v_mfma_f32_16x16x32_bf16 v[16:19], v[152:155], v[216:219], v[16:19]
	s_setprio 2
	s_barrier
	v_mfma_f32_16x16x32_bf16 v[0:3], v[152:155], v[224:227], v[0:3]
	v_mfma_f32_16x16x32_bf16 v[0:3], v[156:159], v[228:231], v[0:3]
	v_mfma_f32_16x16x32_bf16 v[8:11], v[148:151], v[228:231], v[8:11]
	v_mfma_f32_16x16x32_bf16 v[8:11], v[144:147], v[224:227], v[8:11]
	s_setprio 0
	s_add_i32 s44, 0, 0x18000
	s_add_i32 s45, 0, 0x1c000
	v_add_u32_e32 v140, s44, v163
	v_add_u32_e32 v156, s45, v163
	ds_read_b128 v[88:91], v140
	ds_read_b128 v[96:99], v140 offset:1024
	ds_read_b128 v[136:139], v140 offset:2048
	ds_read_b128 v[140:143], v140 offset:3072
	ds_read_b128 v[144:147], v156
	ds_read_b128 v[148:151], v156 offset:1024
	ds_read_b128 v[152:155], v156 offset:2048
	ds_read_b128 v[156:159], v156 offset:3072
	s_add_u32 s58, s58, 0x80000
	s_addc_u32 s59, s59, 0
	s_mov_b32 m0, s66
	v_lshl_add_u64 v[238:239], s[58:59], 0, v[164:165]
	ds_read_b128 v[178:181], v210 offset:32768
	ds_read_b128 v[182:185], v210 offset:33792
	ds_read_b128 v[186:189], v210 offset:34816
	ds_read_b128 v[212:215], v210 offset:35840
	ds_read_b128 v[216:219], v210 offset:36864
	ds_read_b128 v[220:223], v210 offset:37888
	ds_read_b128 v[224:227], v210 offset:38912
	ds_read_b128 v[228:231], v210 offset:39936
	global_load_lds_dwordx4 v[238:239], off
	v_lshl_add_u64 v[238:239], s[58:59], 0, v[168:169]
	s_mov_b32 m0, s67
	s_nop 0
	global_load_lds_dwordx4 v[238:239], off
	s_waitcnt vmcnt(8)
	s_waitcnt lgkmcnt(0)
	s_barrier
	s_setprio 1
	s_waitcnt lgkmcnt(0)
	v_mfma_f32_16x16x32_bf16 v[128:131], v[88:91], v[178:181], v[128:131]
	v_mfma_f32_16x16x32_bf16 v[128:131], v[96:99], v[182:185], v[128:131]
	v_mfma_f32_16x16x32_bf16 v[120:123], v[140:143], v[182:185], v[120:123]
	v_mfma_f32_16x16x32_bf16 v[120:123], v[136:139], v[178:181], v[120:123]
	v_mfma_f32_16x16x32_bf16 v[108:111], v[136:139], v[186:189], v[108:111]
	v_mfma_f32_16x16x32_bf16 v[108:111], v[140:143], v[212:215], v[108:111]
	v_mfma_f32_16x16x32_bf16 v[116:119], v[96:99], v[212:215], v[116:119]
	v_mfma_f32_16x16x32_bf16 v[116:119], v[88:91], v[186:189], v[116:119]
	v_mfma_f32_16x16x32_bf16 v[100:103], v[88:91], v[216:219], v[100:103]
	v_mfma_f32_16x16x32_bf16 v[100:103], v[96:99], v[220:223], v[100:103]
	v_mfma_f32_16x16x32_bf16 v[84:87], v[140:143], v[220:223], v[84:87]
	v_mfma_f32_16x16x32_bf16 v[84:87], v[136:139], v[216:219], v[84:87]
	v_mfma_f32_16x16x32_bf16 v[68:71], v[136:139], v[224:227], v[68:71]
	v_mfma_f32_16x16x32_bf16 v[68:71], v[140:143], v[228:231], v[68:71]
	v_mfma_f32_16x16x32_bf16 v[76:79], v[96:99], v[228:231], v[76:79]
	v_mfma_f32_16x16x32_bf16 v[76:79], v[88:91], v[224:227], v[76:79]
	s_setprio 0
	s_setprio 1
	v_mfma_f32_16x16x32_bf16 v[132:135], v[144:147], v[178:181], v[132:135]
	v_mfma_f32_16x16x32_bf16 v[132:135], v[148:151], v[182:185], v[132:135]
	v_mfma_f32_16x16x32_bf16 v[124:127], v[156:159], v[182:185], v[124:127]
	v_mfma_f32_16x16x32_bf16 v[124:127], v[152:155], v[178:181], v[124:127]
	v_mfma_f32_16x16x32_bf16 v[104:107], v[152:155], v[186:189], v[104:107]
	v_mfma_f32_16x16x32_bf16 v[104:107], v[156:159], v[212:215], v[104:107]
	v_mfma_f32_16x16x32_bf16 v[112:115], v[148:151], v[212:215], v[112:115]
	v_mfma_f32_16x16x32_bf16 v[112:115], v[144:147], v[186:189], v[112:115]
	v_mfma_f32_16x16x32_bf16 v[92:95], v[144:147], v[216:219], v[92:95]
	v_mfma_f32_16x16x32_bf16 v[92:95], v[148:151], v[220:223], v[92:95]
	v_mfma_f32_16x16x32_bf16 v[80:83], v[156:159], v[220:223], v[80:83]
	v_mfma_f32_16x16x32_bf16 v[80:83], v[152:155], v[216:219], v[80:83]
	s_setprio 2
	s_barrier
; #define PG8_STAGE(bufoff, gbase, voff) do { _Pragma("unroll") for (int _i = 0; _i < 2; ++_i) \
;         __builtin_amdgcn_global_load_lds((const unsigned*)((const char*)(gbase) + (voff)[_i]), (PG8_LAS unsigned*)(lds + (bufoff) + ldsw + _i * 8192), 16, 0, 0); } while (0)
; #define PG8_LDA(dst, b, h) do { _Pragma("unroll") for (int m = 0; m < 4; ++m) _Pragma("unroll") for (int k = 0; k < 2; ++k) dst[m][k] = *(const PG8_LAS bf16x8*)(lds + PG8_SA(b, h) + aoff + m * 2048 + k * 1024); } while (0)
; #define PG8_LDB(dst, b, h) do { _Pragma("unroll") for (int n = 0; n < 2; ++n) _Pragma("unroll") for (int k = 0; k < 2; ++k) dst[n][k] = *(const PG8_LAS bf16x8*)(lds + PG8_SB(b, h) + boff + n * 2048 + k * 1024); } while (0)
; template <class Epi, class Sched, bool ALIGN_EPI = false, bool SP2 = false>
; __device__ __forceinline__ void gemm_phase(PG8_LAS unsigned char* lds, const Gemm g, const Sched& S, const Epi& E) {
;     ...
;         for (int t = 0; t < nt; t += 2) {
;             const bool last = (t == nt - 2);
;             const char* a1 = cA + (size_t)(t + 1) * kstep;
;             const char* a2 = last ? nA : cA + (size_t)(t + 2) * kstep; const char* b2 = last ? nB : cB + (size_t)(t + 2) * kstep;
;             const char* a3 = a2 + kstep; const char* b3 = b2 + kstep;
;             if (last && has_next) S.a_ready(nxt);
;             if constexpr (SP2) {
;             PG8_LDB(B0, 0, 0); PG8_LDB(B1, 0, 1); PG8_SCHED; PG8_LDA(At, 0, 0); PG8_STAGE(PG8_SA(1, 1), a1 + hstep, voffA);
;             PG8_WAIT_V(8); PG8_WAIT_L(0); PG8_BAR; PG8_MMA(0, 0, At, B0); PG8_MMA(0, 1, At, B1); PG8_BAR; PG8_SCHED;
;             PG8_LDA(At, 0, 1); PG8_STAGE(PG8_SB(0, 0), b2, voffB); PG8_STAGE(PG8_SB(0, 1), b2 + hstep, voffB); PG8_STAGE(PG8_SA(0, 0), a2, voffA);
;             PG8_WAIT_V(8); PG8_WAIT_L(0); PG8_BAR; PG8_MMA(1, 0, At, B0); PG8_MMA(1, 1, At, B1); PG8_BAR; PG8_SCHED;
;             PG8_LDB(B0, 1, 0); PG8_LDB(B1, 1, 1); PG8_SCHED; PG8_LDA(At, 1, 0); PG8_STAGE(PG8_SA(0, 1), a2 + hstep, voffA);
;             PG8_WAIT_V(8); PG8_WAIT_L(0); PG8_BAR; PG8_MMA(0, 0, At, B0); PG8_MMA(0, 1, At, B1); PG8_BAR; PG8_SCHED;
;             PG8_LDA(At, 1, 1); PG8_STAGE(PG8_SB(1, 0), b3, voffB); PG8_STAGE(PG8_SB(1, 1), b3 + hstep, voffB); PG8_STAGE(PG8_SA(1, 0), a3, voffA);
;             PG8_WAIT_V(8); PG8_WAIT_L(0); PG8_BAR; PG8_MMA(1, 0, At, B0); PG8_MMA(1, 1, At, B1); PG8_BAR; PG8_SCHED;
	v_mfma_f32_16x16x32_bf16 v[64:67], v[152:155], v[224:227], v[64:67]
	v_mfma_f32_16x16x32_bf16 v[64:67], v[156:159], v[228:231], v[64:67]
	v_mfma_f32_16x16x32_bf16 v[72:75], v[148:151], v[228:231], v[72:75]
	v_mfma_f32_16x16x32_bf16 v[72:75], v[144:147], v[224:227], v[72:75]
	s_setprio 0
	s_add_i32 s44, s44, s65
	v_lshl_add_u64 v[200:201], v[200:201], 0, s[18:19]
	s_mov_b32 m0, s44
	ds_read_b128 v[178:181], v210 offset:49152
	ds_read_b128 v[182:185], v210 offset:50176
	ds_read_b128 v[186:189], v210 offset:51200
	ds_read_b128 v[212:215], v210 offset:52224
	ds_read_b128 v[216:219], v210 offset:53248
	ds_read_b128 v[220:223], v210 offset:54272
	ds_read_b128 v[224:227], v210 offset:55296
	ds_read_b128 v[228:231], v210 offset:56320
	global_load_lds_dwordx4 v[200:201], off
	s_add_i32 m0, s44, 0x2000
	s_add_u32 s56, s56, 0x80080
	v_lshl_add_u64 v[200:201], v[232:233], 0, s[18:19]
	s_addc_u32 s57, s57, 0
	s_add_i32 s44, s45, s65
	global_load_lds_dwordx4 v[200:201], off
	v_lshl_add_u64 v[200:201], s[56:57], 0, v[164:165]
	s_mov_b32 m0, s44
	s_nop 0
	global_load_lds_dwordx4 v[200:201], off
	v_lshl_add_u64 v[200:201], s[56:57], 0, v[168:169]
	s_add_i32 m0, s44, 0x2000
	s_nop 0
	global_load_lds_dwordx4 v[200:201], off
	v_lshl_add_u64 v[200:201], v[234:235], 0, s[18:19]
	s_mov_b32 m0, s68
	s_nop 0
	global_load_lds_dwordx4 v[200:201], off
	v_lshl_add_u64 v[200:201], v[236:237], 0, s[18:19]
	s_mov_b32 m0, s69
	s_nop 0
	global_load_lds_dwordx4 v[200:201], off
	s_waitcnt vmcnt(8)
	s_waitcnt lgkmcnt(0)
	s_barrier
	s_setprio 1
	s_waitcnt lgkmcnt(0)
	v_mfma_f32_16x16x32_bf16 v[56:59], v[88:91], v[178:181], v[56:59]
	v_mfma_f32_16x16x32_bf16 v[56:59], v[96:99], v[182:185], v[56:59]
	v_mfma_f32_16x16x32_bf16 v[48:51], v[140:143], v[182:185], v[48:51]
	v_mfma_f32_16x16x32_bf16 v[48:51], v[136:139], v[178:181], v[48:51]
	v_mfma_f32_16x16x32_bf16 v[36:39], v[136:139], v[186:189], v[36:39]
	v_mfma_f32_16x16x32_bf16 v[36:39], v[140:143], v[212:215], v[36:39]
	v_mfma_f32_16x16x32_bf16 v[44:47], v[96:99], v[212:215], v[44:47]
	v_mfma_f32_16x16x32_bf16 v[44:47], v[88:91], v[186:189], v[44:47]
	v_mfma_f32_16x16x32_bf16 v[28:31], v[88:91], v[216:219], v[28:31]
	v_mfma_f32_16x16x32_bf16 v[28:31], v[96:99], v[220:223], v[28:31]
	v_mfma_f32_16x16x32_bf16 v[20:23], v[140:143], v[220:223], v[20:23]
	v_mfma_f32_16x16x32_bf16 v[20:23], v[136:139], v[216:219], v[20:23]
	v_mfma_f32_16x16x32_bf16 v[4:7], v[136:139], v[224:227], v[4:7]
	v_mfma_f32_16x16x32_bf16 v[4:7], v[140:143], v[228:231], v[4:7]
	v_mfma_f32_16x16x32_bf16 v[12:15], v[96:99], v[228:231], v[12:15]
	v_mfma_f32_16x16x32_bf16 v[12:15], v[88:91], v[224:227], v[12:15]
	s_setprio 0
	s_setprio 1
	v_mfma_f32_16x16x32_bf16 v[60:63], v[144:147], v[178:181], v[60:63]
	v_mfma_f32_16x16x32_bf16 v[60:63], v[148:151], v[182:185], v[60:63]
	v_mfma_f32_16x16x32_bf16 v[52:55], v[156:159], v[182:185], v[52:55]
	v_mfma_f32_16x16x32_bf16 v[52:55], v[152:155], v[178:181], v[52:55]
	v_mfma_f32_16x16x32_bf16 v[32:35], v[152:155], v[186:189], v[32:35]
	v_mfma_f32_16x16x32_bf16 v[32:35], v[156:159], v[212:215], v[32:35]
	v_mfma_f32_16x16x32_bf16 v[40:43], v[148:151], v[212:215], v[40:43]
	v_mfma_f32_16x16x32_bf16 v[40:43], v[144:147], v[186:189], v[40:43]
	v_mfma_f32_16x16x32_bf16 v[24:27], v[144:147], v[216:219], v[24:27]
	v_mfma_f32_16x16x32_bf16 v[24:27], v[148:151], v[220:223], v[24:27]
	v_mfma_f32_16x16x32_bf16 v[16:19], v[156:159], v[220:223], v[16:19]
	v_mfma_f32_16x16x32_bf16 v[16:19], v[152:155], v[216:219], v[16:19]
	s_setprio 2
	s_barrier
	v_mfma_f32_16x16x32_bf16 v[0:3], v[152:155], v[224:227], v[0:3]
	v_mfma_f32_16x16x32_bf16 v[0:3], v[156:159], v[228:231], v[0:3]
	v_mfma_f32_16x16x32_bf16 v[8:11], v[148:151], v[228:231], v[8:11]
	v_mfma_f32_16x16x32_bf16 v[8:11], v[144:147], v[224:227], v[8:11]
	s_setprio 0
	s_add_i32 s76, s76, 2
	s_add_u32 s62, s62, 0x100
	s_addc_u32 s63, s63, 0
	s_add_u32 s74, s74, 0x100
	s_addc_u32 s75, s75, 0
	s_cmp_gt_u32 s76, 29
	s_cbranch_scc0 .LBB0_719
	s_and_b64 vcc, exec, s[20:21]
	s_cbranch_vccz .LBB0_722
	s_barrier

; #define PG8_STAGE(bufoff, gbase, voff) do { _Pragma("unroll") for (int _i = 0; _i < 2; ++_i) \
;         __builtin_amdgcn_global_load_lds((const unsigned*)((const char*)(gbase) + (voff)[_i]), (PG8_LAS unsigned*)(lds + (bufoff) + ldsw + _i * 8192), 16, 0, 0); } while (0)
; #define PG8_LDA(dst, b, h) do { _Pragma("unroll") for (int m = 0; m < 4; ++m) _Pragma("unroll") for (int k = 0; k < 2; ++k) dst[m][k] = *(const PG8_LAS bf16x8*)(lds + PG8_SA(b, h) + aoff + m * 2048 + k * 1024); } while (0)
; #define PG8_LDB(dst, b, h) do { _Pragma("unroll") for (int n = 0; n < 2; ++n) _Pragma("unroll") for (int k = 0; k < 2; ++k) dst[n][k] = *(const PG8_LAS bf16x8*)(lds + PG8_SB(b, h) + boff + n * 2048 + k * 1024); } while (0)
; #define PG8_BAR __builtin_amdgcn_s_barrier()
; template <class Epi, class Sched, bool ALIGN_EPI = false, bool SP2 = false>
; __device__ __forceinline__ void gemm_phase(PG8_LAS unsigned char* lds, const Gemm g, const Sched& S, const Epi& E) {
;     ...
;             const bool last = (t == nt - 2);
;             const char* a1 = cA + (size_t)(t + 1) * kstep;
;             const char* a2 = last ? nA : cA + (size_t)(t + 2) * kstep; const char* b2 = last ? nB : cB + (size_t)(t + 2) * kstep;
;             const char* a3 = a2 + kstep; const char* b3 = b2 + kstep;
;             if (last && has_next) S.a_ready(nxt);
;             if constexpr (SP2) {
;             PG8_LDB(B0, 0, 0); PG8_LDB(B1, 0, 1); PG8_SCHED; PG8_LDA(At, 0, 0); PG8_STAGE(PG8_SA(1, 1), a1 + hstep, voffA);
;             PG8_WAIT_V(8); PG8_WAIT_L(0); PG8_BAR; PG8_MMA(0, 0, At, B0); PG8_MMA(0, 1, At, B1); PG8_BAR; PG8_SCHED;
;             PG8_LDA(At, 0, 1); PG8_STAGE(PG8_SB(0, 0), b2, voffB); PG8_STAGE(PG8_SB(0, 1), b2 + hstep, voffB); PG8_STAGE(PG8_SA(0, 0), a2, voffA);
;             PG8_WAIT_V(8); PG8_WAIT_L(0); PG8_BAR; PG8_MMA(1, 0, At, B0); PG8_MMA(1, 1, At, B1); PG8_BAR; PG8_SCHED;
;             PG8_LDB(B0, 1, 0); PG8_LDB(B1, 1, 1); PG8_SCHED; PG8_LDA(At, 1, 0); PG8_STAGE(PG8_SA(0, 1), a2 + hstep, voffA);
;             PG8_WAIT_V(8); PG8_WAIT_L(0); PG8_BAR; PG8_MMA(0, 0, At, B0); PG8_MMA(0, 1, At, B1); PG8_BAR; PG8_SCHED;
;             PG8_LDA(At, 1, 1); PG8_STAGE(PG8_SB(1, 0), b3, voffB); PG8_STAGE(PG8_SB(1, 1), b3 + hstep, voffB); PG8_STAGE(PG8_SA(1, 0), a3, voffA);
;             PG8_WAIT_V(8); PG8_WAIT_L(0); PG8_BAR; PG8_MMA(1, 0, At, B0); PG8_MMA(1, 1, At, B1); PG8_BAR; PG8_SCHED;
.LBB0_774:
	ds_read_b128 v[136:139], v156
	ds_read_b128 v[140:143], v156 offset:1024
	ds_read_b128 v[172:175], v156 offset:2048
	ds_read_b128 v[176:179], v156 offset:3072
	ds_read_b128 v[180:183], v157
	ds_read_b128 v[184:187], v157 offset:1024
	ds_read_b128 v[208:211], v157 offset:2048
	ds_read_b128 v[212:215], v157 offset:3072
	s_add_u32 s42, s40, 0xfff80080
	s_addc_u32 s43, s41, -1
	s_cmp_eq_u32 s71, 28
	s_cselect_b32 s49, s23, s43
	s_cselect_b32 s48, s34, s42
	s_cselect_b32 s43, s21, s70
	s_cselect_b32 s42, s35, s69
	v_lshl_add_u64 v[188:189], s[40:41], 0, v[128:129]
	s_add_i32 m0, s11, 0xc000
	ds_read_b128 v[216:219], v158
	ds_read_b128 v[220:223], v158 offset:1024
	ds_read_b128 v[224:227], v158 offset:2048
	ds_read_b128 v[228:231], v158 offset:3072
	ds_read_b128 v[232:235], v158 offset:4096
	ds_read_b128 v[236:239], v158 offset:5120
	ds_read_b128 v[240:243], v158 offset:6144
	ds_read_b128 v[244:247], v158 offset:7168
	global_load_lds_dwordx4 v[188:189], off
	v_lshl_add_u64 v[188:189], s[40:41], 0, v[130:131]
	s_add_i32 m0, s11, 0xe000
	s_nop 0
	global_load_lds_dwordx4 v[188:189], off
	s_waitcnt vmcnt(8)
	s_waitcnt lgkmcnt(0)
	s_barrier
	s_setprio 1
	s_waitcnt lgkmcnt(0)
	v_mfma_f32_16x16x32_bf16 v[124:127], v[136:139], v[216:219], v[124:127]
	v_mfma_f32_16x16x32_bf16 v[124:127], v[140:143], v[220:223], v[124:127]
	v_mfma_f32_16x16x32_bf16 v[120:123], v[176:179], v[220:223], v[120:123]
	v_mfma_f32_16x16x32_bf16 v[120:123], v[172:175], v[216:219], v[120:123]
	v_mfma_f32_16x16x32_bf16 v[104:107], v[172:175], v[224:227], v[104:107]
	v_mfma_f32_16x16x32_bf16 v[104:107], v[176:179], v[228:231], v[104:107]
	v_mfma_f32_16x16x32_bf16 v[108:111], v[140:143], v[228:231], v[108:111]
	v_mfma_f32_16x16x32_bf16 v[108:111], v[136:139], v[224:227], v[108:111]
	v_mfma_f32_16x16x32_bf16 v[96:99], v[136:139], v[232:235], v[96:99]
	v_mfma_f32_16x16x32_bf16 v[96:99], v[140:143], v[236:239], v[96:99]
	v_mfma_f32_16x16x32_bf16 v[88:91], v[176:179], v[236:239], v[88:91]
	v_mfma_f32_16x16x32_bf16 v[88:91], v[172:175], v[232:235], v[88:91]
	v_mfma_f32_16x16x32_bf16 v[72:75], v[172:175], v[240:243], v[72:75]
	v_mfma_f32_16x16x32_bf16 v[72:75], v[176:179], v[244:247], v[72:75]
	v_mfma_f32_16x16x32_bf16 v[80:83], v[140:143], v[244:247], v[80:83]
	v_mfma_f32_16x16x32_bf16 v[80:83], v[136:139], v[240:243], v[80:83]
	s_setprio 0
	s_setprio 1
	v_mfma_f32_16x16x32_bf16 v[116:119], v[180:183], v[216:219], v[116:119]
	v_mfma_f32_16x16x32_bf16 v[116:119], v[184:187], v[220:223], v[116:119]
	v_mfma_f32_16x16x32_bf16 v[112:115], v[212:215], v[220:223], v[112:115]
	v_mfma_f32_16x16x32_bf16 v[112:115], v[208:211], v[216:219], v[112:115]
	v_mfma_f32_16x16x32_bf16 v[92:95], v[208:211], v[224:227], v[92:95]
	v_mfma_f32_16x16x32_bf16 v[92:95], v[212:215], v[228:231], v[92:95]
	v_mfma_f32_16x16x32_bf16 v[100:103], v[184:187], v[228:231], v[100:103]
	v_mfma_f32_16x16x32_bf16 v[100:103], v[180:183], v[224:227], v[100:103]
	v_mfma_f32_16x16x32_bf16 v[84:87], v[180:183], v[232:235], v[84:87]
	v_mfma_f32_16x16x32_bf16 v[84:87], v[184:187], v[236:239], v[84:87]
	v_mfma_f32_16x16x32_bf16 v[76:79], v[212:215], v[236:239], v[76:79]
	v_mfma_f32_16x16x32_bf16 v[76:79], v[208:211], v[232:235], v[76:79]
	s_setprio 2
	s_barrier
	v_mfma_f32_16x16x32_bf16 v[64:67], v[208:211], v[240:243], v[64:67]
	v_mfma_f32_16x16x32_bf16 v[64:67], v[212:215], v[244:247], v[64:67]
	v_mfma_f32_16x16x32_bf16 v[68:71], v[184:187], v[244:247], v[68:71]
	v_mfma_f32_16x16x32_bf16 v[68:71], v[180:183], v[240:243], v[68:71]
	s_setprio 0
	s_add_i32 s44, s64, s52
	v_lshl_add_u64 v[188:189], s[42:43], 0, v[166:167]
	s_mov_b32 m0, s44
	ds_read_b128 v[216:219], v158 offset:16384
	ds_read_b128 v[220:223], v158 offset:17408
	ds_read_b128 v[224:227], v158 offset:18432
	ds_read_b128 v[228:231], v158 offset:19456
	ds_read_b128 v[232:235], v158 offset:20480
	ds_read_b128 v[236:239], v158 offset:21504
	ds_read_b128 v[240:243], v158 offset:22528
	ds_read_b128 v[244:247], v158 offset:23552
	global_load_lds_dwordx4 v[188:189], off
	s_add_i32 m0, s44, 0x2000
	s_add_u32 s72, s42, 0x80000
	v_lshl_add_u64 v[200:201], s[42:43], 0, v[170:171]
	s_addc_u32 s73, s43, 0
	s_add_i32 s44, s65, s52
	global_load_lds_dwordx4 v[200:201], off
	v_lshl_add_u64 v[248:249], s[72:73], 0, v[166:167]
	s_mov_b32 m0, s44
	v_lshl_add_u64 v[250:251], s[48:49], 0, v[168:169]
	global_load_lds_dwordx4 v[248:249], off
	v_lshl_add_u64 v[248:249], s[72:73], 0, v[170:171]
	s_add_i32 m0, s44, 0x2000
	s_nop 0
	global_load_lds_dwordx4 v[248:249], off
	v_lshl_add_u64 v[248:249], s[48:49], 0, v[164:165]
	s_mov_b32 m0, s11
	s_nop 0
	global_load_lds_dwordx4 v[248:249], off
	s_mov_b32 m0, s58
	s_nop 0
	global_load_lds_dwordx4 v[250:251], off
	s_waitcnt vmcnt(8)
	s_waitcnt lgkmcnt(0)
	s_barrier
; #define PG8_STAGE(bufoff, gbase, voff) do { _Pragma("unroll") for (int _i = 0; _i < 2; ++_i) \
;         __builtin_amdgcn_global_load_lds((const unsigned*)((const char*)(gbase) + (voff)[_i]), (PG8_LAS unsigned*)(lds + (bufoff) + ldsw + _i * 8192), 16, 0, 0); } while (0)
; #define PG8_LDA(dst, b, h) do { _Pragma("unroll") for (int m = 0; m < 4; ++m) _Pragma("unroll") for (int k = 0; k < 2; ++k) dst[m][k] = *(const PG8_LAS bf16x8*)(lds + PG8_SA(b, h) + aoff + m * 2048 + k * 1024); } while (0)
; #define PG8_LDB(dst, b, h) do { _Pragma("unroll") for (int n = 0; n < 2; ++n) _Pragma("unroll") for (int k = 0; k < 2; ++k) dst[n][k] = *(const PG8_LAS bf16x8*)(lds + PG8_SB(b, h) + boff + n * 2048 + k * 1024); } while (0)
; #define PG8_MMA(ai, bj, At, Bt) do { __builtin_amdgcn_s_setprio(1); _Pragma("unroll") for (int m = 0; m < 4; ++m) _Pragma("unroll") for (int n = 0; n < 2; ++n) _Pragma("unroll") for (int k = 0; k < 2; ++k) \
;         acc[ai][bj][m][n] = __builtin_amdgcn_mfma_f32_16x16x32_bf16(Bt[n][k], At[m][k], acc[ai][bj][m][n], 0, 0, 0); __builtin_amdgcn_s_setprio(0); } while (0)
; #define PG8_WAIT_V(n) asm volatile("s_waitcnt vmcnt(" #n ")" ::: "memory")
; template <class Epi, class Sched, bool ALIGN_EPI = false, bool SP2 = false>
; __device__ __forceinline__ void gemm_phase(PG8_LAS unsigned char* lds, const Gemm g, const Sched& S, const Epi& E) {
;     ...
;             PG8_LDB(B0, 0, 0); PG8_LDB(B1, 0, 1); PG8_SCHED; PG8_LDA(At, 0, 0); PG8_STAGE(PG8_SA(1, 1), a1 + hstep, voffA);
;             PG8_WAIT_V(8); PG8_WAIT_L(0); PG8_BAR; PG8_MMA(0, 0, At, B0); PG8_MMA(0, 1, At, B1); PG8_BAR; PG8_SCHED;
;             PG8_LDA(At, 0, 1); PG8_STAGE(PG8_SB(0, 0), b2, voffB); PG8_STAGE(PG8_SB(0, 1), b2 + hstep, voffB); PG8_STAGE(PG8_SA(0, 0), a2, voffA);
;             PG8_WAIT_V(8); PG8_WAIT_L(0); PG8_BAR; PG8_MMA(1, 0, At, B0); PG8_MMA(1, 1, At, B1); PG8_BAR; PG8_SCHED;
;             PG8_LDB(B0, 1, 0); PG8_LDB(B1, 1, 1); PG8_SCHED; PG8_LDA(At, 1, 0); PG8_STAGE(PG8_SA(0, 1), a2 + hstep, voffA);
;             PG8_WAIT_V(8); PG8_WAIT_L(0); PG8_BAR; PG8_MMA(0, 0, At, B0); PG8_MMA(0, 1, At, B1); PG8_BAR; PG8_SCHED;
;             PG8_LDA(At, 1, 1); PG8_STAGE(PG8_SB(1, 0), b3, voffB); PG8_STAGE(PG8_SB(1, 1), b3 + hstep, voffB); PG8_STAGE(PG8_SA(1, 0), a3, voffA);
;             PG8_WAIT_V(8); PG8_WAIT_L(0); PG8_BAR; PG8_MMA(1, 0, At, B0); PG8_MMA(1, 1, At, B1); PG8_BAR; PG8_SCHED;
	s_setprio 1
	s_waitcnt lgkmcnt(0)
	v_mfma_f32_16x16x32_bf16 v[60:63], v[136:139], v[216:219], v[60:63]
	v_mfma_f32_16x16x32_bf16 v[60:63], v[140:143], v[220:223], v[60:63]
	v_mfma_f32_16x16x32_bf16 v[56:59], v[176:179], v[220:223], v[56:59]
	v_mfma_f32_16x16x32_bf16 v[56:59], v[172:175], v[216:219], v[56:59]
	v_mfma_f32_16x16x32_bf16 v[40:43], v[172:175], v[224:227], v[40:43]
	v_mfma_f32_16x16x32_bf16 v[40:43], v[176:179], v[228:231], v[40:43]
	v_mfma_f32_16x16x32_bf16 v[48:51], v[140:143], v[228:231], v[48:51]
	v_mfma_f32_16x16x32_bf16 v[48:51], v[136:139], v[224:227], v[48:51]
	v_mfma_f32_16x16x32_bf16 v[32:35], v[136:139], v[232:235], v[32:35]
	v_mfma_f32_16x16x32_bf16 v[32:35], v[140:143], v[236:239], v[32:35]
	v_mfma_f32_16x16x32_bf16 v[24:27], v[176:179], v[236:239], v[24:27]
	v_mfma_f32_16x16x32_bf16 v[24:27], v[172:175], v[232:235], v[24:27]
	v_mfma_f32_16x16x32_bf16 v[8:11], v[172:175], v[240:243], v[8:11]
	v_mfma_f32_16x16x32_bf16 v[8:11], v[176:179], v[244:247], v[8:11]
	v_mfma_f32_16x16x32_bf16 v[12:15], v[140:143], v[244:247], v[12:15]
	v_mfma_f32_16x16x32_bf16 v[12:15], v[136:139], v[240:243], v[12:15]
	s_setprio 0
	s_setprio 1
	v_mfma_f32_16x16x32_bf16 v[52:55], v[180:183], v[216:219], v[52:55]
	v_mfma_f32_16x16x32_bf16 v[52:55], v[184:187], v[220:223], v[52:55]
	v_mfma_f32_16x16x32_bf16 v[44:47], v[212:215], v[220:223], v[44:47]
	v_mfma_f32_16x16x32_bf16 v[44:47], v[208:211], v[216:219], v[44:47]
	v_mfma_f32_16x16x32_bf16 v[28:31], v[208:211], v[224:227], v[28:31]
	v_mfma_f32_16x16x32_bf16 v[28:31], v[212:215], v[228:231], v[28:31]
	v_mfma_f32_16x16x32_bf16 v[36:39], v[184:187], v[228:231], v[36:39]
	v_mfma_f32_16x16x32_bf16 v[36:39], v[180:183], v[224:227], v[36:39]
	v_mfma_f32_16x16x32_bf16 v[20:23], v[180:183], v[232:235], v[20:23]
	v_mfma_f32_16x16x32_bf16 v[20:23], v[184:187], v[236:239], v[20:23]
	v_mfma_f32_16x16x32_bf16 v[16:19], v[212:215], v[236:239], v[16:19]
	v_mfma_f32_16x16x32_bf16 v[16:19], v[208:211], v[232:235], v[16:19]
	s_setprio 2
	s_barrier
	v_mfma_f32_16x16x32_bf16 v[0:3], v[208:211], v[240:243], v[0:3]
	v_mfma_f32_16x16x32_bf16 v[0:3], v[212:215], v[244:247], v[0:3]
	v_mfma_f32_16x16x32_bf16 v[4:7], v[184:187], v[244:247], v[4:7]
	v_mfma_f32_16x16x32_bf16 v[4:7], v[180:183], v[240:243], v[4:7]
	s_setprio 0
	s_add_i32 s44, 0, 0x18000
	v_add_u32_e32 v144, s44, v146
	s_add_i32 s45, 0, 0x1c000
	ds_read_b128 v[136:139], v144
	ds_read_b128 v[140:143], v144 offset:1024
	ds_read_b128 v[172:175], v144 offset:2048
	ds_read_b128 v[176:179], v144 offset:3072
	v_add_u32_e32 v144, s45, v146
	ds_read_b128 v[180:183], v144
	ds_read_b128 v[184:187], v144 offset:1024
	ds_read_b128 v[208:211], v144 offset:2048
	ds_read_b128 v[212:215], v144 offset:3072
	s_add_u32 s48, s48, 0x80000
	s_addc_u32 s49, s49, 0
	s_mov_b32 m0, s59
	v_lshl_add_u64 v[252:253], s[48:49], 0, v[164:165]
	ds_read_b128 v[216:219], v158 offset:32768
	ds_read_b128 v[220:223], v158 offset:33792
	ds_read_b128 v[224:227], v158 offset:34816
	ds_read_b128 v[228:231], v158 offset:35840
	ds_read_b128 v[232:235], v158 offset:36864
	ds_read_b128 v[236:239], v158 offset:37888
	ds_read_b128 v[240:243], v158 offset:38912
	ds_read_b128 v[244:247], v158 offset:39936
	global_load_lds_dwordx4 v[252:253], off
	v_lshl_add_u64 v[252:253], s[48:49], 0, v[168:169]
	s_mov_b32 m0, s60
	s_nop 0
	global_load_lds_dwordx4 v[252:253], off
	s_waitcnt vmcnt(8)
	s_waitcnt lgkmcnt(0)
	s_barrier
	s_setprio 1
	s_waitcnt lgkmcnt(0)
	v_mfma_f32_16x16x32_bf16 v[124:127], v[136:139], v[216:219], v[124:127]
	v_mfma_f32_16x16x32_bf16 v[124:127], v[140:143], v[220:223], v[124:127]
	v_mfma_f32_16x16x32_bf16 v[120:123], v[176:179], v[220:223], v[120:123]
	v_mfma_f32_16x16x32_bf16 v[120:123], v[172:175], v[216:219], v[120:123]
	v_mfma_f32_16x16x32_bf16 v[104:107], v[172:175], v[224:227], v[104:107]
	v_mfma_f32_16x16x32_bf16 v[104:107], v[176:179], v[228:231], v[104:107]
	v_mfma_f32_16x16x32_bf16 v[108:111], v[140:143], v[228:231], v[108:111]
	v_mfma_f32_16x16x32_bf16 v[108:111], v[136:139], v[224:227], v[108:111]
	v_mfma_f32_16x16x32_bf16 v[96:99], v[136:139], v[232:235], v[96:99]
	v_mfma_f32_16x16x32_bf16 v[96:99], v[140:143], v[236:239], v[96:99]
	v_mfma_f32_16x16x32_bf16 v[88:91], v[176:179], v[236:239], v[88:91]
	v_mfma_f32_16x16x32_bf16 v[88:91], v[172:175], v[232:235], v[88:91]
	v_mfma_f32_16x16x32_bf16 v[72:75], v[172:175], v[240:243], v[72:75]
	v_mfma_f32_16x16x32_bf16 v[72:75], v[176:179], v[244:247], v[72:75]
	v_mfma_f32_16x16x32_bf16 v[80:83], v[140:143], v[244:247], v[80:83]
	v_mfma_f32_16x16x32_bf16 v[80:83], v[136:139], v[240:243], v[80:83]
	s_setprio 0
	s_setprio 1
	v_mfma_f32_16x16x32_bf16 v[116:119], v[180:183], v[216:219], v[116:119]
	v_mfma_f32_16x16x32_bf16 v[116:119], v[184:187], v[220:223], v[116:119]
	v_mfma_f32_16x16x32_bf16 v[112:115], v[212:215], v[220:223], v[112:115]
	v_mfma_f32_16x16x32_bf16 v[112:115], v[208:211], v[216:219], v[112:115]
	v_mfma_f32_16x16x32_bf16 v[92:95], v[208:211], v[224:227], v[92:95]
	v_mfma_f32_16x16x32_bf16 v[92:95], v[212:215], v[228:231], v[92:95]
	v_mfma_f32_16x16x32_bf16 v[100:103], v[184:187], v[228:231], v[100:103]
	v_mfma_f32_16x16x32_bf16 v[100:103], v[180:183], v[224:227], v[100:103]
	v_mfma_f32_16x16x32_bf16 v[84:87], v[180:183], v[232:235], v[84:87]
	v_mfma_f32_16x16x32_bf16 v[84:87], v[184:187], v[236:239], v[84:87]
	v_mfma_f32_16x16x32_bf16 v[76:79], v[212:215], v[236:239], v[76:79]
	v_mfma_f32_16x16x32_bf16 v[76:79], v[208:211], v[232:235], v[76:79]
	s_setprio 2
	s_barrier
; #define PG8_STAGE(bufoff, gbase, voff) do { _Pragma("unroll") for (int _i = 0; _i < 2; ++_i) \
;         __builtin_amdgcn_global_load_lds((const unsigned*)((const char*)(gbase) + (voff)[_i]), (PG8_LAS unsigned*)(lds + (bufoff) + ldsw + _i * 8192), 16, 0, 0); } while (0)
; #define PG8_LDA(dst, b, h) do { _Pragma("unroll") for (int m = 0; m < 4; ++m) _Pragma("unroll") for (int k = 0; k < 2; ++k) dst[m][k] = *(const PG8_LAS bf16x8*)(lds + PG8_SA(b, h) + aoff + m * 2048 + k * 1024); } while (0)
; #define PG8_LDB(dst, b, h) do { _Pragma("unroll") for (int n = 0; n < 2; ++n) _Pragma("unroll") for (int k = 0; k < 2; ++k) dst[n][k] = *(const PG8_LAS bf16x8*)(lds + PG8_SB(b, h) + boff + n * 2048 + k * 1024); } while (0)
; template <class Epi, class Sched, bool ALIGN_EPI = false, bool SP2 = false>
; __device__ __forceinline__ void gemm_phase(PG8_LAS unsigned char* lds, const Gemm g, const Sched& S, const Epi& E) {
;     ...
;         for (int t = 0; t < nt; t += 2) {
;             const bool last = (t == nt - 2);
;             const char* a1 = cA + (size_t)(t + 1) * kstep;
;             const char* a2 = last ? nA : cA + (size_t)(t + 2) * kstep; const char* b2 = last ? nB : cB + (size_t)(t + 2) * kstep;
;             const char* a3 = a2 + kstep; const char* b3 = b2 + kstep;
;             if (last && has_next) S.a_ready(nxt);
;             if constexpr (SP2) {
;             PG8_LDB(B0, 0, 0); PG8_LDB(B1, 0, 1); PG8_SCHED; PG8_LDA(At, 0, 0); PG8_STAGE(PG8_SA(1, 1), a1 + hstep, voffA);
;             PG8_WAIT_V(8); PG8_WAIT_L(0); PG8_BAR; PG8_MMA(0, 0, At, B0); PG8_MMA(0, 1, At, B1); PG8_BAR; PG8_SCHED;
;             PG8_LDA(At, 0, 1); PG8_STAGE(PG8_SB(0, 0), b2, voffB); PG8_STAGE(PG8_SB(0, 1), b2 + hstep, voffB); PG8_STAGE(PG8_SA(0, 0), a2, voffA);
;             PG8_WAIT_V(8); PG8_WAIT_L(0); PG8_BAR; PG8_MMA(1, 0, At, B0); PG8_MMA(1, 1, At, B1); PG8_BAR; PG8_SCHED;
;             PG8_LDB(B0, 1, 0); PG8_LDB(B1, 1, 1); PG8_SCHED; PG8_LDA(At, 1, 0); PG8_STAGE(PG8_SA(0, 1), a2 + hstep, voffA);
;             PG8_WAIT_V(8); PG8_WAIT_L(0); PG8_BAR; PG8_MMA(0, 0, At, B0); PG8_MMA(0, 1, At, B1); PG8_BAR; PG8_SCHED;
;             PG8_LDA(At, 1, 1); PG8_STAGE(PG8_SB(1, 0), b3, voffB); PG8_STAGE(PG8_SB(1, 1), b3 + hstep, voffB); PG8_STAGE(PG8_SA(1, 0), a3, voffA);
;             PG8_WAIT_V(8); PG8_WAIT_L(0); PG8_BAR; PG8_MMA(1, 0, At, B0); PG8_MMA(1, 1, At, B1); PG8_BAR; PG8_SCHED;
	v_mfma_f32_16x16x32_bf16 v[64:67], v[208:211], v[240:243], v[64:67]
	v_mfma_f32_16x16x32_bf16 v[64:67], v[212:215], v[244:247], v[64:67]
	v_mfma_f32_16x16x32_bf16 v[68:71], v[184:187], v[244:247], v[68:71]
	v_mfma_f32_16x16x32_bf16 v[68:71], v[180:183], v[240:243], v[68:71]
	s_setprio 0
	s_add_i32 s44, s44, s52
	v_lshl_add_u64 v[188:189], v[188:189], 0, s[16:17]
	s_mov_b32 m0, s44
	ds_read_b128 v[216:219], v158 offset:49152
	ds_read_b128 v[220:223], v158 offset:50176
	ds_read_b128 v[224:227], v158 offset:51200
	ds_read_b128 v[228:231], v158 offset:52224
	ds_read_b128 v[232:235], v158 offset:53248
	ds_read_b128 v[236:239], v158 offset:54272
	ds_read_b128 v[240:243], v158 offset:55296
	ds_read_b128 v[244:247], v158 offset:56320
	global_load_lds_dwordx4 v[188:189], off
	s_add_i32 m0, s44, 0x2000
	s_add_u32 s42, s42, 0x80080
	v_lshl_add_u64 v[188:189], v[200:201], 0, s[16:17]
	s_addc_u32 s43, s43, 0
	s_add_i32 s44, s45, s52
	global_load_lds_dwordx4 v[188:189], off
	v_lshl_add_u64 v[188:189], s[42:43], 0, v[166:167]
	s_mov_b32 m0, s44
	s_nop 0
	global_load_lds_dwordx4 v[188:189], off
	v_lshl_add_u64 v[188:189], s[42:43], 0, v[170:171]
	s_add_i32 m0, s44, 0x2000
	s_nop 0
	global_load_lds_dwordx4 v[188:189], off
	v_lshl_add_u64 v[188:189], v[248:249], 0, s[16:17]
	s_mov_b32 m0, s62
	s_nop 0
	global_load_lds_dwordx4 v[188:189], off
	v_lshl_add_u64 v[188:189], v[250:251], 0, s[16:17]
	s_mov_b32 m0, s63
	s_nop 0
	global_load_lds_dwordx4 v[188:189], off
	s_waitcnt vmcnt(8)
	s_waitcnt lgkmcnt(0)
	s_barrier
	s_setprio 1
	s_waitcnt lgkmcnt(0)
	v_mfma_f32_16x16x32_bf16 v[60:63], v[136:139], v[216:219], v[60:63]
	v_mfma_f32_16x16x32_bf16 v[60:63], v[140:143], v[220:223], v[60:63]
	v_mfma_f32_16x16x32_bf16 v[56:59], v[176:179], v[220:223], v[56:59]
	v_mfma_f32_16x16x32_bf16 v[56:59], v[172:175], v[216:219], v[56:59]
	v_mfma_f32_16x16x32_bf16 v[40:43], v[172:175], v[224:227], v[40:43]
	v_mfma_f32_16x16x32_bf16 v[40:43], v[176:179], v[228:231], v[40:43]
	v_mfma_f32_16x16x32_bf16 v[48:51], v[140:143], v[228:231], v[48:51]
	v_mfma_f32_16x16x32_bf16 v[48:51], v[136:139], v[224:227], v[48:51]
	v_mfma_f32_16x16x32_bf16 v[32:35], v[136:139], v[232:235], v[32:35]
	v_mfma_f32_16x16x32_bf16 v[32:35], v[140:143], v[236:239], v[32:35]
	v_mfma_f32_16x16x32_bf16 v[24:27], v[176:179], v[236:239], v[24:27]
	v_mfma_f32_16x16x32_bf16 v[24:27], v[172:175], v[232:235], v[24:27]
	v_mfma_f32_16x16x32_bf16 v[8:11], v[172:175], v[240:243], v[8:11]
	v_mfma_f32_16x16x32_bf16 v[8:11], v[176:179], v[244:247], v[8:11]
	v_mfma_f32_16x16x32_bf16 v[12:15], v[140:143], v[244:247], v[12:15]
	v_mfma_f32_16x16x32_bf16 v[12:15], v[136:139], v[240:243], v[12:15]
	s_setprio 0
	s_setprio 1
	v_mfma_f32_16x16x32_bf16 v[52:55], v[180:183], v[216:219], v[52:55]
	v_mfma_f32_16x16x32_bf16 v[52:55], v[184:187], v[220:223], v[52:55]
	v_mfma_f32_16x16x32_bf16 v[44:47], v[212:215], v[220:223], v[44:47]
	v_mfma_f32_16x16x32_bf16 v[44:47], v[208:211], v[216:219], v[44:47]
	v_mfma_f32_16x16x32_bf16 v[28:31], v[208:211], v[224:227], v[28:31]
	v_mfma_f32_16x16x32_bf16 v[28:31], v[212:215], v[228:231], v[28:31]
	v_mfma_f32_16x16x32_bf16 v[36:39], v[184:187], v[228:231], v[36:39]
	v_mfma_f32_16x16x32_bf16 v[36:39], v[180:183], v[224:227], v[36:39]
	v_mfma_f32_16x16x32_bf16 v[20:23], v[180:183], v[232:235], v[20:23]
	v_mfma_f32_16x16x32_bf16 v[20:23], v[184:187], v[236:239], v[20:23]
	v_mfma_f32_16x16x32_bf16 v[16:19], v[212:215], v[236:239], v[16:19]
	v_mfma_f32_16x16x32_bf16 v[16:19], v[208:211], v[232:235], v[16:19]
	s_setprio 2
	s_barrier
	v_mfma_f32_16x16x32_bf16 v[0:3], v[208:211], v[240:243], v[0:3]
	v_mfma_f32_16x16x32_bf16 v[0:3], v[212:215], v[244:247], v[0:3]
	v_mfma_f32_16x16x32_bf16 v[4:7], v[184:187], v[244:247], v[4:7]
	v_mfma_f32_16x16x32_bf16 v[4:7], v[180:183], v[240:243], v[4:7]
	s_setprio 0
	s_add_i32 s71, s71, 2
	s_add_u32 s40, s40, 0x100
	s_addc_u32 s41, s41, 0
	s_add_u32 s69, s69, 0x100
	s_addc_u32 s70, s70, 0
	s_cmp_gt_u32 s71, 29
	s_cbranch_scc0 .LBB0_774
	s_and_b64 vcc, exec, s[18:19]
	s_cbranch_vccz .LBB0_777
	s_barrier

; #define PG8_STAGE(bufoff, gbase, voff) do { _Pragma("unroll") for (int _i = 0; _i < 2; ++_i) \
;         __builtin_amdgcn_global_load_lds((const unsigned*)((const char*)(gbase) + (voff)[_i]), (PG8_LAS unsigned*)(lds + (bufoff) + ldsw + _i * 8192), 16, 0, 0); } while (0)
; #define PG8_LDA(dst, b, h) do { _Pragma("unroll") for (int m = 0; m < 4; ++m) _Pragma("unroll") for (int k = 0; k < 2; ++k) dst[m][k] = *(const PG8_LAS bf16x8*)(lds + PG8_SA(b, h) + aoff + m * 2048 + k * 1024); } while (0)
; #define PG8_LDB(dst, b, h) do { _Pragma("unroll") for (int n = 0; n < 2; ++n) _Pragma("unroll") for (int k = 0; k < 2; ++k) dst[n][k] = *(const PG8_LAS bf16x8*)(lds + PG8_SB(b, h) + boff + n * 2048 + k * 1024); } while (0)
; #define PG8_BAR __builtin_amdgcn_s_barrier()
; template <class Epi, class Sched, bool ALIGN_EPI = false, bool SP2 = false>
; __device__ __forceinline__ void gemm_phase(PG8_LAS unsigned char* lds, const Gemm g, const Sched& S, const Epi& E) {
;     ...
;             const bool last = (t == nt - 2);
;             const char* a1 = cA + (size_t)(t + 1) * kstep;
;             const char* a2 = last ? nA : cA + (size_t)(t + 2) * kstep; const char* b2 = last ? nB : cB + (size_t)(t + 2) * kstep;
;             const char* a3 = a2 + kstep; const char* b3 = b2 + kstep;
;             if (last && has_next) S.a_ready(nxt);
;             if constexpr (SP2) {
;             PG8_LDB(B0, 0, 0); PG8_LDB(B1, 0, 1); PG8_SCHED; PG8_LDA(At, 0, 0); PG8_STAGE(PG8_SA(1, 1), a1 + hstep, voffA);
;             PG8_WAIT_V(8); PG8_WAIT_L(0); PG8_BAR; PG8_MMA(0, 0, At, B0); PG8_MMA(0, 1, At, B1); PG8_BAR; PG8_SCHED;
;             PG8_LDA(At, 0, 1); PG8_STAGE(PG8_SB(0, 0), b2, voffB); PG8_STAGE(PG8_SB(0, 1), b2 + hstep, voffB); PG8_STAGE(PG8_SA(0, 0), a2, voffA);
;             PG8_WAIT_V(8); PG8_WAIT_L(0); PG8_BAR; PG8_MMA(1, 0, At, B0); PG8_MMA(1, 1, At, B1); PG8_BAR; PG8_SCHED;
;             PG8_LDB(B0, 1, 0); PG8_LDB(B1, 1, 1); PG8_SCHED; PG8_LDA(At, 1, 0); PG8_STAGE(PG8_SA(0, 1), a2 + hstep, voffA);
;             PG8_WAIT_V(8); PG8_WAIT_L(0); PG8_BAR; PG8_MMA(0, 0, At, B0); PG8_MMA(0, 1, At, B1); PG8_BAR; PG8_SCHED;
;             PG8_LDA(At, 1, 1); PG8_STAGE(PG8_SB(1, 0), b3, voffB); PG8_STAGE(PG8_SB(1, 1), b3 + hstep, voffB); PG8_STAGE(PG8_SA(1, 0), a3, voffA);
;             PG8_WAIT_V(8); PG8_WAIT_L(0); PG8_BAR; PG8_MMA(1, 0, At, B0); PG8_MMA(1, 1, At, B1); PG8_BAR; PG8_SCHED;
.LBB0_837:
	ds_read_b128 v[134:137], v143
	ds_read_b128 v[146:149], v143 offset:1024
	ds_read_b128 v[150:153], v143 offset:2048
	ds_read_b128 v[154:157], v143 offset:3072
	ds_read_b128 v[172:175], v144
	ds_read_b128 v[176:179], v144 offset:1024
	ds_read_b128 v[180:183], v144 offset:2048
	ds_read_b128 v[184:187], v144 offset:3072
	s_add_u32 s44, s42, 0xffea0080
	s_addc_u32 s45, s43, -1
	s_cmpk_eq_i32 s75, 0x54
	s_cselect_b32 s53, s39, s45
	s_cselect_b32 s52, s38, s44
	s_cselect_b32 s49, s41, s35
	s_cselect_b32 s48, s40, s34
	v_lshl_add_u64 v[138:139], s[42:43], 0, v[128:129]
	s_add_i32 m0, s61, 0xc000
	ds_read_b128 v[208:211], v145
	ds_read_b128 v[212:215], v145 offset:1024
	ds_read_b128 v[216:219], v145 offset:2048
	ds_read_b128 v[220:223], v145 offset:3072
	ds_read_b128 v[224:227], v145 offset:4096
	ds_read_b128 v[228:231], v145 offset:5120
	ds_read_b128 v[232:235], v145 offset:6144
	ds_read_b128 v[236:239], v145 offset:7168
	global_load_lds_dwordx4 v[138:139], off
	v_lshl_add_u64 v[138:139], s[42:43], 0, v[130:131]
	s_add_i32 m0, s61, 0xe000
	s_nop 0
	global_load_lds_dwordx4 v[138:139], off
	s_waitcnt vmcnt(8)
	s_waitcnt lgkmcnt(0)
	s_barrier
	s_setprio 1
	s_waitcnt lgkmcnt(0)
	v_mfma_f32_16x16x32_bf16 v[124:127], v[134:137], v[208:211], v[124:127]
	v_mfma_f32_16x16x32_bf16 v[124:127], v[146:149], v[212:215], v[124:127]
	v_mfma_f32_16x16x32_bf16 v[120:123], v[154:157], v[212:215], v[120:123]
	v_mfma_f32_16x16x32_bf16 v[120:123], v[150:153], v[208:211], v[120:123]
	v_mfma_f32_16x16x32_bf16 v[112:115], v[150:153], v[216:219], v[112:115]
	v_mfma_f32_16x16x32_bf16 v[112:115], v[154:157], v[220:223], v[112:115]
	v_mfma_f32_16x16x32_bf16 v[116:119], v[146:149], v[220:223], v[116:119]
	v_mfma_f32_16x16x32_bf16 v[116:119], v[134:137], v[216:219], v[116:119]
	v_mfma_f32_16x16x32_bf16 v[92:95], v[134:137], v[224:227], v[92:95]
	v_mfma_f32_16x16x32_bf16 v[92:95], v[146:149], v[228:231], v[92:95]
	v_mfma_f32_16x16x32_bf16 v[88:91], v[154:157], v[228:231], v[88:91]
	v_mfma_f32_16x16x32_bf16 v[88:91], v[150:153], v[224:227], v[88:91]
	v_mfma_f32_16x16x32_bf16 v[80:83], v[150:153], v[232:235], v[80:83]
	v_mfma_f32_16x16x32_bf16 v[80:83], v[154:157], v[236:239], v[80:83]
	v_mfma_f32_16x16x32_bf16 v[84:87], v[146:149], v[236:239], v[84:87]
	v_mfma_f32_16x16x32_bf16 v[84:87], v[134:137], v[232:235], v[84:87]
	s_setprio 0
	s_setprio 1
	v_mfma_f32_16x16x32_bf16 v[108:111], v[172:175], v[208:211], v[108:111]
	v_mfma_f32_16x16x32_bf16 v[108:111], v[176:179], v[212:215], v[108:111]
	v_mfma_f32_16x16x32_bf16 v[104:107], v[184:187], v[212:215], v[104:107]
	v_mfma_f32_16x16x32_bf16 v[104:107], v[180:183], v[208:211], v[104:107]
	v_mfma_f32_16x16x32_bf16 v[96:99], v[180:183], v[216:219], v[96:99]
	v_mfma_f32_16x16x32_bf16 v[96:99], v[184:187], v[220:223], v[96:99]
	v_mfma_f32_16x16x32_bf16 v[100:103], v[176:179], v[220:223], v[100:103]
	v_mfma_f32_16x16x32_bf16 v[100:103], v[172:175], v[216:219], v[100:103]
	v_mfma_f32_16x16x32_bf16 v[76:79], v[172:175], v[224:227], v[76:79]
	v_mfma_f32_16x16x32_bf16 v[76:79], v[176:179], v[228:231], v[76:79]
	v_mfma_f32_16x16x32_bf16 v[72:75], v[184:187], v[228:231], v[72:75]
	v_mfma_f32_16x16x32_bf16 v[72:75], v[180:183], v[224:227], v[72:75]
	s_setprio 2
	s_barrier
	v_mfma_f32_16x16x32_bf16 v[64:67], v[180:183], v[232:235], v[64:67]
	v_mfma_f32_16x16x32_bf16 v[64:67], v[184:187], v[236:239], v[64:67]
	v_mfma_f32_16x16x32_bf16 v[68:71], v[176:179], v[236:239], v[68:71]
	v_mfma_f32_16x16x32_bf16 v[68:71], v[172:175], v[232:235], v[68:71]
	s_setprio 0
	s_add_i32 s44, s68, s60
	v_lshl_add_u64 v[138:139], s[48:49], 0, v[160:161]
	s_mov_b32 m0, s44
	ds_read_b128 v[208:211], v145 offset:16384
	ds_read_b128 v[212:215], v145 offset:17408
	ds_read_b128 v[216:219], v145 offset:18432
	ds_read_b128 v[220:223], v145 offset:19456
	ds_read_b128 v[224:227], v145 offset:20480
	ds_read_b128 v[228:231], v145 offset:21504
	ds_read_b128 v[232:235], v145 offset:22528
	ds_read_b128 v[236:239], v145 offset:23552
	global_load_lds_dwordx4 v[138:139], off
	s_add_i32 m0, s44, 0x2000
	s_add_u32 s76, s48, 0x160000
	v_lshl_add_u64 v[158:159], s[48:49], 0, v[162:163]
	s_addc_u32 s77, s49, 0
	s_add_i32 s44, s69, s60
	global_load_lds_dwordx4 v[158:159], off
	v_lshl_add_u64 v[188:189], s[76:77], 0, v[160:161]
	s_mov_b32 m0, s44
	v_lshl_add_u64 v[200:201], s[52:53], 0, v[162:163]
	global_load_lds_dwordx4 v[188:189], off
	v_lshl_add_u64 v[188:189], s[76:77], 0, v[162:163]
	s_add_i32 m0, s44, 0x2000
	s_nop 0
	global_load_lds_dwordx4 v[188:189], off
	v_lshl_add_u64 v[188:189], s[52:53], 0, v[160:161]
	s_mov_b32 m0, s61
	s_nop 0
	global_load_lds_dwordx4 v[188:189], off
	s_mov_b32 m0, s62
	s_nop 0
	global_load_lds_dwordx4 v[200:201], off
	s_waitcnt vmcnt(8)
	s_waitcnt lgkmcnt(0)
	s_barrier
; #define PG8_STAGE(bufoff, gbase, voff) do { _Pragma("unroll") for (int _i = 0; _i < 2; ++_i) \
;         __builtin_amdgcn_global_load_lds((const unsigned*)((const char*)(gbase) + (voff)[_i]), (PG8_LAS unsigned*)(lds + (bufoff) + ldsw + _i * 8192), 16, 0, 0); } while (0)
; #define PG8_LDA(dst, b, h) do { _Pragma("unroll") for (int m = 0; m < 4; ++m) _Pragma("unroll") for (int k = 0; k < 2; ++k) dst[m][k] = *(const PG8_LAS bf16x8*)(lds + PG8_SA(b, h) + aoff + m * 2048 + k * 1024); } while (0)
; #define PG8_LDB(dst, b, h) do { _Pragma("unroll") for (int n = 0; n < 2; ++n) _Pragma("unroll") for (int k = 0; k < 2; ++k) dst[n][k] = *(const PG8_LAS bf16x8*)(lds + PG8_SB(b, h) + boff + n * 2048 + k * 1024); } while (0)
; #define PG8_MMA(ai, bj, At, Bt) do { __builtin_amdgcn_s_setprio(1); _Pragma("unroll") for (int m = 0; m < 4; ++m) _Pragma("unroll") for (int n = 0; n < 2; ++n) _Pragma("unroll") for (int k = 0; k < 2; ++k) \
;         acc[ai][bj][m][n] = __builtin_amdgcn_mfma_f32_16x16x32_bf16(Bt[n][k], At[m][k], acc[ai][bj][m][n], 0, 0, 0); __builtin_amdgcn_s_setprio(0); } while (0)
; #define PG8_WAIT_V(n) asm volatile("s_waitcnt vmcnt(" #n ")" ::: "memory")
; template <class Epi, class Sched, bool ALIGN_EPI = false, bool SP2 = false>
; __device__ __forceinline__ void gemm_phase(PG8_LAS unsigned char* lds, const Gemm g, const Sched& S, const Epi& E) {
;     ...
;             PG8_LDB(B0, 0, 0); PG8_LDB(B1, 0, 1); PG8_SCHED; PG8_LDA(At, 0, 0); PG8_STAGE(PG8_SA(1, 1), a1 + hstep, voffA);
;             PG8_WAIT_V(8); PG8_WAIT_L(0); PG8_BAR; PG8_MMA(0, 0, At, B0); PG8_MMA(0, 1, At, B1); PG8_BAR; PG8_SCHED;
;             PG8_LDA(At, 0, 1); PG8_STAGE(PG8_SB(0, 0), b2, voffB); PG8_STAGE(PG8_SB(0, 1), b2 + hstep, voffB); PG8_STAGE(PG8_SA(0, 0), a2, voffA);
;             PG8_WAIT_V(8); PG8_WAIT_L(0); PG8_BAR; PG8_MMA(1, 0, At, B0); PG8_MMA(1, 1, At, B1); PG8_BAR; PG8_SCHED;
;             PG8_LDB(B0, 1, 0); PG8_LDB(B1, 1, 1); PG8_SCHED; PG8_LDA(At, 1, 0); PG8_STAGE(PG8_SA(0, 1), a2 + hstep, voffA);
;             PG8_WAIT_V(8); PG8_WAIT_L(0); PG8_BAR; PG8_MMA(0, 0, At, B0); PG8_MMA(0, 1, At, B1); PG8_BAR; PG8_SCHED;
;             PG8_LDA(At, 1, 1); PG8_STAGE(PG8_SB(1, 0), b3, voffB); PG8_STAGE(PG8_SB(1, 1), b3 + hstep, voffB); PG8_STAGE(PG8_SA(1, 0), a3, voffA);
;             PG8_WAIT_V(8); PG8_WAIT_L(0); PG8_BAR; PG8_MMA(1, 0, At, B0); PG8_MMA(1, 1, At, B1); PG8_BAR; PG8_SCHED;
	s_setprio 1
	s_waitcnt lgkmcnt(0)
	v_mfma_f32_16x16x32_bf16 v[60:63], v[134:137], v[208:211], v[60:63]
	v_mfma_f32_16x16x32_bf16 v[60:63], v[146:149], v[212:215], v[60:63]
	v_mfma_f32_16x16x32_bf16 v[56:59], v[154:157], v[212:215], v[56:59]
	v_mfma_f32_16x16x32_bf16 v[56:59], v[150:153], v[208:211], v[56:59]
	v_mfma_f32_16x16x32_bf16 v[48:51], v[150:153], v[216:219], v[48:51]
	v_mfma_f32_16x16x32_bf16 v[48:51], v[154:157], v[220:223], v[48:51]
	v_mfma_f32_16x16x32_bf16 v[52:55], v[146:149], v[220:223], v[52:55]
	v_mfma_f32_16x16x32_bf16 v[52:55], v[134:137], v[216:219], v[52:55]
	v_mfma_f32_16x16x32_bf16 v[28:31], v[134:137], v[224:227], v[28:31]
	v_mfma_f32_16x16x32_bf16 v[28:31], v[146:149], v[228:231], v[28:31]
	v_mfma_f32_16x16x32_bf16 v[24:27], v[154:157], v[228:231], v[24:27]
	v_mfma_f32_16x16x32_bf16 v[24:27], v[150:153], v[224:227], v[24:27]
	v_mfma_f32_16x16x32_bf16 v[16:19], v[150:153], v[232:235], v[16:19]
	v_mfma_f32_16x16x32_bf16 v[16:19], v[154:157], v[236:239], v[16:19]
	v_mfma_f32_16x16x32_bf16 v[20:23], v[146:149], v[236:239], v[20:23]
	v_mfma_f32_16x16x32_bf16 v[20:23], v[134:137], v[232:235], v[20:23]
	s_setprio 0
	s_setprio 1
	v_mfma_f32_16x16x32_bf16 v[44:47], v[172:175], v[208:211], v[44:47]
	v_mfma_f32_16x16x32_bf16 v[44:47], v[176:179], v[212:215], v[44:47]
	v_mfma_f32_16x16x32_bf16 v[40:43], v[184:187], v[212:215], v[40:43]
	v_mfma_f32_16x16x32_bf16 v[40:43], v[180:183], v[208:211], v[40:43]
	v_mfma_f32_16x16x32_bf16 v[32:35], v[180:183], v[216:219], v[32:35]
	v_mfma_f32_16x16x32_bf16 v[32:35], v[184:187], v[220:223], v[32:35]
	v_mfma_f32_16x16x32_bf16 v[36:39], v[176:179], v[220:223], v[36:39]
	v_mfma_f32_16x16x32_bf16 v[36:39], v[172:175], v[216:219], v[36:39]
	v_mfma_f32_16x16x32_bf16 v[12:15], v[172:175], v[224:227], v[12:15]
	v_mfma_f32_16x16x32_bf16 v[12:15], v[176:179], v[228:231], v[12:15]
	v_mfma_f32_16x16x32_bf16 v[8:11], v[184:187], v[228:231], v[8:11]
	v_mfma_f32_16x16x32_bf16 v[8:11], v[180:183], v[224:227], v[8:11]
	s_setprio 2
	s_barrier
	v_mfma_f32_16x16x32_bf16 v[0:3], v[180:183], v[232:235], v[0:3]
	v_mfma_f32_16x16x32_bf16 v[0:3], v[184:187], v[236:239], v[0:3]
	v_mfma_f32_16x16x32_bf16 v[4:7], v[176:179], v[236:239], v[4:7]
	v_mfma_f32_16x16x32_bf16 v[4:7], v[172:175], v[232:235], v[4:7]
	s_setprio 0
	s_add_i32 s44, 0, 0x18000
	s_add_i32 s45, 0, 0x1c000
	v_add_u32_e32 v154, s44, v141
	v_add_u32_e32 v165, s45, v141
	ds_read_b128 v[134:137], v154
	ds_read_b128 v[146:149], v154 offset:1024
	ds_read_b128 v[150:153], v154 offset:2048
	ds_read_b128 v[154:157], v154 offset:3072
	ds_read_b128 v[172:175], v165
	ds_read_b128 v[176:179], v165 offset:1024
	ds_read_b128 v[180:183], v165 offset:2048
	ds_read_b128 v[184:187], v165 offset:3072
	s_add_u32 s52, s52, 0x160000
	s_addc_u32 s53, s53, 0
	s_mov_b32 m0, s63
	v_lshl_add_u64 v[240:241], s[52:53], 0, v[160:161]
	ds_read_b128 v[208:211], v145 offset:32768
	ds_read_b128 v[212:215], v145 offset:33792
	ds_read_b128 v[216:219], v145 offset:34816
	ds_read_b128 v[220:223], v145 offset:35840
	ds_read_b128 v[224:227], v145 offset:36864
	ds_read_b128 v[228:231], v145 offset:37888
	ds_read_b128 v[232:235], v145 offset:38912
	ds_read_b128 v[236:239], v145 offset:39936
	global_load_lds_dwordx4 v[240:241], off
	v_lshl_add_u64 v[240:241], s[52:53], 0, v[162:163]
	s_mov_b32 m0, s64
	s_nop 0
	global_load_lds_dwordx4 v[240:241], off
	s_waitcnt vmcnt(8)
	s_waitcnt lgkmcnt(0)
	s_barrier
	s_setprio 1
	s_waitcnt lgkmcnt(0)
	v_mfma_f32_16x16x32_bf16 v[124:127], v[134:137], v[208:211], v[124:127]
	v_mfma_f32_16x16x32_bf16 v[124:127], v[146:149], v[212:215], v[124:127]
	v_mfma_f32_16x16x32_bf16 v[120:123], v[154:157], v[212:215], v[120:123]
	v_mfma_f32_16x16x32_bf16 v[120:123], v[150:153], v[208:211], v[120:123]
	v_mfma_f32_16x16x32_bf16 v[112:115], v[150:153], v[216:219], v[112:115]
	v_mfma_f32_16x16x32_bf16 v[112:115], v[154:157], v[220:223], v[112:115]
	v_mfma_f32_16x16x32_bf16 v[116:119], v[146:149], v[220:223], v[116:119]
	v_mfma_f32_16x16x32_bf16 v[116:119], v[134:137], v[216:219], v[116:119]
	v_mfma_f32_16x16x32_bf16 v[92:95], v[134:137], v[224:227], v[92:95]
	v_mfma_f32_16x16x32_bf16 v[92:95], v[146:149], v[228:231], v[92:95]
	v_mfma_f32_16x16x32_bf16 v[88:91], v[154:157], v[228:231], v[88:91]
	v_mfma_f32_16x16x32_bf16 v[88:91], v[150:153], v[224:227], v[88:91]
	v_mfma_f32_16x16x32_bf16 v[80:83], v[150:153], v[232:235], v[80:83]
	v_mfma_f32_16x16x32_bf16 v[80:83], v[154:157], v[236:239], v[80:83]
	v_mfma_f32_16x16x32_bf16 v[84:87], v[146:149], v[236:239], v[84:87]
	v_mfma_f32_16x16x32_bf16 v[84:87], v[134:137], v[232:235], v[84:87]
	s_setprio 0
	s_setprio 1
	v_mfma_f32_16x16x32_bf16 v[108:111], v[172:175], v[208:211], v[108:111]
	v_mfma_f32_16x16x32_bf16 v[108:111], v[176:179], v[212:215], v[108:111]
	v_mfma_f32_16x16x32_bf16 v[104:107], v[184:187], v[212:215], v[104:107]
	v_mfma_f32_16x16x32_bf16 v[104:107], v[180:183], v[208:211], v[104:107]
	v_mfma_f32_16x16x32_bf16 v[96:99], v[180:183], v[216:219], v[96:99]
	v_mfma_f32_16x16x32_bf16 v[96:99], v[184:187], v[220:223], v[96:99]
	v_mfma_f32_16x16x32_bf16 v[100:103], v[176:179], v[220:223], v[100:103]
	v_mfma_f32_16x16x32_bf16 v[100:103], v[172:175], v[216:219], v[100:103]
	v_mfma_f32_16x16x32_bf16 v[76:79], v[172:175], v[224:227], v[76:79]
	v_mfma_f32_16x16x32_bf16 v[76:79], v[176:179], v[228:231], v[76:79]
	v_mfma_f32_16x16x32_bf16 v[72:75], v[184:187], v[228:231], v[72:75]
	v_mfma_f32_16x16x32_bf16 v[72:75], v[180:183], v[224:227], v[72:75]
	s_setprio 2
	s_barrier
; #define PG8_STAGE(bufoff, gbase, voff) do { _Pragma("unroll") for (int _i = 0; _i < 2; ++_i) \
;         __builtin_amdgcn_global_load_lds((const unsigned*)((const char*)(gbase) + (voff)[_i]), (PG8_LAS unsigned*)(lds + (bufoff) + ldsw + _i * 8192), 16, 0, 0); } while (0)
; #define PG8_LDA(dst, b, h) do { _Pragma("unroll") for (int m = 0; m < 4; ++m) _Pragma("unroll") for (int k = 0; k < 2; ++k) dst[m][k] = *(const PG8_LAS bf16x8*)(lds + PG8_SA(b, h) + aoff + m * 2048 + k * 1024); } while (0)
; #define PG8_LDB(dst, b, h) do { _Pragma("unroll") for (int n = 0; n < 2; ++n) _Pragma("unroll") for (int k = 0; k < 2; ++k) dst[n][k] = *(const PG8_LAS bf16x8*)(lds + PG8_SB(b, h) + boff + n * 2048 + k * 1024); } while (0)
; template <class Epi, class Sched, bool ALIGN_EPI = false, bool SP2 = false>
; __device__ __forceinline__ void gemm_phase(PG8_LAS unsigned char* lds, const Gemm g, const Sched& S, const Epi& E) {
;     ...
;         for (int t = 0; t < nt; t += 2) {
;             const bool last = (t == nt - 2);
;             const char* a1 = cA + (size_t)(t + 1) * kstep;
;             const char* a2 = last ? nA : cA + (size_t)(t + 2) * kstep; const char* b2 = last ? nB : cB + (size_t)(t + 2) * kstep;
;             const char* a3 = a2 + kstep; const char* b3 = b2 + kstep;
;             if (last && has_next) S.a_ready(nxt);
;             if constexpr (SP2) {
;             PG8_LDB(B0, 0, 0); PG8_LDB(B1, 0, 1); PG8_SCHED; PG8_LDA(At, 0, 0); PG8_STAGE(PG8_SA(1, 1), a1 + hstep, voffA);
;             PG8_WAIT_V(8); PG8_WAIT_L(0); PG8_BAR; PG8_MMA(0, 0, At, B0); PG8_MMA(0, 1, At, B1); PG8_BAR; PG8_SCHED;
;             PG8_LDA(At, 0, 1); PG8_STAGE(PG8_SB(0, 0), b2, voffB); PG8_STAGE(PG8_SB(0, 1), b2 + hstep, voffB); PG8_STAGE(PG8_SA(0, 0), a2, voffA);
;             PG8_WAIT_V(8); PG8_WAIT_L(0); PG8_BAR; PG8_MMA(1, 0, At, B0); PG8_MMA(1, 1, At, B1); PG8_BAR; PG8_SCHED;
;             PG8_LDB(B0, 1, 0); PG8_LDB(B1, 1, 1); PG8_SCHED; PG8_LDA(At, 1, 0); PG8_STAGE(PG8_SA(0, 1), a2 + hstep, voffA);
;             PG8_WAIT_V(8); PG8_WAIT_L(0); PG8_BAR; PG8_MMA(0, 0, At, B0); PG8_MMA(0, 1, At, B1); PG8_BAR; PG8_SCHED;
;             PG8_LDA(At, 1, 1); PG8_STAGE(PG8_SB(1, 0), b3, voffB); PG8_STAGE(PG8_SB(1, 1), b3 + hstep, voffB); PG8_STAGE(PG8_SA(1, 0), a3, voffA);
;             PG8_WAIT_V(8); PG8_WAIT_L(0); PG8_BAR; PG8_MMA(1, 0, At, B0); PG8_MMA(1, 1, At, B1); PG8_BAR; PG8_SCHED;
	v_mfma_f32_16x16x32_bf16 v[64:67], v[180:183], v[232:235], v[64:67]
	v_mfma_f32_16x16x32_bf16 v[64:67], v[184:187], v[236:239], v[64:67]
	v_mfma_f32_16x16x32_bf16 v[68:71], v[176:179], v[236:239], v[68:71]
	v_mfma_f32_16x16x32_bf16 v[68:71], v[172:175], v[232:235], v[68:71]
	s_setprio 0
	s_add_i32 s44, s44, s60
	v_lshl_add_u64 v[138:139], v[138:139], 0, s[16:17]
	s_mov_b32 m0, s44
	ds_read_b128 v[208:211], v145 offset:49152
	ds_read_b128 v[212:215], v145 offset:50176
	ds_read_b128 v[216:219], v145 offset:51200
	ds_read_b128 v[220:223], v145 offset:52224
	ds_read_b128 v[224:227], v145 offset:53248
	ds_read_b128 v[228:231], v145 offset:54272
	ds_read_b128 v[232:235], v145 offset:55296
	ds_read_b128 v[236:239], v145 offset:56320
	global_load_lds_dwordx4 v[138:139], off
	s_add_i32 m0, s44, 0x2000
	s_add_u32 s48, s48, 0x160080
	v_lshl_add_u64 v[138:139], v[158:159], 0, s[16:17]
	s_addc_u32 s49, s49, 0
	s_add_i32 s44, s45, s60
	global_load_lds_dwordx4 v[138:139], off
	v_lshl_add_u64 v[138:139], s[48:49], 0, v[160:161]
	s_mov_b32 m0, s44
	s_nop 0
	global_load_lds_dwordx4 v[138:139], off
	v_lshl_add_u64 v[138:139], s[48:49], 0, v[162:163]
	s_add_i32 m0, s44, 0x2000
	s_nop 0
	global_load_lds_dwordx4 v[138:139], off
	v_lshl_add_u64 v[138:139], v[188:189], 0, s[16:17]
	s_mov_b32 m0, s65
	s_nop 0
	global_load_lds_dwordx4 v[138:139], off
	v_lshl_add_u64 v[138:139], v[200:201], 0, s[16:17]
	s_mov_b32 m0, s66
	s_nop 0
	global_load_lds_dwordx4 v[138:139], off
	s_waitcnt vmcnt(8)
	s_waitcnt lgkmcnt(0)
	s_barrier
	s_setprio 1
	s_waitcnt lgkmcnt(0)
	v_mfma_f32_16x16x32_bf16 v[60:63], v[134:137], v[208:211], v[60:63]
	v_mfma_f32_16x16x32_bf16 v[60:63], v[146:149], v[212:215], v[60:63]
	v_mfma_f32_16x16x32_bf16 v[56:59], v[154:157], v[212:215], v[56:59]
	v_mfma_f32_16x16x32_bf16 v[56:59], v[150:153], v[208:211], v[56:59]
	v_mfma_f32_16x16x32_bf16 v[48:51], v[150:153], v[216:219], v[48:51]
	v_mfma_f32_16x16x32_bf16 v[48:51], v[154:157], v[220:223], v[48:51]
	v_mfma_f32_16x16x32_bf16 v[52:55], v[146:149], v[220:223], v[52:55]
	v_mfma_f32_16x16x32_bf16 v[52:55], v[134:137], v[216:219], v[52:55]
	v_mfma_f32_16x16x32_bf16 v[28:31], v[134:137], v[224:227], v[28:31]
	v_mfma_f32_16x16x32_bf16 v[28:31], v[146:149], v[228:231], v[28:31]
	v_mfma_f32_16x16x32_bf16 v[24:27], v[154:157], v[228:231], v[24:27]
	v_mfma_f32_16x16x32_bf16 v[24:27], v[150:153], v[224:227], v[24:27]
	v_mfma_f32_16x16x32_bf16 v[16:19], v[150:153], v[232:235], v[16:19]
	v_mfma_f32_16x16x32_bf16 v[16:19], v[154:157], v[236:239], v[16:19]
	v_mfma_f32_16x16x32_bf16 v[20:23], v[146:149], v[236:239], v[20:23]
	v_mfma_f32_16x16x32_bf16 v[20:23], v[134:137], v[232:235], v[20:23]
	s_setprio 0
	s_setprio 1
	v_mfma_f32_16x16x32_bf16 v[44:47], v[172:175], v[208:211], v[44:47]
	v_mfma_f32_16x16x32_bf16 v[44:47], v[176:179], v[212:215], v[44:47]
	v_mfma_f32_16x16x32_bf16 v[40:43], v[184:187], v[212:215], v[40:43]
	v_mfma_f32_16x16x32_bf16 v[40:43], v[180:183], v[208:211], v[40:43]
	v_mfma_f32_16x16x32_bf16 v[32:35], v[180:183], v[216:219], v[32:35]
	v_mfma_f32_16x16x32_bf16 v[32:35], v[184:187], v[220:223], v[32:35]
	v_mfma_f32_16x16x32_bf16 v[36:39], v[176:179], v[220:223], v[36:39]
	v_mfma_f32_16x16x32_bf16 v[36:39], v[172:175], v[216:219], v[36:39]
	v_mfma_f32_16x16x32_bf16 v[12:15], v[172:175], v[224:227], v[12:15]
	v_mfma_f32_16x16x32_bf16 v[12:15], v[176:179], v[228:231], v[12:15]
	v_mfma_f32_16x16x32_bf16 v[8:11], v[184:187], v[228:231], v[8:11]
	v_mfma_f32_16x16x32_bf16 v[8:11], v[180:183], v[224:227], v[8:11]
	s_setprio 2
	s_barrier
	v_mfma_f32_16x16x32_bf16 v[0:3], v[180:183], v[232:235], v[0:3]
	v_mfma_f32_16x16x32_bf16 v[0:3], v[184:187], v[236:239], v[0:3]
	v_mfma_f32_16x16x32_bf16 v[4:7], v[176:179], v[236:239], v[4:7]
	v_mfma_f32_16x16x32_bf16 v[4:7], v[172:175], v[232:235], v[4:7]
	s_setprio 0
	s_add_i32 s75, s75, 2
	s_add_u32 s42, s42, 0x100
	s_addc_u32 s43, s43, 0
	s_add_u32 s34, s34, 0x100
	s_addc_u32 s35, s35, 0
	s_cmpk_gt_u32 s75, 0x55
	s_cbranch_scc0 .LBB0_837
	s_and_b64 vcc, exec, s[18:19]
	s_cbranch_vccz .LBB0_840
	s_barrier

; #define PG8_STAGE(bufoff, gbase, voff) do { _Pragma("unroll") for (int _i = 0; _i < 2; ++_i) \
;         __builtin_amdgcn_global_load_lds((const unsigned*)((const char*)(gbase) + (voff)[_i]), (PG8_LAS unsigned*)(lds + (bufoff) + ldsw + _i * 8192), 16, 0, 0); } while (0)
; #define PG8_LDA(dst, b, h) do { _Pragma("unroll") for (int m = 0; m < 4; ++m) _Pragma("unroll") for (int k = 0; k < 2; ++k) dst[m][k] = *(const PG8_LAS bf16x8*)(lds + PG8_SA(b, h) + aoff + m * 2048 + k * 1024); } while (0)
; #define PG8_LDB(dst, b, h) do { _Pragma("unroll") for (int n = 0; n < 2; ++n) _Pragma("unroll") for (int k = 0; k < 2; ++k) dst[n][k] = *(const PG8_LAS bf16x8*)(lds + PG8_SB(b, h) + boff + n * 2048 + k * 1024); } while (0)
; #define PG8_BAR __builtin_amdgcn_s_barrier()
; template <class Epi, class Sched, bool ALIGN_EPI = false, bool SP2 = false>
; __device__ __forceinline__ void gemm_phase(PG8_LAS unsigned char* lds, const Gemm g, const Sched& S, const Epi& E) {
;     ...
;             const bool last = (t == nt - 2);
;             const char* a1 = cA + (size_t)(t + 1) * kstep;
;             const char* a2 = last ? nA : cA + (size_t)(t + 2) * kstep; const char* b2 = last ? nB : cB + (size_t)(t + 2) * kstep;
;             const char* a3 = a2 + kstep; const char* b3 = b2 + kstep;
;             if (last && has_next) S.a_ready(nxt);
;             if constexpr (SP2) {
;             PG8_LDB(B0, 0, 0); PG8_LDB(B1, 0, 1); PG8_SCHED; PG8_LDA(At, 0, 0); PG8_STAGE(PG8_SA(1, 1), a1 + hstep, voffA);
;             PG8_WAIT_V(8); PG8_WAIT_L(0); PG8_BAR; PG8_MMA(0, 0, At, B0); PG8_MMA(0, 1, At, B1); PG8_BAR; PG8_SCHED;
;             PG8_LDA(At, 0, 1); PG8_STAGE(PG8_SB(0, 0), b2, voffB); PG8_STAGE(PG8_SB(0, 1), b2 + hstep, voffB); PG8_STAGE(PG8_SA(0, 0), a2, voffA);
;             PG8_WAIT_V(8); PG8_WAIT_L(0); PG8_BAR; PG8_MMA(1, 0, At, B0); PG8_MMA(1, 1, At, B1); PG8_BAR; PG8_SCHED;
;             PG8_LDB(B0, 1, 0); PG8_LDB(B1, 1, 1); PG8_SCHED; PG8_LDA(At, 1, 0); PG8_STAGE(PG8_SA(0, 1), a2 + hstep, voffA);
;             PG8_WAIT_V(8); PG8_WAIT_L(0); PG8_BAR; PG8_MMA(0, 0, At, B0); PG8_MMA(0, 1, At, B1); PG8_BAR; PG8_SCHED;
;             PG8_LDA(At, 1, 1); PG8_STAGE(PG8_SB(1, 0), b3, voffB); PG8_STAGE(PG8_SB(1, 1), b3 + hstep, voffB); PG8_STAGE(PG8_SA(1, 0), a3, voffA);
;             PG8_WAIT_V(8); PG8_WAIT_L(0); PG8_BAR; PG8_MMA(1, 0, At, B0); PG8_MMA(1, 1, At, B1); PG8_BAR; PG8_SCHED;
.LBB0_880:
	ds_read_b128 v[136:139], v156
	ds_read_b128 v[140:143], v156 offset:1024
	ds_read_b128 v[172:175], v156 offset:2048
	ds_read_b128 v[176:179], v156 offset:3072
	ds_read_b128 v[180:183], v157
	ds_read_b128 v[184:187], v157 offset:1024
	ds_read_b128 v[196:199], v157 offset:2048
	ds_read_b128 v[208:211], v157 offset:3072
	s_add_u32 s40, s38, 0xfff80080
	s_addc_u32 s41, s39, -1
	s_cmp_eq_u32 s63, 28
	s_cselect_b32 s43, s19, s41
	s_cselect_b32 s42, s34, s40
	s_cselect_b32 s41, s21, s62
	s_cselect_b32 s40, s35, s61
	v_lshl_add_u64 v[188:189], s[38:39], 0, v[128:129]
	s_add_i32 m0, s7, 0xc000
	ds_read_b128 v[212:215], v158
	ds_read_b128 v[216:219], v158 offset:1024
	ds_read_b128 v[220:223], v158 offset:2048
	ds_read_b128 v[224:227], v158 offset:3072
	ds_read_b128 v[228:231], v158 offset:4096
	ds_read_b128 v[232:235], v158 offset:5120
	ds_read_b128 v[236:239], v158 offset:6144
	ds_read_b128 v[240:243], v158 offset:7168
	global_load_lds_dwordx4 v[188:189], off
	v_lshl_add_u64 v[188:189], s[38:39], 0, v[130:131]
	s_add_i32 m0, s7, 0xe000
	s_nop 0
	global_load_lds_dwordx4 v[188:189], off
	s_waitcnt vmcnt(8)
	s_waitcnt lgkmcnt(0)
	s_barrier
	s_setprio 1
	s_waitcnt lgkmcnt(0)
	v_mfma_f32_16x16x32_bf16 v[124:127], v[136:139], v[212:215], v[124:127]
	v_mfma_f32_16x16x32_bf16 v[124:127], v[140:143], v[216:219], v[124:127]
	v_mfma_f32_16x16x32_bf16 v[120:123], v[176:179], v[216:219], v[120:123]
	v_mfma_f32_16x16x32_bf16 v[120:123], v[172:175], v[212:215], v[120:123]
	v_mfma_f32_16x16x32_bf16 v[104:107], v[172:175], v[220:223], v[104:107]
	v_mfma_f32_16x16x32_bf16 v[104:107], v[176:179], v[224:227], v[104:107]
	v_mfma_f32_16x16x32_bf16 v[108:111], v[140:143], v[224:227], v[108:111]
	v_mfma_f32_16x16x32_bf16 v[108:111], v[136:139], v[220:223], v[108:111]
	v_mfma_f32_16x16x32_bf16 v[96:99], v[136:139], v[228:231], v[96:99]
	v_mfma_f32_16x16x32_bf16 v[96:99], v[140:143], v[232:235], v[96:99]
	v_mfma_f32_16x16x32_bf16 v[88:91], v[176:179], v[232:235], v[88:91]
	v_mfma_f32_16x16x32_bf16 v[88:91], v[172:175], v[228:231], v[88:91]
	v_mfma_f32_16x16x32_bf16 v[72:75], v[172:175], v[236:239], v[72:75]
	v_mfma_f32_16x16x32_bf16 v[72:75], v[176:179], v[240:243], v[72:75]
	v_mfma_f32_16x16x32_bf16 v[80:83], v[140:143], v[240:243], v[80:83]
	v_mfma_f32_16x16x32_bf16 v[80:83], v[136:139], v[236:239], v[80:83]
	s_setprio 0
	s_setprio 1
	v_mfma_f32_16x16x32_bf16 v[116:119], v[180:183], v[212:215], v[116:119]
	v_mfma_f32_16x16x32_bf16 v[116:119], v[184:187], v[216:219], v[116:119]
	v_mfma_f32_16x16x32_bf16 v[112:115], v[208:211], v[216:219], v[112:115]
	v_mfma_f32_16x16x32_bf16 v[112:115], v[196:199], v[212:215], v[112:115]
	v_mfma_f32_16x16x32_bf16 v[92:95], v[196:199], v[220:223], v[92:95]
	v_mfma_f32_16x16x32_bf16 v[92:95], v[208:211], v[224:227], v[92:95]
	v_mfma_f32_16x16x32_bf16 v[100:103], v[184:187], v[224:227], v[100:103]
	v_mfma_f32_16x16x32_bf16 v[100:103], v[180:183], v[220:223], v[100:103]
	v_mfma_f32_16x16x32_bf16 v[84:87], v[180:183], v[228:231], v[84:87]
	v_mfma_f32_16x16x32_bf16 v[84:87], v[184:187], v[232:235], v[84:87]
	v_mfma_f32_16x16x32_bf16 v[76:79], v[208:211], v[232:235], v[76:79]
	v_mfma_f32_16x16x32_bf16 v[76:79], v[196:199], v[228:231], v[76:79]
	s_setprio 2
	s_barrier
	v_mfma_f32_16x16x32_bf16 v[64:67], v[196:199], v[236:239], v[64:67]
	v_mfma_f32_16x16x32_bf16 v[64:67], v[208:211], v[240:243], v[64:67]
	v_mfma_f32_16x16x32_bf16 v[68:71], v[184:187], v[240:243], v[68:71]
	v_mfma_f32_16x16x32_bf16 v[68:71], v[180:183], v[236:239], v[68:71]
	s_setprio 0
	s_add_i32 s44, s52, s33
	v_lshl_add_u64 v[188:189], s[40:41], 0, v[166:167]
	s_mov_b32 m0, s44
	ds_read_b128 v[212:215], v158 offset:16384
	ds_read_b128 v[216:219], v158 offset:17408
	ds_read_b128 v[220:223], v158 offset:18432
	ds_read_b128 v[224:227], v158 offset:19456
	ds_read_b128 v[228:231], v158 offset:20480
	ds_read_b128 v[232:235], v158 offset:21504
	ds_read_b128 v[236:239], v158 offset:22528
	ds_read_b128 v[240:243], v158 offset:23552
	global_load_lds_dwordx4 v[188:189], off
	s_add_i32 m0, s44, 0x2000
	s_add_u32 s64, s40, 0x80000
	v_lshl_add_u64 v[200:201], s[40:41], 0, v[170:171]
	s_addc_u32 s65, s41, 0
	s_add_i32 s44, s53, s33
	global_load_lds_dwordx4 v[200:201], off
	v_lshl_add_u64 v[244:245], s[64:65], 0, v[166:167]
	s_mov_b32 m0, s44
	v_lshl_add_u64 v[246:247], s[42:43], 0, v[168:169]
	global_load_lds_dwordx4 v[244:245], off
	v_lshl_add_u64 v[244:245], s[64:65], 0, v[170:171]
	s_add_i32 m0, s44, 0x2000
	s_nop 0
	global_load_lds_dwordx4 v[244:245], off
	v_lshl_add_u64 v[244:245], s[42:43], 0, v[164:165]
	s_mov_b32 m0, s7
	s_nop 0
	global_load_lds_dwordx4 v[244:245], off
	s_mov_b32 m0, s37
	s_nop 0
	global_load_lds_dwordx4 v[246:247], off
	s_waitcnt vmcnt(8)
	s_waitcnt lgkmcnt(0)
	s_barrier
; #define PG8_STAGE(bufoff, gbase, voff) do { _Pragma("unroll") for (int _i = 0; _i < 2; ++_i) \
;         __builtin_amdgcn_global_load_lds((const unsigned*)((const char*)(gbase) + (voff)[_i]), (PG8_LAS unsigned*)(lds + (bufoff) + ldsw + _i * 8192), 16, 0, 0); } while (0)
; #define PG8_LDA(dst, b, h) do { _Pragma("unroll") for (int m = 0; m < 4; ++m) _Pragma("unroll") for (int k = 0; k < 2; ++k) dst[m][k] = *(const PG8_LAS bf16x8*)(lds + PG8_SA(b, h) + aoff + m * 2048 + k * 1024); } while (0)
; #define PG8_LDB(dst, b, h) do { _Pragma("unroll") for (int n = 0; n < 2; ++n) _Pragma("unroll") for (int k = 0; k < 2; ++k) dst[n][k] = *(const PG8_LAS bf16x8*)(lds + PG8_SB(b, h) + boff + n * 2048 + k * 1024); } while (0)
; #define PG8_MMA(ai, bj, At, Bt) do { __builtin_amdgcn_s_setprio(1); _Pragma("unroll") for (int m = 0; m < 4; ++m) _Pragma("unroll") for (int n = 0; n < 2; ++n) _Pragma("unroll") for (int k = 0; k < 2; ++k) \
;         acc[ai][bj][m][n] = __builtin_amdgcn_mfma_f32_16x16x32_bf16(Bt[n][k], At[m][k], acc[ai][bj][m][n], 0, 0, 0); __builtin_amdgcn_s_setprio(0); } while (0)
; #define PG8_WAIT_V(n) asm volatile("s_waitcnt vmcnt(" #n ")" ::: "memory")
; template <class Epi, class Sched, bool ALIGN_EPI = false, bool SP2 = false>
; __device__ __forceinline__ void gemm_phase(PG8_LAS unsigned char* lds, const Gemm g, const Sched& S, const Epi& E) {
;     ...
;             PG8_LDB(B0, 0, 0); PG8_LDB(B1, 0, 1); PG8_SCHED; PG8_LDA(At, 0, 0); PG8_STAGE(PG8_SA(1, 1), a1 + hstep, voffA);
;             PG8_WAIT_V(8); PG8_WAIT_L(0); PG8_BAR; PG8_MMA(0, 0, At, B0); PG8_MMA(0, 1, At, B1); PG8_BAR; PG8_SCHED;
;             PG8_LDA(At, 0, 1); PG8_STAGE(PG8_SB(0, 0), b2, voffB); PG8_STAGE(PG8_SB(0, 1), b2 + hstep, voffB); PG8_STAGE(PG8_SA(0, 0), a2, voffA);
;             PG8_WAIT_V(8); PG8_WAIT_L(0); PG8_BAR; PG8_MMA(1, 0, At, B0); PG8_MMA(1, 1, At, B1); PG8_BAR; PG8_SCHED;
;             PG8_LDB(B0, 1, 0); PG8_LDB(B1, 1, 1); PG8_SCHED; PG8_LDA(At, 1, 0); PG8_STAGE(PG8_SA(0, 1), a2 + hstep, voffA);
;             PG8_WAIT_V(8); PG8_WAIT_L(0); PG8_BAR; PG8_MMA(0, 0, At, B0); PG8_MMA(0, 1, At, B1); PG8_BAR; PG8_SCHED;
;             PG8_LDA(At, 1, 1); PG8_STAGE(PG8_SB(1, 0), b3, voffB); PG8_STAGE(PG8_SB(1, 1), b3 + hstep, voffB); PG8_STAGE(PG8_SA(1, 0), a3, voffA);
;             PG8_WAIT_V(8); PG8_WAIT_L(0); PG8_BAR; PG8_MMA(1, 0, At, B0); PG8_MMA(1, 1, At, B1); PG8_BAR; PG8_SCHED;
	s_setprio 1
	s_waitcnt lgkmcnt(0)
	v_mfma_f32_16x16x32_bf16 v[60:63], v[136:139], v[212:215], v[60:63]
	v_mfma_f32_16x16x32_bf16 v[60:63], v[140:143], v[216:219], v[60:63]
	v_mfma_f32_16x16x32_bf16 v[56:59], v[176:179], v[216:219], v[56:59]
	v_mfma_f32_16x16x32_bf16 v[56:59], v[172:175], v[212:215], v[56:59]
	v_mfma_f32_16x16x32_bf16 v[40:43], v[172:175], v[220:223], v[40:43]
	v_mfma_f32_16x16x32_bf16 v[40:43], v[176:179], v[224:227], v[40:43]
	v_mfma_f32_16x16x32_bf16 v[48:51], v[140:143], v[224:227], v[48:51]
	v_mfma_f32_16x16x32_bf16 v[48:51], v[136:139], v[220:223], v[48:51]
	v_mfma_f32_16x16x32_bf16 v[32:35], v[136:139], v[228:231], v[32:35]
	v_mfma_f32_16x16x32_bf16 v[32:35], v[140:143], v[232:235], v[32:35]
	v_mfma_f32_16x16x32_bf16 v[24:27], v[176:179], v[232:235], v[24:27]
	v_mfma_f32_16x16x32_bf16 v[24:27], v[172:175], v[228:231], v[24:27]
	v_mfma_f32_16x16x32_bf16 v[8:11], v[172:175], v[236:239], v[8:11]
	v_mfma_f32_16x16x32_bf16 v[8:11], v[176:179], v[240:243], v[8:11]
	v_mfma_f32_16x16x32_bf16 v[12:15], v[140:143], v[240:243], v[12:15]
	v_mfma_f32_16x16x32_bf16 v[12:15], v[136:139], v[236:239], v[12:15]
	s_setprio 0
	s_setprio 1
	v_mfma_f32_16x16x32_bf16 v[52:55], v[180:183], v[212:215], v[52:55]
	v_mfma_f32_16x16x32_bf16 v[52:55], v[184:187], v[216:219], v[52:55]
	v_mfma_f32_16x16x32_bf16 v[44:47], v[208:211], v[216:219], v[44:47]
	v_mfma_f32_16x16x32_bf16 v[44:47], v[196:199], v[212:215], v[44:47]
	v_mfma_f32_16x16x32_bf16 v[28:31], v[196:199], v[220:223], v[28:31]
	v_mfma_f32_16x16x32_bf16 v[28:31], v[208:211], v[224:227], v[28:31]
	v_mfma_f32_16x16x32_bf16 v[36:39], v[184:187], v[224:227], v[36:39]
	v_mfma_f32_16x16x32_bf16 v[36:39], v[180:183], v[220:223], v[36:39]
	v_mfma_f32_16x16x32_bf16 v[20:23], v[180:183], v[228:231], v[20:23]
	v_mfma_f32_16x16x32_bf16 v[20:23], v[184:187], v[232:235], v[20:23]
	v_mfma_f32_16x16x32_bf16 v[16:19], v[208:211], v[232:235], v[16:19]
	v_mfma_f32_16x16x32_bf16 v[16:19], v[196:199], v[228:231], v[16:19]
	s_setprio 2
	s_barrier
	v_mfma_f32_16x16x32_bf16 v[0:3], v[196:199], v[236:239], v[0:3]
	v_mfma_f32_16x16x32_bf16 v[0:3], v[208:211], v[240:243], v[0:3]
	v_mfma_f32_16x16x32_bf16 v[4:7], v[184:187], v[240:243], v[4:7]
	v_mfma_f32_16x16x32_bf16 v[4:7], v[180:183], v[236:239], v[4:7]
	s_setprio 0
	s_add_i32 s44, 0, 0x18000
	v_add_u32_e32 v144, s44, v146
	s_add_i32 s45, 0, 0x1c000
	ds_read_b128 v[136:139], v144
	ds_read_b128 v[140:143], v144 offset:1024
	ds_read_b128 v[172:175], v144 offset:2048
	ds_read_b128 v[176:179], v144 offset:3072
	v_add_u32_e32 v144, s45, v146
	ds_read_b128 v[180:183], v144
	ds_read_b128 v[184:187], v144 offset:1024
	ds_read_b128 v[196:199], v144 offset:2048
	ds_read_b128 v[208:211], v144 offset:3072
	s_add_u32 s42, s42, 0x80000
	s_addc_u32 s43, s43, 0
	s_mov_b32 m0, s48
	v_lshl_add_u64 v[248:249], s[42:43], 0, v[164:165]
	ds_read_b128 v[212:215], v158 offset:32768
	ds_read_b128 v[216:219], v158 offset:33792
	ds_read_b128 v[220:223], v158 offset:34816
	ds_read_b128 v[224:227], v158 offset:35840
	ds_read_b128 v[228:231], v158 offset:36864
	ds_read_b128 v[232:235], v158 offset:37888
	ds_read_b128 v[236:239], v158 offset:38912
	ds_read_b128 v[240:243], v158 offset:39936
	global_load_lds_dwordx4 v[248:249], off
	v_lshl_add_u64 v[248:249], s[42:43], 0, v[168:169]
	s_mov_b32 m0, s49
	s_nop 0
	global_load_lds_dwordx4 v[248:249], off
	s_waitcnt vmcnt(8)
	s_waitcnt lgkmcnt(0)
	s_barrier
	s_setprio 1
	s_waitcnt lgkmcnt(0)
	v_mfma_f32_16x16x32_bf16 v[124:127], v[136:139], v[212:215], v[124:127]
	v_mfma_f32_16x16x32_bf16 v[124:127], v[140:143], v[216:219], v[124:127]
	v_mfma_f32_16x16x32_bf16 v[120:123], v[176:179], v[216:219], v[120:123]
	v_mfma_f32_16x16x32_bf16 v[120:123], v[172:175], v[212:215], v[120:123]
	v_mfma_f32_16x16x32_bf16 v[104:107], v[172:175], v[220:223], v[104:107]
	v_mfma_f32_16x16x32_bf16 v[104:107], v[176:179], v[224:227], v[104:107]
	v_mfma_f32_16x16x32_bf16 v[108:111], v[140:143], v[224:227], v[108:111]
	v_mfma_f32_16x16x32_bf16 v[108:111], v[136:139], v[220:223], v[108:111]
	v_mfma_f32_16x16x32_bf16 v[96:99], v[136:139], v[228:231], v[96:99]
	v_mfma_f32_16x16x32_bf16 v[96:99], v[140:143], v[232:235], v[96:99]
	v_mfma_f32_16x16x32_bf16 v[88:91], v[176:179], v[232:235], v[88:91]
	v_mfma_f32_16x16x32_bf16 v[88:91], v[172:175], v[228:231], v[88:91]
	v_mfma_f32_16x16x32_bf16 v[72:75], v[172:175], v[236:239], v[72:75]
	v_mfma_f32_16x16x32_bf16 v[72:75], v[176:179], v[240:243], v[72:75]
	v_mfma_f32_16x16x32_bf16 v[80:83], v[140:143], v[240:243], v[80:83]
	v_mfma_f32_16x16x32_bf16 v[80:83], v[136:139], v[236:239], v[80:83]
	s_setprio 0
	s_setprio 1
	v_mfma_f32_16x16x32_bf16 v[116:119], v[180:183], v[212:215], v[116:119]
	v_mfma_f32_16x16x32_bf16 v[116:119], v[184:187], v[216:219], v[116:119]
	v_mfma_f32_16x16x32_bf16 v[112:115], v[208:211], v[216:219], v[112:115]
	v_mfma_f32_16x16x32_bf16 v[112:115], v[196:199], v[212:215], v[112:115]
	v_mfma_f32_16x16x32_bf16 v[92:95], v[196:199], v[220:223], v[92:95]
	v_mfma_f32_16x16x32_bf16 v[92:95], v[208:211], v[224:227], v[92:95]
	v_mfma_f32_16x16x32_bf16 v[100:103], v[184:187], v[224:227], v[100:103]
	v_mfma_f32_16x16x32_bf16 v[100:103], v[180:183], v[220:223], v[100:103]
	v_mfma_f32_16x16x32_bf16 v[84:87], v[180:183], v[228:231], v[84:87]
	v_mfma_f32_16x16x32_bf16 v[84:87], v[184:187], v[232:235], v[84:87]
	v_mfma_f32_16x16x32_bf16 v[76:79], v[208:211], v[232:235], v[76:79]
	v_mfma_f32_16x16x32_bf16 v[76:79], v[196:199], v[228:231], v[76:79]
	s_setprio 2
	s_barrier
; #define PG8_STAGE(bufoff, gbase, voff) do { _Pragma("unroll") for (int _i = 0; _i < 2; ++_i) \
;         __builtin_amdgcn_global_load_lds((const unsigned*)((const char*)(gbase) + (voff)[_i]), (PG8_LAS unsigned*)(lds + (bufoff) + ldsw + _i * 8192), 16, 0, 0); } while (0)
; #define PG8_LDA(dst, b, h) do { _Pragma("unroll") for (int m = 0; m < 4; ++m) _Pragma("unroll") for (int k = 0; k < 2; ++k) dst[m][k] = *(const PG8_LAS bf16x8*)(lds + PG8_SA(b, h) + aoff + m * 2048 + k * 1024); } while (0)
; #define PG8_LDB(dst, b, h) do { _Pragma("unroll") for (int n = 0; n < 2; ++n) _Pragma("unroll") for (int k = 0; k < 2; ++k) dst[n][k] = *(const PG8_LAS bf16x8*)(lds + PG8_SB(b, h) + boff + n * 2048 + k * 1024); } while (0)
; template <class Epi, class Sched, bool ALIGN_EPI = false, bool SP2 = false>
; __device__ __forceinline__ void gemm_phase(PG8_LAS unsigned char* lds, const Gemm g, const Sched& S, const Epi& E) {
;     ...
;         for (int t = 0; t < nt; t += 2) {
;             const bool last = (t == nt - 2);
;             const char* a1 = cA + (size_t)(t + 1) * kstep;
;             const char* a2 = last ? nA : cA + (size_t)(t + 2) * kstep; const char* b2 = last ? nB : cB + (size_t)(t + 2) * kstep;
;             const char* a3 = a2 + kstep; const char* b3 = b2 + kstep;
;             if (last && has_next) S.a_ready(nxt);
;             if constexpr (SP2) {
;             PG8_LDB(B0, 0, 0); PG8_LDB(B1, 0, 1); PG8_SCHED; PG8_LDA(At, 0, 0); PG8_STAGE(PG8_SA(1, 1), a1 + hstep, voffA);
;             PG8_WAIT_V(8); PG8_WAIT_L(0); PG8_BAR; PG8_MMA(0, 0, At, B0); PG8_MMA(0, 1, At, B1); PG8_BAR; PG8_SCHED;
;             PG8_LDA(At, 0, 1); PG8_STAGE(PG8_SB(0, 0), b2, voffB); PG8_STAGE(PG8_SB(0, 1), b2 + hstep, voffB); PG8_STAGE(PG8_SA(0, 0), a2, voffA);
;             PG8_WAIT_V(8); PG8_WAIT_L(0); PG8_BAR; PG8_MMA(1, 0, At, B0); PG8_MMA(1, 1, At, B1); PG8_BAR; PG8_SCHED;
;             PG8_LDB(B0, 1, 0); PG8_LDB(B1, 1, 1); PG8_SCHED; PG8_LDA(At, 1, 0); PG8_STAGE(PG8_SA(0, 1), a2 + hstep, voffA);
;             PG8_WAIT_V(8); PG8_WAIT_L(0); PG8_BAR; PG8_MMA(0, 0, At, B0); PG8_MMA(0, 1, At, B1); PG8_BAR; PG8_SCHED;
;             PG8_LDA(At, 1, 1); PG8_STAGE(PG8_SB(1, 0), b3, voffB); PG8_STAGE(PG8_SB(1, 1), b3 + hstep, voffB); PG8_STAGE(PG8_SA(1, 0), a3, voffA);
;             PG8_WAIT_V(8); PG8_WAIT_L(0); PG8_BAR; PG8_MMA(1, 0, At, B0); PG8_MMA(1, 1, At, B1); PG8_BAR; PG8_SCHED;
	v_mfma_f32_16x16x32_bf16 v[64:67], v[196:199], v[236:239], v[64:67]
	v_mfma_f32_16x16x32_bf16 v[64:67], v[208:211], v[240:243], v[64:67]
	v_mfma_f32_16x16x32_bf16 v[68:71], v[184:187], v[240:243], v[68:71]
	v_mfma_f32_16x16x32_bf16 v[68:71], v[180:183], v[236:239], v[68:71]
	s_setprio 0
	s_add_i32 s42, s44, s33
	v_lshl_add_u64 v[188:189], v[188:189], 0, s[14:15]
	s_mov_b32 m0, s42
	ds_read_b128 v[212:215], v158 offset:49152
	ds_read_b128 v[216:219], v158 offset:50176
	ds_read_b128 v[220:223], v158 offset:51200
	ds_read_b128 v[224:227], v158 offset:52224
	ds_read_b128 v[228:231], v158 offset:53248
	ds_read_b128 v[232:235], v158 offset:54272
	ds_read_b128 v[236:239], v158 offset:55296
	ds_read_b128 v[240:243], v158 offset:56320
	global_load_lds_dwordx4 v[188:189], off
	s_add_i32 m0, s42, 0x2000
	s_add_u32 s40, s40, 0x80080
	v_lshl_add_u64 v[188:189], v[200:201], 0, s[14:15]
	s_addc_u32 s41, s41, 0
	s_add_i32 s42, s45, s33
	global_load_lds_dwordx4 v[188:189], off
	v_lshl_add_u64 v[188:189], s[40:41], 0, v[166:167]
	s_mov_b32 m0, s42
	s_nop 0
	global_load_lds_dwordx4 v[188:189], off
	v_lshl_add_u64 v[188:189], s[40:41], 0, v[170:171]
	s_add_i32 m0, s42, 0x2000
	s_nop 0
	global_load_lds_dwordx4 v[188:189], off
	v_lshl_add_u64 v[188:189], v[244:245], 0, s[14:15]
	s_mov_b32 m0, s50
	s_nop 0
	global_load_lds_dwordx4 v[188:189], off
	v_lshl_add_u64 v[188:189], v[246:247], 0, s[14:15]
	s_mov_b32 m0, s51
	s_nop 0
	global_load_lds_dwordx4 v[188:189], off
	s_waitcnt vmcnt(8)
	s_waitcnt lgkmcnt(0)
	s_barrier
	s_setprio 1
	s_waitcnt lgkmcnt(0)
	v_mfma_f32_16x16x32_bf16 v[60:63], v[136:139], v[212:215], v[60:63]
	v_mfma_f32_16x16x32_bf16 v[60:63], v[140:143], v[216:219], v[60:63]
	v_mfma_f32_16x16x32_bf16 v[56:59], v[176:179], v[216:219], v[56:59]
	v_mfma_f32_16x16x32_bf16 v[56:59], v[172:175], v[212:215], v[56:59]
	v_mfma_f32_16x16x32_bf16 v[40:43], v[172:175], v[220:223], v[40:43]
	v_mfma_f32_16x16x32_bf16 v[40:43], v[176:179], v[224:227], v[40:43]
	v_mfma_f32_16x16x32_bf16 v[48:51], v[140:143], v[224:227], v[48:51]
	v_mfma_f32_16x16x32_bf16 v[48:51], v[136:139], v[220:223], v[48:51]
	v_mfma_f32_16x16x32_bf16 v[32:35], v[136:139], v[228:231], v[32:35]
	v_mfma_f32_16x16x32_bf16 v[32:35], v[140:143], v[232:235], v[32:35]
	v_mfma_f32_16x16x32_bf16 v[24:27], v[176:179], v[232:235], v[24:27]
	v_mfma_f32_16x16x32_bf16 v[24:27], v[172:175], v[228:231], v[24:27]
	v_mfma_f32_16x16x32_bf16 v[8:11], v[172:175], v[236:239], v[8:11]
	v_mfma_f32_16x16x32_bf16 v[8:11], v[176:179], v[240:243], v[8:11]
	v_mfma_f32_16x16x32_bf16 v[12:15], v[140:143], v[240:243], v[12:15]
	v_mfma_f32_16x16x32_bf16 v[12:15], v[136:139], v[236:239], v[12:15]
	s_setprio 0
	s_setprio 1
	v_mfma_f32_16x16x32_bf16 v[52:55], v[180:183], v[212:215], v[52:55]
	v_mfma_f32_16x16x32_bf16 v[52:55], v[184:187], v[216:219], v[52:55]
	v_mfma_f32_16x16x32_bf16 v[44:47], v[208:211], v[216:219], v[44:47]
	v_mfma_f32_16x16x32_bf16 v[44:47], v[196:199], v[212:215], v[44:47]
	v_mfma_f32_16x16x32_bf16 v[28:31], v[196:199], v[220:223], v[28:31]
	v_mfma_f32_16x16x32_bf16 v[28:31], v[208:211], v[224:227], v[28:31]
	v_mfma_f32_16x16x32_bf16 v[36:39], v[184:187], v[224:227], v[36:39]
	v_mfma_f32_16x16x32_bf16 v[36:39], v[180:183], v[220:223], v[36:39]
	v_mfma_f32_16x16x32_bf16 v[20:23], v[180:183], v[228:231], v[20:23]
	v_mfma_f32_16x16x32_bf16 v[20:23], v[184:187], v[232:235], v[20:23]
	v_mfma_f32_16x16x32_bf16 v[16:19], v[208:211], v[232:235], v[16:19]
	v_mfma_f32_16x16x32_bf16 v[16:19], v[196:199], v[228:231], v[16:19]
	s_setprio 2
	s_barrier
	v_mfma_f32_16x16x32_bf16 v[0:3], v[196:199], v[236:239], v[0:3]
	v_mfma_f32_16x16x32_bf16 v[0:3], v[208:211], v[240:243], v[0:3]
	v_mfma_f32_16x16x32_bf16 v[4:7], v[184:187], v[240:243], v[4:7]
	v_mfma_f32_16x16x32_bf16 v[4:7], v[180:183], v[236:239], v[4:7]
	s_setprio 0
	s_add_i32 s63, s63, 2
	s_add_u32 s38, s38, 0x100
	s_addc_u32 s39, s39, 0
	s_add_u32 s61, s61, 0x100
	s_addc_u32 s62, s62, 0
	s_cmp_gt_u32 s63, 29
	s_cbranch_scc0 .LBB0_880
	s_and_b64 vcc, exec, s[16:17]
	s_cbranch_vccz .LBB0_883
	s_barrier

; #define PG8_STAGE(bufoff, gbase, voff) do { _Pragma("unroll") for (int _i = 0; _i < 2; ++_i) \
;         __builtin_amdgcn_global_load_lds((const unsigned*)((const char*)(gbase) + (voff)[_i]), (PG8_LAS unsigned*)(lds + (bufoff) + ldsw + _i * 8192), 16, 0, 0); } while (0)
; #define PG8_LDA(dst, b, h) do { _Pragma("unroll") for (int m = 0; m < 4; ++m) _Pragma("unroll") for (int k = 0; k < 2; ++k) dst[m][k] = *(const PG8_LAS bf16x8*)(lds + PG8_SA(b, h) + aoff + m * 2048 + k * 1024); } while (0)
; #define PG8_LDB(dst, b, h) do { _Pragma("unroll") for (int n = 0; n < 2; ++n) _Pragma("unroll") for (int k = 0; k < 2; ++k) dst[n][k] = *(const PG8_LAS bf16x8*)(lds + PG8_SB(b, h) + boff + n * 2048 + k * 1024); } while (0)
; #define PG8_BAR __builtin_amdgcn_s_barrier()
; template <class Epi, class Sched, bool ALIGN_EPI = false, bool SP2 = false>
; __device__ __forceinline__ void gemm_phase(PG8_LAS unsigned char* lds, const Gemm g, const Sched& S, const Epi& E) {
;     ...
;             const bool last = (t == nt - 2);
;             const char* a1 = cA + (size_t)(t + 1) * kstep;
;             const char* a2 = last ? nA : cA + (size_t)(t + 2) * kstep; const char* b2 = last ? nB : cB + (size_t)(t + 2) * kstep;
;             const char* a3 = a2 + kstep; const char* b3 = b2 + kstep;
;             if (last && has_next) S.a_ready(nxt);
;             if constexpr (SP2) {
;             PG8_LDB(B0, 0, 0); PG8_LDB(B1, 0, 1); PG8_SCHED; PG8_LDA(At, 0, 0); PG8_STAGE(PG8_SA(1, 1), a1 + hstep, voffA);
;             PG8_WAIT_V(8); PG8_WAIT_L(0); PG8_BAR; PG8_MMA(0, 0, At, B0); PG8_MMA(0, 1, At, B1); PG8_BAR; PG8_SCHED;
;             PG8_LDA(At, 0, 1); PG8_STAGE(PG8_SB(0, 0), b2, voffB); PG8_STAGE(PG8_SB(0, 1), b2 + hstep, voffB); PG8_STAGE(PG8_SA(0, 0), a2, voffA);
;             PG8_WAIT_V(8); PG8_WAIT_L(0); PG8_BAR; PG8_MMA(1, 0, At, B0); PG8_MMA(1, 1, At, B1); PG8_BAR; PG8_SCHED;
;             PG8_LDB(B0, 1, 0); PG8_LDB(B1, 1, 1); PG8_SCHED; PG8_LDA(At, 1, 0); PG8_STAGE(PG8_SA(0, 1), a2 + hstep, voffA);
;             PG8_WAIT_V(8); PG8_WAIT_L(0); PG8_BAR; PG8_MMA(0, 0, At, B0); PG8_MMA(0, 1, At, B1); PG8_BAR; PG8_SCHED;
;             PG8_LDA(At, 1, 1); PG8_STAGE(PG8_SB(1, 0), b3, voffB); PG8_STAGE(PG8_SB(1, 1), b3 + hstep, voffB); PG8_STAGE(PG8_SA(1, 0), a3, voffA);
;             PG8_WAIT_V(8); PG8_WAIT_L(0); PG8_BAR; PG8_MMA(1, 0, At, B0); PG8_MMA(1, 1, At, B1); PG8_BAR; PG8_SCHED;
.LBB0_937:
	ds_read_b128 v[128:131], v199
	ds_read_b128 v[132:135], v199 offset:1024
	ds_read_b128 v[136:139], v199 offset:2048
	ds_read_b128 v[140:143], v199 offset:3072
	ds_read_b128 v[150:153], v200
	ds_read_b128 v[154:157], v200 offset:1024
	ds_read_b128 v[164:167], v200 offset:2048
	ds_read_b128 v[168:171], v200 offset:3072
	s_add_u32 s22, s20, 0xffea0080
	s_addc_u32 s23, s21, -1
	s_cmpk_eq_i32 s49, 0x54
	s_cselect_b32 s25, s17, s23
	s_cselect_b32 s24, s16, s22
	s_cselect_b32 s23, s19, s48
	s_cselect_b32 s22, s18, s47
	v_lshl_add_u64 v[158:159], s[20:21], 0, v[144:145]
	s_add_i32 m0, s31, 0xc000
	ds_read_b128 v[172:175], v201
	ds_read_b128 v[176:179], v201 offset:1024
	ds_read_b128 v[180:183], v201 offset:2048
	ds_read_b128 v[184:187], v201 offset:3072
	ds_read_b128 v[188:191], v201 offset:4096
	ds_read_b128 v[204:207], v201 offset:5120
	ds_read_b128 v[208:211], v201 offset:6144
	ds_read_b128 v[212:215], v201 offset:7168
	global_load_lds_dwordx4 v[158:159], off
	v_lshl_add_u64 v[158:159], s[20:21], 0, v[146:147]
	s_add_i32 m0, s31, 0xe000
	s_nop 0
	global_load_lds_dwordx4 v[158:159], off
	s_waitcnt vmcnt(8)
	s_waitcnt lgkmcnt(0)
	s_barrier
	s_setprio 1
	s_waitcnt lgkmcnt(0)
	v_mfma_f32_16x16x32_bf16 v[124:127], v[128:131], v[172:175], v[124:127]
	v_mfma_f32_16x16x32_bf16 v[124:127], v[132:135], v[176:179], v[124:127]
	v_mfma_f32_16x16x32_bf16 v[120:123], v[140:143], v[176:179], v[120:123]
	v_mfma_f32_16x16x32_bf16 v[120:123], v[136:139], v[172:175], v[120:123]
	v_mfma_f32_16x16x32_bf16 v[104:107], v[136:139], v[180:183], v[104:107]
	v_mfma_f32_16x16x32_bf16 v[104:107], v[140:143], v[184:187], v[104:107]
	v_mfma_f32_16x16x32_bf16 v[108:111], v[132:135], v[184:187], v[108:111]
	v_mfma_f32_16x16x32_bf16 v[108:111], v[128:131], v[180:183], v[108:111]
	v_mfma_f32_16x16x32_bf16 v[92:95], v[128:131], v[188:191], v[92:95]
	v_mfma_f32_16x16x32_bf16 v[92:95], v[132:135], v[204:207], v[92:95]
	v_mfma_f32_16x16x32_bf16 v[88:91], v[140:143], v[204:207], v[88:91]
	v_mfma_f32_16x16x32_bf16 v[88:91], v[136:139], v[188:191], v[88:91]
	v_mfma_f32_16x16x32_bf16 v[72:75], v[136:139], v[208:211], v[72:75]
	v_mfma_f32_16x16x32_bf16 v[72:75], v[140:143], v[212:215], v[72:75]
	v_mfma_f32_16x16x32_bf16 v[76:79], v[132:135], v[212:215], v[76:79]
	v_mfma_f32_16x16x32_bf16 v[76:79], v[128:131], v[208:211], v[76:79]
	s_setprio 0
	s_setprio 1
	v_mfma_f32_16x16x32_bf16 v[116:119], v[150:153], v[172:175], v[116:119]
	v_mfma_f32_16x16x32_bf16 v[116:119], v[154:157], v[176:179], v[116:119]
	v_mfma_f32_16x16x32_bf16 v[112:115], v[168:171], v[176:179], v[112:115]
	v_mfma_f32_16x16x32_bf16 v[112:115], v[164:167], v[172:175], v[112:115]
	v_mfma_f32_16x16x32_bf16 v[96:99], v[164:167], v[180:183], v[96:99]
	v_mfma_f32_16x16x32_bf16 v[96:99], v[168:171], v[184:187], v[96:99]
	v_mfma_f32_16x16x32_bf16 v[100:103], v[154:157], v[184:187], v[100:103]
	v_mfma_f32_16x16x32_bf16 v[100:103], v[150:153], v[180:183], v[100:103]
	v_mfma_f32_16x16x32_bf16 v[84:87], v[150:153], v[188:191], v[84:87]
	v_mfma_f32_16x16x32_bf16 v[84:87], v[154:157], v[204:207], v[84:87]
	v_mfma_f32_16x16x32_bf16 v[80:83], v[168:171], v[204:207], v[80:83]
	v_mfma_f32_16x16x32_bf16 v[80:83], v[164:167], v[188:191], v[80:83]
	s_setprio 2
	s_barrier
	v_mfma_f32_16x16x32_bf16 v[64:67], v[164:167], v[208:211], v[64:67]
	v_mfma_f32_16x16x32_bf16 v[64:67], v[168:171], v[212:215], v[64:67]
	v_mfma_f32_16x16x32_bf16 v[68:71], v[154:157], v[212:215], v[68:71]
	v_mfma_f32_16x16x32_bf16 v[68:71], v[150:153], v[208:211], v[68:71]
	s_setprio 0
	s_add_i32 s50, s41, s30
	v_lshl_add_u64 v[158:159], s[22:23], 0, v[160:161]
	s_mov_b32 m0, s50
	ds_read_b128 v[172:175], v201 offset:16384
	ds_read_b128 v[176:179], v201 offset:17408
	ds_read_b128 v[180:183], v201 offset:18432
	ds_read_b128 v[184:187], v201 offset:19456
	ds_read_b128 v[188:191], v201 offset:20480
	ds_read_b128 v[204:207], v201 offset:21504
	ds_read_b128 v[208:211], v201 offset:22528
	ds_read_b128 v[212:215], v201 offset:23552
	global_load_lds_dwordx4 v[158:159], off
	s_add_i32 m0, s50, 0x2000
	s_add_u32 s50, s22, 0x160000
	v_lshl_add_u64 v[192:193], s[22:23], 0, v[162:163]
	s_addc_u32 s51, s23, 0
	s_add_i32 s52, s42, s30
	global_load_lds_dwordx4 v[192:193], off
	v_lshl_add_u64 v[216:217], s[50:51], 0, v[160:161]
	s_mov_b32 m0, s52
	v_lshl_add_u64 v[218:219], s[24:25], 0, v[162:163]
	global_load_lds_dwordx4 v[216:217], off
	v_lshl_add_u64 v[216:217], s[50:51], 0, v[162:163]
	s_add_i32 m0, s52, 0x2000
	s_nop 0
	global_load_lds_dwordx4 v[216:217], off
	v_lshl_add_u64 v[216:217], s[24:25], 0, v[160:161]
	s_mov_b32 m0, s31
	s_nop 0
	global_load_lds_dwordx4 v[216:217], off
	s_mov_b32 m0, s33
	s_nop 0
	global_load_lds_dwordx4 v[218:219], off
	s_waitcnt vmcnt(8)
	s_waitcnt lgkmcnt(0)
	s_barrier
; #define PG8_STAGE(bufoff, gbase, voff) do { _Pragma("unroll") for (int _i = 0; _i < 2; ++_i) \
;         __builtin_amdgcn_global_load_lds((const unsigned*)((const char*)(gbase) + (voff)[_i]), (PG8_LAS unsigned*)(lds + (bufoff) + ldsw + _i * 8192), 16, 0, 0); } while (0)
; #define PG8_LDA(dst, b, h) do { _Pragma("unroll") for (int m = 0; m < 4; ++m) _Pragma("unroll") for (int k = 0; k < 2; ++k) dst[m][k] = *(const PG8_LAS bf16x8*)(lds + PG8_SA(b, h) + aoff + m * 2048 + k * 1024); } while (0)
; #define PG8_LDB(dst, b, h) do { _Pragma("unroll") for (int n = 0; n < 2; ++n) _Pragma("unroll") for (int k = 0; k < 2; ++k) dst[n][k] = *(const PG8_LAS bf16x8*)(lds + PG8_SB(b, h) + boff + n * 2048 + k * 1024); } while (0)
; #define PG8_MMA(ai, bj, At, Bt) do { __builtin_amdgcn_s_setprio(1); _Pragma("unroll") for (int m = 0; m < 4; ++m) _Pragma("unroll") for (int n = 0; n < 2; ++n) _Pragma("unroll") for (int k = 0; k < 2; ++k) \
;         acc[ai][bj][m][n] = __builtin_amdgcn_mfma_f32_16x16x32_bf16(Bt[n][k], At[m][k], acc[ai][bj][m][n], 0, 0, 0); __builtin_amdgcn_s_setprio(0); } while (0)
; #define PG8_WAIT_V(n) asm volatile("s_waitcnt vmcnt(" #n ")" ::: "memory")
; template <class Epi, class Sched, bool ALIGN_EPI = false, bool SP2 = false>
; __device__ __forceinline__ void gemm_phase(PG8_LAS unsigned char* lds, const Gemm g, const Sched& S, const Epi& E) {
;     ...
;             PG8_LDB(B0, 0, 0); PG8_LDB(B1, 0, 1); PG8_SCHED; PG8_LDA(At, 0, 0); PG8_STAGE(PG8_SA(1, 1), a1 + hstep, voffA);
;             PG8_WAIT_V(8); PG8_WAIT_L(0); PG8_BAR; PG8_MMA(0, 0, At, B0); PG8_MMA(0, 1, At, B1); PG8_BAR; PG8_SCHED;
;             PG8_LDA(At, 0, 1); PG8_STAGE(PG8_SB(0, 0), b2, voffB); PG8_STAGE(PG8_SB(0, 1), b2 + hstep, voffB); PG8_STAGE(PG8_SA(0, 0), a2, voffA);
;             PG8_WAIT_V(8); PG8_WAIT_L(0); PG8_BAR; PG8_MMA(1, 0, At, B0); PG8_MMA(1, 1, At, B1); PG8_BAR; PG8_SCHED;
;             PG8_LDB(B0, 1, 0); PG8_LDB(B1, 1, 1); PG8_SCHED; PG8_LDA(At, 1, 0); PG8_STAGE(PG8_SA(0, 1), a2 + hstep, voffA);
;             PG8_WAIT_V(8); PG8_WAIT_L(0); PG8_BAR; PG8_MMA(0, 0, At, B0); PG8_MMA(0, 1, At, B1); PG8_BAR; PG8_SCHED;
;             PG8_LDA(At, 1, 1); PG8_STAGE(PG8_SB(1, 0), b3, voffB); PG8_STAGE(PG8_SB(1, 1), b3 + hstep, voffB); PG8_STAGE(PG8_SA(1, 0), a3, voffA);
;             PG8_WAIT_V(8); PG8_WAIT_L(0); PG8_BAR; PG8_MMA(1, 0, At, B0); PG8_MMA(1, 1, At, B1); PG8_BAR; PG8_SCHED;
	s_setprio 1
	s_waitcnt lgkmcnt(0)
	v_mfma_f32_16x16x32_bf16 v[60:63], v[128:131], v[172:175], v[60:63]
	v_mfma_f32_16x16x32_bf16 v[60:63], v[132:135], v[176:179], v[60:63]
	v_mfma_f32_16x16x32_bf16 v[56:59], v[140:143], v[176:179], v[56:59]
	v_mfma_f32_16x16x32_bf16 v[56:59], v[136:139], v[172:175], v[56:59]
	v_mfma_f32_16x16x32_bf16 v[40:43], v[136:139], v[180:183], v[40:43]
	v_mfma_f32_16x16x32_bf16 v[40:43], v[140:143], v[184:187], v[40:43]
	v_mfma_f32_16x16x32_bf16 v[44:47], v[132:135], v[184:187], v[44:47]
	v_mfma_f32_16x16x32_bf16 v[44:47], v[128:131], v[180:183], v[44:47]
	v_mfma_f32_16x16x32_bf16 v[28:31], v[128:131], v[188:191], v[28:31]
	v_mfma_f32_16x16x32_bf16 v[28:31], v[132:135], v[204:207], v[28:31]
	v_mfma_f32_16x16x32_bf16 v[24:27], v[140:143], v[204:207], v[24:27]
	v_mfma_f32_16x16x32_bf16 v[24:27], v[136:139], v[188:191], v[24:27]
	v_mfma_f32_16x16x32_bf16 v[8:11], v[136:139], v[208:211], v[8:11]
	v_mfma_f32_16x16x32_bf16 v[8:11], v[140:143], v[212:215], v[8:11]
	v_mfma_f32_16x16x32_bf16 v[12:15], v[132:135], v[212:215], v[12:15]
	v_mfma_f32_16x16x32_bf16 v[12:15], v[128:131], v[208:211], v[12:15]
	s_setprio 0
	s_setprio 1
	v_mfma_f32_16x16x32_bf16 v[52:55], v[150:153], v[172:175], v[52:55]
	v_mfma_f32_16x16x32_bf16 v[52:55], v[154:157], v[176:179], v[52:55]
	v_mfma_f32_16x16x32_bf16 v[48:51], v[168:171], v[176:179], v[48:51]
	v_mfma_f32_16x16x32_bf16 v[48:51], v[164:167], v[172:175], v[48:51]
	v_mfma_f32_16x16x32_bf16 v[32:35], v[164:167], v[180:183], v[32:35]
	v_mfma_f32_16x16x32_bf16 v[32:35], v[168:171], v[184:187], v[32:35]
	v_mfma_f32_16x16x32_bf16 v[36:39], v[154:157], v[184:187], v[36:39]
	v_mfma_f32_16x16x32_bf16 v[36:39], v[150:153], v[180:183], v[36:39]
	v_mfma_f32_16x16x32_bf16 v[20:23], v[150:153], v[188:191], v[20:23]
	v_mfma_f32_16x16x32_bf16 v[20:23], v[154:157], v[204:207], v[20:23]
	v_mfma_f32_16x16x32_bf16 v[16:19], v[168:171], v[204:207], v[16:19]
	v_mfma_f32_16x16x32_bf16 v[16:19], v[164:167], v[188:191], v[16:19]
	s_setprio 2
	s_barrier
	v_mfma_f32_16x16x32_bf16 v[0:3], v[164:167], v[208:211], v[0:3]
	v_mfma_f32_16x16x32_bf16 v[0:3], v[168:171], v[212:215], v[0:3]
	v_mfma_f32_16x16x32_bf16 v[4:7], v[154:157], v[212:215], v[4:7]
	v_mfma_f32_16x16x32_bf16 v[4:7], v[150:153], v[208:211], v[4:7]
	s_setprio 0
	s_add_i32 s50, 0, 0x18000
	s_add_i32 s51, 0, 0x1c000
	v_add_u32_e32 v140, s50, v196
	v_add_u32_e32 v168, s51, v196
	ds_read_b128 v[128:131], v140
	ds_read_b128 v[132:135], v140 offset:1024
	ds_read_b128 v[136:139], v140 offset:2048
	ds_read_b128 v[140:143], v140 offset:3072
	ds_read_b128 v[150:153], v168
	ds_read_b128 v[154:157], v168 offset:1024
	ds_read_b128 v[164:167], v168 offset:2048
	ds_read_b128 v[168:171], v168 offset:3072
	s_add_u32 s24, s24, 0x160000
	s_addc_u32 s25, s25, 0
	s_mov_b32 m0, s34
	v_lshl_add_u64 v[220:221], s[24:25], 0, v[160:161]
	ds_read_b128 v[172:175], v201 offset:32768
	ds_read_b128 v[176:179], v201 offset:33792
	ds_read_b128 v[180:183], v201 offset:34816
	ds_read_b128 v[184:187], v201 offset:35840
	ds_read_b128 v[188:191], v201 offset:36864
	ds_read_b128 v[204:207], v201 offset:37888
	ds_read_b128 v[208:211], v201 offset:38912
	ds_read_b128 v[212:215], v201 offset:39936
	global_load_lds_dwordx4 v[220:221], off
	v_lshl_add_u64 v[220:221], s[24:25], 0, v[162:163]
	s_mov_b32 m0, s35
	s_nop 0
	global_load_lds_dwordx4 v[220:221], off
	s_waitcnt vmcnt(8)
	s_waitcnt lgkmcnt(0)
	s_barrier
	s_setprio 1
	s_waitcnt lgkmcnt(0)
	v_mfma_f32_16x16x32_bf16 v[124:127], v[128:131], v[172:175], v[124:127]
	v_mfma_f32_16x16x32_bf16 v[124:127], v[132:135], v[176:179], v[124:127]
	v_mfma_f32_16x16x32_bf16 v[120:123], v[140:143], v[176:179], v[120:123]
	v_mfma_f32_16x16x32_bf16 v[120:123], v[136:139], v[172:175], v[120:123]
	v_mfma_f32_16x16x32_bf16 v[104:107], v[136:139], v[180:183], v[104:107]
	v_mfma_f32_16x16x32_bf16 v[104:107], v[140:143], v[184:187], v[104:107]
	v_mfma_f32_16x16x32_bf16 v[108:111], v[132:135], v[184:187], v[108:111]
	v_mfma_f32_16x16x32_bf16 v[108:111], v[128:131], v[180:183], v[108:111]
	v_mfma_f32_16x16x32_bf16 v[92:95], v[128:131], v[188:191], v[92:95]
	v_mfma_f32_16x16x32_bf16 v[92:95], v[132:135], v[204:207], v[92:95]
	v_mfma_f32_16x16x32_bf16 v[88:91], v[140:143], v[204:207], v[88:91]
	v_mfma_f32_16x16x32_bf16 v[88:91], v[136:139], v[188:191], v[88:91]
	v_mfma_f32_16x16x32_bf16 v[72:75], v[136:139], v[208:211], v[72:75]
	v_mfma_f32_16x16x32_bf16 v[72:75], v[140:143], v[212:215], v[72:75]
	v_mfma_f32_16x16x32_bf16 v[76:79], v[132:135], v[212:215], v[76:79]
	v_mfma_f32_16x16x32_bf16 v[76:79], v[128:131], v[208:211], v[76:79]
	s_setprio 0
	s_setprio 1
	v_mfma_f32_16x16x32_bf16 v[116:119], v[150:153], v[172:175], v[116:119]
	v_mfma_f32_16x16x32_bf16 v[116:119], v[154:157], v[176:179], v[116:119]
	v_mfma_f32_16x16x32_bf16 v[112:115], v[168:171], v[176:179], v[112:115]
	v_mfma_f32_16x16x32_bf16 v[112:115], v[164:167], v[172:175], v[112:115]
	v_mfma_f32_16x16x32_bf16 v[96:99], v[164:167], v[180:183], v[96:99]
	v_mfma_f32_16x16x32_bf16 v[96:99], v[168:171], v[184:187], v[96:99]
	v_mfma_f32_16x16x32_bf16 v[100:103], v[154:157], v[184:187], v[100:103]
	v_mfma_f32_16x16x32_bf16 v[100:103], v[150:153], v[180:183], v[100:103]
	v_mfma_f32_16x16x32_bf16 v[84:87], v[150:153], v[188:191], v[84:87]
	v_mfma_f32_16x16x32_bf16 v[84:87], v[154:157], v[204:207], v[84:87]
	v_mfma_f32_16x16x32_bf16 v[80:83], v[168:171], v[204:207], v[80:83]
	v_mfma_f32_16x16x32_bf16 v[80:83], v[164:167], v[188:191], v[80:83]
	s_setprio 2
	s_barrier
; #define PG8_STAGE(bufoff, gbase, voff) do { _Pragma("unroll") for (int _i = 0; _i < 2; ++_i) \
;         __builtin_amdgcn_global_load_lds((const unsigned*)((const char*)(gbase) + (voff)[_i]), (PG8_LAS unsigned*)(lds + (bufoff) + ldsw + _i * 8192), 16, 0, 0); } while (0)
; #define PG8_LDA(dst, b, h) do { _Pragma("unroll") for (int m = 0; m < 4; ++m) _Pragma("unroll") for (int k = 0; k < 2; ++k) dst[m][k] = *(const PG8_LAS bf16x8*)(lds + PG8_SA(b, h) + aoff + m * 2048 + k * 1024); } while (0)
; #define PG8_LDB(dst, b, h) do { _Pragma("unroll") for (int n = 0; n < 2; ++n) _Pragma("unroll") for (int k = 0; k < 2; ++k) dst[n][k] = *(const PG8_LAS bf16x8*)(lds + PG8_SB(b, h) + boff + n * 2048 + k * 1024); } while (0)
; template <class Epi, class Sched, bool ALIGN_EPI = false, bool SP2 = false>
; __device__ __forceinline__ void gemm_phase(PG8_LAS unsigned char* lds, const Gemm g, const Sched& S, const Epi& E) {
;     ...
;         for (int t = 0; t < nt; t += 2) {
;             const bool last = (t == nt - 2);
;             const char* a1 = cA + (size_t)(t + 1) * kstep;
;             const char* a2 = last ? nA : cA + (size_t)(t + 2) * kstep; const char* b2 = last ? nB : cB + (size_t)(t + 2) * kstep;
;             const char* a3 = a2 + kstep; const char* b3 = b2 + kstep;
;             if (last && has_next) S.a_ready(nxt);
;             if constexpr (SP2) {
;             PG8_LDB(B0, 0, 0); PG8_LDB(B1, 0, 1); PG8_SCHED; PG8_LDA(At, 0, 0); PG8_STAGE(PG8_SA(1, 1), a1 + hstep, voffA);
;             PG8_WAIT_V(8); PG8_WAIT_L(0); PG8_BAR; PG8_MMA(0, 0, At, B0); PG8_MMA(0, 1, At, B1); PG8_BAR; PG8_SCHED;
;             PG8_LDA(At, 0, 1); PG8_STAGE(PG8_SB(0, 0), b2, voffB); PG8_STAGE(PG8_SB(0, 1), b2 + hstep, voffB); PG8_STAGE(PG8_SA(0, 0), a2, voffA);
;             PG8_WAIT_V(8); PG8_WAIT_L(0); PG8_BAR; PG8_MMA(1, 0, At, B0); PG8_MMA(1, 1, At, B1); PG8_BAR; PG8_SCHED;
;             PG8_LDB(B0, 1, 0); PG8_LDB(B1, 1, 1); PG8_SCHED; PG8_LDA(At, 1, 0); PG8_STAGE(PG8_SA(0, 1), a2 + hstep, voffA);
;             PG8_WAIT_V(8); PG8_WAIT_L(0); PG8_BAR; PG8_MMA(0, 0, At, B0); PG8_MMA(0, 1, At, B1); PG8_BAR; PG8_SCHED;
;             PG8_LDA(At, 1, 1); PG8_STAGE(PG8_SB(1, 0), b3, voffB); PG8_STAGE(PG8_SB(1, 1), b3 + hstep, voffB); PG8_STAGE(PG8_SA(1, 0), a3, voffA);
;             PG8_WAIT_V(8); PG8_WAIT_L(0); PG8_BAR; PG8_MMA(1, 0, At, B0); PG8_MMA(1, 1, At, B1); PG8_BAR; PG8_SCHED;
	v_mfma_f32_16x16x32_bf16 v[64:67], v[164:167], v[208:211], v[64:67]
	v_mfma_f32_16x16x32_bf16 v[64:67], v[168:171], v[212:215], v[64:67]
	v_mfma_f32_16x16x32_bf16 v[68:71], v[154:157], v[212:215], v[68:71]
	v_mfma_f32_16x16x32_bf16 v[68:71], v[150:153], v[208:211], v[68:71]
	s_setprio 0
	s_add_i32 s24, s50, s30
	v_lshl_add_u64 v[158:159], v[158:159], 0, s[12:13]
	s_mov_b32 m0, s24
	ds_read_b128 v[172:175], v201 offset:49152
	ds_read_b128 v[176:179], v201 offset:50176
	ds_read_b128 v[180:183], v201 offset:51200
	ds_read_b128 v[184:187], v201 offset:52224
	ds_read_b128 v[188:191], v201 offset:53248
	ds_read_b128 v[204:207], v201 offset:54272
	ds_read_b128 v[208:211], v201 offset:55296
	ds_read_b128 v[212:215], v201 offset:56320
	global_load_lds_dwordx4 v[158:159], off
	s_add_i32 m0, s24, 0x2000
	s_add_u32 s22, s22, 0x160080
	v_lshl_add_u64 v[158:159], v[192:193], 0, s[12:13]
	s_addc_u32 s23, s23, 0
	s_add_i32 s24, s51, s30
	global_load_lds_dwordx4 v[158:159], off
	v_lshl_add_u64 v[158:159], s[22:23], 0, v[160:161]
	s_mov_b32 m0, s24
	s_nop 0
	global_load_lds_dwordx4 v[158:159], off
	v_lshl_add_u64 v[158:159], s[22:23], 0, v[162:163]
	s_add_i32 m0, s24, 0x2000
	s_nop 0
	global_load_lds_dwordx4 v[158:159], off
	v_lshl_add_u64 v[158:159], v[216:217], 0, s[12:13]
	s_mov_b32 m0, s39
	s_nop 0
	global_load_lds_dwordx4 v[158:159], off
	v_lshl_add_u64 v[158:159], v[218:219], 0, s[12:13]
	s_mov_b32 m0, s40
	s_nop 0
	global_load_lds_dwordx4 v[158:159], off
	s_waitcnt vmcnt(8)
	s_waitcnt lgkmcnt(0)
	s_barrier
	s_setprio 1
	s_waitcnt lgkmcnt(0)
	v_mfma_f32_16x16x32_bf16 v[60:63], v[128:131], v[172:175], v[60:63]
	v_mfma_f32_16x16x32_bf16 v[60:63], v[132:135], v[176:179], v[60:63]
	v_mfma_f32_16x16x32_bf16 v[56:59], v[140:143], v[176:179], v[56:59]
	v_mfma_f32_16x16x32_bf16 v[56:59], v[136:139], v[172:175], v[56:59]
	v_mfma_f32_16x16x32_bf16 v[40:43], v[136:139], v[180:183], v[40:43]
	v_mfma_f32_16x16x32_bf16 v[40:43], v[140:143], v[184:187], v[40:43]
	v_mfma_f32_16x16x32_bf16 v[44:47], v[132:135], v[184:187], v[44:47]
	v_mfma_f32_16x16x32_bf16 v[44:47], v[128:131], v[180:183], v[44:47]
	v_mfma_f32_16x16x32_bf16 v[28:31], v[128:131], v[188:191], v[28:31]
	v_mfma_f32_16x16x32_bf16 v[28:31], v[132:135], v[204:207], v[28:31]
	v_mfma_f32_16x16x32_bf16 v[24:27], v[140:143], v[204:207], v[24:27]
	v_mfma_f32_16x16x32_bf16 v[24:27], v[136:139], v[188:191], v[24:27]
	v_mfma_f32_16x16x32_bf16 v[8:11], v[136:139], v[208:211], v[8:11]
	v_mfma_f32_16x16x32_bf16 v[8:11], v[140:143], v[212:215], v[8:11]
	v_mfma_f32_16x16x32_bf16 v[12:15], v[132:135], v[212:215], v[12:15]
	v_mfma_f32_16x16x32_bf16 v[12:15], v[128:131], v[208:211], v[12:15]
	s_setprio 0
	s_setprio 1
	v_mfma_f32_16x16x32_bf16 v[52:55], v[150:153], v[172:175], v[52:55]
	v_mfma_f32_16x16x32_bf16 v[52:55], v[154:157], v[176:179], v[52:55]
	v_mfma_f32_16x16x32_bf16 v[48:51], v[168:171], v[176:179], v[48:51]
	v_mfma_f32_16x16x32_bf16 v[48:51], v[164:167], v[172:175], v[48:51]
	v_mfma_f32_16x16x32_bf16 v[32:35], v[164:167], v[180:183], v[32:35]
	v_mfma_f32_16x16x32_bf16 v[32:35], v[168:171], v[184:187], v[32:35]
	v_mfma_f32_16x16x32_bf16 v[36:39], v[154:157], v[184:187], v[36:39]
	v_mfma_f32_16x16x32_bf16 v[36:39], v[150:153], v[180:183], v[36:39]
	v_mfma_f32_16x16x32_bf16 v[20:23], v[150:153], v[188:191], v[20:23]
	v_mfma_f32_16x16x32_bf16 v[20:23], v[154:157], v[204:207], v[20:23]
	v_mfma_f32_16x16x32_bf16 v[16:19], v[168:171], v[204:207], v[16:19]
	v_mfma_f32_16x16x32_bf16 v[16:19], v[164:167], v[188:191], v[16:19]
	s_setprio 2
	s_barrier
	v_mfma_f32_16x16x32_bf16 v[0:3], v[164:167], v[208:211], v[0:3]
	v_mfma_f32_16x16x32_bf16 v[0:3], v[168:171], v[212:215], v[0:3]
	v_mfma_f32_16x16x32_bf16 v[4:7], v[154:157], v[212:215], v[4:7]
	v_mfma_f32_16x16x32_bf16 v[4:7], v[150:153], v[208:211], v[4:7]
	s_setprio 0
	s_add_i32 s49, s49, 2
	s_add_u32 s20, s20, 0x100
	s_addc_u32 s21, s21, 0
	s_add_u32 s47, s47, 0x100
	s_addc_u32 s48, s48, 0
	s_cmpk_gt_u32 s49, 0x55
	s_cbranch_scc0 .LBB0_937
	s_and_b64 vcc, exec, s[14:15]
	s_cbranch_vccz .LBB0_940
	s_barrier
